# issue LDS-DMA tile loads from inside the MFMA blocks (after 4th and 10th MFMA) instead of the load segment, E and A loops
# baseline (speedup 1.0000x reference)
; #define PG8_STAGE(bufoff, gbase, voff) do { _Pragma("unroll") for (int _i = 0; _i < 2; ++_i) \
;         __builtin_amdgcn_global_load_lds((const unsigned*)((const char*)(gbase) + (voff)[_i]), (LAS unsigned*)(lds + (bufoff) + ldsw + _i * 8192), 16, 0, 0); } while (0)
; #define PG8_LDA(dst, b, h) do { _Pragma("unroll") for (int m = 0; m < 4; ++m) _Pragma("unroll") for (int k = 0; k < 2; ++k) dst[m][k] = *(const LAS bf16x8*)(lds + PG8_SA(b, h) + aoff + m * 2048 + k * 1024); } while (0)
; #define PG8_LDB(dst, b, h) do { _Pragma("unroll") for (int n = 0; n < 2; ++n) _Pragma("unroll") for (int k = 0; k < 2; ++k) dst[n][k] = *(const LAS bf16x8*)(lds + PG8_SB(b, h) + boff + n * 2048 + k * 1024); } while (0)
; #define PG8_MMA(ai, bj, At, Bt) do { __builtin_amdgcn_s_setprio(1); _Pragma("unroll") for (int m = 0; m < 4; ++m) _Pragma("unroll") for (int n = 0; n < 2; ++n) _Pragma("unroll") for (int k = 0; k < 2; ++k) \
;         acc[ai][bj][m][n] = __builtin_amdgcn_mfma_f32_16x16x32_bf16(Bt[n][k], At[m][k], acc[ai][bj][m][n], 0, 0, 0); __builtin_amdgcn_s_setprio(0); } while (0)
; #define PG8_WAIT_V(n) asm volatile("s_waitcnt vmcnt(" #n ")" ::: "memory")
; #define PG8_WAIT_L(n) asm volatile("s_waitcnt lgkmcnt(" #n ")" ::: "memory")
; #define PG8_BAR __builtin_amdgcn_s_barrier()
; #define PG8_SCHED __builtin_amdgcn_sched_barrier(0)
; template <class Epi>
; __device__ __forceinline__ void gemm_phase(LAS unsigned char* lds, const Gemm g, const StaticOrder& S, const Epi& E) {
;     ...
;             PG8_LDB(B0, 0, 0); PG8_SCHED; PG8_LDA(At, 0, 0); PG8_STAGE(PG8_SA(1, 1), a1 + hstep, voffA);
;             PG8_WAIT_L(8); PG8_BAR; PG8_WAIT_L(0); PG8_MMA(0, 0, At, B0); PG8_BAR; PG8_SCHED;
;             PG8_LDB(B1, 0, 1); PG8_STAGE(PG8_SB(0, 0), b2, voffB);
;             PG8_BAR; PG8_WAIT_L(0); PG8_MMA(0, 1, At, B1); PG8_BAR;
;             PG8_LDA(At, 0, 1); PG8_STAGE(PG8_SA(0, 0), a2, voffA);
;             PG8_BAR; PG8_WAIT_L(0); PG8_MMA(1, 0, At, B0); PG8_BAR; PG8_SCHED;
;             PG8_STAGE(PG8_SB(0, 1), b2 + hstep, voffB);
;             PG8_WAIT_V(6); PG8_BAR; PG8_MMA(1, 1, At, B1); PG8_BAR;
.LBB0_170:
	s_add_u32 s6, s36, 0xfffc0080
	s_addc_u32 s7, s37, -1
	s_add_i32 s58, 0, 0x10000
	v_add_u32_e32 v144, s58, v147
	ds_read_b128 v[140:143], v144
	ds_read_b128 v[152:155], v144 offset:1024
	ds_read_b128 v[168:171], v144 offset:2048
	ds_read_b128 v[172:175], v144 offset:3072
	s_cmp_eq_u32 s93, 12
	s_cselect_b32 s43, s11, s7
	s_cselect_b32 s42, s71, s6
	s_cselect_b32 s7, s9, s92
	s_cselect_b32 s6, s90, s91
	ds_read_b128 v[176:179], v150
	ds_read_b128 v[180:183], v150 offset:1024
	ds_read_b128 v[184:187], v150 offset:2048
	ds_read_b128 v[204:207], v150 offset:3072
	ds_read_b128 v[208:211], v150 offset:4096
	ds_read_b128 v[212:215], v150 offset:5120
	ds_read_b128 v[216:219], v150 offset:6144
	ds_read_b128 v[226:229], v150 offset:7168
	s_waitcnt lgkmcnt(8)
	s_barrier
	s_waitcnt lgkmcnt(0)
	s_setprio 1
	s_waitcnt lgkmcnt(0)
	v_mfma_f32_16x16x32_bf16 v[126:129], v[140:143], v[176:179], 0
	v_mfma_f32_16x16x32_bf16 v[122:125], v[168:171], v[176:179], 0
	v_mfma_f32_16x16x32_bf16 v[110:113], v[140:143], v[184:187], 0
	v_mfma_f32_16x16x32_bf16 v[106:109], v[168:171], v[184:187], 0
	s_add_i32 m0, s49, 0xc000
	s_nop 0
	global_load_lds_dwordx4 v136, s[36:37]
	v_mfma_f32_16x16x32_bf16 v[94:97], v[140:143], v[208:211], 0
	v_mfma_f32_16x16x32_bf16 v[90:93], v[168:171], v[208:211], 0
	v_mfma_f32_16x16x32_bf16 v[78:81], v[140:143], v[216:219], 0
	v_mfma_f32_16x16x32_bf16 v[74:77], v[168:171], v[216:219], 0
	v_mfma_f32_16x16x32_bf16 v[126:129], v[152:155], v[180:183], v[126:129]
	v_mfma_f32_16x16x32_bf16 v[122:125], v[172:175], v[180:183], v[122:125]
	s_add_i32 m0, s49, 0xe000
	s_nop 0
	global_load_lds_dwordx4 v138, s[36:37]
	v_mfma_f32_16x16x32_bf16 v[110:113], v[152:155], v[204:207], v[110:113]
	v_mfma_f32_16x16x32_bf16 v[106:109], v[172:175], v[204:207], v[106:109]
	v_mfma_f32_16x16x32_bf16 v[94:97], v[152:155], v[212:215], v[94:97]
	v_mfma_f32_16x16x32_bf16 v[90:93], v[172:175], v[212:215], v[90:93]
	v_mfma_f32_16x16x32_bf16 v[78:81], v[152:155], v[226:229], v[78:81]
	v_mfma_f32_16x16x32_bf16 v[74:77], v[172:175], v[226:229], v[74:77]
	s_setprio 0
	s_barrier
	s_add_i32 s70, 0, 0x14000
	v_add_u32_e32 v144, s70, v147
	s_add_i32 s58, s58, s48
	ds_read_b128 v[230:233], v144
	ds_read_b128 v[234:237], v144 offset:1024
	ds_read_b128 v[238:241], v144 offset:2048
	ds_read_b128 v[242:245], v144 offset:3072
	s_barrier
	s_waitcnt lgkmcnt(0)
	s_setprio 1
	s_waitcnt lgkmcnt(0)
	v_mfma_f32_16x16x32_bf16 v[118:121], v[230:233], v[176:179], 0
	v_mfma_f32_16x16x32_bf16 v[114:117], v[238:241], v[176:179], 0
	v_mfma_f32_16x16x32_bf16 v[102:105], v[230:233], v[184:187], 0
	v_mfma_f32_16x16x32_bf16 v[98:101], v[238:241], v[184:187], 0
	s_mov_b32 m0, s58
	s_nop 0
	global_load_lds_dwordx4 v0, s[6:7]
	v_mfma_f32_16x16x32_bf16 v[86:89], v[230:233], v[208:211], 0
	v_mfma_f32_16x16x32_bf16 v[82:85], v[238:241], v[208:211], 0
	v_mfma_f32_16x16x32_bf16 v[70:73], v[230:233], v[216:219], 0
	v_mfma_f32_16x16x32_bf16 v[66:69], v[238:241], v[216:219], 0
	v_mfma_f32_16x16x32_bf16 v[118:121], v[234:237], v[180:183], v[118:121]
	v_mfma_f32_16x16x32_bf16 v[114:117], v[242:245], v[180:183], v[114:117]
	s_add_i32 m0, s58, 0x2000
	s_nop 0
	global_load_lds_dwordx4 v130, s[6:7]
	v_mfma_f32_16x16x32_bf16 v[102:105], v[234:237], v[204:207], v[102:105]
	v_mfma_f32_16x16x32_bf16 v[98:101], v[242:245], v[204:207], v[98:101]
	v_mfma_f32_16x16x32_bf16 v[86:89], v[234:237], v[212:215], v[86:89]
	v_mfma_f32_16x16x32_bf16 v[82:85], v[242:245], v[212:215], v[82:85]
	v_mfma_f32_16x16x32_bf16 v[70:73], v[234:237], v[226:229], v[70:73]
	v_mfma_f32_16x16x32_bf16 v[66:69], v[242:245], v[226:229], v[66:69]
	s_setprio 0
	s_add_u32 vcc_lo, s42, 0x80
	s_addc_u32 vcc_hi, s43, 0
	s_barrier
	ds_read_b128 v[176:179], v150 offset:16384
	ds_read_b128 v[180:183], v150 offset:17408
	ds_read_b128 v[184:187], v150 offset:18432
	ds_read_b128 v[204:207], v150 offset:19456
	ds_read_b128 v[208:211], v150 offset:20480
	ds_read_b128 v[212:215], v150 offset:21504
	ds_read_b128 v[216:219], v150 offset:22528
	ds_read_b128 v[226:229], v150 offset:23552
	s_barrier
	s_waitcnt lgkmcnt(0)
	s_setprio 1
	s_waitcnt lgkmcnt(0)
	v_mfma_f32_16x16x32_bf16 v[62:65], v[140:143], v[176:179], 0
	v_mfma_f32_16x16x32_bf16 v[58:61], v[168:171], v[176:179], 0
	v_mfma_f32_16x16x32_bf16 v[46:49], v[140:143], v[184:187], 0
	v_mfma_f32_16x16x32_bf16 v[42:45], v[168:171], v[184:187], 0
	s_mov_b32 m0, s49
	s_nop 0
	global_load_lds_dwordx4 v134, s[42:43]
	v_mfma_f32_16x16x32_bf16 v[30:33], v[140:143], v[208:211], 0
	v_mfma_f32_16x16x32_bf16 v[26:29], v[168:171], v[208:211], 0
	v_mfma_f32_16x16x32_bf16 v[14:17], v[140:143], v[216:219], 0
	v_mfma_f32_16x16x32_bf16 v[10:13], v[168:171], v[216:219], 0
	v_mfma_f32_16x16x32_bf16 v[62:65], v[152:155], v[180:183], v[62:65]
	v_mfma_f32_16x16x32_bf16 v[58:61], v[172:175], v[180:183], v[58:61]
	s_mov_b32 m0, s54
	s_nop 0
	global_load_lds_dwordx4 v132, s[42:43]
	v_mfma_f32_16x16x32_bf16 v[46:49], v[152:155], v[204:207], v[46:49]
	v_mfma_f32_16x16x32_bf16 v[42:45], v[172:175], v[204:207], v[42:45]
	v_mfma_f32_16x16x32_bf16 v[30:33], v[152:155], v[212:215], v[30:33]
	v_mfma_f32_16x16x32_bf16 v[26:29], v[172:175], v[212:215], v[26:29]
	v_mfma_f32_16x16x32_bf16 v[14:17], v[152:155], v[226:229], v[14:17]
	v_mfma_f32_16x16x32_bf16 v[10:13], v[172:175], v[226:229], v[10:13]
	s_setprio 0
	s_barrier
	s_add_u32 s60, s6, 0x40000
	s_addc_u32 s61, s7, 0
	s_add_i32 s58, s70, s48
	s_waitcnt vmcnt(4)
	s_barrier
	s_setprio 1
	v_mfma_f32_16x16x32_bf16 v[54:57], v[230:233], v[176:179], 0
	v_mfma_f32_16x16x32_bf16 v[50:53], v[238:241], v[176:179], 0
	s_cmp_eq_u32 s89, 0
	s_cbranch_scc1 .LdsE_skip_0
	global_store_dwordx4 v250, v[158:161], s[4:5]
; #define PG8_STAGE(bufoff, gbase, voff) do { _Pragma("unroll") for (int _i = 0; _i < 2; ++_i) \
;         __builtin_amdgcn_global_load_lds((const unsigned*)((const char*)(gbase) + (voff)[_i]), (LAS unsigned*)(lds + (bufoff) + ldsw + _i * 8192), 16, 0, 0); } while (0)
; #define PG8_LDA(dst, b, h) do { _Pragma("unroll") for (int m = 0; m < 4; ++m) _Pragma("unroll") for (int k = 0; k < 2; ++k) dst[m][k] = *(const LAS bf16x8*)(lds + PG8_SA(b, h) + aoff + m * 2048 + k * 1024); } while (0)
; #define PG8_LDB(dst, b, h) do { _Pragma("unroll") for (int n = 0; n < 2; ++n) _Pragma("unroll") for (int k = 0; k < 2; ++k) dst[n][k] = *(const LAS bf16x8*)(lds + PG8_SB(b, h) + boff + n * 2048 + k * 1024); } while (0)
; #define PG8_MMA(ai, bj, At, Bt) do { __builtin_amdgcn_s_setprio(1); _Pragma("unroll") for (int m = 0; m < 4; ++m) _Pragma("unroll") for (int n = 0; n < 2; ++n) _Pragma("unroll") for (int k = 0; k < 2; ++k) \
;         acc[ai][bj][m][n] = __builtin_amdgcn_mfma_f32_16x16x32_bf16(Bt[n][k], At[m][k], acc[ai][bj][m][n], 0, 0, 0); __builtin_amdgcn_s_setprio(0); } while (0)
; #define PG8_WAIT_V(n) asm volatile("s_waitcnt vmcnt(" #n ")" ::: "memory")
; #define PG8_WAIT_L(n) asm volatile("s_waitcnt lgkmcnt(" #n ")" ::: "memory")
; #define PG8_BAR __builtin_amdgcn_s_barrier()
; #define PG8_SCHED __builtin_amdgcn_sched_barrier(0)
; template <class Epi>
; __device__ __forceinline__ void gemm_phase(LAS unsigned char* lds, const Gemm g, const StaticOrder& S, const Epi& E) {
;     ...
;             PG8_WAIT_V(6); PG8_BAR; PG8_MMA(1, 1, At, B1); PG8_BAR;
;             PG8_LDB(B0, 1, 0); PG8_SCHED; PG8_LDA(At, 1, 0); PG8_STAGE(PG8_SA(0, 1), a2 + hstep, voffA);
;             PG8_WAIT_L(8); PG8_BAR; PG8_WAIT_L(0); PG8_MMA(0, 0, At, B0); PG8_BAR; PG8_SCHED;
;             PG8_LDB(B1, 1, 1); PG8_STAGE(PG8_SB(1, 0), b3, voffB);
;             PG8_BAR; PG8_WAIT_L(0); PG8_MMA(0, 1, At, B1); PG8_BAR;
;             PG8_LDA(At, 1, 1); PG8_STAGE(PG8_SA(1, 0), a3, voffA);
;             PG8_BAR; PG8_WAIT_L(0); PG8_MMA(1, 0, At, B0); PG8_BAR; PG8_SCHED;
.LdsE_skip_0:
	v_mfma_f32_16x16x32_bf16 v[38:41], v[230:233], v[184:187], 0
	v_mfma_f32_16x16x32_bf16 v[34:37], v[238:241], v[184:187], 0
	s_mov_b32 m0, s58
	s_nop 0
	global_load_lds_dwordx4 v0, s[60:61]
	v_mfma_f32_16x16x32_bf16 v[22:25], v[230:233], v[208:211], 0
	v_mfma_f32_16x16x32_bf16 v[18:21], v[238:241], v[208:211], 0
	v_mfma_f32_16x16x32_bf16 v[6:9], v[230:233], v[216:219], 0
	v_mfma_f32_16x16x32_bf16 v[2:5], v[238:241], v[216:219], 0
	v_mfma_f32_16x16x32_bf16 v[54:57], v[234:237], v[180:183], v[54:57]
	v_mfma_f32_16x16x32_bf16 v[50:53], v[242:245], v[180:183], v[50:53]
	s_add_i32 m0, s58, 0x2000
	s_nop 0
	global_load_lds_dwordx4 v130, s[60:61]
	v_mfma_f32_16x16x32_bf16 v[38:41], v[234:237], v[204:207], v[38:41]
	v_mfma_f32_16x16x32_bf16 v[34:37], v[242:245], v[204:207], v[34:37]
	v_mfma_f32_16x16x32_bf16 v[22:25], v[234:237], v[212:215], v[22:25]
	v_mfma_f32_16x16x32_bf16 v[18:21], v[242:245], v[212:215], v[18:21]
	v_mfma_f32_16x16x32_bf16 v[6:9], v[234:237], v[226:229], v[6:9]
	v_mfma_f32_16x16x32_bf16 v[2:5], v[242:245], v[226:229], v[2:5]
	s_setprio 0
	s_add_i32 s58, 0, 0x18000
	v_add_u32_e32 v151, s58, v147
	s_barrier
	ds_read_b128 v[140:143], v151
	ds_read_b128 v[152:155], v151 offset:1024
	ds_read_b128 v[168:171], v151 offset:2048
	ds_read_b128 v[172:175], v151 offset:3072
	s_add_u32 s42, s42, 0x40000
	s_addc_u32 s43, s43, 0
	ds_read_b128 v[176:179], v150 offset:32768
	ds_read_b128 v[180:183], v150 offset:33792
	ds_read_b128 v[184:187], v150 offset:34816
	ds_read_b128 v[204:207], v150 offset:35840
	ds_read_b128 v[208:211], v150 offset:36864
	ds_read_b128 v[212:215], v150 offset:37888
	ds_read_b128 v[216:219], v150 offset:38912
	ds_read_b128 v[226:229], v150 offset:39936
	s_waitcnt lgkmcnt(8)
	s_barrier
	s_waitcnt lgkmcnt(0)
	s_setprio 1
	s_waitcnt lgkmcnt(0)
	v_mfma_f32_16x16x32_bf16 v[126:129], v[140:143], v[176:179], v[126:129]
	v_mfma_f32_16x16x32_bf16 v[122:125], v[168:171], v[176:179], v[122:125]
	v_mfma_f32_16x16x32_bf16 v[110:113], v[140:143], v[184:187], v[110:113]
	v_mfma_f32_16x16x32_bf16 v[106:109], v[168:171], v[184:187], v[106:109]
	s_mov_b32 m0, s55
	s_nop 0
	global_load_lds_dwordx4 v134, s[42:43]
	v_mfma_f32_16x16x32_bf16 v[94:97], v[140:143], v[208:211], v[94:97]
	v_mfma_f32_16x16x32_bf16 v[90:93], v[168:171], v[208:211], v[90:93]
	v_mfma_f32_16x16x32_bf16 v[78:81], v[140:143], v[216:219], v[78:81]
	v_mfma_f32_16x16x32_bf16 v[74:77], v[168:171], v[216:219], v[74:77]
	v_mfma_f32_16x16x32_bf16 v[126:129], v[152:155], v[180:183], v[126:129]
	v_mfma_f32_16x16x32_bf16 v[122:125], v[172:175], v[180:183], v[122:125]
	s_mov_b32 m0, s83
	s_nop 0
	global_load_lds_dwordx4 v132, s[42:43]
	v_mfma_f32_16x16x32_bf16 v[110:113], v[152:155], v[204:207], v[110:113]
	v_mfma_f32_16x16x32_bf16 v[106:109], v[172:175], v[204:207], v[106:109]
	v_mfma_f32_16x16x32_bf16 v[94:97], v[152:155], v[212:215], v[94:97]
	v_mfma_f32_16x16x32_bf16 v[90:93], v[172:175], v[212:215], v[90:93]
	v_mfma_f32_16x16x32_bf16 v[78:81], v[152:155], v[226:229], v[78:81]
	v_mfma_f32_16x16x32_bf16 v[74:77], v[172:175], v[226:229], v[74:77]
	s_setprio 0
	s_barrier
	s_add_i32 s42, 0, 0x1c000
	s_add_i32 s43, s58, s48
	v_add_u32_e32 v151, s42, v147
	s_add_u32 s60, s6, 0x80
	s_addc_u32 s61, s7, 0
	ds_read_b128 v[230:233], v151
	ds_read_b128 v[234:237], v151 offset:1024
	ds_read_b128 v[238:241], v151 offset:2048
	ds_read_b128 v[242:245], v151 offset:3072
	s_barrier
	s_waitcnt lgkmcnt(0)
	s_setprio 1
	s_waitcnt lgkmcnt(0)
	v_mfma_f32_16x16x32_bf16 v[118:121], v[230:233], v[176:179], v[118:121]
	v_mfma_f32_16x16x32_bf16 v[114:117], v[238:241], v[176:179], v[114:117]
	v_mfma_f32_16x16x32_bf16 v[102:105], v[230:233], v[184:187], v[102:105]
	v_mfma_f32_16x16x32_bf16 v[98:101], v[238:241], v[184:187], v[98:101]
	s_mov_b32 m0, s43
	s_nop 0
	global_load_lds_dwordx4 v0, s[60:61]
	v_mfma_f32_16x16x32_bf16 v[86:89], v[230:233], v[208:211], v[86:89]
	v_mfma_f32_16x16x32_bf16 v[82:85], v[238:241], v[208:211], v[82:85]
	v_mfma_f32_16x16x32_bf16 v[70:73], v[230:233], v[216:219], v[70:73]
	v_mfma_f32_16x16x32_bf16 v[66:69], v[238:241], v[216:219], v[66:69]
	v_mfma_f32_16x16x32_bf16 v[118:121], v[234:237], v[180:183], v[118:121]
	v_mfma_f32_16x16x32_bf16 v[114:117], v[242:245], v[180:183], v[114:117]
	s_add_i32 m0, s43, 0x2000
	s_nop 0
	global_load_lds_dwordx4 v130, s[60:61]
	v_mfma_f32_16x16x32_bf16 v[102:105], v[234:237], v[204:207], v[102:105]
	v_mfma_f32_16x16x32_bf16 v[98:101], v[242:245], v[204:207], v[98:101]
	v_mfma_f32_16x16x32_bf16 v[86:89], v[234:237], v[212:215], v[86:89]
	v_mfma_f32_16x16x32_bf16 v[82:85], v[242:245], v[212:215], v[82:85]
	v_mfma_f32_16x16x32_bf16 v[70:73], v[234:237], v[226:229], v[70:73]
	v_mfma_f32_16x16x32_bf16 v[66:69], v[242:245], v[226:229], v[66:69]
	s_setprio 0
	s_barrier
	ds_read_b128 v[176:179], v150 offset:49152
	ds_read_b128 v[180:183], v150 offset:50176
	ds_read_b128 v[184:187], v150 offset:51200
	ds_read_b128 v[204:207], v150 offset:52224
	ds_read_b128 v[208:211], v150 offset:53248
	ds_read_b128 v[212:215], v150 offset:54272
	ds_read_b128 v[216:219], v150 offset:55296
	ds_read_b128 v[226:229], v150 offset:56320
	s_barrier
; #define PG8_STAGE(bufoff, gbase, voff) do { _Pragma("unroll") for (int _i = 0; _i < 2; ++_i) \
;         __builtin_amdgcn_global_load_lds((const unsigned*)((const char*)(gbase) + (voff)[_i]), (LAS unsigned*)(lds + (bufoff) + ldsw + _i * 8192), 16, 0, 0); } while (0)
; #define PG8_LDA(dst, b, h) do { _Pragma("unroll") for (int m = 0; m < 4; ++m) _Pragma("unroll") for (int k = 0; k < 2; ++k) dst[m][k] = *(const LAS bf16x8*)(lds + PG8_SA(b, h) + aoff + m * 2048 + k * 1024); } while (0)
; #define PG8_LDB(dst, b, h) do { _Pragma("unroll") for (int n = 0; n < 2; ++n) _Pragma("unroll") for (int k = 0; k < 2; ++k) dst[n][k] = *(const LAS bf16x8*)(lds + PG8_SB(b, h) + boff + n * 2048 + k * 1024); } while (0)
; #define PG8_WAIT_V(n) asm volatile("s_waitcnt vmcnt(" #n ")" ::: "memory")
; #define PG8_WAIT_L(n) asm volatile("s_waitcnt lgkmcnt(" #n ")" ::: "memory")
; #define PG8_BAR __builtin_amdgcn_s_barrier()
; #define PG8_SCHED __builtin_amdgcn_sched_barrier(0)
; template <class Epi>
; __device__ __forceinline__ void gemm_phase(LAS unsigned char* lds, const Gemm g, const StaticOrder& S, const Epi& E) {
;     ...
;             PG8_LDB(B0, 0, 0); PG8_SCHED; PG8_LDA(At, 0, 0); PG8_STAGE(PG8_SA(1, 1), a1 + hstep, voffA);
;             PG8_WAIT_L(8); PG8_BAR; PG8_WAIT_L(0); PG8_MMA(0, 0, At, B0); PG8_BAR; PG8_SCHED;
;             PG8_LDB(B1, 0, 1); PG8_STAGE(PG8_SB(0, 0), b2, voffB);
;             PG8_BAR; PG8_WAIT_L(0); PG8_MMA(0, 1, At, B1); PG8_BAR;
;             PG8_LDA(At, 0, 1); PG8_STAGE(PG8_SA(0, 0), a2, voffA);
;             PG8_BAR; PG8_WAIT_L(0); PG8_MMA(1, 0, At, B0); PG8_BAR; PG8_SCHED;
;             PG8_STAGE(PG8_SB(0, 1), b2 + hstep, voffB);
;             PG8_WAIT_V(6); PG8_BAR; PG8_MMA(1, 1, At, B1); PG8_BAR;
;             PG8_LDB(B0, 1, 0); PG8_SCHED; PG8_LDA(At, 1, 0); PG8_STAGE(PG8_SA(0, 1), a2 + hstep, voffA);
;             PG8_WAIT_L(8); PG8_BAR; PG8_WAIT_L(0); PG8_MMA(0, 0, At, B0); PG8_BAR; PG8_SCHED;
;             PG8_LDB(B1, 1, 1); PG8_STAGE(PG8_SB(1, 0), b3, voffB);
;             PG8_BAR; PG8_WAIT_L(0); PG8_MMA(0, 1, At, B1); PG8_BAR;
;             PG8_LDA(At, 1, 1); PG8_STAGE(PG8_SA(1, 0), a3, voffA);
;             PG8_BAR; PG8_WAIT_L(0); PG8_MMA(1, 0, At, B0); PG8_BAR; PG8_SCHED;
;             PG8_STAGE(PG8_SB(1, 1), b3 + hstep, voffB);
;             PG8_WAIT_V(6); PG8_BAR; PG8_MMA(1, 1, At, B1); PG8_BAR;
	s_waitcnt lgkmcnt(0)
	s_setprio 1
	s_waitcnt lgkmcnt(0)
	v_mfma_f32_16x16x32_bf16 v[62:65], v[140:143], v[176:179], v[62:65]
	v_mfma_f32_16x16x32_bf16 v[58:61], v[168:171], v[176:179], v[58:61]
	v_mfma_f32_16x16x32_bf16 v[46:49], v[140:143], v[184:187], v[46:49]
	v_mfma_f32_16x16x32_bf16 v[42:45], v[168:171], v[184:187], v[42:45]
	s_mov_b32 m0, s84
	s_nop 0
	global_load_lds_dwordx4 v134, vcc
	v_mfma_f32_16x16x32_bf16 v[30:33], v[140:143], v[208:211], v[30:33]
	v_mfma_f32_16x16x32_bf16 v[26:29], v[168:171], v[208:211], v[26:29]
	v_mfma_f32_16x16x32_bf16 v[14:17], v[140:143], v[216:219], v[14:17]
	v_mfma_f32_16x16x32_bf16 v[10:13], v[168:171], v[216:219], v[10:13]
	v_mfma_f32_16x16x32_bf16 v[62:65], v[152:155], v[180:183], v[62:65]
	v_mfma_f32_16x16x32_bf16 v[58:61], v[172:175], v[180:183], v[58:61]
	s_mov_b32 m0, s85
	s_nop 0
	global_load_lds_dwordx4 v132, vcc
	v_mfma_f32_16x16x32_bf16 v[46:49], v[152:155], v[204:207], v[46:49]
	v_mfma_f32_16x16x32_bf16 v[42:45], v[172:175], v[204:207], v[42:45]
	v_mfma_f32_16x16x32_bf16 v[30:33], v[152:155], v[212:215], v[30:33]
	v_mfma_f32_16x16x32_bf16 v[26:29], v[172:175], v[212:215], v[26:29]
	v_mfma_f32_16x16x32_bf16 v[14:17], v[152:155], v[226:229], v[14:17]
	v_mfma_f32_16x16x32_bf16 v[10:13], v[172:175], v[226:229], v[10:13]
	s_setprio 0
	s_barrier
	s_add_u32 s6, s6, 0x40080
	s_addc_u32 s7, s7, 0
	s_add_i32 s42, s42, s48
	s_waitcnt vmcnt(4)
	s_barrier
	s_setprio 1
	v_mfma_f32_16x16x32_bf16 v[54:57], v[230:233], v[176:179], v[54:57]
	v_mfma_f32_16x16x32_bf16 v[50:53], v[238:241], v[176:179], v[50:53]
	v_mfma_f32_16x16x32_bf16 v[38:41], v[230:233], v[184:187], v[38:41]
	v_mfma_f32_16x16x32_bf16 v[34:37], v[238:241], v[184:187], v[34:37]
	s_mov_b32 m0, s42
	s_nop 0
	global_load_lds_dwordx4 v0, s[6:7]
	v_mfma_f32_16x16x32_bf16 v[22:25], v[230:233], v[208:211], v[22:25]
	v_mfma_f32_16x16x32_bf16 v[18:21], v[238:241], v[208:211], v[18:21]
	v_mfma_f32_16x16x32_bf16 v[6:9], v[230:233], v[216:219], v[6:9]
	v_mfma_f32_16x16x32_bf16 v[2:5], v[238:241], v[216:219], v[2:5]
	v_mfma_f32_16x16x32_bf16 v[54:57], v[234:237], v[180:183], v[54:57]
	v_mfma_f32_16x16x32_bf16 v[50:53], v[242:245], v[180:183], v[50:53]
	s_add_i32 m0, s42, 0x2000
	s_nop 0
	global_load_lds_dwordx4 v130, s[6:7]
	v_mfma_f32_16x16x32_bf16 v[38:41], v[234:237], v[204:207], v[38:41]
	v_mfma_f32_16x16x32_bf16 v[34:37], v[242:245], v[204:207], v[34:37]
	v_mfma_f32_16x16x32_bf16 v[22:25], v[234:237], v[212:215], v[22:25]
	v_mfma_f32_16x16x32_bf16 v[18:21], v[242:245], v[212:215], v[18:21]
	v_mfma_f32_16x16x32_bf16 v[6:9], v[234:237], v[226:229], v[6:9]
	v_mfma_f32_16x16x32_bf16 v[2:5], v[242:245], v[226:229], v[2:5]
	s_setprio 0
	s_add_i32 s93, s93, 2
	s_add_u32 s36, s36, 0x100
	s_addc_u32 s37, s37, 0
	s_add_u32 s91, s91, 0x100
	s_addc_u32 s92, s92, 0
	s_cmp_gt_u32 s93, 13
	s_barrier
	s_add_u32 s6, s36, 0xfffc0080
	s_addc_u32 s7, s37, -1
	s_add_i32 s58, 0, 0x10000
	v_add_u32_e32 v144, s58, v147
	ds_read_b128 v[140:143], v144
	ds_read_b128 v[152:155], v144 offset:1024
	ds_read_b128 v[168:171], v144 offset:2048
	ds_read_b128 v[172:175], v144 offset:3072
	s_cmp_eq_u32 s93, 12
	s_cselect_b32 s43, s11, s7
	s_cselect_b32 s42, s71, s6
	s_cselect_b32 s7, s9, s92
	s_cselect_b32 s6, s90, s91
	ds_read_b128 v[176:179], v150
	ds_read_b128 v[180:183], v150 offset:1024
	ds_read_b128 v[184:187], v150 offset:2048
	ds_read_b128 v[204:207], v150 offset:3072
	ds_read_b128 v[208:211], v150 offset:4096
	ds_read_b128 v[212:215], v150 offset:5120
	ds_read_b128 v[216:219], v150 offset:6144
	ds_read_b128 v[226:229], v150 offset:7168
	s_waitcnt lgkmcnt(8)
	s_barrier
	s_waitcnt lgkmcnt(0)
	s_setprio 1
	s_waitcnt lgkmcnt(0)
	v_mfma_f32_16x16x32_bf16 v[126:129], v[140:143], v[176:179], v[126:129]
	v_mfma_f32_16x16x32_bf16 v[122:125], v[168:171], v[176:179], v[122:125]
	v_mfma_f32_16x16x32_bf16 v[110:113], v[140:143], v[184:187], v[110:113]
	v_mfma_f32_16x16x32_bf16 v[106:109], v[168:171], v[184:187], v[106:109]
	s_add_i32 m0, s49, 0xc000
	s_nop 0
	global_load_lds_dwordx4 v136, s[36:37]
	v_mfma_f32_16x16x32_bf16 v[94:97], v[140:143], v[208:211], v[94:97]
	v_mfma_f32_16x16x32_bf16 v[90:93], v[168:171], v[208:211], v[90:93]
	v_mfma_f32_16x16x32_bf16 v[78:81], v[140:143], v[216:219], v[78:81]
	v_mfma_f32_16x16x32_bf16 v[74:77], v[168:171], v[216:219], v[74:77]
	v_mfma_f32_16x16x32_bf16 v[126:129], v[152:155], v[180:183], v[126:129]
	v_mfma_f32_16x16x32_bf16 v[122:125], v[172:175], v[180:183], v[122:125]
	s_add_i32 m0, s49, 0xe000
	s_nop 0
	global_load_lds_dwordx4 v138, s[36:37]
	v_mfma_f32_16x16x32_bf16 v[110:113], v[152:155], v[204:207], v[110:113]
	v_mfma_f32_16x16x32_bf16 v[106:109], v[172:175], v[204:207], v[106:109]
	v_mfma_f32_16x16x32_bf16 v[94:97], v[152:155], v[212:215], v[94:97]
	v_mfma_f32_16x16x32_bf16 v[90:93], v[172:175], v[212:215], v[90:93]
	v_mfma_f32_16x16x32_bf16 v[78:81], v[152:155], v[226:229], v[78:81]
	v_mfma_f32_16x16x32_bf16 v[74:77], v[172:175], v[226:229], v[74:77]
	s_setprio 0
	s_barrier
	s_add_i32 s70, 0, 0x14000
	v_add_u32_e32 v144, s70, v147
	s_add_i32 s58, s58, s48
	ds_read_b128 v[230:233], v144
	ds_read_b128 v[234:237], v144 offset:1024
	ds_read_b128 v[238:241], v144 offset:2048
	ds_read_b128 v[242:245], v144 offset:3072
	s_barrier
; #define PG8_STAGE(bufoff, gbase, voff) do { _Pragma("unroll") for (int _i = 0; _i < 2; ++_i) \
;         __builtin_amdgcn_global_load_lds((const unsigned*)((const char*)(gbase) + (voff)[_i]), (LAS unsigned*)(lds + (bufoff) + ldsw + _i * 8192), 16, 0, 0); } while (0)
; #define PG8_LDA(dst, b, h) do { _Pragma("unroll") for (int m = 0; m < 4; ++m) _Pragma("unroll") for (int k = 0; k < 2; ++k) dst[m][k] = *(const LAS bf16x8*)(lds + PG8_SA(b, h) + aoff + m * 2048 + k * 1024); } while (0)
; #define PG8_LDB(dst, b, h) do { _Pragma("unroll") for (int n = 0; n < 2; ++n) _Pragma("unroll") for (int k = 0; k < 2; ++k) dst[n][k] = *(const LAS bf16x8*)(lds + PG8_SB(b, h) + boff + n * 2048 + k * 1024); } while (0)
; #define PG8_MMA(ai, bj, At, Bt) do { __builtin_amdgcn_s_setprio(1); _Pragma("unroll") for (int m = 0; m < 4; ++m) _Pragma("unroll") for (int n = 0; n < 2; ++n) _Pragma("unroll") for (int k = 0; k < 2; ++k) \
;         acc[ai][bj][m][n] = __builtin_amdgcn_mfma_f32_16x16x32_bf16(Bt[n][k], At[m][k], acc[ai][bj][m][n], 0, 0, 0); __builtin_amdgcn_s_setprio(0); } while (0)
; #define PG8_WAIT_V(n) asm volatile("s_waitcnt vmcnt(" #n ")" ::: "memory")
; #define PG8_WAIT_L(n) asm volatile("s_waitcnt lgkmcnt(" #n ")" ::: "memory")
; #define PG8_BAR __builtin_amdgcn_s_barrier()
; #define PG8_SCHED __builtin_amdgcn_sched_barrier(0)
; template <class Epi>
; __device__ __forceinline__ void gemm_phase(LAS unsigned char* lds, const Gemm g, const StaticOrder& S, const Epi& E) {
;     ...
;             PG8_BAR; PG8_WAIT_L(0); PG8_MMA(0, 1, At, B1); PG8_BAR;
;             PG8_LDA(At, 0, 1); PG8_STAGE(PG8_SA(0, 0), a2, voffA);
;             PG8_BAR; PG8_WAIT_L(0); PG8_MMA(1, 0, At, B0); PG8_BAR; PG8_SCHED;
;             PG8_STAGE(PG8_SB(0, 1), b2 + hstep, voffB);
;             PG8_WAIT_V(6); PG8_BAR; PG8_MMA(1, 1, At, B1); PG8_BAR;
;             PG8_LDB(B0, 1, 0); PG8_SCHED; PG8_LDA(At, 1, 0); PG8_STAGE(PG8_SA(0, 1), a2 + hstep, voffA);
;             PG8_WAIT_L(8); PG8_BAR; PG8_WAIT_L(0); PG8_MMA(0, 0, At, B0); PG8_BAR; PG8_SCHED;
	s_waitcnt lgkmcnt(0)
	s_setprio 1
	s_waitcnt lgkmcnt(0)
	v_mfma_f32_16x16x32_bf16 v[118:121], v[230:233], v[176:179], v[118:121]
	v_mfma_f32_16x16x32_bf16 v[114:117], v[238:241], v[176:179], v[114:117]
	v_mfma_f32_16x16x32_bf16 v[102:105], v[230:233], v[184:187], v[102:105]
	v_mfma_f32_16x16x32_bf16 v[98:101], v[238:241], v[184:187], v[98:101]
	s_mov_b32 m0, s58
	s_nop 0
	global_load_lds_dwordx4 v0, s[6:7]
	v_mfma_f32_16x16x32_bf16 v[86:89], v[230:233], v[208:211], v[86:89]
	v_mfma_f32_16x16x32_bf16 v[82:85], v[238:241], v[208:211], v[82:85]
	v_mfma_f32_16x16x32_bf16 v[70:73], v[230:233], v[216:219], v[70:73]
	v_mfma_f32_16x16x32_bf16 v[66:69], v[238:241], v[216:219], v[66:69]
	v_mfma_f32_16x16x32_bf16 v[118:121], v[234:237], v[180:183], v[118:121]
	v_mfma_f32_16x16x32_bf16 v[114:117], v[242:245], v[180:183], v[114:117]
	s_add_i32 m0, s58, 0x2000
	s_nop 0
	global_load_lds_dwordx4 v130, s[6:7]
	v_mfma_f32_16x16x32_bf16 v[102:105], v[234:237], v[204:207], v[102:105]
	v_mfma_f32_16x16x32_bf16 v[98:101], v[242:245], v[204:207], v[98:101]
	v_mfma_f32_16x16x32_bf16 v[86:89], v[234:237], v[212:215], v[86:89]
	v_mfma_f32_16x16x32_bf16 v[82:85], v[242:245], v[212:215], v[82:85]
	v_mfma_f32_16x16x32_bf16 v[70:73], v[234:237], v[226:229], v[70:73]
	v_mfma_f32_16x16x32_bf16 v[66:69], v[242:245], v[226:229], v[66:69]
	s_setprio 0
	s_add_u32 vcc_lo, s42, 0x80
	s_addc_u32 vcc_hi, s43, 0
	s_barrier
	ds_read_b128 v[176:179], v150 offset:16384
	ds_read_b128 v[180:183], v150 offset:17408
	ds_read_b128 v[184:187], v150 offset:18432
	ds_read_b128 v[204:207], v150 offset:19456
	ds_read_b128 v[208:211], v150 offset:20480
	ds_read_b128 v[212:215], v150 offset:21504
	ds_read_b128 v[216:219], v150 offset:22528
	ds_read_b128 v[226:229], v150 offset:23552
	s_barrier
	s_waitcnt lgkmcnt(0)
	s_setprio 1
	s_waitcnt lgkmcnt(0)
	v_mfma_f32_16x16x32_bf16 v[62:65], v[140:143], v[176:179], v[62:65]
	v_mfma_f32_16x16x32_bf16 v[58:61], v[168:171], v[176:179], v[58:61]
	v_mfma_f32_16x16x32_bf16 v[46:49], v[140:143], v[184:187], v[46:49]
	v_mfma_f32_16x16x32_bf16 v[42:45], v[168:171], v[184:187], v[42:45]
	s_mov_b32 m0, s49
	s_nop 0
	global_load_lds_dwordx4 v134, s[42:43]
	v_mfma_f32_16x16x32_bf16 v[30:33], v[140:143], v[208:211], v[30:33]
	v_mfma_f32_16x16x32_bf16 v[26:29], v[168:171], v[208:211], v[26:29]
	v_mfma_f32_16x16x32_bf16 v[14:17], v[140:143], v[216:219], v[14:17]
	v_mfma_f32_16x16x32_bf16 v[10:13], v[168:171], v[216:219], v[10:13]
	v_mfma_f32_16x16x32_bf16 v[62:65], v[152:155], v[180:183], v[62:65]
	v_mfma_f32_16x16x32_bf16 v[58:61], v[172:175], v[180:183], v[58:61]
	s_mov_b32 m0, s54
	s_nop 0
	global_load_lds_dwordx4 v132, s[42:43]
	v_mfma_f32_16x16x32_bf16 v[46:49], v[152:155], v[204:207], v[46:49]
	v_mfma_f32_16x16x32_bf16 v[42:45], v[172:175], v[204:207], v[42:45]
	v_mfma_f32_16x16x32_bf16 v[30:33], v[152:155], v[212:215], v[30:33]
	v_mfma_f32_16x16x32_bf16 v[26:29], v[172:175], v[212:215], v[26:29]
	v_mfma_f32_16x16x32_bf16 v[14:17], v[152:155], v[226:229], v[14:17]
	v_mfma_f32_16x16x32_bf16 v[10:13], v[172:175], v[226:229], v[10:13]
	s_setprio 0
	s_barrier
	s_add_u32 s60, s6, 0x40000
	s_addc_u32 s61, s7, 0
	s_add_i32 s58, s70, s48
	s_waitcnt vmcnt(4)
	s_barrier
	s_setprio 1
	v_mfma_f32_16x16x32_bf16 v[54:57], v[230:233], v[176:179], v[54:57]
	v_mfma_f32_16x16x32_bf16 v[50:53], v[238:241], v[176:179], v[50:53]
	s_cmp_eq_u32 s89, 0
	s_cbranch_scc1 .LdsE_skip_1
	global_store_dwordx4 v250, v[164:167], s[4:5] offset:256
	s_nop 1
	v_add_u32_e32 v250, 0x20000, v250
.LdsE_skip_1:
	v_mfma_f32_16x16x32_bf16 v[38:41], v[230:233], v[184:187], v[38:41]
	v_mfma_f32_16x16x32_bf16 v[34:37], v[238:241], v[184:187], v[34:37]
	s_mov_b32 m0, s58
	s_nop 0
	global_load_lds_dwordx4 v0, s[60:61]
	v_mfma_f32_16x16x32_bf16 v[22:25], v[230:233], v[208:211], v[22:25]
	v_mfma_f32_16x16x32_bf16 v[18:21], v[238:241], v[208:211], v[18:21]
	v_mfma_f32_16x16x32_bf16 v[6:9], v[230:233], v[216:219], v[6:9]
	v_mfma_f32_16x16x32_bf16 v[2:5], v[238:241], v[216:219], v[2:5]
	v_mfma_f32_16x16x32_bf16 v[54:57], v[234:237], v[180:183], v[54:57]
	v_mfma_f32_16x16x32_bf16 v[50:53], v[242:245], v[180:183], v[50:53]
	s_add_i32 m0, s58, 0x2000
	s_nop 0
	global_load_lds_dwordx4 v130, s[60:61]
	v_mfma_f32_16x16x32_bf16 v[38:41], v[234:237], v[204:207], v[38:41]
	v_mfma_f32_16x16x32_bf16 v[34:37], v[242:245], v[204:207], v[34:37]
	v_mfma_f32_16x16x32_bf16 v[22:25], v[234:237], v[212:215], v[22:25]
	v_mfma_f32_16x16x32_bf16 v[18:21], v[242:245], v[212:215], v[18:21]
	v_mfma_f32_16x16x32_bf16 v[6:9], v[234:237], v[226:229], v[6:9]
	v_mfma_f32_16x16x32_bf16 v[2:5], v[242:245], v[226:229], v[2:5]
	s_setprio 0
	s_add_i32 s58, 0, 0x18000
	v_add_u32_e32 v151, s58, v147
	s_barrier
	ds_read_b128 v[140:143], v151
	ds_read_b128 v[152:155], v151 offset:1024
	ds_read_b128 v[168:171], v151 offset:2048
	ds_read_b128 v[172:175], v151 offset:3072
	s_add_u32 s42, s42, 0x40000
	s_addc_u32 s43, s43, 0
	ds_read_b128 v[176:179], v150 offset:32768
	ds_read_b128 v[180:183], v150 offset:33792
	ds_read_b128 v[184:187], v150 offset:34816
	ds_read_b128 v[204:207], v150 offset:35840
	ds_read_b128 v[208:211], v150 offset:36864
	ds_read_b128 v[212:215], v150 offset:37888
	ds_read_b128 v[216:219], v150 offset:38912
	ds_read_b128 v[226:229], v150 offset:39936
	s_waitcnt lgkmcnt(8)
	s_barrier
; #define PG8_STAGE(bufoff, gbase, voff) do { _Pragma("unroll") for (int _i = 0; _i < 2; ++_i) \
;         __builtin_amdgcn_global_load_lds((const unsigned*)((const char*)(gbase) + (voff)[_i]), (LAS unsigned*)(lds + (bufoff) + ldsw + _i * 8192), 16, 0, 0); } while (0)
; #define PG8_LDA(dst, b, h) do { _Pragma("unroll") for (int m = 0; m < 4; ++m) _Pragma("unroll") for (int k = 0; k < 2; ++k) dst[m][k] = *(const LAS bf16x8*)(lds + PG8_SA(b, h) + aoff + m * 2048 + k * 1024); } while (0)
; #define PG8_LDB(dst, b, h) do { _Pragma("unroll") for (int n = 0; n < 2; ++n) _Pragma("unroll") for (int k = 0; k < 2; ++k) dst[n][k] = *(const LAS bf16x8*)(lds + PG8_SB(b, h) + boff + n * 2048 + k * 1024); } while (0)
; #define PG8_MMA(ai, bj, At, Bt) do { __builtin_amdgcn_s_setprio(1); _Pragma("unroll") for (int m = 0; m < 4; ++m) _Pragma("unroll") for (int n = 0; n < 2; ++n) _Pragma("unroll") for (int k = 0; k < 2; ++k) \
;         acc[ai][bj][m][n] = __builtin_amdgcn_mfma_f32_16x16x32_bf16(Bt[n][k], At[m][k], acc[ai][bj][m][n], 0, 0, 0); __builtin_amdgcn_s_setprio(0); } while (0)
; #define PG8_WAIT_V(n) asm volatile("s_waitcnt vmcnt(" #n ")" ::: "memory")
; #define PG8_WAIT_L(n) asm volatile("s_waitcnt lgkmcnt(" #n ")" ::: "memory")
; #define PG8_BAR __builtin_amdgcn_s_barrier()
; #define PG8_SCHED __builtin_amdgcn_sched_barrier(0)
; template <class Epi>
; __device__ __forceinline__ void gemm_phase(LAS unsigned char* lds, const Gemm g, const StaticOrder& S, const Epi& E) {
;     ...
;             PG8_WAIT_L(8); PG8_BAR; PG8_WAIT_L(0); PG8_MMA(0, 0, At, B0); PG8_BAR; PG8_SCHED;
;             PG8_LDB(B1, 1, 1); PG8_STAGE(PG8_SB(1, 0), b3, voffB);
;             PG8_BAR; PG8_WAIT_L(0); PG8_MMA(0, 1, At, B1); PG8_BAR;
;             PG8_LDA(At, 1, 1); PG8_STAGE(PG8_SA(1, 0), a3, voffA);
;             PG8_BAR; PG8_WAIT_L(0); PG8_MMA(1, 0, At, B0); PG8_BAR; PG8_SCHED;
;             PG8_STAGE(PG8_SB(1, 1), b3 + hstep, voffB);
;             PG8_WAIT_V(6); PG8_BAR; PG8_MMA(1, 1, At, B1); PG8_BAR;
;         }
	s_waitcnt lgkmcnt(0)
	s_setprio 1
	s_waitcnt lgkmcnt(0)
	v_mfma_f32_16x16x32_bf16 v[126:129], v[140:143], v[176:179], v[126:129]
	v_mfma_f32_16x16x32_bf16 v[122:125], v[168:171], v[176:179], v[122:125]
	v_mfma_f32_16x16x32_bf16 v[110:113], v[140:143], v[184:187], v[110:113]
	v_mfma_f32_16x16x32_bf16 v[106:109], v[168:171], v[184:187], v[106:109]
	s_mov_b32 m0, s55
	s_nop 0
	global_load_lds_dwordx4 v134, s[42:43]
	v_mfma_f32_16x16x32_bf16 v[94:97], v[140:143], v[208:211], v[94:97]
	v_mfma_f32_16x16x32_bf16 v[90:93], v[168:171], v[208:211], v[90:93]
	v_mfma_f32_16x16x32_bf16 v[78:81], v[140:143], v[216:219], v[78:81]
	v_mfma_f32_16x16x32_bf16 v[74:77], v[168:171], v[216:219], v[74:77]
	v_mfma_f32_16x16x32_bf16 v[126:129], v[152:155], v[180:183], v[126:129]
	v_mfma_f32_16x16x32_bf16 v[122:125], v[172:175], v[180:183], v[122:125]
	s_mov_b32 m0, s83
	s_nop 0
	global_load_lds_dwordx4 v132, s[42:43]
	v_mfma_f32_16x16x32_bf16 v[110:113], v[152:155], v[204:207], v[110:113]
	v_mfma_f32_16x16x32_bf16 v[106:109], v[172:175], v[204:207], v[106:109]
	v_mfma_f32_16x16x32_bf16 v[94:97], v[152:155], v[212:215], v[94:97]
	v_mfma_f32_16x16x32_bf16 v[90:93], v[172:175], v[212:215], v[90:93]
	v_mfma_f32_16x16x32_bf16 v[78:81], v[152:155], v[226:229], v[78:81]
	v_mfma_f32_16x16x32_bf16 v[74:77], v[172:175], v[226:229], v[74:77]
	s_setprio 0
	s_barrier
	s_add_i32 s42, 0, 0x1c000
	s_add_i32 s43, s58, s48
	v_add_u32_e32 v151, s42, v147
	s_add_u32 s60, s6, 0x80
	s_addc_u32 s61, s7, 0
	ds_read_b128 v[230:233], v151
	ds_read_b128 v[234:237], v151 offset:1024
	ds_read_b128 v[238:241], v151 offset:2048
	ds_read_b128 v[242:245], v151 offset:3072
	s_barrier
	s_waitcnt lgkmcnt(0)
	s_setprio 1
	s_waitcnt lgkmcnt(0)
	v_mfma_f32_16x16x32_bf16 v[118:121], v[230:233], v[176:179], v[118:121]
	v_mfma_f32_16x16x32_bf16 v[114:117], v[238:241], v[176:179], v[114:117]
	v_mfma_f32_16x16x32_bf16 v[102:105], v[230:233], v[184:187], v[102:105]
	v_mfma_f32_16x16x32_bf16 v[98:101], v[238:241], v[184:187], v[98:101]
	s_mov_b32 m0, s43
	s_nop 0
	global_load_lds_dwordx4 v0, s[60:61]
	v_mfma_f32_16x16x32_bf16 v[86:89], v[230:233], v[208:211], v[86:89]
	v_mfma_f32_16x16x32_bf16 v[82:85], v[238:241], v[208:211], v[82:85]
	v_mfma_f32_16x16x32_bf16 v[70:73], v[230:233], v[216:219], v[70:73]
	v_mfma_f32_16x16x32_bf16 v[66:69], v[238:241], v[216:219], v[66:69]
	v_mfma_f32_16x16x32_bf16 v[118:121], v[234:237], v[180:183], v[118:121]
	v_mfma_f32_16x16x32_bf16 v[114:117], v[242:245], v[180:183], v[114:117]
	s_add_i32 m0, s43, 0x2000
	s_nop 0
	global_load_lds_dwordx4 v130, s[60:61]
	v_mfma_f32_16x16x32_bf16 v[102:105], v[234:237], v[204:207], v[102:105]
	v_mfma_f32_16x16x32_bf16 v[98:101], v[242:245], v[204:207], v[98:101]
	v_mfma_f32_16x16x32_bf16 v[86:89], v[234:237], v[212:215], v[86:89]
	v_mfma_f32_16x16x32_bf16 v[82:85], v[242:245], v[212:215], v[82:85]
	v_mfma_f32_16x16x32_bf16 v[70:73], v[234:237], v[226:229], v[70:73]
	v_mfma_f32_16x16x32_bf16 v[66:69], v[242:245], v[226:229], v[66:69]
	s_setprio 0
	s_barrier
	ds_read_b128 v[176:179], v150 offset:49152
	ds_read_b128 v[180:183], v150 offset:50176
	ds_read_b128 v[184:187], v150 offset:51200
	ds_read_b128 v[204:207], v150 offset:52224
	ds_read_b128 v[208:211], v150 offset:53248
	ds_read_b128 v[212:215], v150 offset:54272
	ds_read_b128 v[216:219], v150 offset:55296
	ds_read_b128 v[226:229], v150 offset:56320
	s_barrier
	s_waitcnt lgkmcnt(0)
	s_setprio 1
	s_waitcnt lgkmcnt(0)
	v_mfma_f32_16x16x32_bf16 v[62:65], v[140:143], v[176:179], v[62:65]
	v_mfma_f32_16x16x32_bf16 v[58:61], v[168:171], v[176:179], v[58:61]
	v_mfma_f32_16x16x32_bf16 v[46:49], v[140:143], v[184:187], v[46:49]
	v_mfma_f32_16x16x32_bf16 v[42:45], v[168:171], v[184:187], v[42:45]
	s_mov_b32 m0, s84
	s_nop 0
	global_load_lds_dwordx4 v134, vcc
	v_mfma_f32_16x16x32_bf16 v[30:33], v[140:143], v[208:211], v[30:33]
	v_mfma_f32_16x16x32_bf16 v[26:29], v[168:171], v[208:211], v[26:29]
	v_mfma_f32_16x16x32_bf16 v[14:17], v[140:143], v[216:219], v[14:17]
	v_mfma_f32_16x16x32_bf16 v[10:13], v[168:171], v[216:219], v[10:13]
	v_mfma_f32_16x16x32_bf16 v[62:65], v[152:155], v[180:183], v[62:65]
	v_mfma_f32_16x16x32_bf16 v[58:61], v[172:175], v[180:183], v[58:61]
	s_mov_b32 m0, s85
	s_nop 0
	global_load_lds_dwordx4 v132, vcc
	v_mfma_f32_16x16x32_bf16 v[46:49], v[152:155], v[204:207], v[46:49]
	v_mfma_f32_16x16x32_bf16 v[42:45], v[172:175], v[204:207], v[42:45]
	v_mfma_f32_16x16x32_bf16 v[30:33], v[152:155], v[212:215], v[30:33]
	v_mfma_f32_16x16x32_bf16 v[26:29], v[172:175], v[212:215], v[26:29]
	v_mfma_f32_16x16x32_bf16 v[14:17], v[152:155], v[226:229], v[14:17]
	v_mfma_f32_16x16x32_bf16 v[10:13], v[172:175], v[226:229], v[10:13]
	s_setprio 0
	s_barrier
	s_add_u32 s6, s6, 0x40080
	s_addc_u32 s7, s7, 0
	s_add_i32 s42, s42, s48
	s_waitcnt vmcnt(4)
	s_barrier
	s_setprio 1
	v_mfma_f32_16x16x32_bf16 v[54:57], v[230:233], v[176:179], v[54:57]
	v_mfma_f32_16x16x32_bf16 v[50:53], v[238:241], v[176:179], v[50:53]
	v_mfma_f32_16x16x32_bf16 v[38:41], v[230:233], v[184:187], v[38:41]
	v_mfma_f32_16x16x32_bf16 v[34:37], v[238:241], v[184:187], v[34:37]
	s_mov_b32 m0, s42
	s_nop 0
	global_load_lds_dwordx4 v0, s[6:7]
	v_mfma_f32_16x16x32_bf16 v[22:25], v[230:233], v[208:211], v[22:25]
	v_mfma_f32_16x16x32_bf16 v[18:21], v[238:241], v[208:211], v[18:21]
	v_mfma_f32_16x16x32_bf16 v[6:9], v[230:233], v[216:219], v[6:9]
	v_mfma_f32_16x16x32_bf16 v[2:5], v[238:241], v[216:219], v[2:5]
	v_mfma_f32_16x16x32_bf16 v[54:57], v[234:237], v[180:183], v[54:57]
	v_mfma_f32_16x16x32_bf16 v[50:53], v[242:245], v[180:183], v[50:53]
	s_add_i32 m0, s42, 0x2000
	s_nop 0
	global_load_lds_dwordx4 v130, s[6:7]
	v_mfma_f32_16x16x32_bf16 v[38:41], v[234:237], v[204:207], v[38:41]
	v_mfma_f32_16x16x32_bf16 v[34:37], v[242:245], v[204:207], v[34:37]
	v_mfma_f32_16x16x32_bf16 v[22:25], v[234:237], v[212:215], v[22:25]
	v_mfma_f32_16x16x32_bf16 v[18:21], v[242:245], v[212:215], v[18:21]
	v_mfma_f32_16x16x32_bf16 v[6:9], v[234:237], v[226:229], v[6:9]
	v_mfma_f32_16x16x32_bf16 v[2:5], v[242:245], v[226:229], v[2:5]
	s_setprio 0
	s_add_i32 s93, s93, 2
	s_add_u32 s36, s36, 0x100
	s_addc_u32 s37, s37, 0
	s_add_u32 s91, s91, 0x100
	s_addc_u32 s92, s92, 0
	s_cmp_gt_u32 s93, 13
	s_barrier
; #define PG8_STAGE(bufoff, gbase, voff) do { _Pragma("unroll") for (int _i = 0; _i < 2; ++_i) \
;         __builtin_amdgcn_global_load_lds((const unsigned*)((const char*)(gbase) + (voff)[_i]), (LAS unsigned*)(lds + (bufoff) + ldsw + _i * 8192), 16, 0, 0); } while (0)
; #define PG8_LDA(dst, b, h) do { _Pragma("unroll") for (int m = 0; m < 4; ++m) _Pragma("unroll") for (int k = 0; k < 2; ++k) dst[m][k] = *(const LAS bf16x8*)(lds + PG8_SA(b, h) + aoff + m * 2048 + k * 1024); } while (0)
; #define PG8_LDB(dst, b, h) do { _Pragma("unroll") for (int n = 0; n < 2; ++n) _Pragma("unroll") for (int k = 0; k < 2; ++k) dst[n][k] = *(const LAS bf16x8*)(lds + PG8_SB(b, h) + boff + n * 2048 + k * 1024); } while (0)
; #define PG8_MMA(ai, bj, At, Bt) do { __builtin_amdgcn_s_setprio(1); _Pragma("unroll") for (int m = 0; m < 4; ++m) _Pragma("unroll") for (int n = 0; n < 2; ++n) _Pragma("unroll") for (int k = 0; k < 2; ++k) \
;         acc[ai][bj][m][n] = __builtin_amdgcn_mfma_f32_16x16x32_bf16(Bt[n][k], At[m][k], acc[ai][bj][m][n], 0, 0, 0); __builtin_amdgcn_s_setprio(0); } while (0)
; #define PG8_WAIT_V(n) asm volatile("s_waitcnt vmcnt(" #n ")" ::: "memory")
; #define PG8_WAIT_L(n) asm volatile("s_waitcnt lgkmcnt(" #n ")" ::: "memory")
; #define PG8_BAR __builtin_amdgcn_s_barrier()
; #define PG8_SCHED __builtin_amdgcn_sched_barrier(0)
; template <class Epi>
; __device__ __forceinline__ void gemm_phase(LAS unsigned char* lds, const Gemm g, const StaticOrder& S, const Epi& E) {
;     ...
;             PG8_LDB(B0, 0, 0); PG8_SCHED; PG8_LDA(At, 0, 0); PG8_STAGE(PG8_SA(1, 1), a1 + hstep, voffA);
;             PG8_WAIT_L(8); PG8_BAR; PG8_WAIT_L(0); PG8_MMA(0, 0, At, B0); PG8_BAR; PG8_SCHED;
;             PG8_LDB(B1, 0, 1); PG8_STAGE(PG8_SB(0, 0), b2, voffB);
;             PG8_BAR; PG8_WAIT_L(0); PG8_MMA(0, 1, At, B1); PG8_BAR;
;             PG8_LDA(At, 0, 1); PG8_STAGE(PG8_SA(0, 0), a2, voffA);
;             PG8_BAR; PG8_WAIT_L(0); PG8_MMA(1, 0, At, B0); PG8_BAR; PG8_SCHED;
;             PG8_STAGE(PG8_SB(0, 1), b2 + hstep, voffB);
;             PG8_WAIT_V(6); PG8_BAR; PG8_MMA(1, 1, At, B1); PG8_BAR;
	s_add_u32 s6, s36, 0xfffc0080
	s_addc_u32 s7, s37, -1
	s_add_i32 s58, 0, 0x10000
	v_add_u32_e32 v144, s58, v147
	ds_read_b128 v[140:143], v144
	ds_read_b128 v[152:155], v144 offset:1024
	ds_read_b128 v[168:171], v144 offset:2048
	ds_read_b128 v[172:175], v144 offset:3072
	s_cmp_eq_u32 s93, 12
	s_cselect_b32 s43, s11, s7
	s_cselect_b32 s42, s71, s6
	s_cselect_b32 s7, s9, s92
	s_cselect_b32 s6, s90, s91
	ds_read_b128 v[176:179], v150
	ds_read_b128 v[180:183], v150 offset:1024
	ds_read_b128 v[184:187], v150 offset:2048
	ds_read_b128 v[204:207], v150 offset:3072
	ds_read_b128 v[208:211], v150 offset:4096
	ds_read_b128 v[212:215], v150 offset:5120
	ds_read_b128 v[216:219], v150 offset:6144
	ds_read_b128 v[226:229], v150 offset:7168
	s_waitcnt lgkmcnt(8)
	s_barrier
	s_waitcnt lgkmcnt(0)
	s_setprio 1
	s_waitcnt lgkmcnt(0)
	v_mfma_f32_16x16x32_bf16 v[126:129], v[140:143], v[176:179], v[126:129]
	v_mfma_f32_16x16x32_bf16 v[122:125], v[168:171], v[176:179], v[122:125]
	v_mfma_f32_16x16x32_bf16 v[110:113], v[140:143], v[184:187], v[110:113]
	v_mfma_f32_16x16x32_bf16 v[106:109], v[168:171], v[184:187], v[106:109]
	s_add_i32 m0, s49, 0xc000
	s_nop 0
	global_load_lds_dwordx4 v136, s[36:37]
	v_mfma_f32_16x16x32_bf16 v[94:97], v[140:143], v[208:211], v[94:97]
	v_mfma_f32_16x16x32_bf16 v[90:93], v[168:171], v[208:211], v[90:93]
	v_mfma_f32_16x16x32_bf16 v[78:81], v[140:143], v[216:219], v[78:81]
	v_mfma_f32_16x16x32_bf16 v[74:77], v[168:171], v[216:219], v[74:77]
	v_mfma_f32_16x16x32_bf16 v[126:129], v[152:155], v[180:183], v[126:129]
	v_mfma_f32_16x16x32_bf16 v[122:125], v[172:175], v[180:183], v[122:125]
	s_add_i32 m0, s49, 0xe000
	s_nop 0
	global_load_lds_dwordx4 v138, s[36:37]
	v_mfma_f32_16x16x32_bf16 v[110:113], v[152:155], v[204:207], v[110:113]
	v_mfma_f32_16x16x32_bf16 v[106:109], v[172:175], v[204:207], v[106:109]
	v_mfma_f32_16x16x32_bf16 v[94:97], v[152:155], v[212:215], v[94:97]
	v_mfma_f32_16x16x32_bf16 v[90:93], v[172:175], v[212:215], v[90:93]
	v_mfma_f32_16x16x32_bf16 v[78:81], v[152:155], v[226:229], v[78:81]
	v_mfma_f32_16x16x32_bf16 v[74:77], v[172:175], v[226:229], v[74:77]
	s_setprio 0
	s_barrier
	s_add_i32 s70, 0, 0x14000
	v_add_u32_e32 v144, s70, v147
	s_add_i32 s58, s58, s48
	ds_read_b128 v[230:233], v144
	ds_read_b128 v[234:237], v144 offset:1024
	ds_read_b128 v[238:241], v144 offset:2048
	ds_read_b128 v[242:245], v144 offset:3072
	s_barrier
	s_waitcnt lgkmcnt(0)
	s_setprio 1
	s_waitcnt lgkmcnt(0)
	v_mfma_f32_16x16x32_bf16 v[118:121], v[230:233], v[176:179], v[118:121]
	v_mfma_f32_16x16x32_bf16 v[114:117], v[238:241], v[176:179], v[114:117]
	v_mfma_f32_16x16x32_bf16 v[102:105], v[230:233], v[184:187], v[102:105]
	v_mfma_f32_16x16x32_bf16 v[98:101], v[238:241], v[184:187], v[98:101]
	s_mov_b32 m0, s58
	s_nop 0
	global_load_lds_dwordx4 v0, s[6:7]
	v_mfma_f32_16x16x32_bf16 v[86:89], v[230:233], v[208:211], v[86:89]
	v_mfma_f32_16x16x32_bf16 v[82:85], v[238:241], v[208:211], v[82:85]
	v_mfma_f32_16x16x32_bf16 v[70:73], v[230:233], v[216:219], v[70:73]
	v_mfma_f32_16x16x32_bf16 v[66:69], v[238:241], v[216:219], v[66:69]
	v_mfma_f32_16x16x32_bf16 v[118:121], v[234:237], v[180:183], v[118:121]
	v_mfma_f32_16x16x32_bf16 v[114:117], v[242:245], v[180:183], v[114:117]
	s_add_i32 m0, s58, 0x2000
	s_nop 0
	global_load_lds_dwordx4 v130, s[6:7]
	v_mfma_f32_16x16x32_bf16 v[102:105], v[234:237], v[204:207], v[102:105]
	v_mfma_f32_16x16x32_bf16 v[98:101], v[242:245], v[204:207], v[98:101]
	v_mfma_f32_16x16x32_bf16 v[86:89], v[234:237], v[212:215], v[86:89]
	v_mfma_f32_16x16x32_bf16 v[82:85], v[242:245], v[212:215], v[82:85]
	v_mfma_f32_16x16x32_bf16 v[70:73], v[234:237], v[226:229], v[70:73]
	v_mfma_f32_16x16x32_bf16 v[66:69], v[242:245], v[226:229], v[66:69]
	s_setprio 0
	s_add_u32 vcc_lo, s42, 0x80
	s_addc_u32 vcc_hi, s43, 0
	s_barrier
	ds_read_b128 v[176:179], v150 offset:16384
	ds_read_b128 v[180:183], v150 offset:17408
	ds_read_b128 v[184:187], v150 offset:18432
	ds_read_b128 v[204:207], v150 offset:19456
	ds_read_b128 v[208:211], v150 offset:20480
	ds_read_b128 v[212:215], v150 offset:21504
	ds_read_b128 v[216:219], v150 offset:22528
	ds_read_b128 v[226:229], v150 offset:23552
	s_barrier
	s_waitcnt lgkmcnt(0)
	s_setprio 1
	s_waitcnt lgkmcnt(0)
	v_mfma_f32_16x16x32_bf16 v[62:65], v[140:143], v[176:179], v[62:65]
	v_mfma_f32_16x16x32_bf16 v[58:61], v[168:171], v[176:179], v[58:61]
	v_mfma_f32_16x16x32_bf16 v[46:49], v[140:143], v[184:187], v[46:49]
	v_mfma_f32_16x16x32_bf16 v[42:45], v[168:171], v[184:187], v[42:45]
	s_mov_b32 m0, s49
	s_nop 0
	global_load_lds_dwordx4 v134, s[42:43]
	v_mfma_f32_16x16x32_bf16 v[30:33], v[140:143], v[208:211], v[30:33]
	v_mfma_f32_16x16x32_bf16 v[26:29], v[168:171], v[208:211], v[26:29]
	v_mfma_f32_16x16x32_bf16 v[14:17], v[140:143], v[216:219], v[14:17]
	v_mfma_f32_16x16x32_bf16 v[10:13], v[168:171], v[216:219], v[10:13]
	v_mfma_f32_16x16x32_bf16 v[62:65], v[152:155], v[180:183], v[62:65]
	v_mfma_f32_16x16x32_bf16 v[58:61], v[172:175], v[180:183], v[58:61]
	s_mov_b32 m0, s54
	s_nop 0
	global_load_lds_dwordx4 v132, s[42:43]
	v_mfma_f32_16x16x32_bf16 v[46:49], v[152:155], v[204:207], v[46:49]
	v_mfma_f32_16x16x32_bf16 v[42:45], v[172:175], v[204:207], v[42:45]
	v_mfma_f32_16x16x32_bf16 v[30:33], v[152:155], v[212:215], v[30:33]
	v_mfma_f32_16x16x32_bf16 v[26:29], v[172:175], v[212:215], v[26:29]
	v_mfma_f32_16x16x32_bf16 v[14:17], v[152:155], v[226:229], v[14:17]
	v_mfma_f32_16x16x32_bf16 v[10:13], v[172:175], v[226:229], v[10:13]
	s_setprio 0
	s_barrier
	s_add_u32 s60, s6, 0x40000
	s_addc_u32 s61, s7, 0
	s_add_i32 s58, s70, s48
	s_waitcnt vmcnt(4)
	s_barrier
	s_setprio 1
	v_mfma_f32_16x16x32_bf16 v[54:57], v[230:233], v[176:179], v[54:57]
	v_mfma_f32_16x16x32_bf16 v[50:53], v[238:241], v[176:179], v[50:53]
	s_cmp_eq_u32 s89, 0
	s_cbranch_scc1 .LdsE_skip_2
	global_store_dwordx4 v250, v[188:191], s[4:5]
; #define PG8_STAGE(bufoff, gbase, voff) do { _Pragma("unroll") for (int _i = 0; _i < 2; ++_i) \
;         __builtin_amdgcn_global_load_lds((const unsigned*)((const char*)(gbase) + (voff)[_i]), (LAS unsigned*)(lds + (bufoff) + ldsw + _i * 8192), 16, 0, 0); } while (0)
; #define PG8_LDA(dst, b, h) do { _Pragma("unroll") for (int m = 0; m < 4; ++m) _Pragma("unroll") for (int k = 0; k < 2; ++k) dst[m][k] = *(const LAS bf16x8*)(lds + PG8_SA(b, h) + aoff + m * 2048 + k * 1024); } while (0)
; #define PG8_LDB(dst, b, h) do { _Pragma("unroll") for (int n = 0; n < 2; ++n) _Pragma("unroll") for (int k = 0; k < 2; ++k) dst[n][k] = *(const LAS bf16x8*)(lds + PG8_SB(b, h) + boff + n * 2048 + k * 1024); } while (0)
; #define PG8_MMA(ai, bj, At, Bt) do { __builtin_amdgcn_s_setprio(1); _Pragma("unroll") for (int m = 0; m < 4; ++m) _Pragma("unroll") for (int n = 0; n < 2; ++n) _Pragma("unroll") for (int k = 0; k < 2; ++k) \
;         acc[ai][bj][m][n] = __builtin_amdgcn_mfma_f32_16x16x32_bf16(Bt[n][k], At[m][k], acc[ai][bj][m][n], 0, 0, 0); __builtin_amdgcn_s_setprio(0); } while (0)
; #define PG8_WAIT_V(n) asm volatile("s_waitcnt vmcnt(" #n ")" ::: "memory")
; #define PG8_WAIT_L(n) asm volatile("s_waitcnt lgkmcnt(" #n ")" ::: "memory")
; #define PG8_BAR __builtin_amdgcn_s_barrier()
; #define PG8_SCHED __builtin_amdgcn_sched_barrier(0)
; template <class Epi>
; __device__ __forceinline__ void gemm_phase(LAS unsigned char* lds, const Gemm g, const StaticOrder& S, const Epi& E) {
;     ...
;             PG8_WAIT_V(6); PG8_BAR; PG8_MMA(1, 1, At, B1); PG8_BAR;
;             PG8_LDB(B0, 1, 0); PG8_SCHED; PG8_LDA(At, 1, 0); PG8_STAGE(PG8_SA(0, 1), a2 + hstep, voffA);
;             PG8_WAIT_L(8); PG8_BAR; PG8_WAIT_L(0); PG8_MMA(0, 0, At, B0); PG8_BAR; PG8_SCHED;
;             PG8_LDB(B1, 1, 1); PG8_STAGE(PG8_SB(1, 0), b3, voffB);
;             PG8_BAR; PG8_WAIT_L(0); PG8_MMA(0, 1, At, B1); PG8_BAR;
;             PG8_LDA(At, 1, 1); PG8_STAGE(PG8_SA(1, 0), a3, voffA);
;             PG8_BAR; PG8_WAIT_L(0); PG8_MMA(1, 0, At, B0); PG8_BAR; PG8_SCHED;
.LdsE_skip_2:
	v_mfma_f32_16x16x32_bf16 v[38:41], v[230:233], v[184:187], v[38:41]
	v_mfma_f32_16x16x32_bf16 v[34:37], v[238:241], v[184:187], v[34:37]
	s_mov_b32 m0, s58
	s_nop 0
	global_load_lds_dwordx4 v0, s[60:61]
	v_mfma_f32_16x16x32_bf16 v[22:25], v[230:233], v[208:211], v[22:25]
	v_mfma_f32_16x16x32_bf16 v[18:21], v[238:241], v[208:211], v[18:21]
	v_mfma_f32_16x16x32_bf16 v[6:9], v[230:233], v[216:219], v[6:9]
	v_mfma_f32_16x16x32_bf16 v[2:5], v[238:241], v[216:219], v[2:5]
	v_mfma_f32_16x16x32_bf16 v[54:57], v[234:237], v[180:183], v[54:57]
	v_mfma_f32_16x16x32_bf16 v[50:53], v[242:245], v[180:183], v[50:53]
	s_add_i32 m0, s58, 0x2000
	s_nop 0
	global_load_lds_dwordx4 v130, s[60:61]
	v_mfma_f32_16x16x32_bf16 v[38:41], v[234:237], v[204:207], v[38:41]
	v_mfma_f32_16x16x32_bf16 v[34:37], v[242:245], v[204:207], v[34:37]
	v_mfma_f32_16x16x32_bf16 v[22:25], v[234:237], v[212:215], v[22:25]
	v_mfma_f32_16x16x32_bf16 v[18:21], v[242:245], v[212:215], v[18:21]
	v_mfma_f32_16x16x32_bf16 v[6:9], v[234:237], v[226:229], v[6:9]
	v_mfma_f32_16x16x32_bf16 v[2:5], v[242:245], v[226:229], v[2:5]
	s_setprio 0
	s_add_i32 s58, 0, 0x18000
	v_add_u32_e32 v151, s58, v147
	s_barrier
	ds_read_b128 v[140:143], v151
	ds_read_b128 v[152:155], v151 offset:1024
	ds_read_b128 v[168:171], v151 offset:2048
	ds_read_b128 v[172:175], v151 offset:3072
	s_add_u32 s42, s42, 0x40000
	s_addc_u32 s43, s43, 0
	ds_read_b128 v[176:179], v150 offset:32768
	ds_read_b128 v[180:183], v150 offset:33792
	ds_read_b128 v[184:187], v150 offset:34816
	ds_read_b128 v[204:207], v150 offset:35840
	ds_read_b128 v[208:211], v150 offset:36864
	ds_read_b128 v[212:215], v150 offset:37888
	ds_read_b128 v[216:219], v150 offset:38912
	ds_read_b128 v[226:229], v150 offset:39936
	s_waitcnt lgkmcnt(8)
	s_barrier
	s_waitcnt lgkmcnt(0)
	s_setprio 1
	s_waitcnt lgkmcnt(0)
	v_mfma_f32_16x16x32_bf16 v[126:129], v[140:143], v[176:179], v[126:129]
	v_mfma_f32_16x16x32_bf16 v[122:125], v[168:171], v[176:179], v[122:125]
	v_mfma_f32_16x16x32_bf16 v[110:113], v[140:143], v[184:187], v[110:113]
	v_mfma_f32_16x16x32_bf16 v[106:109], v[168:171], v[184:187], v[106:109]
	s_mov_b32 m0, s55
	s_nop 0
	global_load_lds_dwordx4 v134, s[42:43]
	v_mfma_f32_16x16x32_bf16 v[94:97], v[140:143], v[208:211], v[94:97]
	v_mfma_f32_16x16x32_bf16 v[90:93], v[168:171], v[208:211], v[90:93]
	v_mfma_f32_16x16x32_bf16 v[78:81], v[140:143], v[216:219], v[78:81]
	v_mfma_f32_16x16x32_bf16 v[74:77], v[168:171], v[216:219], v[74:77]
	v_mfma_f32_16x16x32_bf16 v[126:129], v[152:155], v[180:183], v[126:129]
	v_mfma_f32_16x16x32_bf16 v[122:125], v[172:175], v[180:183], v[122:125]
	s_mov_b32 m0, s83
	s_nop 0
	global_load_lds_dwordx4 v132, s[42:43]
	v_mfma_f32_16x16x32_bf16 v[110:113], v[152:155], v[204:207], v[110:113]
	v_mfma_f32_16x16x32_bf16 v[106:109], v[172:175], v[204:207], v[106:109]
	v_mfma_f32_16x16x32_bf16 v[94:97], v[152:155], v[212:215], v[94:97]
	v_mfma_f32_16x16x32_bf16 v[90:93], v[172:175], v[212:215], v[90:93]
	v_mfma_f32_16x16x32_bf16 v[78:81], v[152:155], v[226:229], v[78:81]
	v_mfma_f32_16x16x32_bf16 v[74:77], v[172:175], v[226:229], v[74:77]
	s_setprio 0
	s_barrier
	s_add_i32 s42, 0, 0x1c000
	s_add_i32 s43, s58, s48
	v_add_u32_e32 v151, s42, v147
	s_add_u32 s60, s6, 0x80
	s_addc_u32 s61, s7, 0
	ds_read_b128 v[230:233], v151
	ds_read_b128 v[234:237], v151 offset:1024
	ds_read_b128 v[238:241], v151 offset:2048
	ds_read_b128 v[242:245], v151 offset:3072
	s_barrier
	s_waitcnt lgkmcnt(0)
	s_setprio 1
	s_waitcnt lgkmcnt(0)
	v_mfma_f32_16x16x32_bf16 v[118:121], v[230:233], v[176:179], v[118:121]
	v_mfma_f32_16x16x32_bf16 v[114:117], v[238:241], v[176:179], v[114:117]
	v_mfma_f32_16x16x32_bf16 v[102:105], v[230:233], v[184:187], v[102:105]
	v_mfma_f32_16x16x32_bf16 v[98:101], v[238:241], v[184:187], v[98:101]
	s_mov_b32 m0, s43
	s_nop 0
	global_load_lds_dwordx4 v0, s[60:61]
	v_mfma_f32_16x16x32_bf16 v[86:89], v[230:233], v[208:211], v[86:89]
	v_mfma_f32_16x16x32_bf16 v[82:85], v[238:241], v[208:211], v[82:85]
	v_mfma_f32_16x16x32_bf16 v[70:73], v[230:233], v[216:219], v[70:73]
	v_mfma_f32_16x16x32_bf16 v[66:69], v[238:241], v[216:219], v[66:69]
	v_mfma_f32_16x16x32_bf16 v[118:121], v[234:237], v[180:183], v[118:121]
	v_mfma_f32_16x16x32_bf16 v[114:117], v[242:245], v[180:183], v[114:117]
	s_add_i32 m0, s43, 0x2000
	s_nop 0
	global_load_lds_dwordx4 v130, s[60:61]
	v_mfma_f32_16x16x32_bf16 v[102:105], v[234:237], v[204:207], v[102:105]
	v_mfma_f32_16x16x32_bf16 v[98:101], v[242:245], v[204:207], v[98:101]
	v_mfma_f32_16x16x32_bf16 v[86:89], v[234:237], v[212:215], v[86:89]
	v_mfma_f32_16x16x32_bf16 v[82:85], v[242:245], v[212:215], v[82:85]
	v_mfma_f32_16x16x32_bf16 v[70:73], v[234:237], v[226:229], v[70:73]
	v_mfma_f32_16x16x32_bf16 v[66:69], v[242:245], v[226:229], v[66:69]
	s_setprio 0
	s_barrier
	ds_read_b128 v[176:179], v150 offset:49152
	ds_read_b128 v[180:183], v150 offset:50176
	ds_read_b128 v[184:187], v150 offset:51200
	ds_read_b128 v[204:207], v150 offset:52224
	ds_read_b128 v[208:211], v150 offset:53248
	ds_read_b128 v[212:215], v150 offset:54272
	ds_read_b128 v[216:219], v150 offset:55296
	ds_read_b128 v[226:229], v150 offset:56320
	s_barrier
; #define PG8_STAGE(bufoff, gbase, voff) do { _Pragma("unroll") for (int _i = 0; _i < 2; ++_i) \
;         __builtin_amdgcn_global_load_lds((const unsigned*)((const char*)(gbase) + (voff)[_i]), (LAS unsigned*)(lds + (bufoff) + ldsw + _i * 8192), 16, 0, 0); } while (0)
; #define PG8_LDA(dst, b, h) do { _Pragma("unroll") for (int m = 0; m < 4; ++m) _Pragma("unroll") for (int k = 0; k < 2; ++k) dst[m][k] = *(const LAS bf16x8*)(lds + PG8_SA(b, h) + aoff + m * 2048 + k * 1024); } while (0)
; #define PG8_LDB(dst, b, h) do { _Pragma("unroll") for (int n = 0; n < 2; ++n) _Pragma("unroll") for (int k = 0; k < 2; ++k) dst[n][k] = *(const LAS bf16x8*)(lds + PG8_SB(b, h) + boff + n * 2048 + k * 1024); } while (0)
; #define PG8_WAIT_V(n) asm volatile("s_waitcnt vmcnt(" #n ")" ::: "memory")
; #define PG8_WAIT_L(n) asm volatile("s_waitcnt lgkmcnt(" #n ")" ::: "memory")
; #define PG8_BAR __builtin_amdgcn_s_barrier()
; #define PG8_SCHED __builtin_amdgcn_sched_barrier(0)
; template <class Epi>
; __device__ __forceinline__ void gemm_phase(LAS unsigned char* lds, const Gemm g, const StaticOrder& S, const Epi& E) {
;     ...
;             PG8_LDB(B0, 0, 0); PG8_SCHED; PG8_LDA(At, 0, 0); PG8_STAGE(PG8_SA(1, 1), a1 + hstep, voffA);
;             PG8_WAIT_L(8); PG8_BAR; PG8_WAIT_L(0); PG8_MMA(0, 0, At, B0); PG8_BAR; PG8_SCHED;
;             PG8_LDB(B1, 0, 1); PG8_STAGE(PG8_SB(0, 0), b2, voffB);
;             PG8_BAR; PG8_WAIT_L(0); PG8_MMA(0, 1, At, B1); PG8_BAR;
;             PG8_LDA(At, 0, 1); PG8_STAGE(PG8_SA(0, 0), a2, voffA);
;             PG8_BAR; PG8_WAIT_L(0); PG8_MMA(1, 0, At, B0); PG8_BAR; PG8_SCHED;
;             PG8_STAGE(PG8_SB(0, 1), b2 + hstep, voffB);
;             PG8_WAIT_V(6); PG8_BAR; PG8_MMA(1, 1, At, B1); PG8_BAR;
;             PG8_LDB(B0, 1, 0); PG8_SCHED; PG8_LDA(At, 1, 0); PG8_STAGE(PG8_SA(0, 1), a2 + hstep, voffA);
;             PG8_WAIT_L(8); PG8_BAR; PG8_WAIT_L(0); PG8_MMA(0, 0, At, B0); PG8_BAR; PG8_SCHED;
;             PG8_LDB(B1, 1, 1); PG8_STAGE(PG8_SB(1, 0), b3, voffB);
;             PG8_BAR; PG8_WAIT_L(0); PG8_MMA(0, 1, At, B1); PG8_BAR;
;             PG8_LDA(At, 1, 1); PG8_STAGE(PG8_SA(1, 0), a3, voffA);
;             PG8_BAR; PG8_WAIT_L(0); PG8_MMA(1, 0, At, B0); PG8_BAR; PG8_SCHED;
;             PG8_STAGE(PG8_SB(1, 1), b3 + hstep, voffB);
;             PG8_WAIT_V(6); PG8_BAR; PG8_MMA(1, 1, At, B1); PG8_BAR;
	s_waitcnt lgkmcnt(0)
	s_setprio 1
	s_waitcnt lgkmcnt(0)
	v_mfma_f32_16x16x32_bf16 v[62:65], v[140:143], v[176:179], v[62:65]
	v_mfma_f32_16x16x32_bf16 v[58:61], v[168:171], v[176:179], v[58:61]
	v_mfma_f32_16x16x32_bf16 v[46:49], v[140:143], v[184:187], v[46:49]
	v_mfma_f32_16x16x32_bf16 v[42:45], v[168:171], v[184:187], v[42:45]
	s_mov_b32 m0, s84
	s_nop 0
	global_load_lds_dwordx4 v134, vcc
	v_mfma_f32_16x16x32_bf16 v[30:33], v[140:143], v[208:211], v[30:33]
	v_mfma_f32_16x16x32_bf16 v[26:29], v[168:171], v[208:211], v[26:29]
	v_mfma_f32_16x16x32_bf16 v[14:17], v[140:143], v[216:219], v[14:17]
	v_mfma_f32_16x16x32_bf16 v[10:13], v[168:171], v[216:219], v[10:13]
	v_mfma_f32_16x16x32_bf16 v[62:65], v[152:155], v[180:183], v[62:65]
	v_mfma_f32_16x16x32_bf16 v[58:61], v[172:175], v[180:183], v[58:61]
	s_mov_b32 m0, s85
	s_nop 0
	global_load_lds_dwordx4 v132, vcc
	v_mfma_f32_16x16x32_bf16 v[46:49], v[152:155], v[204:207], v[46:49]
	v_mfma_f32_16x16x32_bf16 v[42:45], v[172:175], v[204:207], v[42:45]
	v_mfma_f32_16x16x32_bf16 v[30:33], v[152:155], v[212:215], v[30:33]
	v_mfma_f32_16x16x32_bf16 v[26:29], v[172:175], v[212:215], v[26:29]
	v_mfma_f32_16x16x32_bf16 v[14:17], v[152:155], v[226:229], v[14:17]
	v_mfma_f32_16x16x32_bf16 v[10:13], v[172:175], v[226:229], v[10:13]
	s_setprio 0
	s_barrier
	s_add_u32 s6, s6, 0x40080
	s_addc_u32 s7, s7, 0
	s_add_i32 s42, s42, s48
	s_waitcnt vmcnt(4)
	s_barrier
	s_setprio 1
	v_mfma_f32_16x16x32_bf16 v[54:57], v[230:233], v[176:179], v[54:57]
	v_mfma_f32_16x16x32_bf16 v[50:53], v[238:241], v[176:179], v[50:53]
	v_mfma_f32_16x16x32_bf16 v[38:41], v[230:233], v[184:187], v[38:41]
	v_mfma_f32_16x16x32_bf16 v[34:37], v[238:241], v[184:187], v[34:37]
	s_mov_b32 m0, s42
	s_nop 0
	global_load_lds_dwordx4 v0, s[6:7]
	v_mfma_f32_16x16x32_bf16 v[22:25], v[230:233], v[208:211], v[22:25]
	v_mfma_f32_16x16x32_bf16 v[18:21], v[238:241], v[208:211], v[18:21]
	v_mfma_f32_16x16x32_bf16 v[6:9], v[230:233], v[216:219], v[6:9]
	v_mfma_f32_16x16x32_bf16 v[2:5], v[238:241], v[216:219], v[2:5]
	v_mfma_f32_16x16x32_bf16 v[54:57], v[234:237], v[180:183], v[54:57]
	v_mfma_f32_16x16x32_bf16 v[50:53], v[242:245], v[180:183], v[50:53]
	s_add_i32 m0, s42, 0x2000
	s_nop 0
	global_load_lds_dwordx4 v130, s[6:7]
	v_mfma_f32_16x16x32_bf16 v[38:41], v[234:237], v[204:207], v[38:41]
	v_mfma_f32_16x16x32_bf16 v[34:37], v[242:245], v[204:207], v[34:37]
	v_mfma_f32_16x16x32_bf16 v[22:25], v[234:237], v[212:215], v[22:25]
	v_mfma_f32_16x16x32_bf16 v[18:21], v[242:245], v[212:215], v[18:21]
	v_mfma_f32_16x16x32_bf16 v[6:9], v[234:237], v[226:229], v[6:9]
	v_mfma_f32_16x16x32_bf16 v[2:5], v[242:245], v[226:229], v[2:5]
	s_setprio 0
	s_add_i32 s93, s93, 2
	s_add_u32 s36, s36, 0x100
	s_addc_u32 s37, s37, 0
	s_add_u32 s91, s91, 0x100
	s_addc_u32 s92, s92, 0
	s_cmp_gt_u32 s93, 13
	s_barrier
	s_add_u32 s6, s36, 0xfffc0080
	s_addc_u32 s7, s37, -1
	s_add_i32 s58, 0, 0x10000
	v_add_u32_e32 v144, s58, v147
	ds_read_b128 v[140:143], v144
	ds_read_b128 v[152:155], v144 offset:1024
	ds_read_b128 v[168:171], v144 offset:2048
	ds_read_b128 v[172:175], v144 offset:3072
	s_cmp_eq_u32 s93, 12
	s_cselect_b32 s43, s11, s7
	s_cselect_b32 s42, s71, s6
	s_cselect_b32 s7, s9, s92
	s_cselect_b32 s6, s90, s91
	ds_read_b128 v[176:179], v150
	ds_read_b128 v[180:183], v150 offset:1024
	ds_read_b128 v[184:187], v150 offset:2048
	ds_read_b128 v[204:207], v150 offset:3072
	ds_read_b128 v[208:211], v150 offset:4096
	ds_read_b128 v[212:215], v150 offset:5120
	ds_read_b128 v[216:219], v150 offset:6144
	ds_read_b128 v[226:229], v150 offset:7168
	s_waitcnt lgkmcnt(8)
	s_barrier
	s_waitcnt lgkmcnt(0)
	s_setprio 1
	s_waitcnt lgkmcnt(0)
	v_mfma_f32_16x16x32_bf16 v[126:129], v[140:143], v[176:179], v[126:129]
	v_mfma_f32_16x16x32_bf16 v[122:125], v[168:171], v[176:179], v[122:125]
	v_mfma_f32_16x16x32_bf16 v[110:113], v[140:143], v[184:187], v[110:113]
	v_mfma_f32_16x16x32_bf16 v[106:109], v[168:171], v[184:187], v[106:109]
	s_add_i32 m0, s49, 0xc000
	s_nop 0
	global_load_lds_dwordx4 v136, s[36:37]
	v_mfma_f32_16x16x32_bf16 v[94:97], v[140:143], v[208:211], v[94:97]
	v_mfma_f32_16x16x32_bf16 v[90:93], v[168:171], v[208:211], v[90:93]
	v_mfma_f32_16x16x32_bf16 v[78:81], v[140:143], v[216:219], v[78:81]
	v_mfma_f32_16x16x32_bf16 v[74:77], v[168:171], v[216:219], v[74:77]
	v_mfma_f32_16x16x32_bf16 v[126:129], v[152:155], v[180:183], v[126:129]
	v_mfma_f32_16x16x32_bf16 v[122:125], v[172:175], v[180:183], v[122:125]
	s_add_i32 m0, s49, 0xe000
	s_nop 0
	global_load_lds_dwordx4 v138, s[36:37]
	v_mfma_f32_16x16x32_bf16 v[110:113], v[152:155], v[204:207], v[110:113]
	v_mfma_f32_16x16x32_bf16 v[106:109], v[172:175], v[204:207], v[106:109]
	v_mfma_f32_16x16x32_bf16 v[94:97], v[152:155], v[212:215], v[94:97]
	v_mfma_f32_16x16x32_bf16 v[90:93], v[172:175], v[212:215], v[90:93]
	v_mfma_f32_16x16x32_bf16 v[78:81], v[152:155], v[226:229], v[78:81]
	v_mfma_f32_16x16x32_bf16 v[74:77], v[172:175], v[226:229], v[74:77]
	s_setprio 0
	s_barrier
	s_add_i32 s70, 0, 0x14000
	v_add_u32_e32 v144, s70, v147
	s_add_i32 s58, s58, s48
	ds_read_b128 v[230:233], v144
	ds_read_b128 v[234:237], v144 offset:1024
	ds_read_b128 v[238:241], v144 offset:2048
	ds_read_b128 v[242:245], v144 offset:3072
	s_barrier
; #define PG8_STAGE(bufoff, gbase, voff) do { _Pragma("unroll") for (int _i = 0; _i < 2; ++_i) \
;         __builtin_amdgcn_global_load_lds((const unsigned*)((const char*)(gbase) + (voff)[_i]), (LAS unsigned*)(lds + (bufoff) + ldsw + _i * 8192), 16, 0, 0); } while (0)
; #define PG8_LDA(dst, b, h) do { _Pragma("unroll") for (int m = 0; m < 4; ++m) _Pragma("unroll") for (int k = 0; k < 2; ++k) dst[m][k] = *(const LAS bf16x8*)(lds + PG8_SA(b, h) + aoff + m * 2048 + k * 1024); } while (0)
; #define PG8_LDB(dst, b, h) do { _Pragma("unroll") for (int n = 0; n < 2; ++n) _Pragma("unroll") for (int k = 0; k < 2; ++k) dst[n][k] = *(const LAS bf16x8*)(lds + PG8_SB(b, h) + boff + n * 2048 + k * 1024); } while (0)
; #define PG8_MMA(ai, bj, At, Bt) do { __builtin_amdgcn_s_setprio(1); _Pragma("unroll") for (int m = 0; m < 4; ++m) _Pragma("unroll") for (int n = 0; n < 2; ++n) _Pragma("unroll") for (int k = 0; k < 2; ++k) \
;         acc[ai][bj][m][n] = __builtin_amdgcn_mfma_f32_16x16x32_bf16(Bt[n][k], At[m][k], acc[ai][bj][m][n], 0, 0, 0); __builtin_amdgcn_s_setprio(0); } while (0)
; #define PG8_WAIT_V(n) asm volatile("s_waitcnt vmcnt(" #n ")" ::: "memory")
; #define PG8_WAIT_L(n) asm volatile("s_waitcnt lgkmcnt(" #n ")" ::: "memory")
; #define PG8_BAR __builtin_amdgcn_s_barrier()
; #define PG8_SCHED __builtin_amdgcn_sched_barrier(0)
; template <class Epi>
; __device__ __forceinline__ void gemm_phase(LAS unsigned char* lds, const Gemm g, const StaticOrder& S, const Epi& E) {
;     ...
;             PG8_BAR; PG8_WAIT_L(0); PG8_MMA(0, 1, At, B1); PG8_BAR;
;             PG8_LDA(At, 0, 1); PG8_STAGE(PG8_SA(0, 0), a2, voffA);
;             PG8_BAR; PG8_WAIT_L(0); PG8_MMA(1, 0, At, B0); PG8_BAR; PG8_SCHED;
;             PG8_STAGE(PG8_SB(0, 1), b2 + hstep, voffB);
;             PG8_WAIT_V(6); PG8_BAR; PG8_MMA(1, 1, At, B1); PG8_BAR;
;             PG8_LDB(B0, 1, 0); PG8_SCHED; PG8_LDA(At, 1, 0); PG8_STAGE(PG8_SA(0, 1), a2 + hstep, voffA);
;             PG8_WAIT_L(8); PG8_BAR; PG8_WAIT_L(0); PG8_MMA(0, 0, At, B0); PG8_BAR; PG8_SCHED;
	s_waitcnt lgkmcnt(0)
	s_setprio 1
	s_waitcnt lgkmcnt(0)
	v_mfma_f32_16x16x32_bf16 v[118:121], v[230:233], v[176:179], v[118:121]
	v_mfma_f32_16x16x32_bf16 v[114:117], v[238:241], v[176:179], v[114:117]
	v_mfma_f32_16x16x32_bf16 v[102:105], v[230:233], v[184:187], v[102:105]
	v_mfma_f32_16x16x32_bf16 v[98:101], v[238:241], v[184:187], v[98:101]
	s_mov_b32 m0, s58
	s_nop 0
	global_load_lds_dwordx4 v0, s[6:7]
	v_mfma_f32_16x16x32_bf16 v[86:89], v[230:233], v[208:211], v[86:89]
	v_mfma_f32_16x16x32_bf16 v[82:85], v[238:241], v[208:211], v[82:85]
	v_mfma_f32_16x16x32_bf16 v[70:73], v[230:233], v[216:219], v[70:73]
	v_mfma_f32_16x16x32_bf16 v[66:69], v[238:241], v[216:219], v[66:69]
	v_mfma_f32_16x16x32_bf16 v[118:121], v[234:237], v[180:183], v[118:121]
	v_mfma_f32_16x16x32_bf16 v[114:117], v[242:245], v[180:183], v[114:117]
	s_add_i32 m0, s58, 0x2000
	s_nop 0
	global_load_lds_dwordx4 v130, s[6:7]
	v_mfma_f32_16x16x32_bf16 v[102:105], v[234:237], v[204:207], v[102:105]
	v_mfma_f32_16x16x32_bf16 v[98:101], v[242:245], v[204:207], v[98:101]
	v_mfma_f32_16x16x32_bf16 v[86:89], v[234:237], v[212:215], v[86:89]
	v_mfma_f32_16x16x32_bf16 v[82:85], v[242:245], v[212:215], v[82:85]
	v_mfma_f32_16x16x32_bf16 v[70:73], v[234:237], v[226:229], v[70:73]
	v_mfma_f32_16x16x32_bf16 v[66:69], v[242:245], v[226:229], v[66:69]
	s_setprio 0
	s_add_u32 vcc_lo, s42, 0x80
	s_addc_u32 vcc_hi, s43, 0
	s_barrier
	ds_read_b128 v[176:179], v150 offset:16384
	ds_read_b128 v[180:183], v150 offset:17408
	ds_read_b128 v[184:187], v150 offset:18432
	ds_read_b128 v[204:207], v150 offset:19456
	ds_read_b128 v[208:211], v150 offset:20480
	ds_read_b128 v[212:215], v150 offset:21504
	ds_read_b128 v[216:219], v150 offset:22528
	ds_read_b128 v[226:229], v150 offset:23552
	s_barrier
	s_waitcnt lgkmcnt(0)
	s_setprio 1
	s_waitcnt lgkmcnt(0)
	v_mfma_f32_16x16x32_bf16 v[62:65], v[140:143], v[176:179], v[62:65]
	v_mfma_f32_16x16x32_bf16 v[58:61], v[168:171], v[176:179], v[58:61]
	v_mfma_f32_16x16x32_bf16 v[46:49], v[140:143], v[184:187], v[46:49]
	v_mfma_f32_16x16x32_bf16 v[42:45], v[168:171], v[184:187], v[42:45]
	s_mov_b32 m0, s49
	s_nop 0
	global_load_lds_dwordx4 v134, s[42:43]
	v_mfma_f32_16x16x32_bf16 v[30:33], v[140:143], v[208:211], v[30:33]
	v_mfma_f32_16x16x32_bf16 v[26:29], v[168:171], v[208:211], v[26:29]
	v_mfma_f32_16x16x32_bf16 v[14:17], v[140:143], v[216:219], v[14:17]
	v_mfma_f32_16x16x32_bf16 v[10:13], v[168:171], v[216:219], v[10:13]
	v_mfma_f32_16x16x32_bf16 v[62:65], v[152:155], v[180:183], v[62:65]
	v_mfma_f32_16x16x32_bf16 v[58:61], v[172:175], v[180:183], v[58:61]
	s_mov_b32 m0, s54
	s_nop 0
	global_load_lds_dwordx4 v132, s[42:43]
	v_mfma_f32_16x16x32_bf16 v[46:49], v[152:155], v[204:207], v[46:49]
	v_mfma_f32_16x16x32_bf16 v[42:45], v[172:175], v[204:207], v[42:45]
	v_mfma_f32_16x16x32_bf16 v[30:33], v[152:155], v[212:215], v[30:33]
	v_mfma_f32_16x16x32_bf16 v[26:29], v[172:175], v[212:215], v[26:29]
	v_mfma_f32_16x16x32_bf16 v[14:17], v[152:155], v[226:229], v[14:17]
	v_mfma_f32_16x16x32_bf16 v[10:13], v[172:175], v[226:229], v[10:13]
	s_setprio 0
	s_barrier
	s_add_u32 s60, s6, 0x40000
	s_addc_u32 s61, s7, 0
	s_add_i32 s58, s70, s48
	s_waitcnt vmcnt(4)
	s_barrier
	s_setprio 1
	v_mfma_f32_16x16x32_bf16 v[54:57], v[230:233], v[176:179], v[54:57]
	v_mfma_f32_16x16x32_bf16 v[50:53], v[238:241], v[176:179], v[50:53]
	s_cmp_eq_u32 s89, 0
	s_cbranch_scc1 .LdsE_skip_3
	global_store_dwordx4 v250, v[192:195], s[4:5] offset:256
	s_nop 1
	v_add_u32_e32 v250, 0x20000, v250
.LdsE_skip_3:
	v_mfma_f32_16x16x32_bf16 v[38:41], v[230:233], v[184:187], v[38:41]
	v_mfma_f32_16x16x32_bf16 v[34:37], v[238:241], v[184:187], v[34:37]
	s_mov_b32 m0, s58
	s_nop 0
	global_load_lds_dwordx4 v0, s[60:61]
	v_mfma_f32_16x16x32_bf16 v[22:25], v[230:233], v[208:211], v[22:25]
	v_mfma_f32_16x16x32_bf16 v[18:21], v[238:241], v[208:211], v[18:21]
	v_mfma_f32_16x16x32_bf16 v[6:9], v[230:233], v[216:219], v[6:9]
	v_mfma_f32_16x16x32_bf16 v[2:5], v[238:241], v[216:219], v[2:5]
	v_mfma_f32_16x16x32_bf16 v[54:57], v[234:237], v[180:183], v[54:57]
	v_mfma_f32_16x16x32_bf16 v[50:53], v[242:245], v[180:183], v[50:53]
	s_add_i32 m0, s58, 0x2000
	s_nop 0
	global_load_lds_dwordx4 v130, s[60:61]
	v_mfma_f32_16x16x32_bf16 v[38:41], v[234:237], v[204:207], v[38:41]
	v_mfma_f32_16x16x32_bf16 v[34:37], v[242:245], v[204:207], v[34:37]
	v_mfma_f32_16x16x32_bf16 v[22:25], v[234:237], v[212:215], v[22:25]
	v_mfma_f32_16x16x32_bf16 v[18:21], v[242:245], v[212:215], v[18:21]
	v_mfma_f32_16x16x32_bf16 v[6:9], v[234:237], v[226:229], v[6:9]
	v_mfma_f32_16x16x32_bf16 v[2:5], v[242:245], v[226:229], v[2:5]
	s_setprio 0
	s_add_i32 s58, 0, 0x18000
	v_add_u32_e32 v151, s58, v147
	s_barrier
	ds_read_b128 v[140:143], v151
	ds_read_b128 v[152:155], v151 offset:1024
	ds_read_b128 v[168:171], v151 offset:2048
	ds_read_b128 v[172:175], v151 offset:3072
	s_add_u32 s42, s42, 0x40000
	s_addc_u32 s43, s43, 0
	ds_read_b128 v[176:179], v150 offset:32768
	ds_read_b128 v[180:183], v150 offset:33792
	ds_read_b128 v[184:187], v150 offset:34816
	ds_read_b128 v[204:207], v150 offset:35840
	ds_read_b128 v[208:211], v150 offset:36864
	ds_read_b128 v[212:215], v150 offset:37888
	ds_read_b128 v[216:219], v150 offset:38912
	ds_read_b128 v[226:229], v150 offset:39936
	s_waitcnt lgkmcnt(8)
	s_barrier
; #define PG8_STAGE(bufoff, gbase, voff) do { _Pragma("unroll") for (int _i = 0; _i < 2; ++_i) \
;         __builtin_amdgcn_global_load_lds((const unsigned*)((const char*)(gbase) + (voff)[_i]), (LAS unsigned*)(lds + (bufoff) + ldsw + _i * 8192), 16, 0, 0); } while (0)
; #define PG8_LDA(dst, b, h) do { _Pragma("unroll") for (int m = 0; m < 4; ++m) _Pragma("unroll") for (int k = 0; k < 2; ++k) dst[m][k] = *(const LAS bf16x8*)(lds + PG8_SA(b, h) + aoff + m * 2048 + k * 1024); } while (0)
; #define PG8_LDB(dst, b, h) do { _Pragma("unroll") for (int n = 0; n < 2; ++n) _Pragma("unroll") for (int k = 0; k < 2; ++k) dst[n][k] = *(const LAS bf16x8*)(lds + PG8_SB(b, h) + boff + n * 2048 + k * 1024); } while (0)
; #define PG8_MMA(ai, bj, At, Bt) do { __builtin_amdgcn_s_setprio(1); _Pragma("unroll") for (int m = 0; m < 4; ++m) _Pragma("unroll") for (int n = 0; n < 2; ++n) _Pragma("unroll") for (int k = 0; k < 2; ++k) \
;         acc[ai][bj][m][n] = __builtin_amdgcn_mfma_f32_16x16x32_bf16(Bt[n][k], At[m][k], acc[ai][bj][m][n], 0, 0, 0); __builtin_amdgcn_s_setprio(0); } while (0)
; #define PG8_WAIT_V(n) asm volatile("s_waitcnt vmcnt(" #n ")" ::: "memory")
; #define PG8_WAIT_L(n) asm volatile("s_waitcnt lgkmcnt(" #n ")" ::: "memory")
; #define PG8_BAR __builtin_amdgcn_s_barrier()
; #define PG8_SCHED __builtin_amdgcn_sched_barrier(0)
; template <class Epi>
; __device__ __forceinline__ void gemm_phase(LAS unsigned char* lds, const Gemm g, const StaticOrder& S, const Epi& E) {
;     ...
;             PG8_WAIT_L(8); PG8_BAR; PG8_WAIT_L(0); PG8_MMA(0, 0, At, B0); PG8_BAR; PG8_SCHED;
;             PG8_LDB(B1, 1, 1); PG8_STAGE(PG8_SB(1, 0), b3, voffB);
;             PG8_BAR; PG8_WAIT_L(0); PG8_MMA(0, 1, At, B1); PG8_BAR;
;             PG8_LDA(At, 1, 1); PG8_STAGE(PG8_SA(1, 0), a3, voffA);
;             PG8_BAR; PG8_WAIT_L(0); PG8_MMA(1, 0, At, B0); PG8_BAR; PG8_SCHED;
;             PG8_STAGE(PG8_SB(1, 1), b3 + hstep, voffB);
;             PG8_WAIT_V(6); PG8_BAR; PG8_MMA(1, 1, At, B1); PG8_BAR;
;         }
	s_waitcnt lgkmcnt(0)
	s_setprio 1
	s_waitcnt lgkmcnt(0)
	v_mfma_f32_16x16x32_bf16 v[126:129], v[140:143], v[176:179], v[126:129]
	v_mfma_f32_16x16x32_bf16 v[122:125], v[168:171], v[176:179], v[122:125]
	v_mfma_f32_16x16x32_bf16 v[110:113], v[140:143], v[184:187], v[110:113]
	v_mfma_f32_16x16x32_bf16 v[106:109], v[168:171], v[184:187], v[106:109]
	s_mov_b32 m0, s55
	s_nop 0
	global_load_lds_dwordx4 v134, s[42:43]
	v_mfma_f32_16x16x32_bf16 v[94:97], v[140:143], v[208:211], v[94:97]
	v_mfma_f32_16x16x32_bf16 v[90:93], v[168:171], v[208:211], v[90:93]
	v_mfma_f32_16x16x32_bf16 v[78:81], v[140:143], v[216:219], v[78:81]
	v_mfma_f32_16x16x32_bf16 v[74:77], v[168:171], v[216:219], v[74:77]
	v_mfma_f32_16x16x32_bf16 v[126:129], v[152:155], v[180:183], v[126:129]
	v_mfma_f32_16x16x32_bf16 v[122:125], v[172:175], v[180:183], v[122:125]
	s_mov_b32 m0, s83
	s_nop 0
	global_load_lds_dwordx4 v132, s[42:43]
	v_mfma_f32_16x16x32_bf16 v[110:113], v[152:155], v[204:207], v[110:113]
	v_mfma_f32_16x16x32_bf16 v[106:109], v[172:175], v[204:207], v[106:109]
	v_mfma_f32_16x16x32_bf16 v[94:97], v[152:155], v[212:215], v[94:97]
	v_mfma_f32_16x16x32_bf16 v[90:93], v[172:175], v[212:215], v[90:93]
	v_mfma_f32_16x16x32_bf16 v[78:81], v[152:155], v[226:229], v[78:81]
	v_mfma_f32_16x16x32_bf16 v[74:77], v[172:175], v[226:229], v[74:77]
	s_setprio 0
	s_barrier
	s_add_i32 s42, 0, 0x1c000
	s_add_i32 s43, s58, s48
	v_add_u32_e32 v151, s42, v147
	s_add_u32 s60, s6, 0x80
	s_addc_u32 s61, s7, 0
	ds_read_b128 v[230:233], v151
	ds_read_b128 v[234:237], v151 offset:1024
	ds_read_b128 v[238:241], v151 offset:2048
	ds_read_b128 v[242:245], v151 offset:3072
	s_barrier
	s_waitcnt lgkmcnt(0)
	s_setprio 1
	s_waitcnt lgkmcnt(0)
	v_mfma_f32_16x16x32_bf16 v[118:121], v[230:233], v[176:179], v[118:121]
	v_mfma_f32_16x16x32_bf16 v[114:117], v[238:241], v[176:179], v[114:117]
	v_mfma_f32_16x16x32_bf16 v[102:105], v[230:233], v[184:187], v[102:105]
	v_mfma_f32_16x16x32_bf16 v[98:101], v[238:241], v[184:187], v[98:101]
	s_mov_b32 m0, s43
	s_nop 0
	global_load_lds_dwordx4 v0, s[60:61]
	v_mfma_f32_16x16x32_bf16 v[86:89], v[230:233], v[208:211], v[86:89]
	v_mfma_f32_16x16x32_bf16 v[82:85], v[238:241], v[208:211], v[82:85]
	v_mfma_f32_16x16x32_bf16 v[70:73], v[230:233], v[216:219], v[70:73]
	v_mfma_f32_16x16x32_bf16 v[66:69], v[238:241], v[216:219], v[66:69]
	v_mfma_f32_16x16x32_bf16 v[118:121], v[234:237], v[180:183], v[118:121]
	v_mfma_f32_16x16x32_bf16 v[114:117], v[242:245], v[180:183], v[114:117]
	s_add_i32 m0, s43, 0x2000
	s_nop 0
	global_load_lds_dwordx4 v130, s[60:61]
	v_mfma_f32_16x16x32_bf16 v[102:105], v[234:237], v[204:207], v[102:105]
	v_mfma_f32_16x16x32_bf16 v[98:101], v[242:245], v[204:207], v[98:101]
	v_mfma_f32_16x16x32_bf16 v[86:89], v[234:237], v[212:215], v[86:89]
	v_mfma_f32_16x16x32_bf16 v[82:85], v[242:245], v[212:215], v[82:85]
	v_mfma_f32_16x16x32_bf16 v[70:73], v[234:237], v[226:229], v[70:73]
	v_mfma_f32_16x16x32_bf16 v[66:69], v[242:245], v[226:229], v[66:69]
	s_setprio 0
	s_barrier
	ds_read_b128 v[176:179], v150 offset:49152
	ds_read_b128 v[180:183], v150 offset:50176
	ds_read_b128 v[184:187], v150 offset:51200
	ds_read_b128 v[204:207], v150 offset:52224
	ds_read_b128 v[208:211], v150 offset:53248
	ds_read_b128 v[212:215], v150 offset:54272
	ds_read_b128 v[216:219], v150 offset:55296
	ds_read_b128 v[226:229], v150 offset:56320
	s_barrier
	s_waitcnt lgkmcnt(0)
	s_setprio 1
	s_waitcnt lgkmcnt(0)
	v_mfma_f32_16x16x32_bf16 v[62:65], v[140:143], v[176:179], v[62:65]
	v_mfma_f32_16x16x32_bf16 v[58:61], v[168:171], v[176:179], v[58:61]
	v_mfma_f32_16x16x32_bf16 v[46:49], v[140:143], v[184:187], v[46:49]
	v_mfma_f32_16x16x32_bf16 v[42:45], v[168:171], v[184:187], v[42:45]
	s_mov_b32 m0, s84
	s_nop 0
	global_load_lds_dwordx4 v134, vcc
	v_mfma_f32_16x16x32_bf16 v[30:33], v[140:143], v[208:211], v[30:33]
	v_mfma_f32_16x16x32_bf16 v[26:29], v[168:171], v[208:211], v[26:29]
	v_mfma_f32_16x16x32_bf16 v[14:17], v[140:143], v[216:219], v[14:17]
	v_mfma_f32_16x16x32_bf16 v[10:13], v[168:171], v[216:219], v[10:13]
	v_mfma_f32_16x16x32_bf16 v[62:65], v[152:155], v[180:183], v[62:65]
	v_mfma_f32_16x16x32_bf16 v[58:61], v[172:175], v[180:183], v[58:61]
	s_mov_b32 m0, s85
	s_nop 0
	global_load_lds_dwordx4 v132, vcc
	v_mfma_f32_16x16x32_bf16 v[46:49], v[152:155], v[204:207], v[46:49]
	v_mfma_f32_16x16x32_bf16 v[42:45], v[172:175], v[204:207], v[42:45]
	v_mfma_f32_16x16x32_bf16 v[30:33], v[152:155], v[212:215], v[30:33]
	v_mfma_f32_16x16x32_bf16 v[26:29], v[172:175], v[212:215], v[26:29]
	v_mfma_f32_16x16x32_bf16 v[14:17], v[152:155], v[226:229], v[14:17]
	v_mfma_f32_16x16x32_bf16 v[10:13], v[172:175], v[226:229], v[10:13]
	s_setprio 0
	s_barrier
	s_add_u32 s6, s6, 0x40080
	s_addc_u32 s7, s7, 0
	s_add_i32 s42, s42, s48
	s_waitcnt vmcnt(4)
	s_barrier
	s_setprio 1
	v_mfma_f32_16x16x32_bf16 v[54:57], v[230:233], v[176:179], v[54:57]
	v_mfma_f32_16x16x32_bf16 v[50:53], v[238:241], v[176:179], v[50:53]
	v_mfma_f32_16x16x32_bf16 v[38:41], v[230:233], v[184:187], v[38:41]
	v_mfma_f32_16x16x32_bf16 v[34:37], v[238:241], v[184:187], v[34:37]
	s_mov_b32 m0, s42
	s_nop 0
	global_load_lds_dwordx4 v0, s[6:7]
	v_mfma_f32_16x16x32_bf16 v[22:25], v[230:233], v[208:211], v[22:25]
	v_mfma_f32_16x16x32_bf16 v[18:21], v[238:241], v[208:211], v[18:21]
	v_mfma_f32_16x16x32_bf16 v[6:9], v[230:233], v[216:219], v[6:9]
	v_mfma_f32_16x16x32_bf16 v[2:5], v[238:241], v[216:219], v[2:5]
	v_mfma_f32_16x16x32_bf16 v[54:57], v[234:237], v[180:183], v[54:57]
	v_mfma_f32_16x16x32_bf16 v[50:53], v[242:245], v[180:183], v[50:53]
	s_add_i32 m0, s42, 0x2000
	s_nop 0
	global_load_lds_dwordx4 v130, s[6:7]
	v_mfma_f32_16x16x32_bf16 v[38:41], v[234:237], v[204:207], v[38:41]
	v_mfma_f32_16x16x32_bf16 v[34:37], v[242:245], v[204:207], v[34:37]
	v_mfma_f32_16x16x32_bf16 v[22:25], v[234:237], v[212:215], v[22:25]
	v_mfma_f32_16x16x32_bf16 v[18:21], v[242:245], v[212:215], v[18:21]
	v_mfma_f32_16x16x32_bf16 v[6:9], v[234:237], v[226:229], v[6:9]
	v_mfma_f32_16x16x32_bf16 v[2:5], v[242:245], v[226:229], v[2:5]
	s_setprio 0
	s_add_i32 s93, s93, 2
	s_add_u32 s36, s36, 0x100
	s_addc_u32 s37, s37, 0
	s_add_u32 s91, s91, 0x100
	s_addc_u32 s92, s92, 0
	s_cmp_gt_u32 s93, 13
	s_barrier
; #define PG8_STAGE(bufoff, gbase, voff) do { _Pragma("unroll") for (int _i = 0; _i < 2; ++_i) \
;         __builtin_amdgcn_global_load_lds((const unsigned*)((const char*)(gbase) + (voff)[_i]), (LAS unsigned*)(lds + (bufoff) + ldsw + _i * 8192), 16, 0, 0); } while (0)
; #define PG8_LDA(dst, b, h) do { _Pragma("unroll") for (int m = 0; m < 4; ++m) _Pragma("unroll") for (int k = 0; k < 2; ++k) dst[m][k] = *(const LAS bf16x8*)(lds + PG8_SA(b, h) + aoff + m * 2048 + k * 1024); } while (0)
; #define PG8_LDB(dst, b, h) do { _Pragma("unroll") for (int n = 0; n < 2; ++n) _Pragma("unroll") for (int k = 0; k < 2; ++k) dst[n][k] = *(const LAS bf16x8*)(lds + PG8_SB(b, h) + boff + n * 2048 + k * 1024); } while (0)
; #define PG8_WAIT_V(n) asm volatile("s_waitcnt vmcnt(" #n ")" ::: "memory")
; template <class Epi>
; __device__ __forceinline__ void gemm_phase(LAS unsigned char* lds, const Gemm g, const StaticOrder& S, const Epi& E) {
;     ...
;             const char* a2 = last ? nA : cA + (size_t)(t + 2) * kstep; const char* b2 = last ? nB : cB + (size_t)(t + 2) * kstep;
;             const char* a3 = a2 + kstep; const char* b3 = b2 + kstep;
;             PG8_LDB(B0, 0, 0); PG8_SCHED; PG8_LDA(At, 0, 0); PG8_STAGE(PG8_SA(1, 1), a1 + hstep, voffA);
;             PG8_WAIT_L(8); PG8_BAR; PG8_WAIT_L(0); PG8_MMA(0, 0, At, B0); PG8_BAR; PG8_SCHED;
;             PG8_LDB(B1, 0, 1); PG8_STAGE(PG8_SB(0, 0), b2, voffB);
;             PG8_BAR; PG8_WAIT_L(0); PG8_MMA(0, 1, At, B1); PG8_BAR;
;             PG8_LDA(At, 0, 1); PG8_STAGE(PG8_SA(0, 0), a2, voffA);
;             PG8_BAR; PG8_WAIT_L(0); PG8_MMA(1, 0, At, B0); PG8_BAR; PG8_SCHED;
;             PG8_STAGE(PG8_SB(0, 1), b2 + hstep, voffB);
;             PG8_WAIT_V(6); PG8_BAR; PG8_MMA(1, 1, At, B1); PG8_BAR;
;             PG8_LDB(B0, 1, 0); PG8_SCHED; PG8_LDA(At, 1, 0); PG8_STAGE(PG8_SA(0, 1), a2 + hstep, voffA);
;             PG8_WAIT_L(8); PG8_BAR; PG8_WAIT_L(0); PG8_MMA(0, 0, At, B0); PG8_BAR; PG8_SCHED;
;             PG8_LDB(B1, 1, 1); PG8_STAGE(PG8_SB(1, 0), b3, voffB);
;             PG8_BAR; PG8_WAIT_L(0); PG8_MMA(0, 1, At, B1); PG8_BAR;
;             PG8_LDA(At, 1, 1); PG8_STAGE(PG8_SA(1, 0), a3, voffA);
;             PG8_BAR; PG8_WAIT_L(0); PG8_MMA(1, 0, At, B0); PG8_BAR; PG8_SCHED;
;             PG8_STAGE(PG8_SB(1, 1), b3 + hstep, voffB);
;             PG8_WAIT_V(6); PG8_BAR; PG8_MMA(1, 1, At, B1); PG8_BAR;
	s_add_u32 s6, s36, 0xfffc0080
	s_addc_u32 s7, s37, -1
	s_add_i32 s58, 0, 0x10000
	v_add_u32_e32 v144, s58, v147
	ds_read_b128 v[140:143], v144
	ds_read_b128 v[152:155], v144 offset:1024
	ds_read_b128 v[168:171], v144 offset:2048
	ds_read_b128 v[172:175], v144 offset:3072
	s_cmp_eq_u32 s93, 12
	s_cselect_b32 s43, s11, s7
	s_cselect_b32 s42, s71, s6
	s_cselect_b32 s7, s9, s92
	s_cselect_b32 s6, s90, s91
	ds_read_b128 v[176:179], v150
	ds_read_b128 v[180:183], v150 offset:1024
	ds_read_b128 v[184:187], v150 offset:2048
	ds_read_b128 v[204:207], v150 offset:3072
	ds_read_b128 v[208:211], v150 offset:4096
	ds_read_b128 v[212:215], v150 offset:5120
	ds_read_b128 v[216:219], v150 offset:6144
	ds_read_b128 v[226:229], v150 offset:7168
	s_waitcnt lgkmcnt(8)
	s_barrier
	s_waitcnt lgkmcnt(0)
	s_setprio 1
	s_waitcnt lgkmcnt(0)
	v_mfma_f32_16x16x32_bf16 v[126:129], v[140:143], v[176:179], v[126:129]
	v_mfma_f32_16x16x32_bf16 v[122:125], v[168:171], v[176:179], v[122:125]
	v_mfma_f32_16x16x32_bf16 v[110:113], v[140:143], v[184:187], v[110:113]
	v_mfma_f32_16x16x32_bf16 v[106:109], v[168:171], v[184:187], v[106:109]
	s_add_i32 m0, s49, 0xc000
	s_nop 0
	global_load_lds_dwordx4 v136, s[36:37]
	v_mfma_f32_16x16x32_bf16 v[94:97], v[140:143], v[208:211], v[94:97]
	v_mfma_f32_16x16x32_bf16 v[90:93], v[168:171], v[208:211], v[90:93]
	v_mfma_f32_16x16x32_bf16 v[78:81], v[140:143], v[216:219], v[78:81]
	v_mfma_f32_16x16x32_bf16 v[74:77], v[168:171], v[216:219], v[74:77]
	v_mfma_f32_16x16x32_bf16 v[126:129], v[152:155], v[180:183], v[126:129]
	v_mfma_f32_16x16x32_bf16 v[122:125], v[172:175], v[180:183], v[122:125]
	s_add_i32 m0, s49, 0xe000
	s_nop 0
	global_load_lds_dwordx4 v138, s[36:37]
	v_mfma_f32_16x16x32_bf16 v[110:113], v[152:155], v[204:207], v[110:113]
	v_mfma_f32_16x16x32_bf16 v[106:109], v[172:175], v[204:207], v[106:109]
	v_mfma_f32_16x16x32_bf16 v[94:97], v[152:155], v[212:215], v[94:97]
	v_mfma_f32_16x16x32_bf16 v[90:93], v[172:175], v[212:215], v[90:93]
	v_mfma_f32_16x16x32_bf16 v[78:81], v[152:155], v[226:229], v[78:81]
	v_mfma_f32_16x16x32_bf16 v[74:77], v[172:175], v[226:229], v[74:77]
	s_setprio 0
	s_barrier
	s_add_i32 s70, 0, 0x14000
	v_add_u32_e32 v144, s70, v147
	s_add_i32 s58, s58, s48
	ds_read_b128 v[230:233], v144
	ds_read_b128 v[234:237], v144 offset:1024
	ds_read_b128 v[238:241], v144 offset:2048
	ds_read_b128 v[242:245], v144 offset:3072
	s_barrier
	s_waitcnt lgkmcnt(0)
	s_setprio 1
	s_waitcnt lgkmcnt(0)
	v_mfma_f32_16x16x32_bf16 v[118:121], v[230:233], v[176:179], v[118:121]
	v_mfma_f32_16x16x32_bf16 v[114:117], v[238:241], v[176:179], v[114:117]
	v_mfma_f32_16x16x32_bf16 v[102:105], v[230:233], v[184:187], v[102:105]
	v_mfma_f32_16x16x32_bf16 v[98:101], v[238:241], v[184:187], v[98:101]
	s_mov_b32 m0, s58
	s_nop 0
	global_load_lds_dwordx4 v0, s[6:7]
	v_mfma_f32_16x16x32_bf16 v[86:89], v[230:233], v[208:211], v[86:89]
	v_mfma_f32_16x16x32_bf16 v[82:85], v[238:241], v[208:211], v[82:85]
	v_mfma_f32_16x16x32_bf16 v[70:73], v[230:233], v[216:219], v[70:73]
	v_mfma_f32_16x16x32_bf16 v[66:69], v[238:241], v[216:219], v[66:69]
	v_mfma_f32_16x16x32_bf16 v[118:121], v[234:237], v[180:183], v[118:121]
	v_mfma_f32_16x16x32_bf16 v[114:117], v[242:245], v[180:183], v[114:117]
	s_add_i32 m0, s58, 0x2000
	s_nop 0
	global_load_lds_dwordx4 v130, s[6:7]
	v_mfma_f32_16x16x32_bf16 v[102:105], v[234:237], v[204:207], v[102:105]
	v_mfma_f32_16x16x32_bf16 v[98:101], v[242:245], v[204:207], v[98:101]
	v_mfma_f32_16x16x32_bf16 v[86:89], v[234:237], v[212:215], v[86:89]
	v_mfma_f32_16x16x32_bf16 v[82:85], v[242:245], v[212:215], v[82:85]
	v_mfma_f32_16x16x32_bf16 v[70:73], v[234:237], v[226:229], v[70:73]
	v_mfma_f32_16x16x32_bf16 v[66:69], v[242:245], v[226:229], v[66:69]
	s_setprio 0
	s_add_u32 vcc_lo, s42, 0x80
	s_addc_u32 vcc_hi, s43, 0
	s_barrier
	ds_read_b128 v[176:179], v150 offset:16384
	ds_read_b128 v[180:183], v150 offset:17408
	ds_read_b128 v[184:187], v150 offset:18432
	ds_read_b128 v[204:207], v150 offset:19456
	ds_read_b128 v[208:211], v150 offset:20480
	ds_read_b128 v[212:215], v150 offset:21504
	ds_read_b128 v[216:219], v150 offset:22528
	ds_read_b128 v[226:229], v150 offset:23552
	s_barrier
	s_waitcnt lgkmcnt(0)
	s_setprio 1
	s_waitcnt lgkmcnt(0)
	v_mfma_f32_16x16x32_bf16 v[62:65], v[140:143], v[176:179], v[62:65]
	v_mfma_f32_16x16x32_bf16 v[58:61], v[168:171], v[176:179], v[58:61]
	v_mfma_f32_16x16x32_bf16 v[46:49], v[140:143], v[184:187], v[46:49]
	v_mfma_f32_16x16x32_bf16 v[42:45], v[168:171], v[184:187], v[42:45]
	s_mov_b32 m0, s49
	s_nop 0
	global_load_lds_dwordx4 v134, s[42:43]
	v_mfma_f32_16x16x32_bf16 v[30:33], v[140:143], v[208:211], v[30:33]
	v_mfma_f32_16x16x32_bf16 v[26:29], v[168:171], v[208:211], v[26:29]
	v_mfma_f32_16x16x32_bf16 v[14:17], v[140:143], v[216:219], v[14:17]
	v_mfma_f32_16x16x32_bf16 v[10:13], v[168:171], v[216:219], v[10:13]
	v_mfma_f32_16x16x32_bf16 v[62:65], v[152:155], v[180:183], v[62:65]
	v_mfma_f32_16x16x32_bf16 v[58:61], v[172:175], v[180:183], v[58:61]
	s_mov_b32 m0, s54
	s_nop 0
	global_load_lds_dwordx4 v132, s[42:43]
	v_mfma_f32_16x16x32_bf16 v[46:49], v[152:155], v[204:207], v[46:49]
	v_mfma_f32_16x16x32_bf16 v[42:45], v[172:175], v[204:207], v[42:45]
	v_mfma_f32_16x16x32_bf16 v[30:33], v[152:155], v[212:215], v[30:33]
	v_mfma_f32_16x16x32_bf16 v[26:29], v[172:175], v[212:215], v[26:29]
	v_mfma_f32_16x16x32_bf16 v[14:17], v[152:155], v[226:229], v[14:17]
	v_mfma_f32_16x16x32_bf16 v[10:13], v[172:175], v[226:229], v[10:13]
	s_setprio 0
	s_barrier
	s_add_u32 s60, s6, 0x40000
	s_addc_u32 s61, s7, 0
	s_add_i32 s58, s70, s48
	s_waitcnt vmcnt(4)
	s_barrier
	s_setprio 1
	v_mfma_f32_16x16x32_bf16 v[54:57], v[230:233], v[176:179], v[54:57]
	v_mfma_f32_16x16x32_bf16 v[50:53], v[238:241], v[176:179], v[50:53]
	s_cmp_eq_u32 s89, 0
	s_cbranch_scc1 .LdsE_skip_4
	global_store_dwordx4 v250, v[196:199], s[4:5]
; #define PG8_STAGE(bufoff, gbase, voff) do { _Pragma("unroll") for (int _i = 0; _i < 2; ++_i) \
;         __builtin_amdgcn_global_load_lds((const unsigned*)((const char*)(gbase) + (voff)[_i]), (LAS unsigned*)(lds + (bufoff) + ldsw + _i * 8192), 16, 0, 0); } while (0)
; #define PG8_LDA(dst, b, h) do { _Pragma("unroll") for (int m = 0; m < 4; ++m) _Pragma("unroll") for (int k = 0; k < 2; ++k) dst[m][k] = *(const LAS bf16x8*)(lds + PG8_SA(b, h) + aoff + m * 2048 + k * 1024); } while (0)
; #define PG8_LDB(dst, b, h) do { _Pragma("unroll") for (int n = 0; n < 2; ++n) _Pragma("unroll") for (int k = 0; k < 2; ++k) dst[n][k] = *(const LAS bf16x8*)(lds + PG8_SB(b, h) + boff + n * 2048 + k * 1024); } while (0)
; #define PG8_WAIT_V(n) asm volatile("s_waitcnt vmcnt(" #n ")" ::: "memory")
; template <class Epi>
; __device__ __forceinline__ void gemm_phase(LAS unsigned char* lds, const Gemm g, const StaticOrder& S, const Epi& E) {
;     ...
;             const char* a2 = last ? nA : cA + (size_t)(t + 2) * kstep; const char* b2 = last ? nB : cB + (size_t)(t + 2) * kstep;
;             const char* a3 = a2 + kstep; const char* b3 = b2 + kstep;
;             PG8_LDB(B0, 0, 0); PG8_SCHED; PG8_LDA(At, 0, 0); PG8_STAGE(PG8_SA(1, 1), a1 + hstep, voffA);
;             PG8_WAIT_L(8); PG8_BAR; PG8_WAIT_L(0); PG8_MMA(0, 0, At, B0); PG8_BAR; PG8_SCHED;
;             PG8_LDB(B1, 0, 1); PG8_STAGE(PG8_SB(0, 0), b2, voffB);
;             PG8_BAR; PG8_WAIT_L(0); PG8_MMA(0, 1, At, B1); PG8_BAR;
;             PG8_LDA(At, 0, 1); PG8_STAGE(PG8_SA(0, 0), a2, voffA);
;             PG8_BAR; PG8_WAIT_L(0); PG8_MMA(1, 0, At, B0); PG8_BAR; PG8_SCHED;
;             PG8_STAGE(PG8_SB(0, 1), b2 + hstep, voffB);
;             PG8_WAIT_V(6); PG8_BAR; PG8_MMA(1, 1, At, B1); PG8_BAR;
;             PG8_LDB(B0, 1, 0); PG8_SCHED; PG8_LDA(At, 1, 0); PG8_STAGE(PG8_SA(0, 1), a2 + hstep, voffA);
;             PG8_WAIT_L(8); PG8_BAR; PG8_WAIT_L(0); PG8_MMA(0, 0, At, B0); PG8_BAR; PG8_SCHED;
;             PG8_LDB(B1, 1, 1); PG8_STAGE(PG8_SB(1, 0), b3, voffB);
;             PG8_BAR; PG8_WAIT_L(0); PG8_MMA(0, 1, At, B1); PG8_BAR;
;             PG8_LDA(At, 1, 1); PG8_STAGE(PG8_SA(1, 0), a3, voffA);
;             PG8_BAR; PG8_WAIT_L(0); PG8_MMA(1, 0, At, B0); PG8_BAR; PG8_SCHED;
;             PG8_STAGE(PG8_SB(1, 1), b3 + hstep, voffB);
;             PG8_WAIT_V(6); PG8_BAR; PG8_MMA(1, 1, At, B1); PG8_BAR;
.LdsE_skip_4:
	v_mfma_f32_16x16x32_bf16 v[38:41], v[230:233], v[184:187], v[38:41]
	v_mfma_f32_16x16x32_bf16 v[34:37], v[238:241], v[184:187], v[34:37]
	s_mov_b32 m0, s58
	s_nop 0
	global_load_lds_dwordx4 v0, s[60:61]
	v_mfma_f32_16x16x32_bf16 v[22:25], v[230:233], v[208:211], v[22:25]
	v_mfma_f32_16x16x32_bf16 v[18:21], v[238:241], v[208:211], v[18:21]
	v_mfma_f32_16x16x32_bf16 v[6:9], v[230:233], v[216:219], v[6:9]
	v_mfma_f32_16x16x32_bf16 v[2:5], v[238:241], v[216:219], v[2:5]
	v_mfma_f32_16x16x32_bf16 v[54:57], v[234:237], v[180:183], v[54:57]
	v_mfma_f32_16x16x32_bf16 v[50:53], v[242:245], v[180:183], v[50:53]
	s_add_i32 m0, s58, 0x2000
	s_nop 0
	global_load_lds_dwordx4 v130, s[60:61]
	v_mfma_f32_16x16x32_bf16 v[38:41], v[234:237], v[204:207], v[38:41]
	v_mfma_f32_16x16x32_bf16 v[34:37], v[242:245], v[204:207], v[34:37]
	v_mfma_f32_16x16x32_bf16 v[22:25], v[234:237], v[212:215], v[22:25]
	v_mfma_f32_16x16x32_bf16 v[18:21], v[242:245], v[212:215], v[18:21]
	v_mfma_f32_16x16x32_bf16 v[6:9], v[234:237], v[226:229], v[6:9]
	v_mfma_f32_16x16x32_bf16 v[2:5], v[242:245], v[226:229], v[2:5]
	s_setprio 0
	s_add_i32 s58, 0, 0x18000
	v_add_u32_e32 v151, s58, v147
	s_barrier
	ds_read_b128 v[140:143], v151
	ds_read_b128 v[152:155], v151 offset:1024
	ds_read_b128 v[168:171], v151 offset:2048
	ds_read_b128 v[172:175], v151 offset:3072
	s_add_u32 s42, s42, 0x40000
	s_addc_u32 s43, s43, 0
	ds_read_b128 v[176:179], v150 offset:32768
	ds_read_b128 v[180:183], v150 offset:33792
	ds_read_b128 v[184:187], v150 offset:34816
	ds_read_b128 v[204:207], v150 offset:35840
	ds_read_b128 v[208:211], v150 offset:36864
	ds_read_b128 v[212:215], v150 offset:37888
	ds_read_b128 v[216:219], v150 offset:38912
	ds_read_b128 v[226:229], v150 offset:39936
	s_waitcnt lgkmcnt(8)
	s_barrier
	s_waitcnt lgkmcnt(0)
	s_setprio 1
	s_waitcnt lgkmcnt(0)
	v_mfma_f32_16x16x32_bf16 v[126:129], v[140:143], v[176:179], v[126:129]
	v_mfma_f32_16x16x32_bf16 v[122:125], v[168:171], v[176:179], v[122:125]
	v_mfma_f32_16x16x32_bf16 v[110:113], v[140:143], v[184:187], v[110:113]
	v_mfma_f32_16x16x32_bf16 v[106:109], v[168:171], v[184:187], v[106:109]
	s_mov_b32 m0, s55
	s_nop 0
	global_load_lds_dwordx4 v134, s[42:43]
	v_mfma_f32_16x16x32_bf16 v[94:97], v[140:143], v[208:211], v[94:97]
	v_mfma_f32_16x16x32_bf16 v[90:93], v[168:171], v[208:211], v[90:93]
	v_mfma_f32_16x16x32_bf16 v[78:81], v[140:143], v[216:219], v[78:81]
	v_mfma_f32_16x16x32_bf16 v[74:77], v[168:171], v[216:219], v[74:77]
	v_mfma_f32_16x16x32_bf16 v[126:129], v[152:155], v[180:183], v[126:129]
	v_mfma_f32_16x16x32_bf16 v[122:125], v[172:175], v[180:183], v[122:125]
	s_mov_b32 m0, s83
	s_nop 0
	global_load_lds_dwordx4 v132, s[42:43]
	v_mfma_f32_16x16x32_bf16 v[110:113], v[152:155], v[204:207], v[110:113]
	v_mfma_f32_16x16x32_bf16 v[106:109], v[172:175], v[204:207], v[106:109]
	v_mfma_f32_16x16x32_bf16 v[94:97], v[152:155], v[212:215], v[94:97]
	v_mfma_f32_16x16x32_bf16 v[90:93], v[172:175], v[212:215], v[90:93]
	v_mfma_f32_16x16x32_bf16 v[78:81], v[152:155], v[226:229], v[78:81]
	v_mfma_f32_16x16x32_bf16 v[74:77], v[172:175], v[226:229], v[74:77]
	s_setprio 0
	s_barrier
	s_add_i32 s42, 0, 0x1c000
	s_add_i32 s43, s58, s48
	v_add_u32_e32 v151, s42, v147
	s_add_u32 s60, s6, 0x80
	s_addc_u32 s61, s7, 0
	ds_read_b128 v[230:233], v151
	ds_read_b128 v[234:237], v151 offset:1024
	ds_read_b128 v[238:241], v151 offset:2048
	ds_read_b128 v[242:245], v151 offset:3072
	s_barrier
	s_waitcnt lgkmcnt(0)
	s_setprio 1
	s_waitcnt lgkmcnt(0)
	v_mfma_f32_16x16x32_bf16 v[118:121], v[230:233], v[176:179], v[118:121]
	v_mfma_f32_16x16x32_bf16 v[114:117], v[238:241], v[176:179], v[114:117]
	v_mfma_f32_16x16x32_bf16 v[102:105], v[230:233], v[184:187], v[102:105]
	v_mfma_f32_16x16x32_bf16 v[98:101], v[238:241], v[184:187], v[98:101]
	s_mov_b32 m0, s43
	s_nop 0
	global_load_lds_dwordx4 v0, s[60:61]
	v_mfma_f32_16x16x32_bf16 v[86:89], v[230:233], v[208:211], v[86:89]
	v_mfma_f32_16x16x32_bf16 v[82:85], v[238:241], v[208:211], v[82:85]
	v_mfma_f32_16x16x32_bf16 v[70:73], v[230:233], v[216:219], v[70:73]
	v_mfma_f32_16x16x32_bf16 v[66:69], v[238:241], v[216:219], v[66:69]
	v_mfma_f32_16x16x32_bf16 v[118:121], v[234:237], v[180:183], v[118:121]
	v_mfma_f32_16x16x32_bf16 v[114:117], v[242:245], v[180:183], v[114:117]
	s_add_i32 m0, s43, 0x2000
	s_nop 0
	global_load_lds_dwordx4 v130, s[60:61]
	v_mfma_f32_16x16x32_bf16 v[102:105], v[234:237], v[204:207], v[102:105]
	v_mfma_f32_16x16x32_bf16 v[98:101], v[242:245], v[204:207], v[98:101]
	v_mfma_f32_16x16x32_bf16 v[86:89], v[234:237], v[212:215], v[86:89]
	v_mfma_f32_16x16x32_bf16 v[82:85], v[242:245], v[212:215], v[82:85]
	v_mfma_f32_16x16x32_bf16 v[70:73], v[234:237], v[226:229], v[70:73]
	v_mfma_f32_16x16x32_bf16 v[66:69], v[242:245], v[226:229], v[66:69]
	s_setprio 0
	s_barrier
	ds_read_b128 v[176:179], v150 offset:49152
	ds_read_b128 v[180:183], v150 offset:50176
	ds_read_b128 v[184:187], v150 offset:51200
	ds_read_b128 v[204:207], v150 offset:52224
	ds_read_b128 v[208:211], v150 offset:53248
	ds_read_b128 v[212:215], v150 offset:54272
	ds_read_b128 v[216:219], v150 offset:55296
	ds_read_b128 v[226:229], v150 offset:56320
	s_barrier
; #define PG8_STAGE(bufoff, gbase, voff) do { _Pragma("unroll") for (int _i = 0; _i < 2; ++_i) \
;         __builtin_amdgcn_global_load_lds((const unsigned*)((const char*)(gbase) + (voff)[_i]), (LAS unsigned*)(lds + (bufoff) + ldsw + _i * 8192), 16, 0, 0); } while (0)
; #define PG8_LDA(dst, b, h) do { _Pragma("unroll") for (int m = 0; m < 4; ++m) _Pragma("unroll") for (int k = 0; k < 2; ++k) dst[m][k] = *(const LAS bf16x8*)(lds + PG8_SA(b, h) + aoff + m * 2048 + k * 1024); } while (0)
; #define PG8_LDB(dst, b, h) do { _Pragma("unroll") for (int n = 0; n < 2; ++n) _Pragma("unroll") for (int k = 0; k < 2; ++k) dst[n][k] = *(const LAS bf16x8*)(lds + PG8_SB(b, h) + boff + n * 2048 + k * 1024); } while (0)
; #define PG8_WAIT_V(n) asm volatile("s_waitcnt vmcnt(" #n ")" ::: "memory")
; template <class Epi>
; __device__ __forceinline__ void gemm_phase(LAS unsigned char* lds, const Gemm g, const StaticOrder& S, const Epi& E) {
;     ...
;             const char* a2 = last ? nA : cA + (size_t)(t + 2) * kstep; const char* b2 = last ? nB : cB + (size_t)(t + 2) * kstep;
;             const char* a3 = a2 + kstep; const char* b3 = b2 + kstep;
;             PG8_LDB(B0, 0, 0); PG8_SCHED; PG8_LDA(At, 0, 0); PG8_STAGE(PG8_SA(1, 1), a1 + hstep, voffA);
;             PG8_WAIT_L(8); PG8_BAR; PG8_WAIT_L(0); PG8_MMA(0, 0, At, B0); PG8_BAR; PG8_SCHED;
;             PG8_LDB(B1, 0, 1); PG8_STAGE(PG8_SB(0, 0), b2, voffB);
;             PG8_BAR; PG8_WAIT_L(0); PG8_MMA(0, 1, At, B1); PG8_BAR;
;             PG8_LDA(At, 0, 1); PG8_STAGE(PG8_SA(0, 0), a2, voffA);
;             PG8_BAR; PG8_WAIT_L(0); PG8_MMA(1, 0, At, B0); PG8_BAR; PG8_SCHED;
;             PG8_STAGE(PG8_SB(0, 1), b2 + hstep, voffB);
;             PG8_WAIT_V(6); PG8_BAR; PG8_MMA(1, 1, At, B1); PG8_BAR;
;             PG8_LDB(B0, 1, 0); PG8_SCHED; PG8_LDA(At, 1, 0); PG8_STAGE(PG8_SA(0, 1), a2 + hstep, voffA);
;             PG8_WAIT_L(8); PG8_BAR; PG8_WAIT_L(0); PG8_MMA(0, 0, At, B0); PG8_BAR; PG8_SCHED;
;             PG8_LDB(B1, 1, 1); PG8_STAGE(PG8_SB(1, 0), b3, voffB);
;             PG8_BAR; PG8_WAIT_L(0); PG8_MMA(0, 1, At, B1); PG8_BAR;
;             PG8_LDA(At, 1, 1); PG8_STAGE(PG8_SA(1, 0), a3, voffA);
;             PG8_BAR; PG8_WAIT_L(0); PG8_MMA(1, 0, At, B0); PG8_BAR; PG8_SCHED;
;             PG8_STAGE(PG8_SB(1, 1), b3 + hstep, voffB);
;             PG8_WAIT_V(6); PG8_BAR; PG8_MMA(1, 1, At, B1); PG8_BAR;
	s_waitcnt lgkmcnt(0)
	s_setprio 1
	s_waitcnt lgkmcnt(0)
	v_mfma_f32_16x16x32_bf16 v[62:65], v[140:143], v[176:179], v[62:65]
	v_mfma_f32_16x16x32_bf16 v[58:61], v[168:171], v[176:179], v[58:61]
	v_mfma_f32_16x16x32_bf16 v[46:49], v[140:143], v[184:187], v[46:49]
	v_mfma_f32_16x16x32_bf16 v[42:45], v[168:171], v[184:187], v[42:45]
	s_mov_b32 m0, s84
	s_nop 0
	global_load_lds_dwordx4 v134, vcc
	v_mfma_f32_16x16x32_bf16 v[30:33], v[140:143], v[208:211], v[30:33]
	v_mfma_f32_16x16x32_bf16 v[26:29], v[168:171], v[208:211], v[26:29]
	v_mfma_f32_16x16x32_bf16 v[14:17], v[140:143], v[216:219], v[14:17]
	v_mfma_f32_16x16x32_bf16 v[10:13], v[168:171], v[216:219], v[10:13]
	v_mfma_f32_16x16x32_bf16 v[62:65], v[152:155], v[180:183], v[62:65]
	v_mfma_f32_16x16x32_bf16 v[58:61], v[172:175], v[180:183], v[58:61]
	s_mov_b32 m0, s85
	s_nop 0
	global_load_lds_dwordx4 v132, vcc
	v_mfma_f32_16x16x32_bf16 v[46:49], v[152:155], v[204:207], v[46:49]
	v_mfma_f32_16x16x32_bf16 v[42:45], v[172:175], v[204:207], v[42:45]
	v_mfma_f32_16x16x32_bf16 v[30:33], v[152:155], v[212:215], v[30:33]
	v_mfma_f32_16x16x32_bf16 v[26:29], v[172:175], v[212:215], v[26:29]
	v_mfma_f32_16x16x32_bf16 v[14:17], v[152:155], v[226:229], v[14:17]
	v_mfma_f32_16x16x32_bf16 v[10:13], v[172:175], v[226:229], v[10:13]
	s_setprio 0
	s_barrier
	s_add_u32 s6, s6, 0x40080
	s_addc_u32 s7, s7, 0
	s_add_i32 s42, s42, s48
	s_waitcnt vmcnt(4)
	s_barrier
	s_setprio 1
	v_mfma_f32_16x16x32_bf16 v[54:57], v[230:233], v[176:179], v[54:57]
	v_mfma_f32_16x16x32_bf16 v[50:53], v[238:241], v[176:179], v[50:53]
	v_mfma_f32_16x16x32_bf16 v[38:41], v[230:233], v[184:187], v[38:41]
	v_mfma_f32_16x16x32_bf16 v[34:37], v[238:241], v[184:187], v[34:37]
	s_mov_b32 m0, s42
	s_nop 0
	global_load_lds_dwordx4 v0, s[6:7]
	v_mfma_f32_16x16x32_bf16 v[22:25], v[230:233], v[208:211], v[22:25]
	v_mfma_f32_16x16x32_bf16 v[18:21], v[238:241], v[208:211], v[18:21]
	v_mfma_f32_16x16x32_bf16 v[6:9], v[230:233], v[216:219], v[6:9]
	v_mfma_f32_16x16x32_bf16 v[2:5], v[238:241], v[216:219], v[2:5]
	v_mfma_f32_16x16x32_bf16 v[54:57], v[234:237], v[180:183], v[54:57]
	v_mfma_f32_16x16x32_bf16 v[50:53], v[242:245], v[180:183], v[50:53]
	s_add_i32 m0, s42, 0x2000
	s_nop 0
	global_load_lds_dwordx4 v130, s[6:7]
	v_mfma_f32_16x16x32_bf16 v[38:41], v[234:237], v[204:207], v[38:41]
	v_mfma_f32_16x16x32_bf16 v[34:37], v[242:245], v[204:207], v[34:37]
	v_mfma_f32_16x16x32_bf16 v[22:25], v[234:237], v[212:215], v[22:25]
	v_mfma_f32_16x16x32_bf16 v[18:21], v[242:245], v[212:215], v[18:21]
	v_mfma_f32_16x16x32_bf16 v[6:9], v[234:237], v[226:229], v[6:9]
	v_mfma_f32_16x16x32_bf16 v[2:5], v[242:245], v[226:229], v[2:5]
	s_setprio 0
	s_add_i32 s93, s93, 2
	s_add_u32 s36, s36, 0x100
	s_addc_u32 s37, s37, 0
	s_add_u32 s91, s91, 0x100
	s_addc_u32 s92, s92, 0
	s_cmp_gt_u32 s93, 13
	s_barrier
	s_add_u32 s6, s36, 0xfffc0080
	s_addc_u32 s7, s37, -1
	s_add_i32 s58, 0, 0x10000
	v_add_u32_e32 v144, s58, v147
	ds_read_b128 v[140:143], v144
	ds_read_b128 v[152:155], v144 offset:1024
	ds_read_b128 v[168:171], v144 offset:2048
	ds_read_b128 v[172:175], v144 offset:3072
	s_cmp_eq_u32 s93, 12
	s_cselect_b32 s43, s11, s7
	s_cselect_b32 s42, s71, s6
	s_cselect_b32 s7, s9, s92
	s_cselect_b32 s6, s90, s91
	ds_read_b128 v[176:179], v150
	ds_read_b128 v[180:183], v150 offset:1024
	ds_read_b128 v[184:187], v150 offset:2048
	ds_read_b128 v[204:207], v150 offset:3072
	ds_read_b128 v[208:211], v150 offset:4096
	ds_read_b128 v[212:215], v150 offset:5120
	ds_read_b128 v[216:219], v150 offset:6144
	ds_read_b128 v[226:229], v150 offset:7168
	s_waitcnt lgkmcnt(8)
	s_barrier
	s_waitcnt lgkmcnt(0)
	s_setprio 1
	s_waitcnt lgkmcnt(0)
	v_mfma_f32_16x16x32_bf16 v[126:129], v[140:143], v[176:179], v[126:129]
	v_mfma_f32_16x16x32_bf16 v[122:125], v[168:171], v[176:179], v[122:125]
	v_mfma_f32_16x16x32_bf16 v[110:113], v[140:143], v[184:187], v[110:113]
	v_mfma_f32_16x16x32_bf16 v[106:109], v[168:171], v[184:187], v[106:109]
	s_add_i32 m0, s49, 0xc000
	s_nop 0
	global_load_lds_dwordx4 v136, s[36:37]
	v_mfma_f32_16x16x32_bf16 v[94:97], v[140:143], v[208:211], v[94:97]
	v_mfma_f32_16x16x32_bf16 v[90:93], v[168:171], v[208:211], v[90:93]
	v_mfma_f32_16x16x32_bf16 v[78:81], v[140:143], v[216:219], v[78:81]
	v_mfma_f32_16x16x32_bf16 v[74:77], v[168:171], v[216:219], v[74:77]
	v_mfma_f32_16x16x32_bf16 v[126:129], v[152:155], v[180:183], v[126:129]
	v_mfma_f32_16x16x32_bf16 v[122:125], v[172:175], v[180:183], v[122:125]
	s_add_i32 m0, s49, 0xe000
	s_nop 0
	global_load_lds_dwordx4 v138, s[36:37]
	v_mfma_f32_16x16x32_bf16 v[110:113], v[152:155], v[204:207], v[110:113]
	v_mfma_f32_16x16x32_bf16 v[106:109], v[172:175], v[204:207], v[106:109]
	v_mfma_f32_16x16x32_bf16 v[94:97], v[152:155], v[212:215], v[94:97]
	v_mfma_f32_16x16x32_bf16 v[90:93], v[172:175], v[212:215], v[90:93]
	v_mfma_f32_16x16x32_bf16 v[78:81], v[152:155], v[226:229], v[78:81]
	v_mfma_f32_16x16x32_bf16 v[74:77], v[172:175], v[226:229], v[74:77]
	s_setprio 0
	s_barrier
	s_add_i32 s70, 0, 0x14000
	v_add_u32_e32 v144, s70, v147
	s_add_i32 s58, s58, s48
	ds_read_b128 v[230:233], v144
	ds_read_b128 v[234:237], v144 offset:1024
	ds_read_b128 v[238:241], v144 offset:2048
	ds_read_b128 v[242:245], v144 offset:3072
	s_barrier
; #define PG8_STAGE(bufoff, gbase, voff) do { _Pragma("unroll") for (int _i = 0; _i < 2; ++_i) \
;         __builtin_amdgcn_global_load_lds((const unsigned*)((const char*)(gbase) + (voff)[_i]), (LAS unsigned*)(lds + (bufoff) + ldsw + _i * 8192), 16, 0, 0); } while (0)
; #define PG8_LDA(dst, b, h) do { _Pragma("unroll") for (int m = 0; m < 4; ++m) _Pragma("unroll") for (int k = 0; k < 2; ++k) dst[m][k] = *(const LAS bf16x8*)(lds + PG8_SA(b, h) + aoff + m * 2048 + k * 1024); } while (0)
; #define PG8_LDB(dst, b, h) do { _Pragma("unroll") for (int n = 0; n < 2; ++n) _Pragma("unroll") for (int k = 0; k < 2; ++k) dst[n][k] = *(const LAS bf16x8*)(lds + PG8_SB(b, h) + boff + n * 2048 + k * 1024); } while (0)
; #define PG8_WAIT_V(n) asm volatile("s_waitcnt vmcnt(" #n ")" ::: "memory")
; template <class Epi>
; __device__ __forceinline__ void gemm_phase(LAS unsigned char* lds, const Gemm g, const StaticOrder& S, const Epi& E) {
;     ...
;             const char* a2 = last ? nA : cA + (size_t)(t + 2) * kstep; const char* b2 = last ? nB : cB + (size_t)(t + 2) * kstep;
;             const char* a3 = a2 + kstep; const char* b3 = b2 + kstep;
;             PG8_LDB(B0, 0, 0); PG8_SCHED; PG8_LDA(At, 0, 0); PG8_STAGE(PG8_SA(1, 1), a1 + hstep, voffA);
;             PG8_WAIT_L(8); PG8_BAR; PG8_WAIT_L(0); PG8_MMA(0, 0, At, B0); PG8_BAR; PG8_SCHED;
;             PG8_LDB(B1, 0, 1); PG8_STAGE(PG8_SB(0, 0), b2, voffB);
;             PG8_BAR; PG8_WAIT_L(0); PG8_MMA(0, 1, At, B1); PG8_BAR;
;             PG8_LDA(At, 0, 1); PG8_STAGE(PG8_SA(0, 0), a2, voffA);
;             PG8_BAR; PG8_WAIT_L(0); PG8_MMA(1, 0, At, B0); PG8_BAR; PG8_SCHED;
;             PG8_STAGE(PG8_SB(0, 1), b2 + hstep, voffB);
;             PG8_WAIT_V(6); PG8_BAR; PG8_MMA(1, 1, At, B1); PG8_BAR;
;             PG8_LDB(B0, 1, 0); PG8_SCHED; PG8_LDA(At, 1, 0); PG8_STAGE(PG8_SA(0, 1), a2 + hstep, voffA);
;             PG8_WAIT_L(8); PG8_BAR; PG8_WAIT_L(0); PG8_MMA(0, 0, At, B0); PG8_BAR; PG8_SCHED;
;             PG8_LDB(B1, 1, 1); PG8_STAGE(PG8_SB(1, 0), b3, voffB);
;             PG8_BAR; PG8_WAIT_L(0); PG8_MMA(0, 1, At, B1); PG8_BAR;
;             PG8_LDA(At, 1, 1); PG8_STAGE(PG8_SA(1, 0), a3, voffA);
;             PG8_BAR; PG8_WAIT_L(0); PG8_MMA(1, 0, At, B0); PG8_BAR; PG8_SCHED;
;             PG8_STAGE(PG8_SB(1, 1), b3 + hstep, voffB);
;             PG8_WAIT_V(6); PG8_BAR; PG8_MMA(1, 1, At, B1); PG8_BAR;
	s_waitcnt lgkmcnt(0)
	s_setprio 1
	s_waitcnt lgkmcnt(0)
	v_mfma_f32_16x16x32_bf16 v[118:121], v[230:233], v[176:179], v[118:121]
	v_mfma_f32_16x16x32_bf16 v[114:117], v[238:241], v[176:179], v[114:117]
	v_mfma_f32_16x16x32_bf16 v[102:105], v[230:233], v[184:187], v[102:105]
	v_mfma_f32_16x16x32_bf16 v[98:101], v[238:241], v[184:187], v[98:101]
	s_mov_b32 m0, s58
	s_nop 0
	global_load_lds_dwordx4 v0, s[6:7]
	v_mfma_f32_16x16x32_bf16 v[86:89], v[230:233], v[208:211], v[86:89]
	v_mfma_f32_16x16x32_bf16 v[82:85], v[238:241], v[208:211], v[82:85]
	v_mfma_f32_16x16x32_bf16 v[70:73], v[230:233], v[216:219], v[70:73]
	v_mfma_f32_16x16x32_bf16 v[66:69], v[238:241], v[216:219], v[66:69]
	v_mfma_f32_16x16x32_bf16 v[118:121], v[234:237], v[180:183], v[118:121]
	v_mfma_f32_16x16x32_bf16 v[114:117], v[242:245], v[180:183], v[114:117]
	s_add_i32 m0, s58, 0x2000
	s_nop 0
	global_load_lds_dwordx4 v130, s[6:7]
	v_mfma_f32_16x16x32_bf16 v[102:105], v[234:237], v[204:207], v[102:105]
	v_mfma_f32_16x16x32_bf16 v[98:101], v[242:245], v[204:207], v[98:101]
	v_mfma_f32_16x16x32_bf16 v[86:89], v[234:237], v[212:215], v[86:89]
	v_mfma_f32_16x16x32_bf16 v[82:85], v[242:245], v[212:215], v[82:85]
	v_mfma_f32_16x16x32_bf16 v[70:73], v[234:237], v[226:229], v[70:73]
	v_mfma_f32_16x16x32_bf16 v[66:69], v[242:245], v[226:229], v[66:69]
	s_setprio 0
	s_add_u32 vcc_lo, s42, 0x80
	s_addc_u32 vcc_hi, s43, 0
	s_barrier
	ds_read_b128 v[176:179], v150 offset:16384
	ds_read_b128 v[180:183], v150 offset:17408
	ds_read_b128 v[184:187], v150 offset:18432
	ds_read_b128 v[204:207], v150 offset:19456
	ds_read_b128 v[208:211], v150 offset:20480
	ds_read_b128 v[212:215], v150 offset:21504
	ds_read_b128 v[216:219], v150 offset:22528
	ds_read_b128 v[226:229], v150 offset:23552
	s_barrier
	s_waitcnt lgkmcnt(0)
	s_setprio 1
	s_waitcnt lgkmcnt(0)
	v_mfma_f32_16x16x32_bf16 v[62:65], v[140:143], v[176:179], v[62:65]
	v_mfma_f32_16x16x32_bf16 v[58:61], v[168:171], v[176:179], v[58:61]
	v_mfma_f32_16x16x32_bf16 v[46:49], v[140:143], v[184:187], v[46:49]
	v_mfma_f32_16x16x32_bf16 v[42:45], v[168:171], v[184:187], v[42:45]
	s_mov_b32 m0, s49
	s_nop 0
	global_load_lds_dwordx4 v134, s[42:43]
	v_mfma_f32_16x16x32_bf16 v[30:33], v[140:143], v[208:211], v[30:33]
	v_mfma_f32_16x16x32_bf16 v[26:29], v[168:171], v[208:211], v[26:29]
	v_mfma_f32_16x16x32_bf16 v[14:17], v[140:143], v[216:219], v[14:17]
	v_mfma_f32_16x16x32_bf16 v[10:13], v[168:171], v[216:219], v[10:13]
	v_mfma_f32_16x16x32_bf16 v[62:65], v[152:155], v[180:183], v[62:65]
	v_mfma_f32_16x16x32_bf16 v[58:61], v[172:175], v[180:183], v[58:61]
	s_mov_b32 m0, s54
	s_nop 0
	global_load_lds_dwordx4 v132, s[42:43]
	v_mfma_f32_16x16x32_bf16 v[46:49], v[152:155], v[204:207], v[46:49]
	v_mfma_f32_16x16x32_bf16 v[42:45], v[172:175], v[204:207], v[42:45]
	v_mfma_f32_16x16x32_bf16 v[30:33], v[152:155], v[212:215], v[30:33]
	v_mfma_f32_16x16x32_bf16 v[26:29], v[172:175], v[212:215], v[26:29]
	v_mfma_f32_16x16x32_bf16 v[14:17], v[152:155], v[226:229], v[14:17]
	v_mfma_f32_16x16x32_bf16 v[10:13], v[172:175], v[226:229], v[10:13]
	s_setprio 0
	s_barrier
	s_add_u32 s60, s6, 0x40000
	s_addc_u32 s61, s7, 0
	s_add_i32 s58, s70, s48
	s_waitcnt vmcnt(4)
	s_barrier
	s_setprio 1
	v_mfma_f32_16x16x32_bf16 v[54:57], v[230:233], v[176:179], v[54:57]
	v_mfma_f32_16x16x32_bf16 v[50:53], v[238:241], v[176:179], v[50:53]
	s_cmp_eq_u32 s89, 0
	s_cbranch_scc1 .LdsE_skip_5
	global_store_dwordx4 v250, v[200:203], s[4:5] offset:256
	s_nop 1
	v_add_u32_e32 v250, 0x20000, v250
.LdsE_skip_5:
	v_mfma_f32_16x16x32_bf16 v[38:41], v[230:233], v[184:187], v[38:41]
	v_mfma_f32_16x16x32_bf16 v[34:37], v[238:241], v[184:187], v[34:37]
	s_mov_b32 m0, s58
	s_nop 0
	global_load_lds_dwordx4 v0, s[60:61]
	v_mfma_f32_16x16x32_bf16 v[22:25], v[230:233], v[208:211], v[22:25]
	v_mfma_f32_16x16x32_bf16 v[18:21], v[238:241], v[208:211], v[18:21]
	v_mfma_f32_16x16x32_bf16 v[6:9], v[230:233], v[216:219], v[6:9]
	v_mfma_f32_16x16x32_bf16 v[2:5], v[238:241], v[216:219], v[2:5]
	v_mfma_f32_16x16x32_bf16 v[54:57], v[234:237], v[180:183], v[54:57]
	v_mfma_f32_16x16x32_bf16 v[50:53], v[242:245], v[180:183], v[50:53]
	s_add_i32 m0, s58, 0x2000
	s_nop 0
	global_load_lds_dwordx4 v130, s[60:61]
	v_mfma_f32_16x16x32_bf16 v[38:41], v[234:237], v[204:207], v[38:41]
	v_mfma_f32_16x16x32_bf16 v[34:37], v[242:245], v[204:207], v[34:37]
	v_mfma_f32_16x16x32_bf16 v[22:25], v[234:237], v[212:215], v[22:25]
	v_mfma_f32_16x16x32_bf16 v[18:21], v[242:245], v[212:215], v[18:21]
	v_mfma_f32_16x16x32_bf16 v[6:9], v[234:237], v[226:229], v[6:9]
	v_mfma_f32_16x16x32_bf16 v[2:5], v[242:245], v[226:229], v[2:5]
	s_setprio 0
	s_add_i32 s58, 0, 0x18000
	v_add_u32_e32 v151, s58, v147
	s_barrier
	ds_read_b128 v[140:143], v151
	ds_read_b128 v[152:155], v151 offset:1024
	ds_read_b128 v[168:171], v151 offset:2048
	ds_read_b128 v[172:175], v151 offset:3072
	s_add_u32 s42, s42, 0x40000
	s_addc_u32 s43, s43, 0
	ds_read_b128 v[176:179], v150 offset:32768
	ds_read_b128 v[180:183], v150 offset:33792
	ds_read_b128 v[184:187], v150 offset:34816
	ds_read_b128 v[204:207], v150 offset:35840
	ds_read_b128 v[208:211], v150 offset:36864
	ds_read_b128 v[212:215], v150 offset:37888
	ds_read_b128 v[216:219], v150 offset:38912
	ds_read_b128 v[226:229], v150 offset:39936
	s_waitcnt lgkmcnt(8)
	s_barrier
; #define PG8_STAGE(bufoff, gbase, voff) do { _Pragma("unroll") for (int _i = 0; _i < 2; ++_i) \
;         __builtin_amdgcn_global_load_lds((const unsigned*)((const char*)(gbase) + (voff)[_i]), (LAS unsigned*)(lds + (bufoff) + ldsw + _i * 8192), 16, 0, 0); } while (0)
; #define PG8_LDA(dst, b, h) do { _Pragma("unroll") for (int m = 0; m < 4; ++m) _Pragma("unroll") for (int k = 0; k < 2; ++k) dst[m][k] = *(const LAS bf16x8*)(lds + PG8_SA(b, h) + aoff + m * 2048 + k * 1024); } while (0)
; #define PG8_LDB(dst, b, h) do { _Pragma("unroll") for (int n = 0; n < 2; ++n) _Pragma("unroll") for (int k = 0; k < 2; ++k) dst[n][k] = *(const LAS bf16x8*)(lds + PG8_SB(b, h) + boff + n * 2048 + k * 1024); } while (0)
; #define PG8_WAIT_V(n) asm volatile("s_waitcnt vmcnt(" #n ")" ::: "memory")
; template <class Epi>
; __device__ __forceinline__ void gemm_phase(LAS unsigned char* lds, const Gemm g, const StaticOrder& S, const Epi& E) {
;     ...
;             const char* a2 = last ? nA : cA + (size_t)(t + 2) * kstep; const char* b2 = last ? nB : cB + (size_t)(t + 2) * kstep;
;             const char* a3 = a2 + kstep; const char* b3 = b2 + kstep;
;             PG8_LDB(B0, 0, 0); PG8_SCHED; PG8_LDA(At, 0, 0); PG8_STAGE(PG8_SA(1, 1), a1 + hstep, voffA);
;             PG8_WAIT_L(8); PG8_BAR; PG8_WAIT_L(0); PG8_MMA(0, 0, At, B0); PG8_BAR; PG8_SCHED;
;             PG8_LDB(B1, 0, 1); PG8_STAGE(PG8_SB(0, 0), b2, voffB);
;             PG8_BAR; PG8_WAIT_L(0); PG8_MMA(0, 1, At, B1); PG8_BAR;
;             PG8_LDA(At, 0, 1); PG8_STAGE(PG8_SA(0, 0), a2, voffA);
;             PG8_BAR; PG8_WAIT_L(0); PG8_MMA(1, 0, At, B0); PG8_BAR; PG8_SCHED;
;             PG8_STAGE(PG8_SB(0, 1), b2 + hstep, voffB);
;             PG8_WAIT_V(6); PG8_BAR; PG8_MMA(1, 1, At, B1); PG8_BAR;
;             PG8_LDB(B0, 1, 0); PG8_SCHED; PG8_LDA(At, 1, 0); PG8_STAGE(PG8_SA(0, 1), a2 + hstep, voffA);
;             PG8_WAIT_L(8); PG8_BAR; PG8_WAIT_L(0); PG8_MMA(0, 0, At, B0); PG8_BAR; PG8_SCHED;
;             PG8_LDB(B1, 1, 1); PG8_STAGE(PG8_SB(1, 0), b3, voffB);
;             PG8_BAR; PG8_WAIT_L(0); PG8_MMA(0, 1, At, B1); PG8_BAR;
;             PG8_LDA(At, 1, 1); PG8_STAGE(PG8_SA(1, 0), a3, voffA);
;             PG8_BAR; PG8_WAIT_L(0); PG8_MMA(1, 0, At, B0); PG8_BAR; PG8_SCHED;
;             PG8_STAGE(PG8_SB(1, 1), b3 + hstep, voffB);
;             PG8_WAIT_V(6); PG8_BAR; PG8_MMA(1, 1, At, B1); PG8_BAR;
	s_waitcnt lgkmcnt(0)
	s_setprio 1
	s_waitcnt lgkmcnt(0)
	v_mfma_f32_16x16x32_bf16 v[126:129], v[140:143], v[176:179], v[126:129]
	v_mfma_f32_16x16x32_bf16 v[122:125], v[168:171], v[176:179], v[122:125]
	v_mfma_f32_16x16x32_bf16 v[110:113], v[140:143], v[184:187], v[110:113]
	v_mfma_f32_16x16x32_bf16 v[106:109], v[168:171], v[184:187], v[106:109]
	s_mov_b32 m0, s55
	s_nop 0
	global_load_lds_dwordx4 v134, s[42:43]
	v_mfma_f32_16x16x32_bf16 v[94:97], v[140:143], v[208:211], v[94:97]
	v_mfma_f32_16x16x32_bf16 v[90:93], v[168:171], v[208:211], v[90:93]
	v_mfma_f32_16x16x32_bf16 v[78:81], v[140:143], v[216:219], v[78:81]
	v_mfma_f32_16x16x32_bf16 v[74:77], v[168:171], v[216:219], v[74:77]
	v_mfma_f32_16x16x32_bf16 v[126:129], v[152:155], v[180:183], v[126:129]
	v_mfma_f32_16x16x32_bf16 v[122:125], v[172:175], v[180:183], v[122:125]
	s_mov_b32 m0, s83
	s_nop 0
	global_load_lds_dwordx4 v132, s[42:43]
	v_mfma_f32_16x16x32_bf16 v[110:113], v[152:155], v[204:207], v[110:113]
	v_mfma_f32_16x16x32_bf16 v[106:109], v[172:175], v[204:207], v[106:109]
	v_mfma_f32_16x16x32_bf16 v[94:97], v[152:155], v[212:215], v[94:97]
	v_mfma_f32_16x16x32_bf16 v[90:93], v[172:175], v[212:215], v[90:93]
	v_mfma_f32_16x16x32_bf16 v[78:81], v[152:155], v[226:229], v[78:81]
	v_mfma_f32_16x16x32_bf16 v[74:77], v[172:175], v[226:229], v[74:77]
	s_setprio 0
	s_barrier
	s_add_i32 s42, 0, 0x1c000
	s_add_i32 s43, s58, s48
	v_add_u32_e32 v151, s42, v147
	s_add_u32 s60, s6, 0x80
	s_addc_u32 s61, s7, 0
	ds_read_b128 v[230:233], v151
	ds_read_b128 v[234:237], v151 offset:1024
	ds_read_b128 v[238:241], v151 offset:2048
	ds_read_b128 v[242:245], v151 offset:3072
	s_barrier
	s_waitcnt lgkmcnt(0)
	s_setprio 1
	s_waitcnt lgkmcnt(0)
	v_mfma_f32_16x16x32_bf16 v[118:121], v[230:233], v[176:179], v[118:121]
	v_mfma_f32_16x16x32_bf16 v[114:117], v[238:241], v[176:179], v[114:117]
	v_mfma_f32_16x16x32_bf16 v[102:105], v[230:233], v[184:187], v[102:105]
	v_mfma_f32_16x16x32_bf16 v[98:101], v[238:241], v[184:187], v[98:101]
	s_mov_b32 m0, s43
	s_nop 0
	global_load_lds_dwordx4 v0, s[60:61]
	v_mfma_f32_16x16x32_bf16 v[86:89], v[230:233], v[208:211], v[86:89]
	v_mfma_f32_16x16x32_bf16 v[82:85], v[238:241], v[208:211], v[82:85]
	v_mfma_f32_16x16x32_bf16 v[70:73], v[230:233], v[216:219], v[70:73]
	v_mfma_f32_16x16x32_bf16 v[66:69], v[238:241], v[216:219], v[66:69]
	v_mfma_f32_16x16x32_bf16 v[118:121], v[234:237], v[180:183], v[118:121]
	v_mfma_f32_16x16x32_bf16 v[114:117], v[242:245], v[180:183], v[114:117]
	s_add_i32 m0, s43, 0x2000
	s_nop 0
	global_load_lds_dwordx4 v130, s[60:61]
	v_mfma_f32_16x16x32_bf16 v[102:105], v[234:237], v[204:207], v[102:105]
	v_mfma_f32_16x16x32_bf16 v[98:101], v[242:245], v[204:207], v[98:101]
	v_mfma_f32_16x16x32_bf16 v[86:89], v[234:237], v[212:215], v[86:89]
	v_mfma_f32_16x16x32_bf16 v[82:85], v[242:245], v[212:215], v[82:85]
	v_mfma_f32_16x16x32_bf16 v[70:73], v[234:237], v[226:229], v[70:73]
	v_mfma_f32_16x16x32_bf16 v[66:69], v[242:245], v[226:229], v[66:69]
	s_setprio 0
	s_barrier
	ds_read_b128 v[176:179], v150 offset:49152
	ds_read_b128 v[180:183], v150 offset:50176
	ds_read_b128 v[184:187], v150 offset:51200
	ds_read_b128 v[204:207], v150 offset:52224
	ds_read_b128 v[208:211], v150 offset:53248
	ds_read_b128 v[212:215], v150 offset:54272
	ds_read_b128 v[216:219], v150 offset:55296
	ds_read_b128 v[226:229], v150 offset:56320
	s_barrier
	s_waitcnt lgkmcnt(0)
	s_setprio 1
	s_waitcnt lgkmcnt(0)
	v_mfma_f32_16x16x32_bf16 v[62:65], v[140:143], v[176:179], v[62:65]
	v_mfma_f32_16x16x32_bf16 v[58:61], v[168:171], v[176:179], v[58:61]
	v_mfma_f32_16x16x32_bf16 v[46:49], v[140:143], v[184:187], v[46:49]
	v_mfma_f32_16x16x32_bf16 v[42:45], v[168:171], v[184:187], v[42:45]
	s_mov_b32 m0, s84
	s_nop 0
	global_load_lds_dwordx4 v134, vcc
	v_mfma_f32_16x16x32_bf16 v[30:33], v[140:143], v[208:211], v[30:33]
	v_mfma_f32_16x16x32_bf16 v[26:29], v[168:171], v[208:211], v[26:29]
	v_mfma_f32_16x16x32_bf16 v[14:17], v[140:143], v[216:219], v[14:17]
	v_mfma_f32_16x16x32_bf16 v[10:13], v[168:171], v[216:219], v[10:13]
	v_mfma_f32_16x16x32_bf16 v[62:65], v[152:155], v[180:183], v[62:65]
	v_mfma_f32_16x16x32_bf16 v[58:61], v[172:175], v[180:183], v[58:61]
	s_mov_b32 m0, s85
	s_nop 0
	global_load_lds_dwordx4 v132, vcc
	v_mfma_f32_16x16x32_bf16 v[46:49], v[152:155], v[204:207], v[46:49]
	v_mfma_f32_16x16x32_bf16 v[42:45], v[172:175], v[204:207], v[42:45]
	v_mfma_f32_16x16x32_bf16 v[30:33], v[152:155], v[212:215], v[30:33]
	v_mfma_f32_16x16x32_bf16 v[26:29], v[172:175], v[212:215], v[26:29]
	v_mfma_f32_16x16x32_bf16 v[14:17], v[152:155], v[226:229], v[14:17]
	v_mfma_f32_16x16x32_bf16 v[10:13], v[172:175], v[226:229], v[10:13]
	s_setprio 0
	s_barrier
	s_add_u32 s6, s6, 0x40080
	s_addc_u32 s7, s7, 0
	s_add_i32 s42, s42, s48
	s_waitcnt vmcnt(4)
	s_barrier
	s_setprio 1
	v_mfma_f32_16x16x32_bf16 v[54:57], v[230:233], v[176:179], v[54:57]
	v_mfma_f32_16x16x32_bf16 v[50:53], v[238:241], v[176:179], v[50:53]
	v_mfma_f32_16x16x32_bf16 v[38:41], v[230:233], v[184:187], v[38:41]
	v_mfma_f32_16x16x32_bf16 v[34:37], v[238:241], v[184:187], v[34:37]
	s_mov_b32 m0, s42
	s_nop 0
	global_load_lds_dwordx4 v0, s[6:7]
	v_mfma_f32_16x16x32_bf16 v[22:25], v[230:233], v[208:211], v[22:25]
	v_mfma_f32_16x16x32_bf16 v[18:21], v[238:241], v[208:211], v[18:21]
	v_mfma_f32_16x16x32_bf16 v[6:9], v[230:233], v[216:219], v[6:9]
	v_mfma_f32_16x16x32_bf16 v[2:5], v[238:241], v[216:219], v[2:5]
	v_mfma_f32_16x16x32_bf16 v[54:57], v[234:237], v[180:183], v[54:57]
	v_mfma_f32_16x16x32_bf16 v[50:53], v[242:245], v[180:183], v[50:53]
	s_add_i32 m0, s42, 0x2000
	s_nop 0
	global_load_lds_dwordx4 v130, s[6:7]
	v_mfma_f32_16x16x32_bf16 v[38:41], v[234:237], v[204:207], v[38:41]
	v_mfma_f32_16x16x32_bf16 v[34:37], v[242:245], v[204:207], v[34:37]
	v_mfma_f32_16x16x32_bf16 v[22:25], v[234:237], v[212:215], v[22:25]
	v_mfma_f32_16x16x32_bf16 v[18:21], v[242:245], v[212:215], v[18:21]
	v_mfma_f32_16x16x32_bf16 v[6:9], v[234:237], v[226:229], v[6:9]
	v_mfma_f32_16x16x32_bf16 v[2:5], v[242:245], v[226:229], v[2:5]
	s_setprio 0
	s_add_i32 s93, s93, 2
	s_add_u32 s36, s36, 0x100
	s_addc_u32 s37, s37, 0
	s_add_u32 s91, s91, 0x100
	s_addc_u32 s92, s92, 0
	s_cmp_gt_u32 s93, 13
	s_barrier
; #define PG8_STAGE(bufoff, gbase, voff) do { _Pragma("unroll") for (int _i = 0; _i < 2; ++_i) \
;         __builtin_amdgcn_global_load_lds((const unsigned*)((const char*)(gbase) + (voff)[_i]), (LAS unsigned*)(lds + (bufoff) + ldsw + _i * 8192), 16, 0, 0); } while (0)
; #define PG8_LDA(dst, b, h) do { _Pragma("unroll") for (int m = 0; m < 4; ++m) _Pragma("unroll") for (int k = 0; k < 2; ++k) dst[m][k] = *(const LAS bf16x8*)(lds + PG8_SA(b, h) + aoff + m * 2048 + k * 1024); } while (0)
; #define PG8_LDB(dst, b, h) do { _Pragma("unroll") for (int n = 0; n < 2; ++n) _Pragma("unroll") for (int k = 0; k < 2; ++k) dst[n][k] = *(const LAS bf16x8*)(lds + PG8_SB(b, h) + boff + n * 2048 + k * 1024); } while (0)
; #define PG8_WAIT_V(n) asm volatile("s_waitcnt vmcnt(" #n ")" ::: "memory")
; template <class Epi>
; __device__ __forceinline__ void gemm_phase(LAS unsigned char* lds, const Gemm g, const StaticOrder& S, const Epi& E) {
;     ...
;             const char* a2 = last ? nA : cA + (size_t)(t + 2) * kstep; const char* b2 = last ? nB : cB + (size_t)(t + 2) * kstep;
;             const char* a3 = a2 + kstep; const char* b3 = b2 + kstep;
;             PG8_LDB(B0, 0, 0); PG8_SCHED; PG8_LDA(At, 0, 0); PG8_STAGE(PG8_SA(1, 1), a1 + hstep, voffA);
;             PG8_WAIT_L(8); PG8_BAR; PG8_WAIT_L(0); PG8_MMA(0, 0, At, B0); PG8_BAR; PG8_SCHED;
;             PG8_LDB(B1, 0, 1); PG8_STAGE(PG8_SB(0, 0), b2, voffB);
;             PG8_BAR; PG8_WAIT_L(0); PG8_MMA(0, 1, At, B1); PG8_BAR;
;             PG8_LDA(At, 0, 1); PG8_STAGE(PG8_SA(0, 0), a2, voffA);
;             PG8_BAR; PG8_WAIT_L(0); PG8_MMA(1, 0, At, B0); PG8_BAR; PG8_SCHED;
;             PG8_STAGE(PG8_SB(0, 1), b2 + hstep, voffB);
;             PG8_WAIT_V(6); PG8_BAR; PG8_MMA(1, 1, At, B1); PG8_BAR;
;             PG8_LDB(B0, 1, 0); PG8_SCHED; PG8_LDA(At, 1, 0); PG8_STAGE(PG8_SA(0, 1), a2 + hstep, voffA);
;             PG8_WAIT_L(8); PG8_BAR; PG8_WAIT_L(0); PG8_MMA(0, 0, At, B0); PG8_BAR; PG8_SCHED;
;             PG8_LDB(B1, 1, 1); PG8_STAGE(PG8_SB(1, 0), b3, voffB);
;             PG8_BAR; PG8_WAIT_L(0); PG8_MMA(0, 1, At, B1); PG8_BAR;
;             PG8_LDA(At, 1, 1); PG8_STAGE(PG8_SA(1, 0), a3, voffA);
;             PG8_BAR; PG8_WAIT_L(0); PG8_MMA(1, 0, At, B0); PG8_BAR; PG8_SCHED;
;             PG8_STAGE(PG8_SB(1, 1), b3 + hstep, voffB);
;             PG8_WAIT_V(6); PG8_BAR; PG8_MMA(1, 1, At, B1); PG8_BAR;
	s_add_u32 s6, s36, 0xfffc0080
	s_addc_u32 s7, s37, -1
	s_add_i32 s58, 0, 0x10000
	v_add_u32_e32 v144, s58, v147
	ds_read_b128 v[140:143], v144
	ds_read_b128 v[152:155], v144 offset:1024
	ds_read_b128 v[168:171], v144 offset:2048
	ds_read_b128 v[172:175], v144 offset:3072
	s_cmp_eq_u32 s93, 12
	s_cselect_b32 s43, s11, s7
	s_cselect_b32 s42, s71, s6
	s_cselect_b32 s7, s9, s92
	s_cselect_b32 s6, s90, s91
	ds_read_b128 v[176:179], v150
	ds_read_b128 v[180:183], v150 offset:1024
	ds_read_b128 v[184:187], v150 offset:2048
	ds_read_b128 v[204:207], v150 offset:3072
	ds_read_b128 v[208:211], v150 offset:4096
	ds_read_b128 v[212:215], v150 offset:5120
	ds_read_b128 v[216:219], v150 offset:6144
	ds_read_b128 v[226:229], v150 offset:7168
	s_waitcnt lgkmcnt(8)
	s_barrier
	s_waitcnt lgkmcnt(0)
	s_setprio 1
	s_waitcnt lgkmcnt(0)
	v_mfma_f32_16x16x32_bf16 v[126:129], v[140:143], v[176:179], v[126:129]
	v_mfma_f32_16x16x32_bf16 v[122:125], v[168:171], v[176:179], v[122:125]
	v_mfma_f32_16x16x32_bf16 v[110:113], v[140:143], v[184:187], v[110:113]
	v_mfma_f32_16x16x32_bf16 v[106:109], v[168:171], v[184:187], v[106:109]
	s_add_i32 m0, s49, 0xc000
	s_nop 0
	global_load_lds_dwordx4 v136, s[36:37]
	v_mfma_f32_16x16x32_bf16 v[94:97], v[140:143], v[208:211], v[94:97]
	v_mfma_f32_16x16x32_bf16 v[90:93], v[168:171], v[208:211], v[90:93]
	v_mfma_f32_16x16x32_bf16 v[78:81], v[140:143], v[216:219], v[78:81]
	v_mfma_f32_16x16x32_bf16 v[74:77], v[168:171], v[216:219], v[74:77]
	v_mfma_f32_16x16x32_bf16 v[126:129], v[152:155], v[180:183], v[126:129]
	v_mfma_f32_16x16x32_bf16 v[122:125], v[172:175], v[180:183], v[122:125]
	s_add_i32 m0, s49, 0xe000
	s_nop 0
	global_load_lds_dwordx4 v138, s[36:37]
	v_mfma_f32_16x16x32_bf16 v[110:113], v[152:155], v[204:207], v[110:113]
	v_mfma_f32_16x16x32_bf16 v[106:109], v[172:175], v[204:207], v[106:109]
	v_mfma_f32_16x16x32_bf16 v[94:97], v[152:155], v[212:215], v[94:97]
	v_mfma_f32_16x16x32_bf16 v[90:93], v[172:175], v[212:215], v[90:93]
	v_mfma_f32_16x16x32_bf16 v[78:81], v[152:155], v[226:229], v[78:81]
	v_mfma_f32_16x16x32_bf16 v[74:77], v[172:175], v[226:229], v[74:77]
	s_setprio 0
	s_barrier
	s_add_i32 s70, 0, 0x14000
	v_add_u32_e32 v144, s70, v147
	s_add_i32 s58, s58, s48
	ds_read_b128 v[230:233], v144
	ds_read_b128 v[234:237], v144 offset:1024
	ds_read_b128 v[238:241], v144 offset:2048
	ds_read_b128 v[242:245], v144 offset:3072
	s_barrier
	s_waitcnt lgkmcnt(0)
	s_setprio 1
	s_waitcnt lgkmcnt(0)
	v_mfma_f32_16x16x32_bf16 v[118:121], v[230:233], v[176:179], v[118:121]
	v_mfma_f32_16x16x32_bf16 v[114:117], v[238:241], v[176:179], v[114:117]
	v_mfma_f32_16x16x32_bf16 v[102:105], v[230:233], v[184:187], v[102:105]
	v_mfma_f32_16x16x32_bf16 v[98:101], v[238:241], v[184:187], v[98:101]
	s_mov_b32 m0, s58
	s_nop 0
	global_load_lds_dwordx4 v0, s[6:7]
	v_mfma_f32_16x16x32_bf16 v[86:89], v[230:233], v[208:211], v[86:89]
	v_mfma_f32_16x16x32_bf16 v[82:85], v[238:241], v[208:211], v[82:85]
	v_mfma_f32_16x16x32_bf16 v[70:73], v[230:233], v[216:219], v[70:73]
	v_mfma_f32_16x16x32_bf16 v[66:69], v[238:241], v[216:219], v[66:69]
	v_mfma_f32_16x16x32_bf16 v[118:121], v[234:237], v[180:183], v[118:121]
	v_mfma_f32_16x16x32_bf16 v[114:117], v[242:245], v[180:183], v[114:117]
	s_add_i32 m0, s58, 0x2000
	s_nop 0
	global_load_lds_dwordx4 v130, s[6:7]
	v_mfma_f32_16x16x32_bf16 v[102:105], v[234:237], v[204:207], v[102:105]
	v_mfma_f32_16x16x32_bf16 v[98:101], v[242:245], v[204:207], v[98:101]
	v_mfma_f32_16x16x32_bf16 v[86:89], v[234:237], v[212:215], v[86:89]
	v_mfma_f32_16x16x32_bf16 v[82:85], v[242:245], v[212:215], v[82:85]
	v_mfma_f32_16x16x32_bf16 v[70:73], v[234:237], v[226:229], v[70:73]
	v_mfma_f32_16x16x32_bf16 v[66:69], v[242:245], v[226:229], v[66:69]
	s_setprio 0
	s_add_u32 vcc_lo, s42, 0x80
	s_addc_u32 vcc_hi, s43, 0
	s_barrier
	ds_read_b128 v[176:179], v150 offset:16384
	ds_read_b128 v[180:183], v150 offset:17408
	ds_read_b128 v[184:187], v150 offset:18432
	ds_read_b128 v[204:207], v150 offset:19456
	ds_read_b128 v[208:211], v150 offset:20480
	ds_read_b128 v[212:215], v150 offset:21504
	ds_read_b128 v[216:219], v150 offset:22528
	ds_read_b128 v[226:229], v150 offset:23552
	s_barrier
	s_waitcnt lgkmcnt(0)
	s_setprio 1
	s_waitcnt lgkmcnt(0)
	v_mfma_f32_16x16x32_bf16 v[62:65], v[140:143], v[176:179], v[62:65]
	v_mfma_f32_16x16x32_bf16 v[58:61], v[168:171], v[176:179], v[58:61]
	v_mfma_f32_16x16x32_bf16 v[46:49], v[140:143], v[184:187], v[46:49]
	v_mfma_f32_16x16x32_bf16 v[42:45], v[168:171], v[184:187], v[42:45]
	s_mov_b32 m0, s49
	s_nop 0
	global_load_lds_dwordx4 v134, s[42:43]
	v_mfma_f32_16x16x32_bf16 v[30:33], v[140:143], v[208:211], v[30:33]
	v_mfma_f32_16x16x32_bf16 v[26:29], v[168:171], v[208:211], v[26:29]
	v_mfma_f32_16x16x32_bf16 v[14:17], v[140:143], v[216:219], v[14:17]
	v_mfma_f32_16x16x32_bf16 v[10:13], v[168:171], v[216:219], v[10:13]
	v_mfma_f32_16x16x32_bf16 v[62:65], v[152:155], v[180:183], v[62:65]
	v_mfma_f32_16x16x32_bf16 v[58:61], v[172:175], v[180:183], v[58:61]
	s_mov_b32 m0, s54
	s_nop 0
	global_load_lds_dwordx4 v132, s[42:43]
	v_mfma_f32_16x16x32_bf16 v[46:49], v[152:155], v[204:207], v[46:49]
	v_mfma_f32_16x16x32_bf16 v[42:45], v[172:175], v[204:207], v[42:45]
	v_mfma_f32_16x16x32_bf16 v[30:33], v[152:155], v[212:215], v[30:33]
	v_mfma_f32_16x16x32_bf16 v[26:29], v[172:175], v[212:215], v[26:29]
	v_mfma_f32_16x16x32_bf16 v[14:17], v[152:155], v[226:229], v[14:17]
	v_mfma_f32_16x16x32_bf16 v[10:13], v[172:175], v[226:229], v[10:13]
	s_setprio 0
	s_barrier
	s_add_u32 s60, s6, 0x40000
	s_addc_u32 s61, s7, 0
	s_add_i32 s58, s70, s48
	s_waitcnt vmcnt(4)
	s_barrier
	s_setprio 1
	v_mfma_f32_16x16x32_bf16 v[54:57], v[230:233], v[176:179], v[54:57]
	v_mfma_f32_16x16x32_bf16 v[50:53], v[238:241], v[176:179], v[50:53]
	s_cmp_eq_u32 s89, 0
	s_cbranch_scc1 .LdsE_skip_6
	global_store_dwordx4 v250, v[222:225], s[4:5]
; #define PG8_STAGE(bufoff, gbase, voff) do { _Pragma("unroll") for (int _i = 0; _i < 2; ++_i) \
;         __builtin_amdgcn_global_load_lds((const unsigned*)((const char*)(gbase) + (voff)[_i]), (LAS unsigned*)(lds + (bufoff) + ldsw + _i * 8192), 16, 0, 0); } while (0)
; #define PG8_LDA(dst, b, h) do { _Pragma("unroll") for (int m = 0; m < 4; ++m) _Pragma("unroll") for (int k = 0; k < 2; ++k) dst[m][k] = *(const LAS bf16x8*)(lds + PG8_SA(b, h) + aoff + m * 2048 + k * 1024); } while (0)
; #define PG8_LDB(dst, b, h) do { _Pragma("unroll") for (int n = 0; n < 2; ++n) _Pragma("unroll") for (int k = 0; k < 2; ++k) dst[n][k] = *(const LAS bf16x8*)(lds + PG8_SB(b, h) + boff + n * 2048 + k * 1024); } while (0)
; #define PG8_WAIT_V(n) asm volatile("s_waitcnt vmcnt(" #n ")" ::: "memory")
; template <class Epi>
; __device__ __forceinline__ void gemm_phase(LAS unsigned char* lds, const Gemm g, const StaticOrder& S, const Epi& E) {
;     ...
;             const char* a2 = last ? nA : cA + (size_t)(t + 2) * kstep; const char* b2 = last ? nB : cB + (size_t)(t + 2) * kstep;
;             const char* a3 = a2 + kstep; const char* b3 = b2 + kstep;
;             PG8_LDB(B0, 0, 0); PG8_SCHED; PG8_LDA(At, 0, 0); PG8_STAGE(PG8_SA(1, 1), a1 + hstep, voffA);
;             PG8_WAIT_L(8); PG8_BAR; PG8_WAIT_L(0); PG8_MMA(0, 0, At, B0); PG8_BAR; PG8_SCHED;
;             PG8_LDB(B1, 0, 1); PG8_STAGE(PG8_SB(0, 0), b2, voffB);
;             PG8_BAR; PG8_WAIT_L(0); PG8_MMA(0, 1, At, B1); PG8_BAR;
;             PG8_LDA(At, 0, 1); PG8_STAGE(PG8_SA(0, 0), a2, voffA);
;             PG8_BAR; PG8_WAIT_L(0); PG8_MMA(1, 0, At, B0); PG8_BAR; PG8_SCHED;
;             PG8_STAGE(PG8_SB(0, 1), b2 + hstep, voffB);
;             PG8_WAIT_V(6); PG8_BAR; PG8_MMA(1, 1, At, B1); PG8_BAR;
;             PG8_LDB(B0, 1, 0); PG8_SCHED; PG8_LDA(At, 1, 0); PG8_STAGE(PG8_SA(0, 1), a2 + hstep, voffA);
;             PG8_WAIT_L(8); PG8_BAR; PG8_WAIT_L(0); PG8_MMA(0, 0, At, B0); PG8_BAR; PG8_SCHED;
;             PG8_LDB(B1, 1, 1); PG8_STAGE(PG8_SB(1, 0), b3, voffB);
;             PG8_BAR; PG8_WAIT_L(0); PG8_MMA(0, 1, At, B1); PG8_BAR;
;             PG8_LDA(At, 1, 1); PG8_STAGE(PG8_SA(1, 0), a3, voffA);
;             PG8_BAR; PG8_WAIT_L(0); PG8_MMA(1, 0, At, B0); PG8_BAR; PG8_SCHED;
;             PG8_STAGE(PG8_SB(1, 1), b3 + hstep, voffB);
;             PG8_WAIT_V(6); PG8_BAR; PG8_MMA(1, 1, At, B1); PG8_BAR;
.LdsE_skip_6:
	v_mfma_f32_16x16x32_bf16 v[38:41], v[230:233], v[184:187], v[38:41]
	v_mfma_f32_16x16x32_bf16 v[34:37], v[238:241], v[184:187], v[34:37]
	s_mov_b32 m0, s58
	s_nop 0
	global_load_lds_dwordx4 v0, s[60:61]
	v_mfma_f32_16x16x32_bf16 v[22:25], v[230:233], v[208:211], v[22:25]
	v_mfma_f32_16x16x32_bf16 v[18:21], v[238:241], v[208:211], v[18:21]
	v_mfma_f32_16x16x32_bf16 v[6:9], v[230:233], v[216:219], v[6:9]
	v_mfma_f32_16x16x32_bf16 v[2:5], v[238:241], v[216:219], v[2:5]
	v_mfma_f32_16x16x32_bf16 v[54:57], v[234:237], v[180:183], v[54:57]
	v_mfma_f32_16x16x32_bf16 v[50:53], v[242:245], v[180:183], v[50:53]
	s_add_i32 m0, s58, 0x2000
	s_nop 0
	global_load_lds_dwordx4 v130, s[60:61]
	v_mfma_f32_16x16x32_bf16 v[38:41], v[234:237], v[204:207], v[38:41]
	v_mfma_f32_16x16x32_bf16 v[34:37], v[242:245], v[204:207], v[34:37]
	v_mfma_f32_16x16x32_bf16 v[22:25], v[234:237], v[212:215], v[22:25]
	v_mfma_f32_16x16x32_bf16 v[18:21], v[242:245], v[212:215], v[18:21]
	v_mfma_f32_16x16x32_bf16 v[6:9], v[234:237], v[226:229], v[6:9]
	v_mfma_f32_16x16x32_bf16 v[2:5], v[242:245], v[226:229], v[2:5]
	s_setprio 0
	s_add_i32 s58, 0, 0x18000
	v_add_u32_e32 v151, s58, v147
	s_barrier
	ds_read_b128 v[140:143], v151
	ds_read_b128 v[152:155], v151 offset:1024
	ds_read_b128 v[168:171], v151 offset:2048
	ds_read_b128 v[172:175], v151 offset:3072
	s_add_u32 s42, s42, 0x40000
	s_addc_u32 s43, s43, 0
	ds_read_b128 v[176:179], v150 offset:32768
	ds_read_b128 v[180:183], v150 offset:33792
	ds_read_b128 v[184:187], v150 offset:34816
	ds_read_b128 v[204:207], v150 offset:35840
	ds_read_b128 v[208:211], v150 offset:36864
	ds_read_b128 v[212:215], v150 offset:37888
	ds_read_b128 v[216:219], v150 offset:38912
	ds_read_b128 v[226:229], v150 offset:39936
	s_waitcnt lgkmcnt(8)
	s_barrier
	s_waitcnt lgkmcnt(0)
	s_setprio 1
	s_waitcnt lgkmcnt(0)
	v_mfma_f32_16x16x32_bf16 v[126:129], v[140:143], v[176:179], v[126:129]
	v_mfma_f32_16x16x32_bf16 v[122:125], v[168:171], v[176:179], v[122:125]
	v_mfma_f32_16x16x32_bf16 v[110:113], v[140:143], v[184:187], v[110:113]
	v_mfma_f32_16x16x32_bf16 v[106:109], v[168:171], v[184:187], v[106:109]
	s_mov_b32 m0, s55
	s_nop 0
	global_load_lds_dwordx4 v134, s[42:43]
	v_mfma_f32_16x16x32_bf16 v[94:97], v[140:143], v[208:211], v[94:97]
	v_mfma_f32_16x16x32_bf16 v[90:93], v[168:171], v[208:211], v[90:93]
	v_mfma_f32_16x16x32_bf16 v[78:81], v[140:143], v[216:219], v[78:81]
	v_mfma_f32_16x16x32_bf16 v[74:77], v[168:171], v[216:219], v[74:77]
	v_mfma_f32_16x16x32_bf16 v[126:129], v[152:155], v[180:183], v[126:129]
	v_mfma_f32_16x16x32_bf16 v[122:125], v[172:175], v[180:183], v[122:125]
	s_mov_b32 m0, s83
	s_nop 0
	global_load_lds_dwordx4 v132, s[42:43]
	v_mfma_f32_16x16x32_bf16 v[110:113], v[152:155], v[204:207], v[110:113]
	v_mfma_f32_16x16x32_bf16 v[106:109], v[172:175], v[204:207], v[106:109]
	v_mfma_f32_16x16x32_bf16 v[94:97], v[152:155], v[212:215], v[94:97]
	v_mfma_f32_16x16x32_bf16 v[90:93], v[172:175], v[212:215], v[90:93]
	v_mfma_f32_16x16x32_bf16 v[78:81], v[152:155], v[226:229], v[78:81]
	v_mfma_f32_16x16x32_bf16 v[74:77], v[172:175], v[226:229], v[74:77]
	s_setprio 0
	s_barrier
	s_add_i32 s42, 0, 0x1c000
	s_add_i32 s43, s58, s48
	v_add_u32_e32 v151, s42, v147
	s_add_u32 s60, s6, 0x80
	s_addc_u32 s61, s7, 0
	ds_read_b128 v[230:233], v151
	ds_read_b128 v[234:237], v151 offset:1024
	ds_read_b128 v[238:241], v151 offset:2048
	ds_read_b128 v[242:245], v151 offset:3072
	s_barrier
	s_waitcnt lgkmcnt(0)
	s_setprio 1
	s_waitcnt lgkmcnt(0)
	v_mfma_f32_16x16x32_bf16 v[118:121], v[230:233], v[176:179], v[118:121]
	v_mfma_f32_16x16x32_bf16 v[114:117], v[238:241], v[176:179], v[114:117]
	v_mfma_f32_16x16x32_bf16 v[102:105], v[230:233], v[184:187], v[102:105]
	v_mfma_f32_16x16x32_bf16 v[98:101], v[238:241], v[184:187], v[98:101]
	s_mov_b32 m0, s43
	s_nop 0
	global_load_lds_dwordx4 v0, s[60:61]
	v_mfma_f32_16x16x32_bf16 v[86:89], v[230:233], v[208:211], v[86:89]
	v_mfma_f32_16x16x32_bf16 v[82:85], v[238:241], v[208:211], v[82:85]
	v_mfma_f32_16x16x32_bf16 v[70:73], v[230:233], v[216:219], v[70:73]
	v_mfma_f32_16x16x32_bf16 v[66:69], v[238:241], v[216:219], v[66:69]
	v_mfma_f32_16x16x32_bf16 v[118:121], v[234:237], v[180:183], v[118:121]
	v_mfma_f32_16x16x32_bf16 v[114:117], v[242:245], v[180:183], v[114:117]
	s_add_i32 m0, s43, 0x2000
	s_nop 0
	global_load_lds_dwordx4 v130, s[60:61]
	v_mfma_f32_16x16x32_bf16 v[102:105], v[234:237], v[204:207], v[102:105]
	v_mfma_f32_16x16x32_bf16 v[98:101], v[242:245], v[204:207], v[98:101]
	v_mfma_f32_16x16x32_bf16 v[86:89], v[234:237], v[212:215], v[86:89]
	v_mfma_f32_16x16x32_bf16 v[82:85], v[242:245], v[212:215], v[82:85]
	v_mfma_f32_16x16x32_bf16 v[70:73], v[234:237], v[226:229], v[70:73]
	v_mfma_f32_16x16x32_bf16 v[66:69], v[242:245], v[226:229], v[66:69]
	s_setprio 0
	s_barrier
	ds_read_b128 v[176:179], v150 offset:49152
	ds_read_b128 v[180:183], v150 offset:50176
	ds_read_b128 v[184:187], v150 offset:51200
	ds_read_b128 v[204:207], v150 offset:52224
	ds_read_b128 v[208:211], v150 offset:53248
	ds_read_b128 v[212:215], v150 offset:54272
	ds_read_b128 v[216:219], v150 offset:55296
	ds_read_b128 v[226:229], v150 offset:56320
	s_barrier
; #define PG8_STAGE(bufoff, gbase, voff) do { _Pragma("unroll") for (int _i = 0; _i < 2; ++_i) \
;         __builtin_amdgcn_global_load_lds((const unsigned*)((const char*)(gbase) + (voff)[_i]), (LAS unsigned*)(lds + (bufoff) + ldsw + _i * 8192), 16, 0, 0); } while (0)
; #define PG8_LDA(dst, b, h) do { _Pragma("unroll") for (int m = 0; m < 4; ++m) _Pragma("unroll") for (int k = 0; k < 2; ++k) dst[m][k] = *(const LAS bf16x8*)(lds + PG8_SA(b, h) + aoff + m * 2048 + k * 1024); } while (0)
; #define PG8_LDB(dst, b, h) do { _Pragma("unroll") for (int n = 0; n < 2; ++n) _Pragma("unroll") for (int k = 0; k < 2; ++k) dst[n][k] = *(const LAS bf16x8*)(lds + PG8_SB(b, h) + boff + n * 2048 + k * 1024); } while (0)
; #define PG8_WAIT_V(n) asm volatile("s_waitcnt vmcnt(" #n ")" ::: "memory")
; template <class Epi>
; __device__ __forceinline__ void gemm_phase(LAS unsigned char* lds, const Gemm g, const StaticOrder& S, const Epi& E) {
;     ...
;             const char* a2 = last ? nA : cA + (size_t)(t + 2) * kstep; const char* b2 = last ? nB : cB + (size_t)(t + 2) * kstep;
;             const char* a3 = a2 + kstep; const char* b3 = b2 + kstep;
;             PG8_LDB(B0, 0, 0); PG8_SCHED; PG8_LDA(At, 0, 0); PG8_STAGE(PG8_SA(1, 1), a1 + hstep, voffA);
;             PG8_WAIT_L(8); PG8_BAR; PG8_WAIT_L(0); PG8_MMA(0, 0, At, B0); PG8_BAR; PG8_SCHED;
;             PG8_LDB(B1, 0, 1); PG8_STAGE(PG8_SB(0, 0), b2, voffB);
;             PG8_BAR; PG8_WAIT_L(0); PG8_MMA(0, 1, At, B1); PG8_BAR;
;             PG8_LDA(At, 0, 1); PG8_STAGE(PG8_SA(0, 0), a2, voffA);
;             PG8_BAR; PG8_WAIT_L(0); PG8_MMA(1, 0, At, B0); PG8_BAR; PG8_SCHED;
;             PG8_STAGE(PG8_SB(0, 1), b2 + hstep, voffB);
;             PG8_WAIT_V(6); PG8_BAR; PG8_MMA(1, 1, At, B1); PG8_BAR;
;             PG8_LDB(B0, 1, 0); PG8_SCHED; PG8_LDA(At, 1, 0); PG8_STAGE(PG8_SA(0, 1), a2 + hstep, voffA);
;             PG8_WAIT_L(8); PG8_BAR; PG8_WAIT_L(0); PG8_MMA(0, 0, At, B0); PG8_BAR; PG8_SCHED;
;             PG8_LDB(B1, 1, 1); PG8_STAGE(PG8_SB(1, 0), b3, voffB);
;             PG8_BAR; PG8_WAIT_L(0); PG8_MMA(0, 1, At, B1); PG8_BAR;
;             PG8_LDA(At, 1, 1); PG8_STAGE(PG8_SA(1, 0), a3, voffA);
;             PG8_BAR; PG8_WAIT_L(0); PG8_MMA(1, 0, At, B0); PG8_BAR; PG8_SCHED;
;             PG8_STAGE(PG8_SB(1, 1), b3 + hstep, voffB);
;             PG8_WAIT_V(6); PG8_BAR; PG8_MMA(1, 1, At, B1); PG8_BAR;
	s_waitcnt lgkmcnt(0)
	s_setprio 1
	s_waitcnt lgkmcnt(0)
	v_mfma_f32_16x16x32_bf16 v[62:65], v[140:143], v[176:179], v[62:65]
	v_mfma_f32_16x16x32_bf16 v[58:61], v[168:171], v[176:179], v[58:61]
	v_mfma_f32_16x16x32_bf16 v[46:49], v[140:143], v[184:187], v[46:49]
	v_mfma_f32_16x16x32_bf16 v[42:45], v[168:171], v[184:187], v[42:45]
	s_mov_b32 m0, s84
	s_nop 0
	global_load_lds_dwordx4 v134, vcc
	v_mfma_f32_16x16x32_bf16 v[30:33], v[140:143], v[208:211], v[30:33]
	v_mfma_f32_16x16x32_bf16 v[26:29], v[168:171], v[208:211], v[26:29]
	v_mfma_f32_16x16x32_bf16 v[14:17], v[140:143], v[216:219], v[14:17]
	v_mfma_f32_16x16x32_bf16 v[10:13], v[168:171], v[216:219], v[10:13]
	v_mfma_f32_16x16x32_bf16 v[62:65], v[152:155], v[180:183], v[62:65]
	v_mfma_f32_16x16x32_bf16 v[58:61], v[172:175], v[180:183], v[58:61]
	s_mov_b32 m0, s85
	s_nop 0
	global_load_lds_dwordx4 v132, vcc
	v_mfma_f32_16x16x32_bf16 v[46:49], v[152:155], v[204:207], v[46:49]
	v_mfma_f32_16x16x32_bf16 v[42:45], v[172:175], v[204:207], v[42:45]
	v_mfma_f32_16x16x32_bf16 v[30:33], v[152:155], v[212:215], v[30:33]
	v_mfma_f32_16x16x32_bf16 v[26:29], v[172:175], v[212:215], v[26:29]
	v_mfma_f32_16x16x32_bf16 v[14:17], v[152:155], v[226:229], v[14:17]
	v_mfma_f32_16x16x32_bf16 v[10:13], v[172:175], v[226:229], v[10:13]
	s_setprio 0
	s_barrier
	s_add_u32 s6, s6, 0x40080
	s_addc_u32 s7, s7, 0
	s_add_i32 s42, s42, s48
	s_waitcnt vmcnt(4)
	s_barrier
	s_setprio 1
	v_mfma_f32_16x16x32_bf16 v[54:57], v[230:233], v[176:179], v[54:57]
	v_mfma_f32_16x16x32_bf16 v[50:53], v[238:241], v[176:179], v[50:53]
	v_mfma_f32_16x16x32_bf16 v[38:41], v[230:233], v[184:187], v[38:41]
	v_mfma_f32_16x16x32_bf16 v[34:37], v[238:241], v[184:187], v[34:37]
	s_mov_b32 m0, s42
	s_nop 0
	global_load_lds_dwordx4 v0, s[6:7]
	v_mfma_f32_16x16x32_bf16 v[22:25], v[230:233], v[208:211], v[22:25]
	v_mfma_f32_16x16x32_bf16 v[18:21], v[238:241], v[208:211], v[18:21]
	v_mfma_f32_16x16x32_bf16 v[6:9], v[230:233], v[216:219], v[6:9]
	v_mfma_f32_16x16x32_bf16 v[2:5], v[238:241], v[216:219], v[2:5]
	v_mfma_f32_16x16x32_bf16 v[54:57], v[234:237], v[180:183], v[54:57]
	v_mfma_f32_16x16x32_bf16 v[50:53], v[242:245], v[180:183], v[50:53]
	s_add_i32 m0, s42, 0x2000
	s_nop 0
	global_load_lds_dwordx4 v130, s[6:7]
	v_mfma_f32_16x16x32_bf16 v[38:41], v[234:237], v[204:207], v[38:41]
	v_mfma_f32_16x16x32_bf16 v[34:37], v[242:245], v[204:207], v[34:37]
	v_mfma_f32_16x16x32_bf16 v[22:25], v[234:237], v[212:215], v[22:25]
	v_mfma_f32_16x16x32_bf16 v[18:21], v[242:245], v[212:215], v[18:21]
	v_mfma_f32_16x16x32_bf16 v[6:9], v[234:237], v[226:229], v[6:9]
	v_mfma_f32_16x16x32_bf16 v[2:5], v[242:245], v[226:229], v[2:5]
	s_setprio 0
	s_add_i32 s93, s93, 2
	s_add_u32 s36, s36, 0x100
	s_addc_u32 s37, s37, 0
	s_add_u32 s91, s91, 0x100
	s_addc_u32 s92, s92, 0
	s_cmp_gt_u32 s93, 13
	s_barrier
	s_add_u32 s6, s36, 0xfffc0080
	s_addc_u32 s7, s37, -1
	s_add_i32 s58, 0, 0x10000
	v_add_u32_e32 v144, s58, v147
	ds_read_b128 v[140:143], v144
	ds_read_b128 v[152:155], v144 offset:1024
	ds_read_b128 v[168:171], v144 offset:2048
	ds_read_b128 v[172:175], v144 offset:3072
	s_cmp_eq_u32 s93, 12
	s_cselect_b32 s43, s11, s7
	s_cselect_b32 s42, s71, s6
	s_cselect_b32 s7, s9, s92
	s_cselect_b32 s6, s90, s91
	ds_read_b128 v[176:179], v150
	ds_read_b128 v[180:183], v150 offset:1024
	ds_read_b128 v[184:187], v150 offset:2048
	ds_read_b128 v[204:207], v150 offset:3072
	ds_read_b128 v[208:211], v150 offset:4096
	ds_read_b128 v[212:215], v150 offset:5120
	ds_read_b128 v[216:219], v150 offset:6144
	ds_read_b128 v[226:229], v150 offset:7168
	s_waitcnt lgkmcnt(8)
	s_barrier
	s_waitcnt lgkmcnt(0)
	s_setprio 1
	s_waitcnt lgkmcnt(0)
	v_mfma_f32_16x16x32_bf16 v[126:129], v[140:143], v[176:179], v[126:129]
	v_mfma_f32_16x16x32_bf16 v[122:125], v[168:171], v[176:179], v[122:125]
	v_mfma_f32_16x16x32_bf16 v[110:113], v[140:143], v[184:187], v[110:113]
	v_mfma_f32_16x16x32_bf16 v[106:109], v[168:171], v[184:187], v[106:109]
	s_add_i32 m0, s49, 0xc000
	s_nop 0
	global_load_lds_dwordx4 v136, s[36:37]
	v_mfma_f32_16x16x32_bf16 v[94:97], v[140:143], v[208:211], v[94:97]
	v_mfma_f32_16x16x32_bf16 v[90:93], v[168:171], v[208:211], v[90:93]
	v_mfma_f32_16x16x32_bf16 v[78:81], v[140:143], v[216:219], v[78:81]
	v_mfma_f32_16x16x32_bf16 v[74:77], v[168:171], v[216:219], v[74:77]
	v_mfma_f32_16x16x32_bf16 v[126:129], v[152:155], v[180:183], v[126:129]
	v_mfma_f32_16x16x32_bf16 v[122:125], v[172:175], v[180:183], v[122:125]
	s_add_i32 m0, s49, 0xe000
	s_nop 0
	global_load_lds_dwordx4 v138, s[36:37]
	v_mfma_f32_16x16x32_bf16 v[110:113], v[152:155], v[204:207], v[110:113]
	v_mfma_f32_16x16x32_bf16 v[106:109], v[172:175], v[204:207], v[106:109]
	v_mfma_f32_16x16x32_bf16 v[94:97], v[152:155], v[212:215], v[94:97]
	v_mfma_f32_16x16x32_bf16 v[90:93], v[172:175], v[212:215], v[90:93]
	v_mfma_f32_16x16x32_bf16 v[78:81], v[152:155], v[226:229], v[78:81]
	v_mfma_f32_16x16x32_bf16 v[74:77], v[172:175], v[226:229], v[74:77]
	s_setprio 0
	s_barrier
	s_add_i32 s70, 0, 0x14000
	v_add_u32_e32 v144, s70, v147
	s_add_i32 s58, s58, s48
	ds_read_b128 v[230:233], v144
	ds_read_b128 v[234:237], v144 offset:1024
	ds_read_b128 v[238:241], v144 offset:2048
	ds_read_b128 v[242:245], v144 offset:3072
	s_barrier
; #define PG8_STAGE(bufoff, gbase, voff) do { _Pragma("unroll") for (int _i = 0; _i < 2; ++_i) \
;         __builtin_amdgcn_global_load_lds((const unsigned*)((const char*)(gbase) + (voff)[_i]), (LAS unsigned*)(lds + (bufoff) + ldsw + _i * 8192), 16, 0, 0); } while (0)
; #define PG8_LDA(dst, b, h) do { _Pragma("unroll") for (int m = 0; m < 4; ++m) _Pragma("unroll") for (int k = 0; k < 2; ++k) dst[m][k] = *(const LAS bf16x8*)(lds + PG8_SA(b, h) + aoff + m * 2048 + k * 1024); } while (0)
; #define PG8_LDB(dst, b, h) do { _Pragma("unroll") for (int n = 0; n < 2; ++n) _Pragma("unroll") for (int k = 0; k < 2; ++k) dst[n][k] = *(const LAS bf16x8*)(lds + PG8_SB(b, h) + boff + n * 2048 + k * 1024); } while (0)
; #define PG8_WAIT_V(n) asm volatile("s_waitcnt vmcnt(" #n ")" ::: "memory")
; template <class Epi>
; __device__ __forceinline__ void gemm_phase(LAS unsigned char* lds, const Gemm g, const StaticOrder& S, const Epi& E) {
;     ...
;             const char* a2 = last ? nA : cA + (size_t)(t + 2) * kstep; const char* b2 = last ? nB : cB + (size_t)(t + 2) * kstep;
;             const char* a3 = a2 + kstep; const char* b3 = b2 + kstep;
;             PG8_LDB(B0, 0, 0); PG8_SCHED; PG8_LDA(At, 0, 0); PG8_STAGE(PG8_SA(1, 1), a1 + hstep, voffA);
;             PG8_WAIT_L(8); PG8_BAR; PG8_WAIT_L(0); PG8_MMA(0, 0, At, B0); PG8_BAR; PG8_SCHED;
;             PG8_LDB(B1, 0, 1); PG8_STAGE(PG8_SB(0, 0), b2, voffB);
;             PG8_BAR; PG8_WAIT_L(0); PG8_MMA(0, 1, At, B1); PG8_BAR;
;             PG8_LDA(At, 0, 1); PG8_STAGE(PG8_SA(0, 0), a2, voffA);
;             PG8_BAR; PG8_WAIT_L(0); PG8_MMA(1, 0, At, B0); PG8_BAR; PG8_SCHED;
;             PG8_STAGE(PG8_SB(0, 1), b2 + hstep, voffB);
;             PG8_WAIT_V(6); PG8_BAR; PG8_MMA(1, 1, At, B1); PG8_BAR;
;             PG8_LDB(B0, 1, 0); PG8_SCHED; PG8_LDA(At, 1, 0); PG8_STAGE(PG8_SA(0, 1), a2 + hstep, voffA);
;             PG8_WAIT_L(8); PG8_BAR; PG8_WAIT_L(0); PG8_MMA(0, 0, At, B0); PG8_BAR; PG8_SCHED;
;             PG8_LDB(B1, 1, 1); PG8_STAGE(PG8_SB(1, 0), b3, voffB);
;             PG8_BAR; PG8_WAIT_L(0); PG8_MMA(0, 1, At, B1); PG8_BAR;
;             PG8_LDA(At, 1, 1); PG8_STAGE(PG8_SA(1, 0), a3, voffA);
;             PG8_BAR; PG8_WAIT_L(0); PG8_MMA(1, 0, At, B0); PG8_BAR; PG8_SCHED;
;             PG8_STAGE(PG8_SB(1, 1), b3 + hstep, voffB);
;             PG8_WAIT_V(6); PG8_BAR; PG8_MMA(1, 1, At, B1); PG8_BAR;
	s_waitcnt lgkmcnt(0)
	s_setprio 1
	s_waitcnt lgkmcnt(0)
	v_mfma_f32_16x16x32_bf16 v[118:121], v[230:233], v[176:179], v[118:121]
	v_mfma_f32_16x16x32_bf16 v[114:117], v[238:241], v[176:179], v[114:117]
	v_mfma_f32_16x16x32_bf16 v[102:105], v[230:233], v[184:187], v[102:105]
	v_mfma_f32_16x16x32_bf16 v[98:101], v[238:241], v[184:187], v[98:101]
	s_mov_b32 m0, s58
	s_nop 0
	global_load_lds_dwordx4 v0, s[6:7]
	v_mfma_f32_16x16x32_bf16 v[86:89], v[230:233], v[208:211], v[86:89]
	v_mfma_f32_16x16x32_bf16 v[82:85], v[238:241], v[208:211], v[82:85]
	v_mfma_f32_16x16x32_bf16 v[70:73], v[230:233], v[216:219], v[70:73]
	v_mfma_f32_16x16x32_bf16 v[66:69], v[238:241], v[216:219], v[66:69]
	v_mfma_f32_16x16x32_bf16 v[118:121], v[234:237], v[180:183], v[118:121]
	v_mfma_f32_16x16x32_bf16 v[114:117], v[242:245], v[180:183], v[114:117]
	s_add_i32 m0, s58, 0x2000
	s_nop 0
	global_load_lds_dwordx4 v130, s[6:7]
	v_mfma_f32_16x16x32_bf16 v[102:105], v[234:237], v[204:207], v[102:105]
	v_mfma_f32_16x16x32_bf16 v[98:101], v[242:245], v[204:207], v[98:101]
	v_mfma_f32_16x16x32_bf16 v[86:89], v[234:237], v[212:215], v[86:89]
	v_mfma_f32_16x16x32_bf16 v[82:85], v[242:245], v[212:215], v[82:85]
	v_mfma_f32_16x16x32_bf16 v[70:73], v[234:237], v[226:229], v[70:73]
	v_mfma_f32_16x16x32_bf16 v[66:69], v[242:245], v[226:229], v[66:69]
	s_setprio 0
	s_add_u32 vcc_lo, s42, 0x80
	s_addc_u32 vcc_hi, s43, 0
	s_barrier
	ds_read_b128 v[176:179], v150 offset:16384
	ds_read_b128 v[180:183], v150 offset:17408
	ds_read_b128 v[184:187], v150 offset:18432
	ds_read_b128 v[204:207], v150 offset:19456
	ds_read_b128 v[208:211], v150 offset:20480
	ds_read_b128 v[212:215], v150 offset:21504
	ds_read_b128 v[216:219], v150 offset:22528
	ds_read_b128 v[226:229], v150 offset:23552
	s_barrier
	s_waitcnt lgkmcnt(0)
	s_setprio 1
	s_waitcnt lgkmcnt(0)
	v_mfma_f32_16x16x32_bf16 v[62:65], v[140:143], v[176:179], v[62:65]
	v_mfma_f32_16x16x32_bf16 v[58:61], v[168:171], v[176:179], v[58:61]
	v_mfma_f32_16x16x32_bf16 v[46:49], v[140:143], v[184:187], v[46:49]
	v_mfma_f32_16x16x32_bf16 v[42:45], v[168:171], v[184:187], v[42:45]
	s_mov_b32 m0, s49
	s_nop 0
	global_load_lds_dwordx4 v134, s[42:43]
	v_mfma_f32_16x16x32_bf16 v[30:33], v[140:143], v[208:211], v[30:33]
	v_mfma_f32_16x16x32_bf16 v[26:29], v[168:171], v[208:211], v[26:29]
	v_mfma_f32_16x16x32_bf16 v[14:17], v[140:143], v[216:219], v[14:17]
	v_mfma_f32_16x16x32_bf16 v[10:13], v[168:171], v[216:219], v[10:13]
	v_mfma_f32_16x16x32_bf16 v[62:65], v[152:155], v[180:183], v[62:65]
	v_mfma_f32_16x16x32_bf16 v[58:61], v[172:175], v[180:183], v[58:61]
	s_mov_b32 m0, s54
	s_nop 0
	global_load_lds_dwordx4 v132, s[42:43]
	v_mfma_f32_16x16x32_bf16 v[46:49], v[152:155], v[204:207], v[46:49]
	v_mfma_f32_16x16x32_bf16 v[42:45], v[172:175], v[204:207], v[42:45]
	v_mfma_f32_16x16x32_bf16 v[30:33], v[152:155], v[212:215], v[30:33]
	v_mfma_f32_16x16x32_bf16 v[26:29], v[172:175], v[212:215], v[26:29]
	v_mfma_f32_16x16x32_bf16 v[14:17], v[152:155], v[226:229], v[14:17]
	v_mfma_f32_16x16x32_bf16 v[10:13], v[172:175], v[226:229], v[10:13]
	s_setprio 0
	s_barrier
	s_add_u32 s60, s6, 0x40000
	s_addc_u32 s61, s7, 0
	s_add_i32 s58, s70, s48
	s_waitcnt vmcnt(4)
	s_barrier
	s_setprio 1
	v_mfma_f32_16x16x32_bf16 v[54:57], v[230:233], v[176:179], v[54:57]
	v_mfma_f32_16x16x32_bf16 v[50:53], v[238:241], v[176:179], v[50:53]
	s_cmp_eq_u32 s89, 0
	s_cbranch_scc1 .LdsE_skip_7
	global_store_dwordx4 v250, v[246:249], s[4:5] offset:256
.LdsE_skip_7:
	v_mfma_f32_16x16x32_bf16 v[38:41], v[230:233], v[184:187], v[38:41]
	v_mfma_f32_16x16x32_bf16 v[34:37], v[238:241], v[184:187], v[34:37]
	s_mov_b32 m0, s58
	s_nop 0
	global_load_lds_dwordx4 v0, s[60:61]
	v_mfma_f32_16x16x32_bf16 v[22:25], v[230:233], v[208:211], v[22:25]
	v_mfma_f32_16x16x32_bf16 v[18:21], v[238:241], v[208:211], v[18:21]
	v_mfma_f32_16x16x32_bf16 v[6:9], v[230:233], v[216:219], v[6:9]
	v_mfma_f32_16x16x32_bf16 v[2:5], v[238:241], v[216:219], v[2:5]
	v_mfma_f32_16x16x32_bf16 v[54:57], v[234:237], v[180:183], v[54:57]
	v_mfma_f32_16x16x32_bf16 v[50:53], v[242:245], v[180:183], v[50:53]
	s_add_i32 m0, s58, 0x2000
	s_nop 0
	global_load_lds_dwordx4 v130, s[60:61]
	v_mfma_f32_16x16x32_bf16 v[38:41], v[234:237], v[204:207], v[38:41]
	v_mfma_f32_16x16x32_bf16 v[34:37], v[242:245], v[204:207], v[34:37]
	v_mfma_f32_16x16x32_bf16 v[22:25], v[234:237], v[212:215], v[22:25]
	v_mfma_f32_16x16x32_bf16 v[18:21], v[242:245], v[212:215], v[18:21]
	v_mfma_f32_16x16x32_bf16 v[6:9], v[234:237], v[226:229], v[6:9]
	v_mfma_f32_16x16x32_bf16 v[2:5], v[242:245], v[226:229], v[2:5]
	s_setprio 0
	s_add_i32 s58, 0, 0x18000
	v_add_u32_e32 v151, s58, v147
	s_barrier
	ds_read_b128 v[140:143], v151
	ds_read_b128 v[152:155], v151 offset:1024
	ds_read_b128 v[168:171], v151 offset:2048
	ds_read_b128 v[172:175], v151 offset:3072
	s_add_u32 s42, s42, 0x40000
	s_addc_u32 s43, s43, 0
	ds_read_b128 v[176:179], v150 offset:32768
	ds_read_b128 v[180:183], v150 offset:33792
	ds_read_b128 v[184:187], v150 offset:34816
	ds_read_b128 v[204:207], v150 offset:35840
	ds_read_b128 v[208:211], v150 offset:36864
	ds_read_b128 v[212:215], v150 offset:37888
	ds_read_b128 v[216:219], v150 offset:38912
	ds_read_b128 v[226:229], v150 offset:39936
	s_waitcnt lgkmcnt(8)
	s_barrier
; #define PG8_STAGE(bufoff, gbase, voff) do { _Pragma("unroll") for (int _i = 0; _i < 2; ++_i) \
;         __builtin_amdgcn_global_load_lds((const unsigned*)((const char*)(gbase) + (voff)[_i]), (LAS unsigned*)(lds + (bufoff) + ldsw + _i * 8192), 16, 0, 0); } while (0)
; #define PG8_LDA(dst, b, h) do { _Pragma("unroll") for (int m = 0; m < 4; ++m) _Pragma("unroll") for (int k = 0; k < 2; ++k) dst[m][k] = *(const LAS bf16x8*)(lds + PG8_SA(b, h) + aoff + m * 2048 + k * 1024); } while (0)
; #define PG8_LDB(dst, b, h) do { _Pragma("unroll") for (int n = 0; n < 2; ++n) _Pragma("unroll") for (int k = 0; k < 2; ++k) dst[n][k] = *(const LAS bf16x8*)(lds + PG8_SB(b, h) + boff + n * 2048 + k * 1024); } while (0)
; #define PG8_WAIT_V(n) asm volatile("s_waitcnt vmcnt(" #n ")" ::: "memory")
; template <class Epi>
; __device__ __forceinline__ void gemm_phase(LAS unsigned char* lds, const Gemm g, const StaticOrder& S, const Epi& E) {
;     ...
;             const char* a2 = last ? nA : cA + (size_t)(t + 2) * kstep; const char* b2 = last ? nB : cB + (size_t)(t + 2) * kstep;
;             const char* a3 = a2 + kstep; const char* b3 = b2 + kstep;
;             PG8_LDB(B0, 0, 0); PG8_SCHED; PG8_LDA(At, 0, 0); PG8_STAGE(PG8_SA(1, 1), a1 + hstep, voffA);
;             PG8_WAIT_L(8); PG8_BAR; PG8_WAIT_L(0); PG8_MMA(0, 0, At, B0); PG8_BAR; PG8_SCHED;
;             PG8_LDB(B1, 0, 1); PG8_STAGE(PG8_SB(0, 0), b2, voffB);
;             PG8_BAR; PG8_WAIT_L(0); PG8_MMA(0, 1, At, B1); PG8_BAR;
;             PG8_LDA(At, 0, 1); PG8_STAGE(PG8_SA(0, 0), a2, voffA);
;             PG8_BAR; PG8_WAIT_L(0); PG8_MMA(1, 0, At, B0); PG8_BAR; PG8_SCHED;
;             PG8_STAGE(PG8_SB(0, 1), b2 + hstep, voffB);
;             PG8_WAIT_V(6); PG8_BAR; PG8_MMA(1, 1, At, B1); PG8_BAR;
;             PG8_LDB(B0, 1, 0); PG8_SCHED; PG8_LDA(At, 1, 0); PG8_STAGE(PG8_SA(0, 1), a2 + hstep, voffA);
;             PG8_WAIT_L(8); PG8_BAR; PG8_WAIT_L(0); PG8_MMA(0, 0, At, B0); PG8_BAR; PG8_SCHED;
;             PG8_LDB(B1, 1, 1); PG8_STAGE(PG8_SB(1, 0), b3, voffB);
;             PG8_BAR; PG8_WAIT_L(0); PG8_MMA(0, 1, At, B1); PG8_BAR;
;             PG8_LDA(At, 1, 1); PG8_STAGE(PG8_SA(1, 0), a3, voffA);
;             PG8_BAR; PG8_WAIT_L(0); PG8_MMA(1, 0, At, B0); PG8_BAR; PG8_SCHED;
;             PG8_STAGE(PG8_SB(1, 1), b3 + hstep, voffB);
;             PG8_WAIT_V(6); PG8_BAR; PG8_MMA(1, 1, At, B1); PG8_BAR;
	s_waitcnt lgkmcnt(0)
	s_setprio 1
	s_waitcnt lgkmcnt(0)
	v_mfma_f32_16x16x32_bf16 v[126:129], v[140:143], v[176:179], v[126:129]
	v_mfma_f32_16x16x32_bf16 v[122:125], v[168:171], v[176:179], v[122:125]
	v_mfma_f32_16x16x32_bf16 v[110:113], v[140:143], v[184:187], v[110:113]
	v_mfma_f32_16x16x32_bf16 v[106:109], v[168:171], v[184:187], v[106:109]
	s_mov_b32 m0, s55
	s_nop 0
	global_load_lds_dwordx4 v134, s[42:43]
	v_mfma_f32_16x16x32_bf16 v[94:97], v[140:143], v[208:211], v[94:97]
	v_mfma_f32_16x16x32_bf16 v[90:93], v[168:171], v[208:211], v[90:93]
	v_mfma_f32_16x16x32_bf16 v[78:81], v[140:143], v[216:219], v[78:81]
	v_mfma_f32_16x16x32_bf16 v[74:77], v[168:171], v[216:219], v[74:77]
	v_mfma_f32_16x16x32_bf16 v[126:129], v[152:155], v[180:183], v[126:129]
	v_mfma_f32_16x16x32_bf16 v[122:125], v[172:175], v[180:183], v[122:125]
	s_mov_b32 m0, s83
	s_nop 0
	global_load_lds_dwordx4 v132, s[42:43]
	v_mfma_f32_16x16x32_bf16 v[110:113], v[152:155], v[204:207], v[110:113]
	v_mfma_f32_16x16x32_bf16 v[106:109], v[172:175], v[204:207], v[106:109]
	v_mfma_f32_16x16x32_bf16 v[94:97], v[152:155], v[212:215], v[94:97]
	v_mfma_f32_16x16x32_bf16 v[90:93], v[172:175], v[212:215], v[90:93]
	v_mfma_f32_16x16x32_bf16 v[78:81], v[152:155], v[226:229], v[78:81]
	v_mfma_f32_16x16x32_bf16 v[74:77], v[172:175], v[226:229], v[74:77]
	s_setprio 0
	s_barrier
	s_add_i32 s42, 0, 0x1c000
	s_add_i32 s43, s58, s48
	v_add_u32_e32 v151, s42, v147
	s_add_u32 s60, s6, 0x80
	s_addc_u32 s61, s7, 0
	ds_read_b128 v[230:233], v151
	ds_read_b128 v[234:237], v151 offset:1024
	ds_read_b128 v[238:241], v151 offset:2048
	ds_read_b128 v[242:245], v151 offset:3072
	s_barrier
	s_waitcnt lgkmcnt(0)
	s_setprio 1
	s_waitcnt lgkmcnt(0)
	v_mfma_f32_16x16x32_bf16 v[118:121], v[230:233], v[176:179], v[118:121]
	v_mfma_f32_16x16x32_bf16 v[114:117], v[238:241], v[176:179], v[114:117]
	v_mfma_f32_16x16x32_bf16 v[102:105], v[230:233], v[184:187], v[102:105]
	v_mfma_f32_16x16x32_bf16 v[98:101], v[238:241], v[184:187], v[98:101]
	s_mov_b32 m0, s43
	s_nop 0
	global_load_lds_dwordx4 v0, s[60:61]
	v_mfma_f32_16x16x32_bf16 v[86:89], v[230:233], v[208:211], v[86:89]
	v_mfma_f32_16x16x32_bf16 v[82:85], v[238:241], v[208:211], v[82:85]
	v_mfma_f32_16x16x32_bf16 v[70:73], v[230:233], v[216:219], v[70:73]
	v_mfma_f32_16x16x32_bf16 v[66:69], v[238:241], v[216:219], v[66:69]
	v_mfma_f32_16x16x32_bf16 v[118:121], v[234:237], v[180:183], v[118:121]
	v_mfma_f32_16x16x32_bf16 v[114:117], v[242:245], v[180:183], v[114:117]
	s_add_i32 m0, s43, 0x2000
	s_nop 0
	global_load_lds_dwordx4 v130, s[60:61]
	v_mfma_f32_16x16x32_bf16 v[102:105], v[234:237], v[204:207], v[102:105]
	v_mfma_f32_16x16x32_bf16 v[98:101], v[242:245], v[204:207], v[98:101]
	v_mfma_f32_16x16x32_bf16 v[86:89], v[234:237], v[212:215], v[86:89]
	v_mfma_f32_16x16x32_bf16 v[82:85], v[242:245], v[212:215], v[82:85]
	v_mfma_f32_16x16x32_bf16 v[70:73], v[234:237], v[226:229], v[70:73]
	v_mfma_f32_16x16x32_bf16 v[66:69], v[242:245], v[226:229], v[66:69]
	s_setprio 0
	s_barrier
	ds_read_b128 v[176:179], v150 offset:49152
	ds_read_b128 v[180:183], v150 offset:50176
	ds_read_b128 v[184:187], v150 offset:51200
	ds_read_b128 v[204:207], v150 offset:52224
	ds_read_b128 v[208:211], v150 offset:53248
	ds_read_b128 v[212:215], v150 offset:54272
	ds_read_b128 v[216:219], v150 offset:55296
	ds_read_b128 v[226:229], v150 offset:56320
	s_barrier
	s_waitcnt lgkmcnt(0)
	s_setprio 1
	s_waitcnt lgkmcnt(0)
	v_mfma_f32_16x16x32_bf16 v[62:65], v[140:143], v[176:179], v[62:65]
	v_mfma_f32_16x16x32_bf16 v[58:61], v[168:171], v[176:179], v[58:61]
	v_mfma_f32_16x16x32_bf16 v[46:49], v[140:143], v[184:187], v[46:49]
	v_mfma_f32_16x16x32_bf16 v[42:45], v[168:171], v[184:187], v[42:45]
	s_mov_b32 m0, s84
	s_nop 0
	global_load_lds_dwordx4 v134, vcc
	v_mfma_f32_16x16x32_bf16 v[30:33], v[140:143], v[208:211], v[30:33]
	v_mfma_f32_16x16x32_bf16 v[26:29], v[168:171], v[208:211], v[26:29]
	v_mfma_f32_16x16x32_bf16 v[14:17], v[140:143], v[216:219], v[14:17]
	v_mfma_f32_16x16x32_bf16 v[10:13], v[168:171], v[216:219], v[10:13]
	v_mfma_f32_16x16x32_bf16 v[62:65], v[152:155], v[180:183], v[62:65]
	v_mfma_f32_16x16x32_bf16 v[58:61], v[172:175], v[180:183], v[58:61]
	s_mov_b32 m0, s85
	s_nop 0
	global_load_lds_dwordx4 v132, vcc
	v_mfma_f32_16x16x32_bf16 v[46:49], v[152:155], v[204:207], v[46:49]
	v_mfma_f32_16x16x32_bf16 v[42:45], v[172:175], v[204:207], v[42:45]
	v_mfma_f32_16x16x32_bf16 v[30:33], v[152:155], v[212:215], v[30:33]
	v_mfma_f32_16x16x32_bf16 v[26:29], v[172:175], v[212:215], v[26:29]
	v_mfma_f32_16x16x32_bf16 v[14:17], v[152:155], v[226:229], v[14:17]
	v_mfma_f32_16x16x32_bf16 v[10:13], v[172:175], v[226:229], v[10:13]
	s_setprio 0
	s_barrier
	s_add_u32 s6, s6, 0x40080
	s_addc_u32 s7, s7, 0
	s_add_i32 s42, s42, s48
	s_waitcnt vmcnt(4)
	s_barrier
	s_setprio 1
	v_mfma_f32_16x16x32_bf16 v[54:57], v[230:233], v[176:179], v[54:57]
	v_mfma_f32_16x16x32_bf16 v[50:53], v[238:241], v[176:179], v[50:53]
	v_mfma_f32_16x16x32_bf16 v[38:41], v[230:233], v[184:187], v[38:41]
	v_mfma_f32_16x16x32_bf16 v[34:37], v[238:241], v[184:187], v[34:37]
	s_mov_b32 m0, s42
	s_nop 0
	global_load_lds_dwordx4 v0, s[6:7]
	v_mfma_f32_16x16x32_bf16 v[22:25], v[230:233], v[208:211], v[22:25]
	v_mfma_f32_16x16x32_bf16 v[18:21], v[238:241], v[208:211], v[18:21]
	v_mfma_f32_16x16x32_bf16 v[6:9], v[230:233], v[216:219], v[6:9]
	v_mfma_f32_16x16x32_bf16 v[2:5], v[238:241], v[216:219], v[2:5]
	v_mfma_f32_16x16x32_bf16 v[54:57], v[234:237], v[180:183], v[54:57]
	v_mfma_f32_16x16x32_bf16 v[50:53], v[242:245], v[180:183], v[50:53]
	s_add_i32 m0, s42, 0x2000
	s_nop 0
	global_load_lds_dwordx4 v130, s[6:7]
	v_mfma_f32_16x16x32_bf16 v[38:41], v[234:237], v[204:207], v[38:41]
	v_mfma_f32_16x16x32_bf16 v[34:37], v[242:245], v[204:207], v[34:37]
	v_mfma_f32_16x16x32_bf16 v[22:25], v[234:237], v[212:215], v[22:25]
	v_mfma_f32_16x16x32_bf16 v[18:21], v[242:245], v[212:215], v[18:21]
	v_mfma_f32_16x16x32_bf16 v[6:9], v[234:237], v[226:229], v[6:9]
	v_mfma_f32_16x16x32_bf16 v[2:5], v[242:245], v[226:229], v[2:5]
	s_setprio 0
	s_add_i32 s93, s93, 2
	s_add_u32 s36, s36, 0x100
	s_addc_u32 s37, s37, 0
	s_add_u32 s91, s91, 0x100
	s_addc_u32 s92, s92, 0
	s_cmp_gt_u32 s93, 13
	s_barrier
; __device__ __forceinline__ unsigned pk2(float lo, float hi) { unsigned r; asm("v_cvt_pk_bf16_f32 %0, %1, %2" : "=v"(r) : "v"(lo), "v"(hi)); return r; }
;     __device__ __forceinline__ void operator()(const f32x4 (&acc)[2][2][4][2], const Unit& u, int ui, int wr, int wc, int fr, int fq) const {
;         const int lrow0 = wr * 64 + fr, row0 = u.pm * BM + lrow0, col0 = u.pn * BM + wc * 32 + 8 * fq;
;         float rsv[2][4];
; #pragma unroll
;         for (int ai = 0; ai < 2; ++ai)
; #pragma unroll
;             for (int m = 0; m < 4; ++m) rsv[ai][m] = rstab[ui * 256 + lrow0 + ai * HALF + m * 16];
; #pragma unroll
;         for (int ai = 0; ai < 2; ++ai)
; #pragma unroll
;             for (int m = 0; m < 4; ++m) {
;                 const int row = row0 + ai * HALF + m * 16; const float rs = rsv[ai][m];
;                 bf16_t* rowp = O + (size_t)row * ldc + col0;
; #pragma unroll
;                 for (int bj = 0; bj < 2; ++bj) {
;                     f32x4 v0 = acc[ai][bj][m][0] * rs, v1 = acc[ai][bj][m][1] * rs;
;                     if (ACT == 1) {
; #pragma unroll
;                         for (int j = 0; j < 4; ++j) { const float a = fmaxf(v0[j], 0.f), b = fmaxf(v1[j], 0.f); v0[j] = a * a; v1[j] = b * b; }
;                     }
;                     u32x4 w; w.x = pk2(v0[0], v0[1]); w.y = pk2(v0[2], v0[3]); w.z = pk2(v1[0], v1[1]); w.w = pk2(v1[2], v1[3]);
;                     *(u32x4*)(rowp + bj * HALF) = w;
;                 }
;             }
	v_lshl_add_u32 v140, s89, 10, v148
	ds_read2_b32 v[154:155], v140 offset1:16
	ds_read2_b32 v[156:157], v140 offset0:32 offset1:48
	ds_read2_b32 v[144:145], v140 offset0:128 offset1:144
	ds_read2_b32 v[142:143], v140 offset0:160 offset1:176
	v_lshl_add_u32 v152, s88, 8, v146
	s_waitcnt lgkmcnt(0)
	v_pk_mul_f32 v[122:123], v[122:123], v[154:155] op_sel_hi:[1,0]
	v_lshl_or_b32 v140, s87, 8, v149
	v_lshlrev_b32_e32 v250, 13, v152
	v_lshl_add_u32 v250, v140, 1, v250
	v_add_u32_e32 v250, 0x100000, v250
	v_ashrrev_i32_e32 v153, 31, v152
	v_pk_mul_f32 v[126:127], v[126:127], v[154:155] op_sel_hi:[1,0]
	v_pk_mul_f32 v[124:125], v[124:125], v[154:155] op_sel_hi:[1,0]
	v_max_f32_e32 v122, 0, v122
	v_ashrrev_i32_e32 v141, 31, v140
	v_lshlrev_b64 v[162:163], 13, v[152:153]
	v_pk_mul_f32 v[128:129], v[128:129], v[154:155] op_sel_hi:[1,0]
	v_mul_f32_e32 v151, v122, v122
	v_max_f32_e32 v122, 0, v127
	v_max_f32_e32 v123, 0, v123
	v_max_f32_e32 v124, 0, v124
	v_lshl_add_u64 v[162:163], s[4:5], 0, v[162:163]
	v_lshlrev_b64 v[168:169], 1, v[140:141]
	v_max_f32_e32 v126, 0, v126
	v_mul_f32_e32 v122, v122, v122
	v_mul_f32_e32 v127, v123, v123
	v_max_f32_e32 v123, 0, v128
	v_mul_f32_e32 v128, v124, v124
	v_max_f32_e32 v124, 0, v129
	v_max_f32_e32 v125, 0, v125
	v_pk_mul_f32 v[116:117], v[116:117], v[154:155] op_sel_hi:[1,0]
	v_pk_mul_f32 v[114:115], v[114:115], v[154:155] op_sel_hi:[1,0]
	v_lshl_add_u64 v[140:141], v[162:163], 0, v[168:169]
	v_mul_f32_e32 v126, v126, v126
	v_mul_f32_e32 v123, v123, v123
	v_mul_f32_e32 v124, v124, v124
	v_mul_f32_e32 v125, v125, v125
	v_cvt_pk_bf16_f32 v122, v126, v122
	v_pk_mul_f32 v[120:121], v[120:121], v[154:155] op_sel_hi:[1,0]
	v_pk_mul_f32 v[118:119], v[118:119], v[154:155] op_sel_hi:[1,0]
	v_max_f32_e32 v114, 0, v114
	v_max_f32_e32 v115, 0, v115
	v_max_f32_e32 v116, 0, v116
	v_cvt_pk_bf16_f32 v123, v123, v124
	v_cvt_pk_bf16_f32 v124, v151, v127
	v_cvt_pk_bf16_f32 v125, v128, v125
	global_store_dwordx4 v[140:141], v[122:125], off
	v_max_f32_e32 v117, 0, v117
	v_max_f32_e32 v118, 0, v118
	v_mul_f32_e32 v122, v114, v114
	v_max_f32_e32 v114, 0, v119
	v_mul_f32_e32 v119, v115, v115
	v_max_f32_e32 v115, 0, v120
	v_mul_f32_e32 v120, v116, v116
	v_max_f32_e32 v116, 0, v121
	v_mul_f32_e32 v115, v115, v115
	v_mul_f32_e32 v116, v116, v116
	v_mul_f32_e32 v114, v114, v114
	v_mul_f32_e32 v117, v117, v117
	v_cvt_pk_bf16_f32 v115, v115, v116
	v_cvt_pk_bf16_f32 v116, v122, v119
	v_mul_f32_e32 v118, v118, v118
	v_cvt_pk_bf16_f32 v114, v118, v114
	v_cvt_pk_bf16_f32 v117, v120, v117
	global_store_dwordx4 v[140:141], v[114:117], off offset:256
	v_pk_mul_f32 v[90:91], v[90:91], v[156:157] op_sel_hi:[1,0]
	v_pk_mul_f32 v[94:95], v[94:95], v[156:157] op_sel_hi:[1,0]
	v_mov_b32_e32 v116, v155
	v_or_b32_e32 v114, 16, v152
	v_pk_mul_f32 v[106:107], v[106:107], v[116:117] op_sel_hi:[1,0]
	v_ashrrev_i32_e32 v115, 31, v114
	v_pk_mul_f32 v[110:111], v[110:111], v[116:117] op_sel_hi:[1,0]
	v_pk_mul_f32 v[108:109], v[108:109], v[116:117] op_sel_hi:[1,0]
	v_max_f32_e32 v106, 0, v106
	v_lshlrev_b64 v[114:115], 13, v[114:115]
	v_pk_mul_f32 v[112:113], v[112:113], v[116:117] op_sel_hi:[1,0]
	v_mul_f32_e32 v117, v106, v106
	v_max_f32_e32 v106, 0, v111
	v_max_f32_e32 v107, 0, v107
	v_max_f32_e32 v108, 0, v108
	v_lshl_add_u64 v[114:115], s[4:5], 0, v[114:115]
	v_max_f32_e32 v110, 0, v110
	v_mul_f32_e32 v106, v106, v106
	v_mul_f32_e32 v111, v107, v107
	v_max_f32_e32 v107, 0, v112
	v_mul_f32_e32 v112, v108, v108
	v_max_f32_e32 v108, 0, v113
	v_max_f32_e32 v109, 0, v109
	v_pk_mul_f32 v[98:99], v[98:99], v[116:117] op_sel_hi:[1,0]
	v_lshl_add_u64 v[114:115], v[114:115], 0, v[168:169]
	v_mul_f32_e32 v110, v110, v110
	v_mul_f32_e32 v107, v107, v107
	v_mul_f32_e32 v108, v108, v108
	v_mul_f32_e32 v109, v109, v109
	v_cvt_pk_bf16_f32 v106, v110, v106
	v_pk_mul_f32 v[102:103], v[102:103], v[116:117] op_sel_hi:[1,0]
	v_pk_mul_f32 v[100:101], v[100:101], v[116:117] op_sel_hi:[1,0]
	v_max_f32_e32 v98, 0, v98
	v_cvt_pk_bf16_f32 v107, v107, v108
	v_cvt_pk_bf16_f32 v108, v117, v111
	v_cvt_pk_bf16_f32 v109, v112, v109
	global_store_dwordx4 v[114:115], v[106:109], off
	v_pk_mul_f32 v[104:105], v[104:105], v[116:117] op_sel_hi:[1,0]
	v_max_f32_e32 v99, 0, v99
	v_mul_f32_e32 v106, v98, v98
	v_max_f32_e32 v98, 0, v103
	v_max_f32_e32 v100, 0, v100
	v_max_f32_e32 v102, 0, v102
	v_mul_f32_e32 v98, v98, v98
	v_mul_f32_e32 v103, v99, v99
	v_max_f32_e32 v99, 0, v104
	v_mul_f32_e32 v104, v100, v100
	v_max_f32_e32 v100, 0, v105
	v_max_f32_e32 v101, 0, v101
	v_mul_f32_e32 v102, v102, v102
	v_mul_f32_e32 v99, v99, v99
	v_mul_f32_e32 v100, v100, v100
	v_mul_f32_e32 v101, v101, v101
	v_cvt_pk_bf16_f32 v98, v102, v98
	v_cvt_pk_bf16_f32 v99, v99, v100
	v_cvt_pk_bf16_f32 v100, v106, v103
	v_cvt_pk_bf16_f32 v101, v104, v101
	global_store_dwordx4 v[114:115], v[98:101], off offset:256
	v_pk_mul_f32 v[92:93], v[92:93], v[156:157] op_sel_hi:[1,0]
	v_max_f32_e32 v90, 0, v90
	v_or_b32_e32 v98, 32, v152
	v_ashrrev_i32_e32 v99, 31, v98
	v_lshlrev_b64 v[98:99], 13, v[98:99]
	v_pk_mul_f32 v[96:97], v[96:97], v[156:157] op_sel_hi:[1,0]
	v_mul_f32_e32 v100, v90, v90
	v_max_f32_e32 v90, 0, v95
	v_max_f32_e32 v91, 0, v91
	v_max_f32_e32 v92, 0, v92
	v_lshl_add_u64 v[98:99], s[4:5], 0, v[98:99]
	v_max_f32_e32 v94, 0, v94
	v_mul_f32_e32 v90, v90, v90
	v_mul_f32_e32 v95, v91, v91
	v_max_f32_e32 v91, 0, v96
	v_mul_f32_e32 v96, v92, v92
	v_max_f32_e32 v92, 0, v97
	v_max_f32_e32 v93, 0, v93
	v_pk_mul_f32 v[84:85], v[84:85], v[156:157] op_sel_hi:[1,0]
	v_pk_mul_f32 v[82:83], v[82:83], v[156:157] op_sel_hi:[1,0]
	v_lshl_add_u64 v[98:99], v[98:99], 0, v[168:169]
	v_mul_f32_e32 v94, v94, v94
	v_mul_f32_e32 v91, v91, v91
; __device__ __forceinline__ unsigned pk2(float lo, float hi) { unsigned r; asm("v_cvt_pk_bf16_f32 %0, %1, %2" : "=v"(r) : "v"(lo), "v"(hi)); return r; }
;     __device__ __forceinline__ void operator()(const f32x4 (&acc)[2][2][4][2], const Unit& u, int ui, int wr, int wc, int fr, int fq) const {
;         const int lrow0 = wr * 64 + fr, row0 = u.pm * BM + lrow0, col0 = u.pn * BM + wc * 32 + 8 * fq;
;         float rsv[2][4];
; #pragma unroll
;         for (int ai = 0; ai < 2; ++ai)
; #pragma unroll
;             for (int m = 0; m < 4; ++m) rsv[ai][m] = rstab[ui * 256 + lrow0 + ai * HALF + m * 16];
; #pragma unroll
;         for (int ai = 0; ai < 2; ++ai)
; #pragma unroll
;             for (int m = 0; m < 4; ++m) {
;                 const int row = row0 + ai * HALF + m * 16; const float rs = rsv[ai][m];
;                 bf16_t* rowp = O + (size_t)row * ldc + col0;
; #pragma unroll
;                 for (int bj = 0; bj < 2; ++bj) {
;                     f32x4 v0 = acc[ai][bj][m][0] * rs, v1 = acc[ai][bj][m][1] * rs;
;                     if (ACT == 1) {
; #pragma unroll
;                         for (int j = 0; j < 4; ++j) { const float a = fmaxf(v0[j], 0.f), b = fmaxf(v1[j], 0.f); v0[j] = a * a; v1[j] = b * b; }
;                     }
;                     u32x4 w; w.x = pk2(v0[0], v0[1]); w.y = pk2(v0[2], v0[3]); w.z = pk2(v1[0], v1[1]); w.w = pk2(v1[2], v1[3]);
;                     *(u32x4*)(rowp + bj * HALF) = w;
;                 }
;             }
	v_mul_f32_e32 v92, v92, v92
	v_mul_f32_e32 v93, v93, v93
	v_cvt_pk_bf16_f32 v90, v94, v90
	v_pk_mul_f32 v[88:89], v[88:89], v[156:157] op_sel_hi:[1,0]
	v_pk_mul_f32 v[86:87], v[86:87], v[156:157] op_sel_hi:[1,0]
	v_max_f32_e32 v82, 0, v82
	v_max_f32_e32 v83, 0, v83
	v_max_f32_e32 v84, 0, v84
	v_cvt_pk_bf16_f32 v91, v91, v92
	v_cvt_pk_bf16_f32 v92, v100, v95
	v_cvt_pk_bf16_f32 v93, v96, v93
	global_store_dwordx4 v[98:99], v[90:93], off
	v_max_f32_e32 v85, 0, v85
	v_max_f32_e32 v86, 0, v86
	v_mul_f32_e32 v90, v82, v82
	v_max_f32_e32 v82, 0, v87
	v_mul_f32_e32 v87, v83, v83
	v_max_f32_e32 v83, 0, v88
	v_mul_f32_e32 v88, v84, v84
	v_max_f32_e32 v84, 0, v89
	v_mul_f32_e32 v83, v83, v83
	v_mul_f32_e32 v84, v84, v84
	v_mul_f32_e32 v82, v82, v82
	v_mul_f32_e32 v85, v85, v85
	v_cvt_pk_bf16_f32 v83, v83, v84
	v_cvt_pk_bf16_f32 v84, v90, v87
	v_mul_f32_e32 v86, v86, v86
	v_cvt_pk_bf16_f32 v82, v86, v82
	v_cvt_pk_bf16_f32 v85, v88, v85
	global_store_dwordx4 v[98:99], v[82:85], off offset:256
	v_pk_mul_f32 v[58:59], v[58:59], v[144:145] op_sel_hi:[1,0]
	v_pk_mul_f32 v[62:63], v[62:63], v[144:145] op_sel_hi:[1,0]
	v_mov_b32_e32 v84, v157
	v_or_b32_e32 v82, 48, v152
	v_pk_mul_f32 v[74:75], v[74:75], v[84:85] op_sel_hi:[1,0]
	v_ashrrev_i32_e32 v83, 31, v82
	v_pk_mul_f32 v[78:79], v[78:79], v[84:85] op_sel_hi:[1,0]
	v_pk_mul_f32 v[76:77], v[76:77], v[84:85] op_sel_hi:[1,0]
	v_max_f32_e32 v74, 0, v74
	v_lshlrev_b64 v[82:83], 13, v[82:83]
	v_pk_mul_f32 v[80:81], v[80:81], v[84:85] op_sel_hi:[1,0]
	v_mul_f32_e32 v85, v74, v74
	v_max_f32_e32 v74, 0, v79
	v_max_f32_e32 v75, 0, v75
	v_max_f32_e32 v76, 0, v76
	v_lshl_add_u64 v[82:83], s[4:5], 0, v[82:83]
	v_max_f32_e32 v78, 0, v78
	v_mul_f32_e32 v74, v74, v74
	v_mul_f32_e32 v79, v75, v75
	v_max_f32_e32 v75, 0, v80
	v_mul_f32_e32 v80, v76, v76
	v_max_f32_e32 v76, 0, v81
	v_max_f32_e32 v77, 0, v77
	v_pk_mul_f32 v[68:69], v[68:69], v[84:85] op_sel_hi:[1,0]
	v_pk_mul_f32 v[66:67], v[66:67], v[84:85] op_sel_hi:[1,0]
	v_lshl_add_u64 v[82:83], v[82:83], 0, v[168:169]
	v_mul_f32_e32 v78, v78, v78
	v_mul_f32_e32 v75, v75, v75
	v_mul_f32_e32 v76, v76, v76
	v_mul_f32_e32 v77, v77, v77
	v_cvt_pk_bf16_f32 v74, v78, v74
	v_pk_mul_f32 v[72:73], v[72:73], v[84:85] op_sel_hi:[1,0]
	v_pk_mul_f32 v[70:71], v[70:71], v[84:85] op_sel_hi:[1,0]
	v_max_f32_e32 v66, 0, v66
	v_max_f32_e32 v67, 0, v67
	v_max_f32_e32 v68, 0, v68
	v_cvt_pk_bf16_f32 v75, v75, v76
	v_cvt_pk_bf16_f32 v76, v85, v79
	v_cvt_pk_bf16_f32 v77, v80, v77
	global_store_dwordx4 v[82:83], v[74:77], off
	v_max_f32_e32 v69, 0, v69
	v_max_f32_e32 v70, 0, v70
	v_mul_f32_e32 v74, v66, v66
	v_max_f32_e32 v66, 0, v71
	v_mul_f32_e32 v71, v67, v67
	v_max_f32_e32 v67, 0, v72
	v_mul_f32_e32 v72, v68, v68
	v_max_f32_e32 v68, 0, v73
	v_mul_f32_e32 v67, v67, v67
	v_mul_f32_e32 v68, v68, v68
	v_mul_f32_e32 v66, v66, v66
	v_mul_f32_e32 v69, v69, v69
	v_cvt_pk_bf16_f32 v67, v67, v68
	v_cvt_pk_bf16_f32 v68, v74, v71
	v_pk_mul_f32 v[60:61], v[60:61], v[144:145] op_sel_hi:[1,0]
	v_max_f32_e32 v58, 0, v58
	v_mul_f32_e32 v70, v70, v70
	v_cvt_pk_bf16_f32 v66, v70, v66
	v_cvt_pk_bf16_f32 v69, v72, v69
	global_store_dwordx4 v[82:83], v[66:69], off offset:256
	s_mov_b64 s[6:7], 0x100000
	v_pk_mul_f32 v[64:65], v[64:65], v[144:145] op_sel_hi:[1,0]
	v_max_f32_e32 v62, 0, v62
	v_mul_f32_e32 v68, v58, v58
	v_max_f32_e32 v58, 0, v63
	v_max_f32_e32 v59, 0, v59
	v_max_f32_e32 v60, 0, v60
	v_lshl_add_u64 v[66:67], v[140:141], 0, s[6:7]
	v_mul_f32_e32 v62, v62, v62
	v_mul_f32_e32 v58, v58, v58
	v_mul_f32_e32 v63, v59, v59
	v_max_f32_e32 v59, 0, v64
	v_mul_f32_e32 v64, v60, v60
	v_max_f32_e32 v60, 0, v65
	s_mov_b32 s6, 0x100000
	v_mul_f32_e32 v59, v59, v59
	v_max_f32_e32 v61, 0, v61
	v_mul_f32_e32 v60, v60, v60
	v_cvt_pk_bf16_f32 v58, v62, v58
	v_add_co_u32_e32 v62, vcc, s6, v140
	v_pk_mul_f32 v[52:53], v[52:53], v[144:145] op_sel_hi:[1,0]
	v_pk_mul_f32 v[50:51], v[50:51], v[144:145] op_sel_hi:[1,0]
	v_mul_f32_e32 v61, v61, v61
	v_cvt_pk_bf16_f32 v59, v59, v60
	v_cvt_pk_bf16_f32 v60, v68, v63
	v_addc_co_u32_e32 v63, vcc, 0, v141, vcc
	v_pk_mul_f32 v[56:57], v[56:57], v[144:145] op_sel_hi:[1,0]
	v_pk_mul_f32 v[54:55], v[54:55], v[144:145] op_sel_hi:[1,0]
	v_max_f32_e32 v50, 0, v50
	v_max_f32_e32 v51, 0, v51
	v_max_f32_e32 v52, 0, v52
	v_cvt_pk_bf16_f32 v61, v64, v61
	v_mov_b32_e32 v158, v58
	v_mov_b32_e32 v159, v59
	v_mov_b32_e32 v160, v60
	v_mov_b32_e32 v161, v61
	v_max_f32_e32 v53, 0, v53
	v_max_f32_e32 v54, 0, v54
	v_mul_f32_e32 v58, v50, v50
	v_max_f32_e32 v50, 0, v55
	v_mul_f32_e32 v55, v51, v51
	v_max_f32_e32 v51, 0, v56
	v_mul_f32_e32 v56, v52, v52
	v_max_f32_e32 v52, 0, v57
	v_mul_f32_e32 v51, v51, v51
	v_mul_f32_e32 v52, v52, v52
	v_mul_f32_e32 v50, v50, v50
	v_mul_f32_e32 v53, v53, v53
	v_cvt_pk_bf16_f32 v51, v51, v52
	v_cvt_pk_bf16_f32 v52, v58, v55
	v_mul_f32_e32 v54, v54, v54
	v_cvt_pk_bf16_f32 v50, v54, v50
	v_cvt_pk_bf16_f32 v53, v56, v53
	v_mov_b32_e32 v164, v50
	v_mov_b32_e32 v165, v51
	v_mov_b32_e32 v166, v52
	v_mov_b32_e32 v167, v53
	s_mov_b64 s[6:7], 0x120000
	v_pk_mul_f32 v[26:27], v[26:27], v[142:143] op_sel_hi:[1,0]
	v_mov_b32_e32 v52, v145
	v_pk_mul_f32 v[42:43], v[42:43], v[52:53] op_sel_hi:[1,0]
	v_pk_mul_f32 v[46:47], v[46:47], v[52:53] op_sel_hi:[1,0]
	v_pk_mul_f32 v[44:45], v[44:45], v[52:53] op_sel_hi:[1,0]
	v_max_f32_e32 v42, 0, v42
	v_pk_mul_f32 v[48:49], v[48:49], v[52:53] op_sel_hi:[1,0]
	v_max_f32_e32 v46, 0, v46
	v_mul_f32_e32 v53, v42, v42
	v_max_f32_e32 v42, 0, v47
	v_max_f32_e32 v43, 0, v43
	v_max_f32_e32 v44, 0, v44
	v_lshl_add_u64 v[50:51], v[140:141], 0, s[6:7]
	v_mul_f32_e32 v46, v46, v46
	v_mul_f32_e32 v42, v42, v42
	v_mul_f32_e32 v47, v43, v43
	v_max_f32_e32 v43, 0, v48
; __device__ __forceinline__ unsigned pk2(float lo, float hi) { unsigned r; asm("v_cvt_pk_bf16_f32 %0, %1, %2" : "=v"(r) : "v"(lo), "v"(hi)); return r; }
; #define PG8_WAIT_V(n) asm volatile("s_waitcnt vmcnt(" #n ")" ::: "memory")
; #define PG8_BAR __builtin_amdgcn_s_barrier()
;     __device__ __forceinline__ void operator()(const f32x4 (&acc)[2][2][4][2], const Unit& u, int ui, int wr, int wc, int fr, int fq) const {
;     ...
;         for (int ai = 0; ai < 2; ++ai)
; #pragma unroll
;             for (int m = 0; m < 4; ++m) {
;                 const int row = row0 + ai * HALF + m * 16; const float rs = rsv[ai][m];
;                 bf16_t* rowp = O + (size_t)row * ldc + col0;
; #pragma unroll
;                 for (int bj = 0; bj < 2; ++bj) {
;                     f32x4 v0 = acc[ai][bj][m][0] * rs, v1 = acc[ai][bj][m][1] * rs;
;                     if (ACT == 1) {
; #pragma unroll
;                         for (int j = 0; j < 4; ++j) { const float a = fmaxf(v0[j], 0.f), b = fmaxf(v1[j], 0.f); v0[j] = a * a; v1[j] = b * b; }
;                     }
;                     u32x4 w; w.x = pk2(v0[0], v0[1]); w.y = pk2(v0[2], v0[3]); w.z = pk2(v1[0], v1[1]); w.w = pk2(v1[2], v1[3]);
;                     *(u32x4*)(rowp + bj * HALF) = w;
;                 }
;             }
; template <class Epi>
; __device__ __forceinline__ void gemm_phase(LAS unsigned char* lds, const Gemm g, const StaticOrder& S, const Epi& E) {
;     ...
;         E(acc, cur, ui, wr, wc, fr, fq);
;         if (!has_next) break;
; #pragma unroll
;         for (int a = 0; a < 2; ++a)
; #pragma unroll
;             for (int b = 0; b < 2; ++b)
; #pragma unroll
;                 for (int m = 0; m < 4; ++m)
; #pragma unroll
;                     for (int n = 0; n < 2; ++n) acc[a][b][m][n] = (f32x4){0.f, 0.f, 0.f, 0.f};
;         cur = nxt; cA = nA; cB = nB; ++ui;
;     }
;     PG8_WAIT_V(0);
;     if (wr == 0) PG8_BAR;
;     PG8_BAR;
	v_mul_f32_e32 v48, v44, v44
	v_max_f32_e32 v44, 0, v49
	s_mov_b32 s6, 0x120000
	v_mul_f32_e32 v43, v43, v43
	v_max_f32_e32 v45, 0, v45
	v_mul_f32_e32 v44, v44, v44
	v_cvt_pk_bf16_f32 v42, v46, v42
	v_add_co_u32_e32 v46, vcc, s6, v140
	v_pk_mul_f32 v[36:37], v[36:37], v[52:53] op_sel_hi:[1,0]
	v_pk_mul_f32 v[34:35], v[34:35], v[52:53] op_sel_hi:[1,0]
	v_mul_f32_e32 v45, v45, v45
	v_cvt_pk_bf16_f32 v43, v43, v44
	v_cvt_pk_bf16_f32 v44, v53, v47
	v_addc_co_u32_e32 v47, vcc, 0, v141, vcc
	v_pk_mul_f32 v[40:41], v[40:41], v[52:53] op_sel_hi:[1,0]
	v_pk_mul_f32 v[38:39], v[38:39], v[52:53] op_sel_hi:[1,0]
	v_max_f32_e32 v34, 0, v34
	v_max_f32_e32 v35, 0, v35
	v_max_f32_e32 v36, 0, v36
	v_cvt_pk_bf16_f32 v45, v48, v45
	v_mov_b32_e32 v188, v42
	v_mov_b32_e32 v189, v43
	v_mov_b32_e32 v190, v44
	v_mov_b32_e32 v191, v45
	v_max_f32_e32 v37, 0, v37
	v_max_f32_e32 v38, 0, v38
	v_mul_f32_e32 v42, v34, v34
	v_max_f32_e32 v34, 0, v39
	v_mul_f32_e32 v39, v35, v35
	v_max_f32_e32 v35, 0, v40
	v_mul_f32_e32 v40, v36, v36
	v_max_f32_e32 v36, 0, v41
	v_mul_f32_e32 v35, v35, v35
	v_mul_f32_e32 v36, v36, v36
	v_mul_f32_e32 v34, v34, v34
	v_mul_f32_e32 v37, v37, v37
	v_cvt_pk_bf16_f32 v35, v35, v36
	v_cvt_pk_bf16_f32 v36, v42, v39
	v_pk_mul_f32 v[30:31], v[30:31], v[142:143] op_sel_hi:[1,0]
	v_pk_mul_f32 v[28:29], v[28:29], v[142:143] op_sel_hi:[1,0]
	v_max_f32_e32 v26, 0, v26
	v_mul_f32_e32 v38, v38, v38
	v_cvt_pk_bf16_f32 v34, v38, v34
	v_cvt_pk_bf16_f32 v37, v40, v37
	v_mov_b32_e32 v192, v34
	v_mov_b32_e32 v193, v35
	v_mov_b32_e32 v194, v36
	v_mov_b32_e32 v195, v37
	s_mov_b64 s[6:7], 0x140000
	v_pk_mul_f32 v[32:33], v[32:33], v[142:143] op_sel_hi:[1,0]
	v_max_f32_e32 v30, 0, v30
	v_mul_f32_e32 v36, v26, v26
	v_max_f32_e32 v26, 0, v31
	v_max_f32_e32 v27, 0, v27
	v_max_f32_e32 v28, 0, v28
	v_lshl_add_u64 v[34:35], v[140:141], 0, s[6:7]
	v_mul_f32_e32 v30, v30, v30
	v_mul_f32_e32 v26, v26, v26
	v_mul_f32_e32 v31, v27, v27
	v_max_f32_e32 v27, 0, v32
	v_mul_f32_e32 v32, v28, v28
	v_max_f32_e32 v28, 0, v33
	s_mov_b32 s6, 0x140000
	v_mul_f32_e32 v27, v27, v27
	v_max_f32_e32 v29, 0, v29
	v_mul_f32_e32 v28, v28, v28
	v_cvt_pk_bf16_f32 v26, v30, v26
	v_add_co_u32_e32 v30, vcc, s6, v140
	v_pk_mul_f32 v[20:21], v[20:21], v[142:143] op_sel_hi:[1,0]
	v_pk_mul_f32 v[18:19], v[18:19], v[142:143] op_sel_hi:[1,0]
	v_mul_f32_e32 v29, v29, v29
	v_cvt_pk_bf16_f32 v27, v27, v28
	v_cvt_pk_bf16_f32 v28, v36, v31
	v_addc_co_u32_e32 v31, vcc, 0, v141, vcc
	v_pk_mul_f32 v[24:25], v[24:25], v[142:143] op_sel_hi:[1,0]
	v_pk_mul_f32 v[22:23], v[22:23], v[142:143] op_sel_hi:[1,0]
	v_max_f32_e32 v18, 0, v18
	v_max_f32_e32 v19, 0, v19
	v_max_f32_e32 v20, 0, v20
	v_cvt_pk_bf16_f32 v29, v32, v29
	v_mov_b32_e32 v196, v26
	v_mov_b32_e32 v197, v27
	v_mov_b32_e32 v198, v28
	v_mov_b32_e32 v199, v29
	v_max_f32_e32 v21, 0, v21
	v_max_f32_e32 v22, 0, v22
	v_mul_f32_e32 v26, v18, v18
	v_max_f32_e32 v18, 0, v23
	v_mul_f32_e32 v23, v19, v19
	v_max_f32_e32 v19, 0, v24
	v_mul_f32_e32 v24, v20, v20
	v_max_f32_e32 v20, 0, v25
	v_mul_f32_e32 v19, v19, v19
	v_mul_f32_e32 v20, v20, v20
	v_mul_f32_e32 v18, v18, v18
	v_mul_f32_e32 v21, v21, v21
	v_cvt_pk_bf16_f32 v19, v19, v20
	v_cvt_pk_bf16_f32 v20, v26, v23
	v_mul_f32_e32 v22, v22, v22
	v_cvt_pk_bf16_f32 v18, v22, v18
	v_cvt_pk_bf16_f32 v21, v24, v21
	v_mov_b32_e32 v200, v18
	v_mov_b32_e32 v201, v19
	v_mov_b32_e32 v202, v20
	v_mov_b32_e32 v203, v21
	s_mov_b64 s[6:7], 0x160000
	s_mov_b32 s87, s8
	v_mov_b32_e32 v20, v143
	v_pk_mul_f32 v[10:11], v[10:11], v[20:21] op_sel_hi:[1,0]
	v_pk_mul_f32 v[14:15], v[14:15], v[20:21] op_sel_hi:[1,0]
	v_pk_mul_f32 v[12:13], v[12:13], v[20:21] op_sel_hi:[1,0]
	v_max_f32_e32 v10, 0, v10
	v_pk_mul_f32 v[16:17], v[16:17], v[20:21] op_sel_hi:[1,0]
	v_max_f32_e32 v14, 0, v14
	v_mul_f32_e32 v21, v10, v10
	v_max_f32_e32 v10, 0, v15
	v_max_f32_e32 v11, 0, v11
	v_max_f32_e32 v12, 0, v12
	v_lshl_add_u64 v[18:19], v[140:141], 0, s[6:7]
	v_mul_f32_e32 v14, v14, v14
	v_mul_f32_e32 v10, v10, v10
	v_mul_f32_e32 v15, v11, v11
	v_max_f32_e32 v11, 0, v16
	v_mul_f32_e32 v16, v12, v12
	v_max_f32_e32 v12, 0, v17
	s_mov_b32 s6, 0x160000
	v_mul_f32_e32 v11, v11, v11
	v_max_f32_e32 v13, 0, v13
	v_mul_f32_e32 v12, v12, v12
	v_cvt_pk_bf16_f32 v10, v14, v10
	v_add_co_u32_e32 v14, vcc, s6, v140
	v_pk_mul_f32 v[4:5], v[4:5], v[20:21] op_sel_hi:[1,0]
	v_pk_mul_f32 v[2:3], v[2:3], v[20:21] op_sel_hi:[1,0]
	v_mul_f32_e32 v13, v13, v13
	v_cvt_pk_bf16_f32 v11, v11, v12
	v_cvt_pk_bf16_f32 v12, v21, v15
	v_addc_co_u32_e32 v15, vcc, 0, v141, vcc
	v_pk_mul_f32 v[8:9], v[8:9], v[20:21] op_sel_hi:[1,0]
	v_pk_mul_f32 v[6:7], v[6:7], v[20:21] op_sel_hi:[1,0]
	v_max_f32_e32 v2, 0, v2
	v_max_f32_e32 v3, 0, v3
	v_max_f32_e32 v4, 0, v4
	v_cvt_pk_bf16_f32 v13, v16, v13
	v_mov_b32_e32 v222, v10
	v_mov_b32_e32 v223, v11
	v_mov_b32_e32 v224, v12
	v_mov_b32_e32 v225, v13
	v_max_f32_e32 v5, 0, v5
	v_max_f32_e32 v6, 0, v6
	v_mul_f32_e32 v10, v2, v2
	v_max_f32_e32 v2, 0, v7
	v_mul_f32_e32 v7, v3, v3
	v_max_f32_e32 v3, 0, v8
	v_mul_f32_e32 v8, v4, v4
	v_max_f32_e32 v4, 0, v9
	v_mul_f32_e32 v2, v2, v2
	v_mul_f32_e32 v3, v3, v3
	v_mul_f32_e32 v4, v4, v4
	v_mul_f32_e32 v5, v5, v5
	s_and_b64 vcc, exec, s[40:41]
	s_mov_b32 s88, s10
	s_mov_b64 s[6:7], s[24:25]
	s_mov_b64 s[36:37], s[12:13]
	s_mov_b32 s89, s86
	v_mul_f32_e32 v6, v6, v6
	v_cvt_pk_bf16_f32 v2, v6, v2
	v_cvt_pk_bf16_f32 v3, v3, v4
	v_cvt_pk_bf16_f32 v4, v10, v7
	v_cvt_pk_bf16_f32 v5, v8, v5
	v_mov_b32_e32 v246, v2
	v_mov_b32_e32 v247, v3
	v_mov_b32_e32 v248, v4
	v_mov_b32_e32 v249, v5
	s_cbranch_vccz .LBB0_163
	global_store_dwordx4 v250, v[158:161], s[4:5]
	global_store_dwordx4 v250, v[164:167], s[4:5] offset:256
	s_nop 1
	v_add_u32_e32 v250, 0x20000, v250
	global_store_dwordx4 v250, v[188:191], s[4:5]
	global_store_dwordx4 v250, v[192:195], s[4:5] offset:256
	s_nop 1
	v_add_u32_e32 v250, 0x20000, v250
	global_store_dwordx4 v250, v[196:199], s[4:5]
	global_store_dwordx4 v250, v[200:203], s[4:5] offset:256
	s_nop 1
	v_add_u32_e32 v250, 0x20000, v250
	global_store_dwordx4 v250, v[222:225], s[4:5]
	global_store_dwordx4 v250, v[246:249], s[4:5] offset:256
	s_nop 1
	v_mov_b64_e32 v[164:165], 0x200
	v_mbcnt_lo_u32_b32 v193, -1, 0
	v_mbcnt_hi_u32_b32 v193, -1, v193
	v_add_u32_e32 v167, s18, v193
	v_mov_b32_e32 v188, 1
	v_mov_b32_e32 v189, 0x358637bd
	v_mov_b32_e32 v190, 0x260
	v_mov_b32_e32 v191, 0x3c0881c4
	v_mov_b32_e32 v192, 0xbab64f3b
	v_mov_b32_e32 v194, 0xf149f2ca
	v_mov_b32_e32 v195, 0xc0
	v_mov_b32_e32 v196, 0x70
	v_mov_b32_e32 v197, 0x71
	v_mov_b32_e32 v198, 5
	v_mov_b32_e32 v199, 2
	v_mov_b32_e32 v200, 3
	v_not_b32_e32 v201, 63
	v_not_b32_e32 v202, 31
	v_mov_b32_e32 v203, 0x7fc00000
	v_mov_b32_e32 v222, 0
	v_mov_b32_e32 v223, 0
	v_mov_b32_e32 v224, 0
	v_mov_b32_e32 v225, 0
	s_waitcnt vmcnt(0)
	v_readlane_b32 s70, v254, 40
	v_readlane_b32 s84, v254, 42
	s_cmpk_gt_u32 s18, 0xff
	v_readlane_b32 s71, v254, 41
	v_readlane_b32 s86, v254, 44
	v_readlane_b32 s87, v254, 45
	v_readlane_b32 s85, v254, 43
	s_cbranch_scc1 .LBB0_174
	s_barrier

; template <class Epi>
; __device__ __forceinline__ void gemm_phase(LAS unsigned char* lds, const Gemm g, const StaticOrder& S, const Epi& E) {
;     ...
;         for (int t = 0; t < nt; t += 2) {
;             if constexpr (Epi::MIDSCALE) {
;                 if (t == 4 || t == 8) {
;                     float f[2][4];
; #pragma unroll
;                     for (int ai = 0; ai < 2; ++ai)
; #pragma unroll
;                         for (int m = 0; m < 4; ++m) f[ai][m] = E.rstab[ui * 256 + wr * 64 + fr + ai * HALF + m * 16];
;                     asm volatile("s_waitcnt lgkmcnt(0)" ::: "memory");
; #pragma unroll
;                     for (int ai = 0; ai < 2; ++ai)
; #pragma unroll
;                         for (int m = 0; m < 4; ++m) { const float ff = (t == 4) ? __builtin_amdgcn_rcpf(f[ai][m]) : f[ai][m];
; #pragma unroll
;                             for (int bj = 0; bj < 2; ++bj)
; #pragma unroll
;                                 for (int n = 0; n < 2; ++n) acc[ai][bj][m][n] = acc[ai][bj][m][n] * ff; }
;                 }
;             }
;             const bool last = (t == nt - 2);
;             const char* a1 = cA + (size_t)(t + 1) * kstep;
;             const char* a2 = last ? nA : cA + (size_t)(t + 2) * kstep; const char* b2 = last ? nB : cB + (size_t)(t + 2) * kstep;
;             const char* a3 = a2 + kstep; const char* b3 = b2 + kstep;
;             PG8_LDB(B0, 0, 0); PG8_SCHED; PG8_LDA(At, 0, 0); PG8_STAGE(PG8_SA(1, 1), a1 + hstep, voffA);
;             PG8_WAIT_L(8); PG8_BAR; PG8_WAIT_L(0); PG8_MMA(0, 0, At, B0); PG8_BAR; PG8_SCHED;
;             PG8_LDB(B1, 0, 1); PG8_STAGE(PG8_SB(0, 0), b2, voffB);
;             PG8_BAR; PG8_WAIT_L(0); PG8_MMA(0, 1, At, B1); PG8_BAR;
;             PG8_LDA(At, 0, 1); PG8_STAGE(PG8_SA(0, 0), a2, voffA);
;             PG8_BAR; PG8_WAIT_L(0); PG8_MMA(1, 0, At, B0); PG8_BAR; PG8_SCHED;
;             PG8_STAGE(PG8_SB(0, 1), b2 + hstep, voffB);
;             PG8_WAIT_V(6); PG8_BAR; PG8_MMA(1, 1, At, B1); PG8_BAR;
;             PG8_LDB(B0, 1, 0); PG8_SCHED; PG8_LDA(At, 1, 0); PG8_STAGE(PG8_SA(0, 1), a2 + hstep, voffA);
;             PG8_WAIT_L(8); PG8_BAR; PG8_WAIT_L(0); PG8_MMA(0, 0, At, B0); PG8_BAR; PG8_SCHED;
;             PG8_LDB(B1, 1, 1); PG8_STAGE(PG8_SB(1, 0), b3, voffB);
;             PG8_BAR; PG8_WAIT_L(0); PG8_MMA(0, 1, At, B1); PG8_BAR;
;             PG8_LDA(At, 1, 1); PG8_STAGE(PG8_SA(1, 0), a3, voffA);
.LBB0_463:
	s_add_u32 s6, s24, 0xfffc0080
	s_addc_u32 s7, s25, -1
	s_add_i32 s58, 0, 0x10000
	v_add_u32_e32 v153, s58, v149
	ds_read_b128 v[140:143], v153
	ds_read_b128 v[144:147], v153 offset:1024
	ds_read_b128 v[154:157], v153 offset:2048
	ds_read_b128 v[158:161], v153 offset:3072
	s_cmp_eq_u32 s91, 12
	s_cselect_b32 s37, s11, s7
	s_cselect_b32 s36, s71, s6
	s_cselect_b32 s7, s9, s90
	s_cselect_b32 s6, s88, s89
	ds_read_b128 v[168:171], v152
	ds_read_b128 v[172:175], v152 offset:1024
	ds_read_b128 v[176:179], v152 offset:2048
	ds_read_b128 v[180:183], v152 offset:3072
	ds_read_b128 v[184:187], v152 offset:4096
	ds_read_b128 v[204:207], v152 offset:5120
	ds_read_b128 v[208:211], v152 offset:6144
	ds_read_b128 v[212:215], v152 offset:7168
	s_waitcnt lgkmcnt(8)
	s_barrier
	s_waitcnt lgkmcnt(0)
	s_setprio 1
	s_waitcnt lgkmcnt(0)
	v_mfma_f32_16x16x32_bf16 v[126:129], v[140:143], v[168:171], 0
	v_mfma_f32_16x16x32_bf16 v[122:125], v[154:157], v[168:171], 0
	v_mfma_f32_16x16x32_bf16 v[114:117], v[140:143], v[176:179], 0
	v_mfma_f32_16x16x32_bf16 v[106:109], v[154:157], v[176:179], 0
	s_add_i32 m0, s47, 0xc000
	s_nop 0
	global_load_lds_dwordx4 v136, s[24:25]
	v_mfma_f32_16x16x32_bf16 v[98:101], v[140:143], v[184:187], 0
	v_mfma_f32_16x16x32_bf16 v[90:93], v[154:157], v[184:187], 0
	v_mfma_f32_16x16x32_bf16 v[82:85], v[140:143], v[208:211], 0
	v_mfma_f32_16x16x32_bf16 v[74:77], v[154:157], v[208:211], 0
	v_mfma_f32_16x16x32_bf16 v[126:129], v[144:147], v[172:175], v[126:129]
	v_mfma_f32_16x16x32_bf16 v[122:125], v[158:161], v[172:175], v[122:125]
	s_add_i32 m0, s47, 0xe000
	s_nop 0
	global_load_lds_dwordx4 v138, s[24:25]
	v_mfma_f32_16x16x32_bf16 v[114:117], v[144:147], v[180:183], v[114:117]
	v_mfma_f32_16x16x32_bf16 v[106:109], v[158:161], v[180:183], v[106:109]
	v_mfma_f32_16x16x32_bf16 v[98:101], v[144:147], v[204:207], v[98:101]
	v_mfma_f32_16x16x32_bf16 v[90:93], v[158:161], v[204:207], v[90:93]
	v_mfma_f32_16x16x32_bf16 v[82:85], v[144:147], v[212:215], v[82:85]
	v_mfma_f32_16x16x32_bf16 v[74:77], v[158:161], v[212:215], v[74:77]
	s_setprio 0
	s_barrier
	s_add_i32 s70, 0, 0x14000
	s_add_i32 s58, s58, s44
	v_add_u32_e32 v153, s70, v149
	ds_read_b128 v[216:219], v153
	ds_read_b128 v[226:229], v153 offset:1024
	ds_read_b128 v[230:233], v153 offset:2048
	ds_read_b128 v[234:237], v153 offset:3072
	s_barrier
	s_waitcnt lgkmcnt(0)
	s_setprio 1
	s_waitcnt lgkmcnt(0)
	v_mfma_f32_16x16x32_bf16 v[118:121], v[216:219], v[168:171], 0
	v_mfma_f32_16x16x32_bf16 v[110:113], v[230:233], v[168:171], 0
	v_mfma_f32_16x16x32_bf16 v[102:105], v[216:219], v[176:179], 0
	v_mfma_f32_16x16x32_bf16 v[94:97], v[230:233], v[176:179], 0
	s_mov_b32 m0, s58
	s_nop 0
	global_load_lds_dwordx4 v0, s[6:7]
	v_mfma_f32_16x16x32_bf16 v[86:89], v[216:219], v[184:187], 0
	v_mfma_f32_16x16x32_bf16 v[78:81], v[230:233], v[184:187], 0
	v_mfma_f32_16x16x32_bf16 v[70:73], v[216:219], v[208:211], 0
	v_mfma_f32_16x16x32_bf16 v[66:69], v[230:233], v[208:211], 0
	v_mfma_f32_16x16x32_bf16 v[118:121], v[226:229], v[172:175], v[118:121]
	v_mfma_f32_16x16x32_bf16 v[110:113], v[234:237], v[172:175], v[110:113]
	s_add_i32 m0, s58, 0x2000
	s_nop 0
	global_load_lds_dwordx4 v130, s[6:7]
	v_mfma_f32_16x16x32_bf16 v[102:105], v[226:229], v[180:183], v[102:105]
	v_mfma_f32_16x16x32_bf16 v[94:97], v[234:237], v[180:183], v[94:97]
	v_mfma_f32_16x16x32_bf16 v[86:89], v[226:229], v[204:207], v[86:89]
	v_mfma_f32_16x16x32_bf16 v[78:81], v[234:237], v[204:207], v[78:81]
	v_mfma_f32_16x16x32_bf16 v[70:73], v[226:229], v[212:215], v[70:73]
	v_mfma_f32_16x16x32_bf16 v[66:69], v[234:237], v[212:215], v[66:69]
	s_setprio 0
	s_add_u32 vcc_lo, s36, 0x80
	s_addc_u32 vcc_hi, s37, 0
	s_barrier
	ds_read_b128 v[168:171], v152 offset:16384
	ds_read_b128 v[172:175], v152 offset:17408
	ds_read_b128 v[176:179], v152 offset:18432
	ds_read_b128 v[180:183], v152 offset:19456
	ds_read_b128 v[184:187], v152 offset:20480
	ds_read_b128 v[204:207], v152 offset:21504
	ds_read_b128 v[208:211], v152 offset:22528
	ds_read_b128 v[212:215], v152 offset:23552
	s_barrier
	s_waitcnt lgkmcnt(0)
	s_setprio 1
	s_waitcnt lgkmcnt(0)
	v_mfma_f32_16x16x32_bf16 v[62:65], v[140:143], v[168:171], 0
	v_mfma_f32_16x16x32_bf16 v[58:61], v[154:157], v[168:171], 0
	v_mfma_f32_16x16x32_bf16 v[50:53], v[140:143], v[176:179], 0
	v_mfma_f32_16x16x32_bf16 v[42:45], v[154:157], v[176:179], 0
	s_mov_b32 m0, s47
	s_nop 0
	global_load_lds_dwordx4 v134, s[36:37]
	v_mfma_f32_16x16x32_bf16 v[34:37], v[140:143], v[184:187], 0
	v_mfma_f32_16x16x32_bf16 v[26:29], v[154:157], v[184:187], 0
	v_mfma_f32_16x16x32_bf16 v[18:21], v[140:143], v[208:211], 0
	v_mfma_f32_16x16x32_bf16 v[10:13], v[154:157], v[208:211], 0
	v_mfma_f32_16x16x32_bf16 v[62:65], v[144:147], v[172:175], v[62:65]
	v_mfma_f32_16x16x32_bf16 v[58:61], v[158:161], v[172:175], v[58:61]
	s_mov_b32 m0, s48
	s_nop 0
	global_load_lds_dwordx4 v132, s[36:37]
	v_mfma_f32_16x16x32_bf16 v[50:53], v[144:147], v[180:183], v[50:53]
	v_mfma_f32_16x16x32_bf16 v[42:45], v[158:161], v[180:183], v[42:45]
	v_mfma_f32_16x16x32_bf16 v[34:37], v[144:147], v[204:207], v[34:37]
	v_mfma_f32_16x16x32_bf16 v[26:29], v[158:161], v[204:207], v[26:29]
	v_mfma_f32_16x16x32_bf16 v[18:21], v[144:147], v[212:215], v[18:21]
	v_mfma_f32_16x16x32_bf16 v[10:13], v[158:161], v[212:215], v[10:13]
	s_setprio 0
	s_barrier
	s_add_u32 s60, s6, 0x40000
	s_addc_u32 s61, s7, 0
	s_add_i32 s58, s70, s44
	s_waitcnt vmcnt(4)
	s_barrier
; template <class Epi>
; __device__ __forceinline__ void gemm_phase(LAS unsigned char* lds, const Gemm g, const StaticOrder& S, const Epi& E) {
;     ...
;         for (int t = 0; t < nt; t += 2) {
;             if constexpr (Epi::MIDSCALE) {
;                 if (t == 4 || t == 8) {
;                     float f[2][4];
; #pragma unroll
;                     for (int ai = 0; ai < 2; ++ai)
; #pragma unroll
;                         for (int m = 0; m < 4; ++m) f[ai][m] = E.rstab[ui * 256 + wr * 64 + fr + ai * HALF + m * 16];
;                     asm volatile("s_waitcnt lgkmcnt(0)" ::: "memory");
; #pragma unroll
;                     for (int ai = 0; ai < 2; ++ai)
; #pragma unroll
;                         for (int m = 0; m < 4; ++m) { const float ff = (t == 4) ? __builtin_amdgcn_rcpf(f[ai][m]) : f[ai][m];
; #pragma unroll
;                             for (int bj = 0; bj < 2; ++bj)
; #pragma unroll
;                                 for (int n = 0; n < 2; ++n) acc[ai][bj][m][n] = acc[ai][bj][m][n] * ff; }
;                 }
;             }
;             const bool last = (t == nt - 2);
;             const char* a1 = cA + (size_t)(t + 1) * kstep;
;             const char* a2 = last ? nA : cA + (size_t)(t + 2) * kstep; const char* b2 = last ? nB : cB + (size_t)(t + 2) * kstep;
;             const char* a3 = a2 + kstep; const char* b3 = b2 + kstep;
;             PG8_LDB(B0, 0, 0); PG8_SCHED; PG8_LDA(At, 0, 0); PG8_STAGE(PG8_SA(1, 1), a1 + hstep, voffA);
;             PG8_WAIT_L(8); PG8_BAR; PG8_WAIT_L(0); PG8_MMA(0, 0, At, B0); PG8_BAR; PG8_SCHED;
;             PG8_LDB(B1, 0, 1); PG8_STAGE(PG8_SB(0, 0), b2, voffB);
;             PG8_BAR; PG8_WAIT_L(0); PG8_MMA(0, 1, At, B1); PG8_BAR;
;             PG8_LDA(At, 0, 1); PG8_STAGE(PG8_SA(0, 0), a2, voffA);
;             PG8_BAR; PG8_WAIT_L(0); PG8_MMA(1, 0, At, B0); PG8_BAR; PG8_SCHED;
;             PG8_STAGE(PG8_SB(0, 1), b2 + hstep, voffB);
;             PG8_WAIT_V(6); PG8_BAR; PG8_MMA(1, 1, At, B1); PG8_BAR;
;             PG8_LDB(B0, 1, 0); PG8_SCHED; PG8_LDA(At, 1, 0); PG8_STAGE(PG8_SA(0, 1), a2 + hstep, voffA);
;             PG8_WAIT_L(8); PG8_BAR; PG8_WAIT_L(0); PG8_MMA(0, 0, At, B0); PG8_BAR; PG8_SCHED;
;             PG8_LDB(B1, 1, 1); PG8_STAGE(PG8_SB(1, 0), b3, voffB);
;             PG8_BAR; PG8_WAIT_L(0); PG8_MMA(0, 1, At, B1); PG8_BAR;
;             PG8_LDA(At, 1, 1); PG8_STAGE(PG8_SA(1, 0), a3, voffA);
	s_setprio 1
	v_mfma_f32_16x16x32_bf16 v[54:57], v[216:219], v[168:171], 0
	v_mfma_f32_16x16x32_bf16 v[46:49], v[230:233], v[168:171], 0
	v_mfma_f32_16x16x32_bf16 v[38:41], v[216:219], v[176:179], 0
	v_mfma_f32_16x16x32_bf16 v[30:33], v[230:233], v[176:179], 0
	s_mov_b32 m0, s58
	s_nop 0
	global_load_lds_dwordx4 v0, s[60:61]
	v_mfma_f32_16x16x32_bf16 v[22:25], v[216:219], v[184:187], 0
	v_mfma_f32_16x16x32_bf16 v[14:17], v[230:233], v[184:187], 0
	v_mfma_f32_16x16x32_bf16 v[6:9], v[216:219], v[208:211], 0
	v_mfma_f32_16x16x32_bf16 v[2:5], v[230:233], v[208:211], 0
	v_mfma_f32_16x16x32_bf16 v[54:57], v[226:229], v[172:175], v[54:57]
	v_mfma_f32_16x16x32_bf16 v[46:49], v[234:237], v[172:175], v[46:49]
	s_add_i32 m0, s58, 0x2000
	s_nop 0
	global_load_lds_dwordx4 v130, s[60:61]
	v_mfma_f32_16x16x32_bf16 v[38:41], v[226:229], v[180:183], v[38:41]
	v_mfma_f32_16x16x32_bf16 v[30:33], v[234:237], v[180:183], v[30:33]
	v_mfma_f32_16x16x32_bf16 v[22:25], v[226:229], v[204:207], v[22:25]
	v_mfma_f32_16x16x32_bf16 v[14:17], v[234:237], v[204:207], v[14:17]
	v_mfma_f32_16x16x32_bf16 v[6:9], v[226:229], v[212:215], v[6:9]
	v_mfma_f32_16x16x32_bf16 v[2:5], v[234:237], v[212:215], v[2:5]
	s_setprio 0
	s_add_i32 s58, 0, 0x18000
	v_add_u32_e32 v153, s58, v149
	s_barrier
	ds_read_b128 v[140:143], v153
	ds_read_b128 v[144:147], v153 offset:1024
	ds_read_b128 v[154:157], v153 offset:2048
	ds_read_b128 v[158:161], v153 offset:3072
	s_add_u32 s36, s36, 0x40000
	s_addc_u32 s37, s37, 0
	ds_read_b128 v[168:171], v152 offset:32768
	ds_read_b128 v[172:175], v152 offset:33792
	ds_read_b128 v[176:179], v152 offset:34816
	ds_read_b128 v[180:183], v152 offset:35840
	ds_read_b128 v[184:187], v152 offset:36864
	ds_read_b128 v[204:207], v152 offset:37888
	ds_read_b128 v[208:211], v152 offset:38912
	ds_read_b128 v[212:215], v152 offset:39936
	s_waitcnt lgkmcnt(8)
	s_barrier
	s_waitcnt lgkmcnt(0)
	s_setprio 1
	s_waitcnt lgkmcnt(0)
	v_mfma_f32_16x16x32_bf16 v[126:129], v[140:143], v[168:171], v[126:129]
	v_mfma_f32_16x16x32_bf16 v[122:125], v[154:157], v[168:171], v[122:125]
	s_cmp_eq_u32 s87, 0
	s_cbranch_scc1 .LdsA_skip_0
	global_store_dwordx4 v166, v[162:165], s[4:5]
.LdsA_skip_0:
	v_mfma_f32_16x16x32_bf16 v[114:117], v[140:143], v[176:179], v[114:117]
	v_mfma_f32_16x16x32_bf16 v[106:109], v[154:157], v[176:179], v[106:109]
	s_mov_b32 m0, s49
	s_nop 0
	global_load_lds_dwordx4 v134, s[36:37]
	v_mfma_f32_16x16x32_bf16 v[98:101], v[140:143], v[184:187], v[98:101]
	v_mfma_f32_16x16x32_bf16 v[90:93], v[154:157], v[184:187], v[90:93]
	v_mfma_f32_16x16x32_bf16 v[82:85], v[140:143], v[208:211], v[82:85]
	v_mfma_f32_16x16x32_bf16 v[74:77], v[154:157], v[208:211], v[74:77]
	v_mfma_f32_16x16x32_bf16 v[126:129], v[144:147], v[172:175], v[126:129]
	v_mfma_f32_16x16x32_bf16 v[122:125], v[158:161], v[172:175], v[122:125]
	s_mov_b32 m0, s54
	s_nop 0
	global_load_lds_dwordx4 v132, s[36:37]
	v_mfma_f32_16x16x32_bf16 v[114:117], v[144:147], v[180:183], v[114:117]
	v_mfma_f32_16x16x32_bf16 v[106:109], v[158:161], v[180:183], v[106:109]
	v_mfma_f32_16x16x32_bf16 v[98:101], v[144:147], v[204:207], v[98:101]
	v_mfma_f32_16x16x32_bf16 v[90:93], v[158:161], v[204:207], v[90:93]
	v_mfma_f32_16x16x32_bf16 v[82:85], v[144:147], v[212:215], v[82:85]
	v_mfma_f32_16x16x32_bf16 v[74:77], v[158:161], v[212:215], v[74:77]
	s_setprio 0
	s_barrier
	s_add_i32 s36, 0, 0x1c000
	s_add_i32 s37, s58, s44
	v_add_u32_e32 v153, s36, v149
	s_add_u32 s60, s6, 0x80
	s_addc_u32 s61, s7, 0
	ds_read_b128 v[216:219], v153
	ds_read_b128 v[226:229], v153 offset:1024
	ds_read_b128 v[230:233], v153 offset:2048
	ds_read_b128 v[234:237], v153 offset:3072
	s_barrier
	s_waitcnt lgkmcnt(0)
	s_setprio 1
	s_waitcnt lgkmcnt(0)
	v_mfma_f32_16x16x32_bf16 v[118:121], v[216:219], v[168:171], v[118:121]
	v_mfma_f32_16x16x32_bf16 v[110:113], v[230:233], v[168:171], v[110:113]
	v_mfma_f32_16x16x32_bf16 v[102:105], v[216:219], v[176:179], v[102:105]
	v_mfma_f32_16x16x32_bf16 v[94:97], v[230:233], v[176:179], v[94:97]
	s_mov_b32 m0, s37
	s_nop 0
	global_load_lds_dwordx4 v0, s[60:61]
	v_mfma_f32_16x16x32_bf16 v[86:89], v[216:219], v[184:187], v[86:89]
	v_mfma_f32_16x16x32_bf16 v[78:81], v[230:233], v[184:187], v[78:81]
	v_mfma_f32_16x16x32_bf16 v[70:73], v[216:219], v[208:211], v[70:73]
	v_mfma_f32_16x16x32_bf16 v[66:69], v[230:233], v[208:211], v[66:69]
	v_mfma_f32_16x16x32_bf16 v[118:121], v[226:229], v[172:175], v[118:121]
	v_mfma_f32_16x16x32_bf16 v[110:113], v[234:237], v[172:175], v[110:113]
	s_add_i32 m0, s37, 0x2000
	s_nop 0
	global_load_lds_dwordx4 v130, s[60:61]
	v_mfma_f32_16x16x32_bf16 v[102:105], v[226:229], v[180:183], v[102:105]
	v_mfma_f32_16x16x32_bf16 v[94:97], v[234:237], v[180:183], v[94:97]
	v_mfma_f32_16x16x32_bf16 v[86:89], v[226:229], v[204:207], v[86:89]
	v_mfma_f32_16x16x32_bf16 v[78:81], v[234:237], v[204:207], v[78:81]
	v_mfma_f32_16x16x32_bf16 v[70:73], v[226:229], v[212:215], v[70:73]
	v_mfma_f32_16x16x32_bf16 v[66:69], v[234:237], v[212:215], v[66:69]
	s_setprio 0
	s_barrier
	ds_read_b128 v[168:171], v152 offset:49152
	ds_read_b128 v[172:175], v152 offset:50176
	ds_read_b128 v[176:179], v152 offset:51200
	ds_read_b128 v[180:183], v152 offset:52224
	ds_read_b128 v[184:187], v152 offset:53248
	ds_read_b128 v[204:207], v152 offset:54272
	ds_read_b128 v[208:211], v152 offset:55296
	ds_read_b128 v[212:215], v152 offset:56320
	s_barrier
; template <class Epi>
; __device__ __forceinline__ void gemm_phase(LAS unsigned char* lds, const Gemm g, const StaticOrder& S, const Epi& E) {
;     ...
;         for (int t = 0; t < nt; t += 2) {
;             if constexpr (Epi::MIDSCALE) {
;                 if (t == 4 || t == 8) {
;                     float f[2][4];
; #pragma unroll
;                     for (int ai = 0; ai < 2; ++ai)
; #pragma unroll
;                         for (int m = 0; m < 4; ++m) f[ai][m] = E.rstab[ui * 256 + wr * 64 + fr + ai * HALF + m * 16];
;                     asm volatile("s_waitcnt lgkmcnt(0)" ::: "memory");
; #pragma unroll
;                     for (int ai = 0; ai < 2; ++ai)
; #pragma unroll
;                         for (int m = 0; m < 4; ++m) { const float ff = (t == 4) ? __builtin_amdgcn_rcpf(f[ai][m]) : f[ai][m];
; #pragma unroll
;                             for (int bj = 0; bj < 2; ++bj)
; #pragma unroll
;                                 for (int n = 0; n < 2; ++n) acc[ai][bj][m][n] = acc[ai][bj][m][n] * ff; }
;                 }
;             }
;             const bool last = (t == nt - 2);
;             const char* a1 = cA + (size_t)(t + 1) * kstep;
;             const char* a2 = last ? nA : cA + (size_t)(t + 2) * kstep; const char* b2 = last ? nB : cB + (size_t)(t + 2) * kstep;
;             const char* a3 = a2 + kstep; const char* b3 = b2 + kstep;
;             PG8_LDB(B0, 0, 0); PG8_SCHED; PG8_LDA(At, 0, 0); PG8_STAGE(PG8_SA(1, 1), a1 + hstep, voffA);
;             PG8_WAIT_L(8); PG8_BAR; PG8_WAIT_L(0); PG8_MMA(0, 0, At, B0); PG8_BAR; PG8_SCHED;
;             PG8_LDB(B1, 0, 1); PG8_STAGE(PG8_SB(0, 0), b2, voffB);
;             PG8_BAR; PG8_WAIT_L(0); PG8_MMA(0, 1, At, B1); PG8_BAR;
;             PG8_LDA(At, 0, 1); PG8_STAGE(PG8_SA(0, 0), a2, voffA);
;             PG8_BAR; PG8_WAIT_L(0); PG8_MMA(1, 0, At, B0); PG8_BAR; PG8_SCHED;
;             PG8_STAGE(PG8_SB(0, 1), b2 + hstep, voffB);
;             PG8_WAIT_V(6); PG8_BAR; PG8_MMA(1, 1, At, B1); PG8_BAR;
;             PG8_LDB(B0, 1, 0); PG8_SCHED; PG8_LDA(At, 1, 0); PG8_STAGE(PG8_SA(0, 1), a2 + hstep, voffA);
;             PG8_WAIT_L(8); PG8_BAR; PG8_WAIT_L(0); PG8_MMA(0, 0, At, B0); PG8_BAR; PG8_SCHED;
;             PG8_LDB(B1, 1, 1); PG8_STAGE(PG8_SB(1, 0), b3, voffB);
;             PG8_BAR; PG8_WAIT_L(0); PG8_MMA(0, 1, At, B1); PG8_BAR;
;             PG8_LDA(At, 1, 1); PG8_STAGE(PG8_SA(1, 0), a3, voffA);
	s_waitcnt lgkmcnt(0)
	s_setprio 1
	s_waitcnt lgkmcnt(0)
	v_mfma_f32_16x16x32_bf16 v[62:65], v[140:143], v[168:171], v[62:65]
	v_mfma_f32_16x16x32_bf16 v[58:61], v[154:157], v[168:171], v[58:61]
	v_mfma_f32_16x16x32_bf16 v[50:53], v[140:143], v[176:179], v[50:53]
	v_mfma_f32_16x16x32_bf16 v[42:45], v[154:157], v[176:179], v[42:45]
	s_mov_b32 m0, s55
	s_nop 0
	global_load_lds_dwordx4 v134, vcc
	v_mfma_f32_16x16x32_bf16 v[34:37], v[140:143], v[184:187], v[34:37]
	v_mfma_f32_16x16x32_bf16 v[26:29], v[154:157], v[184:187], v[26:29]
	v_mfma_f32_16x16x32_bf16 v[18:21], v[140:143], v[208:211], v[18:21]
	v_mfma_f32_16x16x32_bf16 v[10:13], v[154:157], v[208:211], v[10:13]
	v_mfma_f32_16x16x32_bf16 v[62:65], v[144:147], v[172:175], v[62:65]
	v_mfma_f32_16x16x32_bf16 v[58:61], v[158:161], v[172:175], v[58:61]
	s_mov_b32 m0, s83
	s_nop 0
	global_load_lds_dwordx4 v132, vcc
	v_mfma_f32_16x16x32_bf16 v[50:53], v[144:147], v[180:183], v[50:53]
	v_mfma_f32_16x16x32_bf16 v[42:45], v[158:161], v[180:183], v[42:45]
	v_mfma_f32_16x16x32_bf16 v[34:37], v[144:147], v[204:207], v[34:37]
	v_mfma_f32_16x16x32_bf16 v[26:29], v[158:161], v[204:207], v[26:29]
	v_mfma_f32_16x16x32_bf16 v[18:21], v[144:147], v[212:215], v[18:21]
	v_mfma_f32_16x16x32_bf16 v[10:13], v[158:161], v[212:215], v[10:13]
	s_setprio 0
	s_barrier
	s_add_u32 s6, s6, 0x40080
	s_addc_u32 s7, s7, 0
	s_add_i32 s36, s36, s44
	s_waitcnt vmcnt(4)
	s_barrier
	s_setprio 1
	v_mfma_f32_16x16x32_bf16 v[54:57], v[216:219], v[168:171], v[54:57]
	v_mfma_f32_16x16x32_bf16 v[46:49], v[230:233], v[168:171], v[46:49]
	v_mfma_f32_16x16x32_bf16 v[38:41], v[216:219], v[176:179], v[38:41]
	v_mfma_f32_16x16x32_bf16 v[30:33], v[230:233], v[176:179], v[30:33]
	s_mov_b32 m0, s36
	s_nop 0
	global_load_lds_dwordx4 v0, s[6:7]
	v_mfma_f32_16x16x32_bf16 v[22:25], v[216:219], v[184:187], v[22:25]
	v_mfma_f32_16x16x32_bf16 v[14:17], v[230:233], v[184:187], v[14:17]
	v_mfma_f32_16x16x32_bf16 v[6:9], v[216:219], v[208:211], v[6:9]
	v_mfma_f32_16x16x32_bf16 v[2:5], v[230:233], v[208:211], v[2:5]
	v_mfma_f32_16x16x32_bf16 v[54:57], v[226:229], v[172:175], v[54:57]
	v_mfma_f32_16x16x32_bf16 v[46:49], v[234:237], v[172:175], v[46:49]
	s_add_i32 m0, s36, 0x2000
	s_nop 0
	global_load_lds_dwordx4 v130, s[6:7]
	v_mfma_f32_16x16x32_bf16 v[38:41], v[226:229], v[180:183], v[38:41]
	v_mfma_f32_16x16x32_bf16 v[30:33], v[234:237], v[180:183], v[30:33]
	v_mfma_f32_16x16x32_bf16 v[22:25], v[226:229], v[204:207], v[22:25]
	v_mfma_f32_16x16x32_bf16 v[14:17], v[234:237], v[204:207], v[14:17]
	v_mfma_f32_16x16x32_bf16 v[6:9], v[226:229], v[212:215], v[6:9]
	v_mfma_f32_16x16x32_bf16 v[2:5], v[234:237], v[212:215], v[2:5]
	s_setprio 0
	s_add_i32 s91, s91, 2
	s_add_u32 s24, s24, 0x100
	s_addc_u32 s25, s25, 0
	s_add_u32 s89, s89, 0x100
	s_addc_u32 s90, s90, 0
	s_cmp_gt_u32 s91, 13
	s_barrier
	s_add_u32 s6, s24, 0xfffc0080
	s_addc_u32 s7, s25, -1
	s_add_i32 s58, 0, 0x10000
	v_add_u32_e32 v153, s58, v149
	ds_read_b128 v[140:143], v153
	ds_read_b128 v[144:147], v153 offset:1024
	ds_read_b128 v[154:157], v153 offset:2048
	ds_read_b128 v[158:161], v153 offset:3072
	s_cmp_eq_u32 s91, 12
	s_cselect_b32 s37, s11, s7
	s_cselect_b32 s36, s71, s6
	s_cselect_b32 s7, s9, s90
	s_cselect_b32 s6, s88, s89
	ds_read_b128 v[168:171], v152
	ds_read_b128 v[172:175], v152 offset:1024
	ds_read_b128 v[176:179], v152 offset:2048
	ds_read_b128 v[180:183], v152 offset:3072
	ds_read_b128 v[184:187], v152 offset:4096
	ds_read_b128 v[204:207], v152 offset:5120
	ds_read_b128 v[208:211], v152 offset:6144
	ds_read_b128 v[212:215], v152 offset:7168
	s_waitcnt lgkmcnt(8)
	s_barrier
	s_waitcnt lgkmcnt(0)
	s_setprio 1
	s_waitcnt lgkmcnt(0)
	v_mfma_f32_16x16x32_bf16 v[126:129], v[140:143], v[168:171], v[126:129]
	v_mfma_f32_16x16x32_bf16 v[122:125], v[154:157], v[168:171], v[122:125]
	v_mfma_f32_16x16x32_bf16 v[114:117], v[140:143], v[176:179], v[114:117]
	v_mfma_f32_16x16x32_bf16 v[106:109], v[154:157], v[176:179], v[106:109]
	s_add_i32 m0, s47, 0xc000
	s_nop 0
	global_load_lds_dwordx4 v136, s[24:25]
	v_mfma_f32_16x16x32_bf16 v[98:101], v[140:143], v[184:187], v[98:101]
	v_mfma_f32_16x16x32_bf16 v[90:93], v[154:157], v[184:187], v[90:93]
	v_mfma_f32_16x16x32_bf16 v[82:85], v[140:143], v[208:211], v[82:85]
	v_mfma_f32_16x16x32_bf16 v[74:77], v[154:157], v[208:211], v[74:77]
	v_mfma_f32_16x16x32_bf16 v[126:129], v[144:147], v[172:175], v[126:129]
	v_mfma_f32_16x16x32_bf16 v[122:125], v[158:161], v[172:175], v[122:125]
	s_add_i32 m0, s47, 0xe000
	s_nop 0
	global_load_lds_dwordx4 v138, s[24:25]
	v_mfma_f32_16x16x32_bf16 v[114:117], v[144:147], v[180:183], v[114:117]
	v_mfma_f32_16x16x32_bf16 v[106:109], v[158:161], v[180:183], v[106:109]
	v_mfma_f32_16x16x32_bf16 v[98:101], v[144:147], v[204:207], v[98:101]
	v_mfma_f32_16x16x32_bf16 v[90:93], v[158:161], v[204:207], v[90:93]
	v_mfma_f32_16x16x32_bf16 v[82:85], v[144:147], v[212:215], v[82:85]
	v_mfma_f32_16x16x32_bf16 v[74:77], v[158:161], v[212:215], v[74:77]
	s_setprio 0
	s_barrier
	s_add_i32 s70, 0, 0x14000
	s_add_i32 s58, s58, s44
	v_add_u32_e32 v153, s70, v149
	ds_read_b128 v[216:219], v153
	ds_read_b128 v[226:229], v153 offset:1024
	ds_read_b128 v[230:233], v153 offset:2048
	ds_read_b128 v[234:237], v153 offset:3072
	s_barrier
; template <class Epi>
; __device__ __forceinline__ void gemm_phase(LAS unsigned char* lds, const Gemm g, const StaticOrder& S, const Epi& E) {
;     ...
;         for (int t = 0; t < nt; t += 2) {
;             if constexpr (Epi::MIDSCALE) {
;                 if (t == 4 || t == 8) {
;                     float f[2][4];
; #pragma unroll
;                     for (int ai = 0; ai < 2; ++ai)
; #pragma unroll
;                         for (int m = 0; m < 4; ++m) f[ai][m] = E.rstab[ui * 256 + wr * 64 + fr + ai * HALF + m * 16];
;                     asm volatile("s_waitcnt lgkmcnt(0)" ::: "memory");
; #pragma unroll
;                     for (int ai = 0; ai < 2; ++ai)
; #pragma unroll
;                         for (int m = 0; m < 4; ++m) { const float ff = (t == 4) ? __builtin_amdgcn_rcpf(f[ai][m]) : f[ai][m];
; #pragma unroll
;                             for (int bj = 0; bj < 2; ++bj)
; #pragma unroll
;                                 for (int n = 0; n < 2; ++n) acc[ai][bj][m][n] = acc[ai][bj][m][n] * ff; }
;                 }
;             }
;             const bool last = (t == nt - 2);
;             const char* a1 = cA + (size_t)(t + 1) * kstep;
;             const char* a2 = last ? nA : cA + (size_t)(t + 2) * kstep; const char* b2 = last ? nB : cB + (size_t)(t + 2) * kstep;
;             const char* a3 = a2 + kstep; const char* b3 = b2 + kstep;
;             PG8_LDB(B0, 0, 0); PG8_SCHED; PG8_LDA(At, 0, 0); PG8_STAGE(PG8_SA(1, 1), a1 + hstep, voffA);
;             PG8_WAIT_L(8); PG8_BAR; PG8_WAIT_L(0); PG8_MMA(0, 0, At, B0); PG8_BAR; PG8_SCHED;
;             PG8_LDB(B1, 0, 1); PG8_STAGE(PG8_SB(0, 0), b2, voffB);
;             PG8_BAR; PG8_WAIT_L(0); PG8_MMA(0, 1, At, B1); PG8_BAR;
;             PG8_LDA(At, 0, 1); PG8_STAGE(PG8_SA(0, 0), a2, voffA);
;             PG8_BAR; PG8_WAIT_L(0); PG8_MMA(1, 0, At, B0); PG8_BAR; PG8_SCHED;
;             PG8_STAGE(PG8_SB(0, 1), b2 + hstep, voffB);
;             PG8_WAIT_V(6); PG8_BAR; PG8_MMA(1, 1, At, B1); PG8_BAR;
;             PG8_LDB(B0, 1, 0); PG8_SCHED; PG8_LDA(At, 1, 0); PG8_STAGE(PG8_SA(0, 1), a2 + hstep, voffA);
;             PG8_WAIT_L(8); PG8_BAR; PG8_WAIT_L(0); PG8_MMA(0, 0, At, B0); PG8_BAR; PG8_SCHED;
;             PG8_LDB(B1, 1, 1); PG8_STAGE(PG8_SB(1, 0), b3, voffB);
;             PG8_BAR; PG8_WAIT_L(0); PG8_MMA(0, 1, At, B1); PG8_BAR;
;             PG8_LDA(At, 1, 1); PG8_STAGE(PG8_SA(1, 0), a3, voffA);
	s_waitcnt lgkmcnt(0)
	s_setprio 1
	s_waitcnt lgkmcnt(0)
	v_mfma_f32_16x16x32_bf16 v[118:121], v[216:219], v[168:171], v[118:121]
	v_mfma_f32_16x16x32_bf16 v[110:113], v[230:233], v[168:171], v[110:113]
	v_mfma_f32_16x16x32_bf16 v[102:105], v[216:219], v[176:179], v[102:105]
	v_mfma_f32_16x16x32_bf16 v[94:97], v[230:233], v[176:179], v[94:97]
	s_mov_b32 m0, s58
	s_nop 0
	global_load_lds_dwordx4 v0, s[6:7]
	v_mfma_f32_16x16x32_bf16 v[86:89], v[216:219], v[184:187], v[86:89]
	v_mfma_f32_16x16x32_bf16 v[78:81], v[230:233], v[184:187], v[78:81]
	v_mfma_f32_16x16x32_bf16 v[70:73], v[216:219], v[208:211], v[70:73]
	v_mfma_f32_16x16x32_bf16 v[66:69], v[230:233], v[208:211], v[66:69]
	v_mfma_f32_16x16x32_bf16 v[118:121], v[226:229], v[172:175], v[118:121]
	v_mfma_f32_16x16x32_bf16 v[110:113], v[234:237], v[172:175], v[110:113]
	s_add_i32 m0, s58, 0x2000
	s_nop 0
	global_load_lds_dwordx4 v130, s[6:7]
	v_mfma_f32_16x16x32_bf16 v[102:105], v[226:229], v[180:183], v[102:105]
	v_mfma_f32_16x16x32_bf16 v[94:97], v[234:237], v[180:183], v[94:97]
	v_mfma_f32_16x16x32_bf16 v[86:89], v[226:229], v[204:207], v[86:89]
	v_mfma_f32_16x16x32_bf16 v[78:81], v[234:237], v[204:207], v[78:81]
	v_mfma_f32_16x16x32_bf16 v[70:73], v[226:229], v[212:215], v[70:73]
	v_mfma_f32_16x16x32_bf16 v[66:69], v[234:237], v[212:215], v[66:69]
	s_setprio 0
	s_add_u32 vcc_lo, s36, 0x80
	s_addc_u32 vcc_hi, s37, 0
	s_barrier
	ds_read_b128 v[168:171], v152 offset:16384
	ds_read_b128 v[172:175], v152 offset:17408
	ds_read_b128 v[176:179], v152 offset:18432
	ds_read_b128 v[180:183], v152 offset:19456
	ds_read_b128 v[184:187], v152 offset:20480
	ds_read_b128 v[204:207], v152 offset:21504
	ds_read_b128 v[208:211], v152 offset:22528
	ds_read_b128 v[212:215], v152 offset:23552
	s_barrier
	s_waitcnt lgkmcnt(0)
	s_setprio 1
	s_waitcnt lgkmcnt(0)
	v_mfma_f32_16x16x32_bf16 v[62:65], v[140:143], v[168:171], v[62:65]
	v_mfma_f32_16x16x32_bf16 v[58:61], v[154:157], v[168:171], v[58:61]
	v_mfma_f32_16x16x32_bf16 v[50:53], v[140:143], v[176:179], v[50:53]
	v_mfma_f32_16x16x32_bf16 v[42:45], v[154:157], v[176:179], v[42:45]
	s_mov_b32 m0, s47
	s_nop 0
	global_load_lds_dwordx4 v134, s[36:37]
	v_mfma_f32_16x16x32_bf16 v[34:37], v[140:143], v[184:187], v[34:37]
	v_mfma_f32_16x16x32_bf16 v[26:29], v[154:157], v[184:187], v[26:29]
	v_mfma_f32_16x16x32_bf16 v[18:21], v[140:143], v[208:211], v[18:21]
	v_mfma_f32_16x16x32_bf16 v[10:13], v[154:157], v[208:211], v[10:13]
	v_mfma_f32_16x16x32_bf16 v[62:65], v[144:147], v[172:175], v[62:65]
	v_mfma_f32_16x16x32_bf16 v[58:61], v[158:161], v[172:175], v[58:61]
	s_mov_b32 m0, s48
	s_nop 0
	global_load_lds_dwordx4 v132, s[36:37]
	v_mfma_f32_16x16x32_bf16 v[50:53], v[144:147], v[180:183], v[50:53]
	v_mfma_f32_16x16x32_bf16 v[42:45], v[158:161], v[180:183], v[42:45]
	v_mfma_f32_16x16x32_bf16 v[34:37], v[144:147], v[204:207], v[34:37]
	v_mfma_f32_16x16x32_bf16 v[26:29], v[158:161], v[204:207], v[26:29]
	v_mfma_f32_16x16x32_bf16 v[18:21], v[144:147], v[212:215], v[18:21]
	v_mfma_f32_16x16x32_bf16 v[10:13], v[158:161], v[212:215], v[10:13]
	s_setprio 0
	s_barrier
	s_add_u32 s60, s6, 0x40000
	s_addc_u32 s61, s7, 0
	s_add_i32 s58, s70, s44
	s_waitcnt vmcnt(4)
	s_barrier
	s_setprio 1
	v_mfma_f32_16x16x32_bf16 v[54:57], v[216:219], v[168:171], v[54:57]
	v_mfma_f32_16x16x32_bf16 v[46:49], v[230:233], v[168:171], v[46:49]
	v_mfma_f32_16x16x32_bf16 v[38:41], v[216:219], v[176:179], v[38:41]
	v_mfma_f32_16x16x32_bf16 v[30:33], v[230:233], v[176:179], v[30:33]
	s_mov_b32 m0, s58
	s_nop 0
	global_load_lds_dwordx4 v0, s[60:61]
	v_mfma_f32_16x16x32_bf16 v[22:25], v[216:219], v[184:187], v[22:25]
	v_mfma_f32_16x16x32_bf16 v[14:17], v[230:233], v[184:187], v[14:17]
	v_mfma_f32_16x16x32_bf16 v[6:9], v[216:219], v[208:211], v[6:9]
	v_mfma_f32_16x16x32_bf16 v[2:5], v[230:233], v[208:211], v[2:5]
	v_mfma_f32_16x16x32_bf16 v[54:57], v[226:229], v[172:175], v[54:57]
	v_mfma_f32_16x16x32_bf16 v[46:49], v[234:237], v[172:175], v[46:49]
	s_add_i32 m0, s58, 0x2000
	s_nop 0
	global_load_lds_dwordx4 v130, s[60:61]
	v_mfma_f32_16x16x32_bf16 v[38:41], v[226:229], v[180:183], v[38:41]
	v_mfma_f32_16x16x32_bf16 v[30:33], v[234:237], v[180:183], v[30:33]
	v_mfma_f32_16x16x32_bf16 v[22:25], v[226:229], v[204:207], v[22:25]
	v_mfma_f32_16x16x32_bf16 v[14:17], v[234:237], v[204:207], v[14:17]
	v_mfma_f32_16x16x32_bf16 v[6:9], v[226:229], v[212:215], v[6:9]
	v_mfma_f32_16x16x32_bf16 v[2:5], v[234:237], v[212:215], v[2:5]
	s_setprio 0
	s_add_i32 s58, 0, 0x18000
	v_add_u32_e32 v153, s58, v149
	s_barrier
	ds_read_b128 v[140:143], v153
	ds_read_b128 v[144:147], v153 offset:1024
	ds_read_b128 v[154:157], v153 offset:2048
	ds_read_b128 v[158:161], v153 offset:3072
	s_add_u32 s36, s36, 0x40000
	s_addc_u32 s37, s37, 0
	ds_read_b128 v[168:171], v152 offset:32768
	ds_read_b128 v[172:175], v152 offset:33792
	ds_read_b128 v[176:179], v152 offset:34816
	ds_read_b128 v[180:183], v152 offset:35840
	ds_read_b128 v[184:187], v152 offset:36864
	ds_read_b128 v[204:207], v152 offset:37888
	ds_read_b128 v[208:211], v152 offset:38912
	ds_read_b128 v[212:215], v152 offset:39936
	s_waitcnt lgkmcnt(8)
	s_barrier
	s_waitcnt lgkmcnt(0)
	s_setprio 1
	s_waitcnt lgkmcnt(0)
	v_mfma_f32_16x16x32_bf16 v[126:129], v[140:143], v[168:171], v[126:129]
	v_mfma_f32_16x16x32_bf16 v[122:125], v[154:157], v[168:171], v[122:125]
	s_cmp_eq_u32 s87, 0
	s_cbranch_scc1 .LdsA_skip_1
	global_store_dwordx4 v166, v[188:191], s[4:5] offset:256
	s_nop 1
	v_add_u32_e32 v166, 0xe000, v166
; template <class Epi>
; __device__ __forceinline__ void gemm_phase(LAS unsigned char* lds, const Gemm g, const StaticOrder& S, const Epi& E) {
;     ...
;         for (int t = 0; t < nt; t += 2) {
;             if constexpr (Epi::MIDSCALE) {
;                 if (t == 4 || t == 8) {
;                     float f[2][4];
; #pragma unroll
;                     for (int ai = 0; ai < 2; ++ai)
; #pragma unroll
;                         for (int m = 0; m < 4; ++m) f[ai][m] = E.rstab[ui * 256 + wr * 64 + fr + ai * HALF + m * 16];
;                     asm volatile("s_waitcnt lgkmcnt(0)" ::: "memory");
; #pragma unroll
;                     for (int ai = 0; ai < 2; ++ai)
; #pragma unroll
;                         for (int m = 0; m < 4; ++m) { const float ff = (t == 4) ? __builtin_amdgcn_rcpf(f[ai][m]) : f[ai][m];
; #pragma unroll
;                             for (int bj = 0; bj < 2; ++bj)
; #pragma unroll
;                                 for (int n = 0; n < 2; ++n) acc[ai][bj][m][n] = acc[ai][bj][m][n] * ff; }
;                 }
;             }
;             const bool last = (t == nt - 2);
;             const char* a1 = cA + (size_t)(t + 1) * kstep;
;             const char* a2 = last ? nA : cA + (size_t)(t + 2) * kstep; const char* b2 = last ? nB : cB + (size_t)(t + 2) * kstep;
;             const char* a3 = a2 + kstep; const char* b3 = b2 + kstep;
;             PG8_LDB(B0, 0, 0); PG8_SCHED; PG8_LDA(At, 0, 0); PG8_STAGE(PG8_SA(1, 1), a1 + hstep, voffA);
;             PG8_WAIT_L(8); PG8_BAR; PG8_WAIT_L(0); PG8_MMA(0, 0, At, B0); PG8_BAR; PG8_SCHED;
;             PG8_LDB(B1, 0, 1); PG8_STAGE(PG8_SB(0, 0), b2, voffB);
;             PG8_BAR; PG8_WAIT_L(0); PG8_MMA(0, 1, At, B1); PG8_BAR;
;             PG8_LDA(At, 0, 1); PG8_STAGE(PG8_SA(0, 0), a2, voffA);
;             PG8_BAR; PG8_WAIT_L(0); PG8_MMA(1, 0, At, B0); PG8_BAR; PG8_SCHED;
;             PG8_STAGE(PG8_SB(0, 1), b2 + hstep, voffB);
;             PG8_WAIT_V(6); PG8_BAR; PG8_MMA(1, 1, At, B1); PG8_BAR;
;             PG8_LDB(B0, 1, 0); PG8_SCHED; PG8_LDA(At, 1, 0); PG8_STAGE(PG8_SA(0, 1), a2 + hstep, voffA);
;             PG8_WAIT_L(8); PG8_BAR; PG8_WAIT_L(0); PG8_MMA(0, 0, At, B0); PG8_BAR; PG8_SCHED;
;             PG8_LDB(B1, 1, 1); PG8_STAGE(PG8_SB(1, 0), b3, voffB);
;             PG8_BAR; PG8_WAIT_L(0); PG8_MMA(0, 1, At, B1); PG8_BAR;
;             PG8_LDA(At, 1, 1); PG8_STAGE(PG8_SA(1, 0), a3, voffA);
.LdsA_skip_1:
	v_mfma_f32_16x16x32_bf16 v[114:117], v[140:143], v[176:179], v[114:117]
	v_mfma_f32_16x16x32_bf16 v[106:109], v[154:157], v[176:179], v[106:109]
	s_mov_b32 m0, s49
	s_nop 0
	global_load_lds_dwordx4 v134, s[36:37]
	v_mfma_f32_16x16x32_bf16 v[98:101], v[140:143], v[184:187], v[98:101]
	v_mfma_f32_16x16x32_bf16 v[90:93], v[154:157], v[184:187], v[90:93]
	v_mfma_f32_16x16x32_bf16 v[82:85], v[140:143], v[208:211], v[82:85]
	v_mfma_f32_16x16x32_bf16 v[74:77], v[154:157], v[208:211], v[74:77]
	v_mfma_f32_16x16x32_bf16 v[126:129], v[144:147], v[172:175], v[126:129]
	v_mfma_f32_16x16x32_bf16 v[122:125], v[158:161], v[172:175], v[122:125]
	s_mov_b32 m0, s54
	s_nop 0
	global_load_lds_dwordx4 v132, s[36:37]
	v_mfma_f32_16x16x32_bf16 v[114:117], v[144:147], v[180:183], v[114:117]
	v_mfma_f32_16x16x32_bf16 v[106:109], v[158:161], v[180:183], v[106:109]
	v_mfma_f32_16x16x32_bf16 v[98:101], v[144:147], v[204:207], v[98:101]
	v_mfma_f32_16x16x32_bf16 v[90:93], v[158:161], v[204:207], v[90:93]
	v_mfma_f32_16x16x32_bf16 v[82:85], v[144:147], v[212:215], v[82:85]
	v_mfma_f32_16x16x32_bf16 v[74:77], v[158:161], v[212:215], v[74:77]
	s_setprio 0
	s_barrier
	s_add_i32 s36, 0, 0x1c000
	s_add_i32 s37, s58, s44
	v_add_u32_e32 v153, s36, v149
	s_add_u32 s60, s6, 0x80
	s_addc_u32 s61, s7, 0
	ds_read_b128 v[216:219], v153
	ds_read_b128 v[226:229], v153 offset:1024
	ds_read_b128 v[230:233], v153 offset:2048
	ds_read_b128 v[234:237], v153 offset:3072
	s_barrier
	s_waitcnt lgkmcnt(0)
	s_setprio 1
	s_waitcnt lgkmcnt(0)
	v_mfma_f32_16x16x32_bf16 v[118:121], v[216:219], v[168:171], v[118:121]
	v_mfma_f32_16x16x32_bf16 v[110:113], v[230:233], v[168:171], v[110:113]
	v_mfma_f32_16x16x32_bf16 v[102:105], v[216:219], v[176:179], v[102:105]
	v_mfma_f32_16x16x32_bf16 v[94:97], v[230:233], v[176:179], v[94:97]
	s_mov_b32 m0, s37
	s_nop 0
	global_load_lds_dwordx4 v0, s[60:61]
	v_mfma_f32_16x16x32_bf16 v[86:89], v[216:219], v[184:187], v[86:89]
	v_mfma_f32_16x16x32_bf16 v[78:81], v[230:233], v[184:187], v[78:81]
	v_mfma_f32_16x16x32_bf16 v[70:73], v[216:219], v[208:211], v[70:73]
	v_mfma_f32_16x16x32_bf16 v[66:69], v[230:233], v[208:211], v[66:69]
	v_mfma_f32_16x16x32_bf16 v[118:121], v[226:229], v[172:175], v[118:121]
	v_mfma_f32_16x16x32_bf16 v[110:113], v[234:237], v[172:175], v[110:113]
	s_add_i32 m0, s37, 0x2000
	s_nop 0
	global_load_lds_dwordx4 v130, s[60:61]
	v_mfma_f32_16x16x32_bf16 v[102:105], v[226:229], v[180:183], v[102:105]
	v_mfma_f32_16x16x32_bf16 v[94:97], v[234:237], v[180:183], v[94:97]
	v_mfma_f32_16x16x32_bf16 v[86:89], v[226:229], v[204:207], v[86:89]
	v_mfma_f32_16x16x32_bf16 v[78:81], v[234:237], v[204:207], v[78:81]
	v_mfma_f32_16x16x32_bf16 v[70:73], v[226:229], v[212:215], v[70:73]
	v_mfma_f32_16x16x32_bf16 v[66:69], v[234:237], v[212:215], v[66:69]
	s_setprio 0
	s_barrier
	ds_read_b128 v[168:171], v152 offset:49152
	ds_read_b128 v[172:175], v152 offset:50176
	ds_read_b128 v[176:179], v152 offset:51200
	ds_read_b128 v[180:183], v152 offset:52224
	ds_read_b128 v[184:187], v152 offset:53248
	ds_read_b128 v[204:207], v152 offset:54272
	ds_read_b128 v[208:211], v152 offset:55296
	ds_read_b128 v[212:215], v152 offset:56320
	s_barrier
	s_waitcnt lgkmcnt(0)
	s_setprio 1
	s_waitcnt lgkmcnt(0)
	v_mfma_f32_16x16x32_bf16 v[62:65], v[140:143], v[168:171], v[62:65]
	v_mfma_f32_16x16x32_bf16 v[58:61], v[154:157], v[168:171], v[58:61]
	v_mfma_f32_16x16x32_bf16 v[50:53], v[140:143], v[176:179], v[50:53]
	v_mfma_f32_16x16x32_bf16 v[42:45], v[154:157], v[176:179], v[42:45]
	s_mov_b32 m0, s55
	s_nop 0
	global_load_lds_dwordx4 v134, vcc
	v_mfma_f32_16x16x32_bf16 v[34:37], v[140:143], v[184:187], v[34:37]
	v_mfma_f32_16x16x32_bf16 v[26:29], v[154:157], v[184:187], v[26:29]
	v_mfma_f32_16x16x32_bf16 v[18:21], v[140:143], v[208:211], v[18:21]
	v_mfma_f32_16x16x32_bf16 v[10:13], v[154:157], v[208:211], v[10:13]
	v_mfma_f32_16x16x32_bf16 v[62:65], v[144:147], v[172:175], v[62:65]
	v_mfma_f32_16x16x32_bf16 v[58:61], v[158:161], v[172:175], v[58:61]
	s_mov_b32 m0, s83
	s_nop 0
	global_load_lds_dwordx4 v132, vcc
	v_mfma_f32_16x16x32_bf16 v[50:53], v[144:147], v[180:183], v[50:53]
	v_mfma_f32_16x16x32_bf16 v[42:45], v[158:161], v[180:183], v[42:45]
	v_mfma_f32_16x16x32_bf16 v[34:37], v[144:147], v[204:207], v[34:37]
	v_mfma_f32_16x16x32_bf16 v[26:29], v[158:161], v[204:207], v[26:29]
	v_mfma_f32_16x16x32_bf16 v[18:21], v[144:147], v[212:215], v[18:21]
	v_mfma_f32_16x16x32_bf16 v[10:13], v[158:161], v[212:215], v[10:13]
	s_setprio 0
	s_barrier
	s_add_u32 s6, s6, 0x40080
	s_addc_u32 s7, s7, 0
	s_add_i32 s36, s36, s44
	s_waitcnt vmcnt(4)
	s_barrier
	s_setprio 1
	v_mfma_f32_16x16x32_bf16 v[54:57], v[216:219], v[168:171], v[54:57]
	v_mfma_f32_16x16x32_bf16 v[46:49], v[230:233], v[168:171], v[46:49]
	v_mfma_f32_16x16x32_bf16 v[38:41], v[216:219], v[176:179], v[38:41]
	v_mfma_f32_16x16x32_bf16 v[30:33], v[230:233], v[176:179], v[30:33]
	s_mov_b32 m0, s36
	s_nop 0
	global_load_lds_dwordx4 v0, s[6:7]
	v_mfma_f32_16x16x32_bf16 v[22:25], v[216:219], v[184:187], v[22:25]
	v_mfma_f32_16x16x32_bf16 v[14:17], v[230:233], v[184:187], v[14:17]
	v_mfma_f32_16x16x32_bf16 v[6:9], v[216:219], v[208:211], v[6:9]
	v_mfma_f32_16x16x32_bf16 v[2:5], v[230:233], v[208:211], v[2:5]
	v_mfma_f32_16x16x32_bf16 v[54:57], v[226:229], v[172:175], v[54:57]
	v_mfma_f32_16x16x32_bf16 v[46:49], v[234:237], v[172:175], v[46:49]
	s_add_i32 m0, s36, 0x2000
	s_nop 0
	global_load_lds_dwordx4 v130, s[6:7]
	v_mfma_f32_16x16x32_bf16 v[38:41], v[226:229], v[180:183], v[38:41]
	v_mfma_f32_16x16x32_bf16 v[30:33], v[234:237], v[180:183], v[30:33]
	v_mfma_f32_16x16x32_bf16 v[22:25], v[226:229], v[204:207], v[22:25]
	v_mfma_f32_16x16x32_bf16 v[14:17], v[234:237], v[204:207], v[14:17]
	v_mfma_f32_16x16x32_bf16 v[6:9], v[226:229], v[212:215], v[6:9]
	v_mfma_f32_16x16x32_bf16 v[2:5], v[234:237], v[212:215], v[2:5]
	s_setprio 0
	s_add_i32 s91, s91, 2
	s_add_u32 s24, s24, 0x100
	s_addc_u32 s25, s25, 0
	s_add_u32 s89, s89, 0x100
	s_addc_u32 s90, s90, 0
	s_cmp_gt_u32 s91, 13
	s_barrier
; template <class Epi>
; __device__ __forceinline__ void gemm_phase(LAS unsigned char* lds, const Gemm g, const StaticOrder& S, const Epi& E) {
;     ...
;         for (int t = 0; t < nt; t += 2) {
;             if constexpr (Epi::MIDSCALE) {
;                 if (t == 4 || t == 8) {
;                     float f[2][4];
; #pragma unroll
;                     for (int ai = 0; ai < 2; ++ai)
; #pragma unroll
;                         for (int m = 0; m < 4; ++m) f[ai][m] = E.rstab[ui * 256 + wr * 64 + fr + ai * HALF + m * 16];
;                     asm volatile("s_waitcnt lgkmcnt(0)" ::: "memory");
; #pragma unroll
;                     for (int ai = 0; ai < 2; ++ai)
; #pragma unroll
;                         for (int m = 0; m < 4; ++m) { const float ff = (t == 4) ? __builtin_amdgcn_rcpf(f[ai][m]) : f[ai][m];
; #pragma unroll
;                             for (int bj = 0; bj < 2; ++bj)
; #pragma unroll
;                                 for (int n = 0; n < 2; ++n) acc[ai][bj][m][n] = acc[ai][bj][m][n] * ff; }
;                 }
;             }
;             const bool last = (t == nt - 2);
;             const char* a1 = cA + (size_t)(t + 1) * kstep;
;             const char* a2 = last ? nA : cA + (size_t)(t + 2) * kstep; const char* b2 = last ? nB : cB + (size_t)(t + 2) * kstep;
;             const char* a3 = a2 + kstep; const char* b3 = b2 + kstep;
;             PG8_LDB(B0, 0, 0); PG8_SCHED; PG8_LDA(At, 0, 0); PG8_STAGE(PG8_SA(1, 1), a1 + hstep, voffA);
;             PG8_WAIT_L(8); PG8_BAR; PG8_WAIT_L(0); PG8_MMA(0, 0, At, B0); PG8_BAR; PG8_SCHED;
;             PG8_LDB(B1, 0, 1); PG8_STAGE(PG8_SB(0, 0), b2, voffB);
;             PG8_BAR; PG8_WAIT_L(0); PG8_MMA(0, 1, At, B1); PG8_BAR;
;             PG8_LDA(At, 0, 1); PG8_STAGE(PG8_SA(0, 0), a2, voffA);
;             PG8_BAR; PG8_WAIT_L(0); PG8_MMA(1, 0, At, B0); PG8_BAR; PG8_SCHED;
;             PG8_STAGE(PG8_SB(0, 1), b2 + hstep, voffB);
;             PG8_WAIT_V(6); PG8_BAR; PG8_MMA(1, 1, At, B1); PG8_BAR;
;             PG8_LDB(B0, 1, 0); PG8_SCHED; PG8_LDA(At, 1, 0); PG8_STAGE(PG8_SA(0, 1), a2 + hstep, voffA);
;             PG8_WAIT_L(8); PG8_BAR; PG8_WAIT_L(0); PG8_MMA(0, 0, At, B0); PG8_BAR; PG8_SCHED;
;             PG8_LDB(B1, 1, 1); PG8_STAGE(PG8_SB(1, 0), b3, voffB);
;             PG8_BAR; PG8_WAIT_L(0); PG8_MMA(0, 1, At, B1); PG8_BAR;
;             PG8_LDA(At, 1, 1); PG8_STAGE(PG8_SA(1, 0), a3, voffA);
	s_add_u32 s6, s24, 0xfffc0080
	s_addc_u32 s7, s25, -1
	s_add_i32 s58, 0, 0x10000
	v_add_u32_e32 v153, s58, v149
	ds_read_b128 v[140:143], v153
	ds_read_b128 v[144:147], v153 offset:1024
	ds_read_b128 v[154:157], v153 offset:2048
	ds_read_b128 v[158:161], v153 offset:3072
	s_cmp_eq_u32 s91, 12
	s_cselect_b32 s37, s11, s7
	s_cselect_b32 s36, s71, s6
	s_cselect_b32 s7, s9, s90
	s_cselect_b32 s6, s88, s89
	ds_read_b128 v[168:171], v152
	ds_read_b128 v[172:175], v152 offset:1024
	ds_read_b128 v[176:179], v152 offset:2048
	ds_read_b128 v[180:183], v152 offset:3072
	ds_read_b128 v[184:187], v152 offset:4096
	ds_read_b128 v[204:207], v152 offset:5120
	ds_read_b128 v[208:211], v152 offset:6144
	ds_read_b128 v[212:215], v152 offset:7168
	s_waitcnt lgkmcnt(8)
	s_barrier
	s_waitcnt lgkmcnt(0)
	s_setprio 1
	s_waitcnt lgkmcnt(0)
	v_mfma_f32_16x16x32_bf16 v[126:129], v[140:143], v[168:171], v[126:129]
	v_mfma_f32_16x16x32_bf16 v[122:125], v[154:157], v[168:171], v[122:125]
	v_mfma_f32_16x16x32_bf16 v[114:117], v[140:143], v[176:179], v[114:117]
	v_mfma_f32_16x16x32_bf16 v[106:109], v[154:157], v[176:179], v[106:109]
	s_add_i32 m0, s47, 0xc000
	s_nop 0
	global_load_lds_dwordx4 v136, s[24:25]
	v_mfma_f32_16x16x32_bf16 v[98:101], v[140:143], v[184:187], v[98:101]
	v_mfma_f32_16x16x32_bf16 v[90:93], v[154:157], v[184:187], v[90:93]
	v_mfma_f32_16x16x32_bf16 v[82:85], v[140:143], v[208:211], v[82:85]
	v_mfma_f32_16x16x32_bf16 v[74:77], v[154:157], v[208:211], v[74:77]
	v_mfma_f32_16x16x32_bf16 v[126:129], v[144:147], v[172:175], v[126:129]
	v_mfma_f32_16x16x32_bf16 v[122:125], v[158:161], v[172:175], v[122:125]
	s_add_i32 m0, s47, 0xe000
	s_nop 0
	global_load_lds_dwordx4 v138, s[24:25]
	v_mfma_f32_16x16x32_bf16 v[114:117], v[144:147], v[180:183], v[114:117]
	v_mfma_f32_16x16x32_bf16 v[106:109], v[158:161], v[180:183], v[106:109]
	v_mfma_f32_16x16x32_bf16 v[98:101], v[144:147], v[204:207], v[98:101]
	v_mfma_f32_16x16x32_bf16 v[90:93], v[158:161], v[204:207], v[90:93]
	v_mfma_f32_16x16x32_bf16 v[82:85], v[144:147], v[212:215], v[82:85]
	v_mfma_f32_16x16x32_bf16 v[74:77], v[158:161], v[212:215], v[74:77]
	s_setprio 0
	s_barrier
	s_add_i32 s70, 0, 0x14000
	s_add_i32 s58, s58, s44
	v_add_u32_e32 v153, s70, v149
	ds_read_b128 v[216:219], v153
	ds_read_b128 v[226:229], v153 offset:1024
	ds_read_b128 v[230:233], v153 offset:2048
	ds_read_b128 v[234:237], v153 offset:3072
	s_barrier
	s_waitcnt lgkmcnt(0)
	s_setprio 1
	s_waitcnt lgkmcnt(0)
	v_mfma_f32_16x16x32_bf16 v[118:121], v[216:219], v[168:171], v[118:121]
	v_mfma_f32_16x16x32_bf16 v[110:113], v[230:233], v[168:171], v[110:113]
	v_mfma_f32_16x16x32_bf16 v[102:105], v[216:219], v[176:179], v[102:105]
	v_mfma_f32_16x16x32_bf16 v[94:97], v[230:233], v[176:179], v[94:97]
	s_mov_b32 m0, s58
	s_nop 0
	global_load_lds_dwordx4 v0, s[6:7]
	v_mfma_f32_16x16x32_bf16 v[86:89], v[216:219], v[184:187], v[86:89]
	v_mfma_f32_16x16x32_bf16 v[78:81], v[230:233], v[184:187], v[78:81]
	v_mfma_f32_16x16x32_bf16 v[70:73], v[216:219], v[208:211], v[70:73]
	v_mfma_f32_16x16x32_bf16 v[66:69], v[230:233], v[208:211], v[66:69]
	v_mfma_f32_16x16x32_bf16 v[118:121], v[226:229], v[172:175], v[118:121]
	v_mfma_f32_16x16x32_bf16 v[110:113], v[234:237], v[172:175], v[110:113]
	s_add_i32 m0, s58, 0x2000
	s_nop 0
	global_load_lds_dwordx4 v130, s[6:7]
	v_mfma_f32_16x16x32_bf16 v[102:105], v[226:229], v[180:183], v[102:105]
	v_mfma_f32_16x16x32_bf16 v[94:97], v[234:237], v[180:183], v[94:97]
	v_mfma_f32_16x16x32_bf16 v[86:89], v[226:229], v[204:207], v[86:89]
	v_mfma_f32_16x16x32_bf16 v[78:81], v[234:237], v[204:207], v[78:81]
	v_mfma_f32_16x16x32_bf16 v[70:73], v[226:229], v[212:215], v[70:73]
	v_mfma_f32_16x16x32_bf16 v[66:69], v[234:237], v[212:215], v[66:69]
	s_setprio 0
	s_add_u32 vcc_lo, s36, 0x80
	s_addc_u32 vcc_hi, s37, 0
	s_barrier
	ds_read_b128 v[168:171], v152 offset:16384
	ds_read_b128 v[172:175], v152 offset:17408
	ds_read_b128 v[176:179], v152 offset:18432
	ds_read_b128 v[180:183], v152 offset:19456
	ds_read_b128 v[184:187], v152 offset:20480
	ds_read_b128 v[204:207], v152 offset:21504
	ds_read_b128 v[208:211], v152 offset:22528
	ds_read_b128 v[212:215], v152 offset:23552
	s_barrier
	s_waitcnt lgkmcnt(0)
	s_setprio 1
	s_waitcnt lgkmcnt(0)
	v_mfma_f32_16x16x32_bf16 v[62:65], v[140:143], v[168:171], v[62:65]
	v_mfma_f32_16x16x32_bf16 v[58:61], v[154:157], v[168:171], v[58:61]
	v_mfma_f32_16x16x32_bf16 v[50:53], v[140:143], v[176:179], v[50:53]
	v_mfma_f32_16x16x32_bf16 v[42:45], v[154:157], v[176:179], v[42:45]
	s_mov_b32 m0, s47
	s_nop 0
	global_load_lds_dwordx4 v134, s[36:37]
	v_mfma_f32_16x16x32_bf16 v[34:37], v[140:143], v[184:187], v[34:37]
	v_mfma_f32_16x16x32_bf16 v[26:29], v[154:157], v[184:187], v[26:29]
	v_mfma_f32_16x16x32_bf16 v[18:21], v[140:143], v[208:211], v[18:21]
	v_mfma_f32_16x16x32_bf16 v[10:13], v[154:157], v[208:211], v[10:13]
	v_mfma_f32_16x16x32_bf16 v[62:65], v[144:147], v[172:175], v[62:65]
	v_mfma_f32_16x16x32_bf16 v[58:61], v[158:161], v[172:175], v[58:61]
	s_mov_b32 m0, s48
	s_nop 0
	global_load_lds_dwordx4 v132, s[36:37]
	v_mfma_f32_16x16x32_bf16 v[50:53], v[144:147], v[180:183], v[50:53]
	v_mfma_f32_16x16x32_bf16 v[42:45], v[158:161], v[180:183], v[42:45]
	v_mfma_f32_16x16x32_bf16 v[34:37], v[144:147], v[204:207], v[34:37]
	v_mfma_f32_16x16x32_bf16 v[26:29], v[158:161], v[204:207], v[26:29]
	v_mfma_f32_16x16x32_bf16 v[18:21], v[144:147], v[212:215], v[18:21]
	v_mfma_f32_16x16x32_bf16 v[10:13], v[158:161], v[212:215], v[10:13]
	s_setprio 0
	s_barrier
	s_add_u32 s60, s6, 0x40000
	s_addc_u32 s61, s7, 0
	s_add_i32 s58, s70, s44
	s_waitcnt vmcnt(4)
	s_barrier
; template <class Epi>
; __device__ __forceinline__ void gemm_phase(LAS unsigned char* lds, const Gemm g, const StaticOrder& S, const Epi& E) {
;     ...
;         for (int t = 0; t < nt; t += 2) {
;             if constexpr (Epi::MIDSCALE) {
;                 if (t == 4 || t == 8) {
;                     float f[2][4];
; #pragma unroll
;                     for (int ai = 0; ai < 2; ++ai)
; #pragma unroll
;                         for (int m = 0; m < 4; ++m) f[ai][m] = E.rstab[ui * 256 + wr * 64 + fr + ai * HALF + m * 16];
;                     asm volatile("s_waitcnt lgkmcnt(0)" ::: "memory");
; #pragma unroll
;                     for (int ai = 0; ai < 2; ++ai)
; #pragma unroll
;                         for (int m = 0; m < 4; ++m) { const float ff = (t == 4) ? __builtin_amdgcn_rcpf(f[ai][m]) : f[ai][m];
; #pragma unroll
;                             for (int bj = 0; bj < 2; ++bj)
; #pragma unroll
;                                 for (int n = 0; n < 2; ++n) acc[ai][bj][m][n] = acc[ai][bj][m][n] * ff; }
;                 }
;             }
;             const bool last = (t == nt - 2);
;             const char* a1 = cA + (size_t)(t + 1) * kstep;
;             const char* a2 = last ? nA : cA + (size_t)(t + 2) * kstep; const char* b2 = last ? nB : cB + (size_t)(t + 2) * kstep;
;             const char* a3 = a2 + kstep; const char* b3 = b2 + kstep;
;             PG8_LDB(B0, 0, 0); PG8_SCHED; PG8_LDA(At, 0, 0); PG8_STAGE(PG8_SA(1, 1), a1 + hstep, voffA);
;             PG8_WAIT_L(8); PG8_BAR; PG8_WAIT_L(0); PG8_MMA(0, 0, At, B0); PG8_BAR; PG8_SCHED;
;             PG8_LDB(B1, 0, 1); PG8_STAGE(PG8_SB(0, 0), b2, voffB);
;             PG8_BAR; PG8_WAIT_L(0); PG8_MMA(0, 1, At, B1); PG8_BAR;
;             PG8_LDA(At, 0, 1); PG8_STAGE(PG8_SA(0, 0), a2, voffA);
;             PG8_BAR; PG8_WAIT_L(0); PG8_MMA(1, 0, At, B0); PG8_BAR; PG8_SCHED;
;             PG8_STAGE(PG8_SB(0, 1), b2 + hstep, voffB);
;             PG8_WAIT_V(6); PG8_BAR; PG8_MMA(1, 1, At, B1); PG8_BAR;
;             PG8_LDB(B0, 1, 0); PG8_SCHED; PG8_LDA(At, 1, 0); PG8_STAGE(PG8_SA(0, 1), a2 + hstep, voffA);
;             PG8_WAIT_L(8); PG8_BAR; PG8_WAIT_L(0); PG8_MMA(0, 0, At, B0); PG8_BAR; PG8_SCHED;
;             PG8_LDB(B1, 1, 1); PG8_STAGE(PG8_SB(1, 0), b3, voffB);
;             PG8_BAR; PG8_WAIT_L(0); PG8_MMA(0, 1, At, B1); PG8_BAR;
;             PG8_LDA(At, 1, 1); PG8_STAGE(PG8_SA(1, 0), a3, voffA);
	s_setprio 1
	v_mfma_f32_16x16x32_bf16 v[54:57], v[216:219], v[168:171], v[54:57]
	v_mfma_f32_16x16x32_bf16 v[46:49], v[230:233], v[168:171], v[46:49]
	v_mfma_f32_16x16x32_bf16 v[38:41], v[216:219], v[176:179], v[38:41]
	v_mfma_f32_16x16x32_bf16 v[30:33], v[230:233], v[176:179], v[30:33]
	s_mov_b32 m0, s58
	s_nop 0
	global_load_lds_dwordx4 v0, s[60:61]
	v_mfma_f32_16x16x32_bf16 v[22:25], v[216:219], v[184:187], v[22:25]
	v_mfma_f32_16x16x32_bf16 v[14:17], v[230:233], v[184:187], v[14:17]
	v_mfma_f32_16x16x32_bf16 v[6:9], v[216:219], v[208:211], v[6:9]
	v_mfma_f32_16x16x32_bf16 v[2:5], v[230:233], v[208:211], v[2:5]
	v_mfma_f32_16x16x32_bf16 v[54:57], v[226:229], v[172:175], v[54:57]
	v_mfma_f32_16x16x32_bf16 v[46:49], v[234:237], v[172:175], v[46:49]
	s_add_i32 m0, s58, 0x2000
	s_nop 0
	global_load_lds_dwordx4 v130, s[60:61]
	v_mfma_f32_16x16x32_bf16 v[38:41], v[226:229], v[180:183], v[38:41]
	v_mfma_f32_16x16x32_bf16 v[30:33], v[234:237], v[180:183], v[30:33]
	v_mfma_f32_16x16x32_bf16 v[22:25], v[226:229], v[204:207], v[22:25]
	v_mfma_f32_16x16x32_bf16 v[14:17], v[234:237], v[204:207], v[14:17]
	v_mfma_f32_16x16x32_bf16 v[6:9], v[226:229], v[212:215], v[6:9]
	v_mfma_f32_16x16x32_bf16 v[2:5], v[234:237], v[212:215], v[2:5]
	s_setprio 0
	s_add_i32 s58, 0, 0x18000
	v_add_u32_e32 v153, s58, v149
	s_barrier
	ds_read_b128 v[140:143], v153
	ds_read_b128 v[144:147], v153 offset:1024
	ds_read_b128 v[154:157], v153 offset:2048
	ds_read_b128 v[158:161], v153 offset:3072
	s_add_u32 s36, s36, 0x40000
	s_addc_u32 s37, s37, 0
	ds_read_b128 v[168:171], v152 offset:32768
	ds_read_b128 v[172:175], v152 offset:33792
	ds_read_b128 v[176:179], v152 offset:34816
	ds_read_b128 v[180:183], v152 offset:35840
	ds_read_b128 v[184:187], v152 offset:36864
	ds_read_b128 v[204:207], v152 offset:37888
	ds_read_b128 v[208:211], v152 offset:38912
	ds_read_b128 v[212:215], v152 offset:39936
	s_waitcnt lgkmcnt(8)
	s_barrier
	s_waitcnt lgkmcnt(0)
	s_setprio 1
	s_waitcnt lgkmcnt(0)
	v_mfma_f32_16x16x32_bf16 v[126:129], v[140:143], v[168:171], v[126:129]
	v_mfma_f32_16x16x32_bf16 v[122:125], v[154:157], v[168:171], v[122:125]
	s_cmp_eq_u32 s87, 0
	s_cbranch_scc1 .LdsA_skip_2
	global_store_dwordx4 v166, v[192:195], s[4:5]
.LdsA_skip_2:
	v_mfma_f32_16x16x32_bf16 v[114:117], v[140:143], v[176:179], v[114:117]
	v_mfma_f32_16x16x32_bf16 v[106:109], v[154:157], v[176:179], v[106:109]
	s_mov_b32 m0, s49
	s_nop 0
	global_load_lds_dwordx4 v134, s[36:37]
	v_mfma_f32_16x16x32_bf16 v[98:101], v[140:143], v[184:187], v[98:101]
	v_mfma_f32_16x16x32_bf16 v[90:93], v[154:157], v[184:187], v[90:93]
	v_mfma_f32_16x16x32_bf16 v[82:85], v[140:143], v[208:211], v[82:85]
	v_mfma_f32_16x16x32_bf16 v[74:77], v[154:157], v[208:211], v[74:77]
	v_mfma_f32_16x16x32_bf16 v[126:129], v[144:147], v[172:175], v[126:129]
	v_mfma_f32_16x16x32_bf16 v[122:125], v[158:161], v[172:175], v[122:125]
	s_mov_b32 m0, s54
	s_nop 0
	global_load_lds_dwordx4 v132, s[36:37]
	v_mfma_f32_16x16x32_bf16 v[114:117], v[144:147], v[180:183], v[114:117]
	v_mfma_f32_16x16x32_bf16 v[106:109], v[158:161], v[180:183], v[106:109]
	v_mfma_f32_16x16x32_bf16 v[98:101], v[144:147], v[204:207], v[98:101]
	v_mfma_f32_16x16x32_bf16 v[90:93], v[158:161], v[204:207], v[90:93]
	v_mfma_f32_16x16x32_bf16 v[82:85], v[144:147], v[212:215], v[82:85]
	v_mfma_f32_16x16x32_bf16 v[74:77], v[158:161], v[212:215], v[74:77]
	s_setprio 0
	s_barrier
	s_add_i32 s36, 0, 0x1c000
	s_add_i32 s37, s58, s44
	v_add_u32_e32 v153, s36, v149
	s_add_u32 s60, s6, 0x80
	s_addc_u32 s61, s7, 0
	ds_read_b128 v[216:219], v153
	ds_read_b128 v[226:229], v153 offset:1024
	ds_read_b128 v[230:233], v153 offset:2048
	ds_read_b128 v[234:237], v153 offset:3072
	s_barrier
	s_waitcnt lgkmcnt(0)
	s_setprio 1
	s_waitcnt lgkmcnt(0)
	v_mfma_f32_16x16x32_bf16 v[118:121], v[216:219], v[168:171], v[118:121]
	v_mfma_f32_16x16x32_bf16 v[110:113], v[230:233], v[168:171], v[110:113]
	v_mfma_f32_16x16x32_bf16 v[102:105], v[216:219], v[176:179], v[102:105]
	v_mfma_f32_16x16x32_bf16 v[94:97], v[230:233], v[176:179], v[94:97]
	s_mov_b32 m0, s37
	s_nop 0
	global_load_lds_dwordx4 v0, s[60:61]
	v_mfma_f32_16x16x32_bf16 v[86:89], v[216:219], v[184:187], v[86:89]
	v_mfma_f32_16x16x32_bf16 v[78:81], v[230:233], v[184:187], v[78:81]
	v_mfma_f32_16x16x32_bf16 v[70:73], v[216:219], v[208:211], v[70:73]
	v_mfma_f32_16x16x32_bf16 v[66:69], v[230:233], v[208:211], v[66:69]
	v_mfma_f32_16x16x32_bf16 v[118:121], v[226:229], v[172:175], v[118:121]
	v_mfma_f32_16x16x32_bf16 v[110:113], v[234:237], v[172:175], v[110:113]
	s_add_i32 m0, s37, 0x2000
	s_nop 0
	global_load_lds_dwordx4 v130, s[60:61]
	v_mfma_f32_16x16x32_bf16 v[102:105], v[226:229], v[180:183], v[102:105]
	v_mfma_f32_16x16x32_bf16 v[94:97], v[234:237], v[180:183], v[94:97]
	v_mfma_f32_16x16x32_bf16 v[86:89], v[226:229], v[204:207], v[86:89]
	v_mfma_f32_16x16x32_bf16 v[78:81], v[234:237], v[204:207], v[78:81]
	v_mfma_f32_16x16x32_bf16 v[70:73], v[226:229], v[212:215], v[70:73]
	v_mfma_f32_16x16x32_bf16 v[66:69], v[234:237], v[212:215], v[66:69]
	s_setprio 0
	s_barrier
	ds_read_b128 v[168:171], v152 offset:49152
	ds_read_b128 v[172:175], v152 offset:50176
	ds_read_b128 v[176:179], v152 offset:51200
	ds_read_b128 v[180:183], v152 offset:52224
	ds_read_b128 v[184:187], v152 offset:53248
	ds_read_b128 v[204:207], v152 offset:54272
	ds_read_b128 v[208:211], v152 offset:55296
	ds_read_b128 v[212:215], v152 offset:56320
	s_barrier
; #define PG8_STAGE(bufoff, gbase, voff) do { _Pragma("unroll") for (int _i = 0; _i < 2; ++_i) \
;         __builtin_amdgcn_global_load_lds((const unsigned*)((const char*)(gbase) + (voff)[_i]), (LAS unsigned*)(lds + (bufoff) + ldsw + _i * 8192), 16, 0, 0); } while (0)
; #define PG8_LDA(dst, b, h) do { _Pragma("unroll") for (int m = 0; m < 4; ++m) _Pragma("unroll") for (int k = 0; k < 2; ++k) dst[m][k] = *(const LAS bf16x8*)(lds + PG8_SA(b, h) + aoff + m * 2048 + k * 1024); } while (0)
; #define PG8_LDB(dst, b, h) do { _Pragma("unroll") for (int n = 0; n < 2; ++n) _Pragma("unroll") for (int k = 0; k < 2; ++k) dst[n][k] = *(const LAS bf16x8*)(lds + PG8_SB(b, h) + boff + n * 2048 + k * 1024); } while (0)
; #define PG8_WAIT_V(n) asm volatile("s_waitcnt vmcnt(" #n ")" ::: "memory")
; #define PG8_WAIT_L(n) asm volatile("s_waitcnt lgkmcnt(" #n ")" ::: "memory")
; #define PG8_BAR __builtin_amdgcn_s_barrier()
; #define PG8_SCHED __builtin_amdgcn_sched_barrier(0)
; template <class Epi>
; __device__ __forceinline__ void gemm_phase(LAS unsigned char* lds, const Gemm g, const StaticOrder& S, const Epi& E) {
;     ...
;             PG8_LDB(B0, 0, 0); PG8_SCHED; PG8_LDA(At, 0, 0); PG8_STAGE(PG8_SA(1, 1), a1 + hstep, voffA);
;             PG8_WAIT_L(8); PG8_BAR; PG8_WAIT_L(0); PG8_MMA(0, 0, At, B0); PG8_BAR; PG8_SCHED;
;             PG8_LDB(B1, 0, 1); PG8_STAGE(PG8_SB(0, 0), b2, voffB);
;             PG8_BAR; PG8_WAIT_L(0); PG8_MMA(0, 1, At, B1); PG8_BAR;
;             PG8_LDA(At, 0, 1); PG8_STAGE(PG8_SA(0, 0), a2, voffA);
;             PG8_BAR; PG8_WAIT_L(0); PG8_MMA(1, 0, At, B0); PG8_BAR; PG8_SCHED;
;             PG8_STAGE(PG8_SB(0, 1), b2 + hstep, voffB);
;             PG8_WAIT_V(6); PG8_BAR; PG8_MMA(1, 1, At, B1); PG8_BAR;
;             PG8_LDB(B0, 1, 0); PG8_SCHED; PG8_LDA(At, 1, 0); PG8_STAGE(PG8_SA(0, 1), a2 + hstep, voffA);
;             PG8_WAIT_L(8); PG8_BAR; PG8_WAIT_L(0); PG8_MMA(0, 0, At, B0); PG8_BAR; PG8_SCHED;
;             PG8_LDB(B1, 1, 1); PG8_STAGE(PG8_SB(1, 0), b3, voffB);
;             PG8_BAR; PG8_WAIT_L(0); PG8_MMA(0, 1, At, B1); PG8_BAR;
;             PG8_LDA(At, 1, 1); PG8_STAGE(PG8_SA(1, 0), a3, voffA);
;             PG8_BAR; PG8_WAIT_L(0); PG8_MMA(1, 0, At, B0); PG8_BAR; PG8_SCHED;
;             PG8_STAGE(PG8_SB(1, 1), b3 + hstep, voffB);
;             PG8_WAIT_V(6); PG8_BAR; PG8_MMA(1, 1, At, B1); PG8_BAR;
	s_waitcnt lgkmcnt(0)
	s_setprio 1
	s_waitcnt lgkmcnt(0)
	v_mfma_f32_16x16x32_bf16 v[62:65], v[140:143], v[168:171], v[62:65]
	v_mfma_f32_16x16x32_bf16 v[58:61], v[154:157], v[168:171], v[58:61]
	v_mfma_f32_16x16x32_bf16 v[50:53], v[140:143], v[176:179], v[50:53]
	v_mfma_f32_16x16x32_bf16 v[42:45], v[154:157], v[176:179], v[42:45]
	s_mov_b32 m0, s55
	s_nop 0
	global_load_lds_dwordx4 v134, vcc
	v_mfma_f32_16x16x32_bf16 v[34:37], v[140:143], v[184:187], v[34:37]
	v_mfma_f32_16x16x32_bf16 v[26:29], v[154:157], v[184:187], v[26:29]
	v_mfma_f32_16x16x32_bf16 v[18:21], v[140:143], v[208:211], v[18:21]
	v_mfma_f32_16x16x32_bf16 v[10:13], v[154:157], v[208:211], v[10:13]
	v_mfma_f32_16x16x32_bf16 v[62:65], v[144:147], v[172:175], v[62:65]
	v_mfma_f32_16x16x32_bf16 v[58:61], v[158:161], v[172:175], v[58:61]
	s_mov_b32 m0, s83
	s_nop 0
	global_load_lds_dwordx4 v132, vcc
	v_mfma_f32_16x16x32_bf16 v[50:53], v[144:147], v[180:183], v[50:53]
	v_mfma_f32_16x16x32_bf16 v[42:45], v[158:161], v[180:183], v[42:45]
	v_mfma_f32_16x16x32_bf16 v[34:37], v[144:147], v[204:207], v[34:37]
	v_mfma_f32_16x16x32_bf16 v[26:29], v[158:161], v[204:207], v[26:29]
	v_mfma_f32_16x16x32_bf16 v[18:21], v[144:147], v[212:215], v[18:21]
	v_mfma_f32_16x16x32_bf16 v[10:13], v[158:161], v[212:215], v[10:13]
	s_setprio 0
	s_barrier
	s_add_u32 s6, s6, 0x40080
	s_addc_u32 s7, s7, 0
	s_add_i32 s36, s36, s44
	s_waitcnt vmcnt(4)
	s_barrier
	s_setprio 1
	v_mfma_f32_16x16x32_bf16 v[54:57], v[216:219], v[168:171], v[54:57]
	v_mfma_f32_16x16x32_bf16 v[46:49], v[230:233], v[168:171], v[46:49]
	v_mfma_f32_16x16x32_bf16 v[38:41], v[216:219], v[176:179], v[38:41]
	v_mfma_f32_16x16x32_bf16 v[30:33], v[230:233], v[176:179], v[30:33]
	s_mov_b32 m0, s36
	s_nop 0
	global_load_lds_dwordx4 v0, s[6:7]
	v_mfma_f32_16x16x32_bf16 v[22:25], v[216:219], v[184:187], v[22:25]
	v_mfma_f32_16x16x32_bf16 v[14:17], v[230:233], v[184:187], v[14:17]
	v_mfma_f32_16x16x32_bf16 v[6:9], v[216:219], v[208:211], v[6:9]
	v_mfma_f32_16x16x32_bf16 v[2:5], v[230:233], v[208:211], v[2:5]
	v_mfma_f32_16x16x32_bf16 v[54:57], v[226:229], v[172:175], v[54:57]
	v_mfma_f32_16x16x32_bf16 v[46:49], v[234:237], v[172:175], v[46:49]
	s_add_i32 m0, s36, 0x2000
	s_nop 0
	global_load_lds_dwordx4 v130, s[6:7]
	v_mfma_f32_16x16x32_bf16 v[38:41], v[226:229], v[180:183], v[38:41]
	v_mfma_f32_16x16x32_bf16 v[30:33], v[234:237], v[180:183], v[30:33]
	v_mfma_f32_16x16x32_bf16 v[22:25], v[226:229], v[204:207], v[22:25]
	v_mfma_f32_16x16x32_bf16 v[14:17], v[234:237], v[204:207], v[14:17]
	v_mfma_f32_16x16x32_bf16 v[6:9], v[226:229], v[212:215], v[6:9]
	v_mfma_f32_16x16x32_bf16 v[2:5], v[234:237], v[212:215], v[2:5]
	s_setprio 0
	s_add_i32 s91, s91, 2
	s_add_u32 s24, s24, 0x100
	s_addc_u32 s25, s25, 0
	s_add_u32 s89, s89, 0x100
	s_addc_u32 s90, s90, 0
	s_cmp_gt_u32 s91, 13
	s_barrier
	s_add_u32 s6, s24, 0xfffc0080
	s_addc_u32 s7, s25, -1
	s_add_i32 s58, 0, 0x10000
	v_add_u32_e32 v153, s58, v149
	ds_read_b128 v[140:143], v153
	ds_read_b128 v[144:147], v153 offset:1024
	ds_read_b128 v[154:157], v153 offset:2048
	ds_read_b128 v[158:161], v153 offset:3072
	s_cmp_eq_u32 s91, 12
	s_cselect_b32 s37, s11, s7
	s_cselect_b32 s36, s71, s6
	s_cselect_b32 s7, s9, s90
	s_cselect_b32 s6, s88, s89
	ds_read_b128 v[168:171], v152
	ds_read_b128 v[172:175], v152 offset:1024
	ds_read_b128 v[176:179], v152 offset:2048
	ds_read_b128 v[180:183], v152 offset:3072
	ds_read_b128 v[184:187], v152 offset:4096
	ds_read_b128 v[204:207], v152 offset:5120
	ds_read_b128 v[208:211], v152 offset:6144
	ds_read_b128 v[212:215], v152 offset:7168
	s_waitcnt lgkmcnt(8)
	s_barrier
	s_waitcnt lgkmcnt(0)
	s_setprio 1
	s_waitcnt lgkmcnt(0)
	v_mfma_f32_16x16x32_bf16 v[126:129], v[140:143], v[168:171], v[126:129]
	v_mfma_f32_16x16x32_bf16 v[122:125], v[154:157], v[168:171], v[122:125]
	v_mfma_f32_16x16x32_bf16 v[114:117], v[140:143], v[176:179], v[114:117]
	v_mfma_f32_16x16x32_bf16 v[106:109], v[154:157], v[176:179], v[106:109]
	s_add_i32 m0, s47, 0xc000
	s_nop 0
	global_load_lds_dwordx4 v136, s[24:25]
	v_mfma_f32_16x16x32_bf16 v[98:101], v[140:143], v[184:187], v[98:101]
	v_mfma_f32_16x16x32_bf16 v[90:93], v[154:157], v[184:187], v[90:93]
	v_mfma_f32_16x16x32_bf16 v[82:85], v[140:143], v[208:211], v[82:85]
	v_mfma_f32_16x16x32_bf16 v[74:77], v[154:157], v[208:211], v[74:77]
	v_mfma_f32_16x16x32_bf16 v[126:129], v[144:147], v[172:175], v[126:129]
	v_mfma_f32_16x16x32_bf16 v[122:125], v[158:161], v[172:175], v[122:125]
	s_add_i32 m0, s47, 0xe000
	s_nop 0
	global_load_lds_dwordx4 v138, s[24:25]
	v_mfma_f32_16x16x32_bf16 v[114:117], v[144:147], v[180:183], v[114:117]
	v_mfma_f32_16x16x32_bf16 v[106:109], v[158:161], v[180:183], v[106:109]
	v_mfma_f32_16x16x32_bf16 v[98:101], v[144:147], v[204:207], v[98:101]
	v_mfma_f32_16x16x32_bf16 v[90:93], v[158:161], v[204:207], v[90:93]
	v_mfma_f32_16x16x32_bf16 v[82:85], v[144:147], v[212:215], v[82:85]
	v_mfma_f32_16x16x32_bf16 v[74:77], v[158:161], v[212:215], v[74:77]
	s_setprio 0
	s_barrier
	s_add_i32 s70, 0, 0x14000
	s_add_i32 s58, s58, s44
	v_add_u32_e32 v153, s70, v149
	ds_read_b128 v[216:219], v153
	ds_read_b128 v[226:229], v153 offset:1024
	ds_read_b128 v[230:233], v153 offset:2048
	ds_read_b128 v[234:237], v153 offset:3072
	s_barrier
; #define PG8_STAGE(bufoff, gbase, voff) do { _Pragma("unroll") for (int _i = 0; _i < 2; ++_i) \
;         __builtin_amdgcn_global_load_lds((const unsigned*)((const char*)(gbase) + (voff)[_i]), (LAS unsigned*)(lds + (bufoff) + ldsw + _i * 8192), 16, 0, 0); } while (0)
; #define PG8_LDA(dst, b, h) do { _Pragma("unroll") for (int m = 0; m < 4; ++m) _Pragma("unroll") for (int k = 0; k < 2; ++k) dst[m][k] = *(const LAS bf16x8*)(lds + PG8_SA(b, h) + aoff + m * 2048 + k * 1024); } while (0)
; #define PG8_LDB(dst, b, h) do { _Pragma("unroll") for (int n = 0; n < 2; ++n) _Pragma("unroll") for (int k = 0; k < 2; ++k) dst[n][k] = *(const LAS bf16x8*)(lds + PG8_SB(b, h) + boff + n * 2048 + k * 1024); } while (0)
; #define PG8_WAIT_V(n) asm volatile("s_waitcnt vmcnt(" #n ")" ::: "memory")
; #define PG8_WAIT_L(n) asm volatile("s_waitcnt lgkmcnt(" #n ")" ::: "memory")
; #define PG8_BAR __builtin_amdgcn_s_barrier()
; #define PG8_SCHED __builtin_amdgcn_sched_barrier(0)
; template <class Epi>
; __device__ __forceinline__ void gemm_phase(LAS unsigned char* lds, const Gemm g, const StaticOrder& S, const Epi& E) {
;     ...
;             PG8_LDB(B0, 0, 0); PG8_SCHED; PG8_LDA(At, 0, 0); PG8_STAGE(PG8_SA(1, 1), a1 + hstep, voffA);
;             PG8_WAIT_L(8); PG8_BAR; PG8_WAIT_L(0); PG8_MMA(0, 0, At, B0); PG8_BAR; PG8_SCHED;
;             PG8_LDB(B1, 0, 1); PG8_STAGE(PG8_SB(0, 0), b2, voffB);
;             PG8_BAR; PG8_WAIT_L(0); PG8_MMA(0, 1, At, B1); PG8_BAR;
;             PG8_LDA(At, 0, 1); PG8_STAGE(PG8_SA(0, 0), a2, voffA);
;             PG8_BAR; PG8_WAIT_L(0); PG8_MMA(1, 0, At, B0); PG8_BAR; PG8_SCHED;
;             PG8_STAGE(PG8_SB(0, 1), b2 + hstep, voffB);
;             PG8_WAIT_V(6); PG8_BAR; PG8_MMA(1, 1, At, B1); PG8_BAR;
;             PG8_LDB(B0, 1, 0); PG8_SCHED; PG8_LDA(At, 1, 0); PG8_STAGE(PG8_SA(0, 1), a2 + hstep, voffA);
;             PG8_WAIT_L(8); PG8_BAR; PG8_WAIT_L(0); PG8_MMA(0, 0, At, B0); PG8_BAR; PG8_SCHED;
;             PG8_LDB(B1, 1, 1); PG8_STAGE(PG8_SB(1, 0), b3, voffB);
;             PG8_BAR; PG8_WAIT_L(0); PG8_MMA(0, 1, At, B1); PG8_BAR;
;             PG8_LDA(At, 1, 1); PG8_STAGE(PG8_SA(1, 0), a3, voffA);
;             PG8_BAR; PG8_WAIT_L(0); PG8_MMA(1, 0, At, B0); PG8_BAR; PG8_SCHED;
;             PG8_STAGE(PG8_SB(1, 1), b3 + hstep, voffB);
;             PG8_WAIT_V(6); PG8_BAR; PG8_MMA(1, 1, At, B1); PG8_BAR;
	s_waitcnt lgkmcnt(0)
	s_setprio 1
	s_waitcnt lgkmcnt(0)
	v_mfma_f32_16x16x32_bf16 v[118:121], v[216:219], v[168:171], v[118:121]
	v_mfma_f32_16x16x32_bf16 v[110:113], v[230:233], v[168:171], v[110:113]
	v_mfma_f32_16x16x32_bf16 v[102:105], v[216:219], v[176:179], v[102:105]
	v_mfma_f32_16x16x32_bf16 v[94:97], v[230:233], v[176:179], v[94:97]
	s_mov_b32 m0, s58
	s_nop 0
	global_load_lds_dwordx4 v0, s[6:7]
	v_mfma_f32_16x16x32_bf16 v[86:89], v[216:219], v[184:187], v[86:89]
	v_mfma_f32_16x16x32_bf16 v[78:81], v[230:233], v[184:187], v[78:81]
	v_mfma_f32_16x16x32_bf16 v[70:73], v[216:219], v[208:211], v[70:73]
	v_mfma_f32_16x16x32_bf16 v[66:69], v[230:233], v[208:211], v[66:69]
	v_mfma_f32_16x16x32_bf16 v[118:121], v[226:229], v[172:175], v[118:121]
	v_mfma_f32_16x16x32_bf16 v[110:113], v[234:237], v[172:175], v[110:113]
	s_add_i32 m0, s58, 0x2000
	s_nop 0
	global_load_lds_dwordx4 v130, s[6:7]
	v_mfma_f32_16x16x32_bf16 v[102:105], v[226:229], v[180:183], v[102:105]
	v_mfma_f32_16x16x32_bf16 v[94:97], v[234:237], v[180:183], v[94:97]
	v_mfma_f32_16x16x32_bf16 v[86:89], v[226:229], v[204:207], v[86:89]
	v_mfma_f32_16x16x32_bf16 v[78:81], v[234:237], v[204:207], v[78:81]
	v_mfma_f32_16x16x32_bf16 v[70:73], v[226:229], v[212:215], v[70:73]
	v_mfma_f32_16x16x32_bf16 v[66:69], v[234:237], v[212:215], v[66:69]
	s_setprio 0
	s_add_u32 vcc_lo, s36, 0x80
	s_addc_u32 vcc_hi, s37, 0
	s_barrier
	ds_read_b128 v[168:171], v152 offset:16384
	ds_read_b128 v[172:175], v152 offset:17408
	ds_read_b128 v[176:179], v152 offset:18432
	ds_read_b128 v[180:183], v152 offset:19456
	ds_read_b128 v[184:187], v152 offset:20480
	ds_read_b128 v[204:207], v152 offset:21504
	ds_read_b128 v[208:211], v152 offset:22528
	ds_read_b128 v[212:215], v152 offset:23552
	s_barrier
	s_waitcnt lgkmcnt(0)
	s_setprio 1
	s_waitcnt lgkmcnt(0)
	v_mfma_f32_16x16x32_bf16 v[62:65], v[140:143], v[168:171], v[62:65]
	v_mfma_f32_16x16x32_bf16 v[58:61], v[154:157], v[168:171], v[58:61]
	v_mfma_f32_16x16x32_bf16 v[50:53], v[140:143], v[176:179], v[50:53]
	v_mfma_f32_16x16x32_bf16 v[42:45], v[154:157], v[176:179], v[42:45]
	s_mov_b32 m0, s47
	s_nop 0
	global_load_lds_dwordx4 v134, s[36:37]
	v_mfma_f32_16x16x32_bf16 v[34:37], v[140:143], v[184:187], v[34:37]
	v_mfma_f32_16x16x32_bf16 v[26:29], v[154:157], v[184:187], v[26:29]
	v_mfma_f32_16x16x32_bf16 v[18:21], v[140:143], v[208:211], v[18:21]
	v_mfma_f32_16x16x32_bf16 v[10:13], v[154:157], v[208:211], v[10:13]
	v_mfma_f32_16x16x32_bf16 v[62:65], v[144:147], v[172:175], v[62:65]
	v_mfma_f32_16x16x32_bf16 v[58:61], v[158:161], v[172:175], v[58:61]
	s_mov_b32 m0, s48
	s_nop 0
	global_load_lds_dwordx4 v132, s[36:37]
	v_mfma_f32_16x16x32_bf16 v[50:53], v[144:147], v[180:183], v[50:53]
	v_mfma_f32_16x16x32_bf16 v[42:45], v[158:161], v[180:183], v[42:45]
	v_mfma_f32_16x16x32_bf16 v[34:37], v[144:147], v[204:207], v[34:37]
	v_mfma_f32_16x16x32_bf16 v[26:29], v[158:161], v[204:207], v[26:29]
	v_mfma_f32_16x16x32_bf16 v[18:21], v[144:147], v[212:215], v[18:21]
	v_mfma_f32_16x16x32_bf16 v[10:13], v[158:161], v[212:215], v[10:13]
	s_setprio 0
	s_barrier
	s_add_u32 s60, s6, 0x40000
	s_addc_u32 s61, s7, 0
	s_add_i32 s58, s70, s44
	s_waitcnt vmcnt(4)
	s_barrier
	s_setprio 1
	v_mfma_f32_16x16x32_bf16 v[54:57], v[216:219], v[168:171], v[54:57]
	v_mfma_f32_16x16x32_bf16 v[46:49], v[230:233], v[168:171], v[46:49]
	v_mfma_f32_16x16x32_bf16 v[38:41], v[216:219], v[176:179], v[38:41]
	v_mfma_f32_16x16x32_bf16 v[30:33], v[230:233], v[176:179], v[30:33]
	s_mov_b32 m0, s58
	s_nop 0
	global_load_lds_dwordx4 v0, s[60:61]
	v_mfma_f32_16x16x32_bf16 v[22:25], v[216:219], v[184:187], v[22:25]
	v_mfma_f32_16x16x32_bf16 v[14:17], v[230:233], v[184:187], v[14:17]
	v_mfma_f32_16x16x32_bf16 v[6:9], v[216:219], v[208:211], v[6:9]
	v_mfma_f32_16x16x32_bf16 v[2:5], v[230:233], v[208:211], v[2:5]
	v_mfma_f32_16x16x32_bf16 v[54:57], v[226:229], v[172:175], v[54:57]
	v_mfma_f32_16x16x32_bf16 v[46:49], v[234:237], v[172:175], v[46:49]
	s_add_i32 m0, s58, 0x2000
	s_nop 0
	global_load_lds_dwordx4 v130, s[60:61]
	v_mfma_f32_16x16x32_bf16 v[38:41], v[226:229], v[180:183], v[38:41]
	v_mfma_f32_16x16x32_bf16 v[30:33], v[234:237], v[180:183], v[30:33]
	v_mfma_f32_16x16x32_bf16 v[22:25], v[226:229], v[204:207], v[22:25]
	v_mfma_f32_16x16x32_bf16 v[14:17], v[234:237], v[204:207], v[14:17]
	v_mfma_f32_16x16x32_bf16 v[6:9], v[226:229], v[212:215], v[6:9]
	v_mfma_f32_16x16x32_bf16 v[2:5], v[234:237], v[212:215], v[2:5]
	s_setprio 0
	s_add_i32 s58, 0, 0x18000
	v_add_u32_e32 v153, s58, v149
	s_barrier
	ds_read_b128 v[140:143], v153
	ds_read_b128 v[144:147], v153 offset:1024
	ds_read_b128 v[154:157], v153 offset:2048
	ds_read_b128 v[158:161], v153 offset:3072
	s_add_u32 s36, s36, 0x40000
	s_addc_u32 s37, s37, 0
	ds_read_b128 v[168:171], v152 offset:32768
	ds_read_b128 v[172:175], v152 offset:33792
	ds_read_b128 v[176:179], v152 offset:34816
	ds_read_b128 v[180:183], v152 offset:35840
	ds_read_b128 v[184:187], v152 offset:36864
	ds_read_b128 v[204:207], v152 offset:37888
	ds_read_b128 v[208:211], v152 offset:38912
	ds_read_b128 v[212:215], v152 offset:39936
	s_waitcnt lgkmcnt(8)
	s_barrier
	s_waitcnt lgkmcnt(0)
	s_setprio 1
	s_waitcnt lgkmcnt(0)
	v_mfma_f32_16x16x32_bf16 v[126:129], v[140:143], v[168:171], v[126:129]
	v_mfma_f32_16x16x32_bf16 v[122:125], v[154:157], v[168:171], v[122:125]
	s_cmp_eq_u32 s87, 0
	s_cbranch_scc1 .LdsA_skip_3
	global_store_dwordx4 v166, v[196:199], s[4:5] offset:256
	s_nop 1
	v_add_u32_e32 v166, 0xe000, v166
; #define PG8_STAGE(bufoff, gbase, voff) do { _Pragma("unroll") for (int _i = 0; _i < 2; ++_i) \
;         __builtin_amdgcn_global_load_lds((const unsigned*)((const char*)(gbase) + (voff)[_i]), (LAS unsigned*)(lds + (bufoff) + ldsw + _i * 8192), 16, 0, 0); } while (0)
; #define PG8_LDA(dst, b, h) do { _Pragma("unroll") for (int m = 0; m < 4; ++m) _Pragma("unroll") for (int k = 0; k < 2; ++k) dst[m][k] = *(const LAS bf16x8*)(lds + PG8_SA(b, h) + aoff + m * 2048 + k * 1024); } while (0)
; #define PG8_LDB(dst, b, h) do { _Pragma("unroll") for (int n = 0; n < 2; ++n) _Pragma("unroll") for (int k = 0; k < 2; ++k) dst[n][k] = *(const LAS bf16x8*)(lds + PG8_SB(b, h) + boff + n * 2048 + k * 1024); } while (0)
; #define PG8_WAIT_V(n) asm volatile("s_waitcnt vmcnt(" #n ")" ::: "memory")
; #define PG8_WAIT_L(n) asm volatile("s_waitcnt lgkmcnt(" #n ")" ::: "memory")
; #define PG8_BAR __builtin_amdgcn_s_barrier()
; #define PG8_SCHED __builtin_amdgcn_sched_barrier(0)
; template <class Epi>
; __device__ __forceinline__ void gemm_phase(LAS unsigned char* lds, const Gemm g, const StaticOrder& S, const Epi& E) {
;     ...
;             PG8_LDB(B0, 0, 0); PG8_SCHED; PG8_LDA(At, 0, 0); PG8_STAGE(PG8_SA(1, 1), a1 + hstep, voffA);
;             PG8_WAIT_L(8); PG8_BAR; PG8_WAIT_L(0); PG8_MMA(0, 0, At, B0); PG8_BAR; PG8_SCHED;
;             PG8_LDB(B1, 0, 1); PG8_STAGE(PG8_SB(0, 0), b2, voffB);
;             PG8_BAR; PG8_WAIT_L(0); PG8_MMA(0, 1, At, B1); PG8_BAR;
;             PG8_LDA(At, 0, 1); PG8_STAGE(PG8_SA(0, 0), a2, voffA);
;             PG8_BAR; PG8_WAIT_L(0); PG8_MMA(1, 0, At, B0); PG8_BAR; PG8_SCHED;
;             PG8_STAGE(PG8_SB(0, 1), b2 + hstep, voffB);
;             PG8_WAIT_V(6); PG8_BAR; PG8_MMA(1, 1, At, B1); PG8_BAR;
;             PG8_LDB(B0, 1, 0); PG8_SCHED; PG8_LDA(At, 1, 0); PG8_STAGE(PG8_SA(0, 1), a2 + hstep, voffA);
;             PG8_WAIT_L(8); PG8_BAR; PG8_WAIT_L(0); PG8_MMA(0, 0, At, B0); PG8_BAR; PG8_SCHED;
;             PG8_LDB(B1, 1, 1); PG8_STAGE(PG8_SB(1, 0), b3, voffB);
;             PG8_BAR; PG8_WAIT_L(0); PG8_MMA(0, 1, At, B1); PG8_BAR;
;             PG8_LDA(At, 1, 1); PG8_STAGE(PG8_SA(1, 0), a3, voffA);
;             PG8_BAR; PG8_WAIT_L(0); PG8_MMA(1, 0, At, B0); PG8_BAR; PG8_SCHED;
;             PG8_STAGE(PG8_SB(1, 1), b3 + hstep, voffB);
;             PG8_WAIT_V(6); PG8_BAR; PG8_MMA(1, 1, At, B1); PG8_BAR;
.LdsA_skip_3:
	v_mfma_f32_16x16x32_bf16 v[114:117], v[140:143], v[176:179], v[114:117]
	v_mfma_f32_16x16x32_bf16 v[106:109], v[154:157], v[176:179], v[106:109]
	s_mov_b32 m0, s49
	s_nop 0
	global_load_lds_dwordx4 v134, s[36:37]
	v_mfma_f32_16x16x32_bf16 v[98:101], v[140:143], v[184:187], v[98:101]
	v_mfma_f32_16x16x32_bf16 v[90:93], v[154:157], v[184:187], v[90:93]
	v_mfma_f32_16x16x32_bf16 v[82:85], v[140:143], v[208:211], v[82:85]
	v_mfma_f32_16x16x32_bf16 v[74:77], v[154:157], v[208:211], v[74:77]
	v_mfma_f32_16x16x32_bf16 v[126:129], v[144:147], v[172:175], v[126:129]
	v_mfma_f32_16x16x32_bf16 v[122:125], v[158:161], v[172:175], v[122:125]
	s_mov_b32 m0, s54
	s_nop 0
	global_load_lds_dwordx4 v132, s[36:37]
	v_mfma_f32_16x16x32_bf16 v[114:117], v[144:147], v[180:183], v[114:117]
	v_mfma_f32_16x16x32_bf16 v[106:109], v[158:161], v[180:183], v[106:109]
	v_mfma_f32_16x16x32_bf16 v[98:101], v[144:147], v[204:207], v[98:101]
	v_mfma_f32_16x16x32_bf16 v[90:93], v[158:161], v[204:207], v[90:93]
	v_mfma_f32_16x16x32_bf16 v[82:85], v[144:147], v[212:215], v[82:85]
	v_mfma_f32_16x16x32_bf16 v[74:77], v[158:161], v[212:215], v[74:77]
	s_setprio 0
	s_barrier
	s_add_i32 s36, 0, 0x1c000
	s_add_i32 s37, s58, s44
	v_add_u32_e32 v153, s36, v149
	s_add_u32 s60, s6, 0x80
	s_addc_u32 s61, s7, 0
	ds_read_b128 v[216:219], v153
	ds_read_b128 v[226:229], v153 offset:1024
	ds_read_b128 v[230:233], v153 offset:2048
	ds_read_b128 v[234:237], v153 offset:3072
	s_barrier
	s_waitcnt lgkmcnt(0)
	s_setprio 1
	s_waitcnt lgkmcnt(0)
	v_mfma_f32_16x16x32_bf16 v[118:121], v[216:219], v[168:171], v[118:121]
	v_mfma_f32_16x16x32_bf16 v[110:113], v[230:233], v[168:171], v[110:113]
	v_mfma_f32_16x16x32_bf16 v[102:105], v[216:219], v[176:179], v[102:105]
	v_mfma_f32_16x16x32_bf16 v[94:97], v[230:233], v[176:179], v[94:97]
	s_mov_b32 m0, s37
	s_nop 0
	global_load_lds_dwordx4 v0, s[60:61]
	v_mfma_f32_16x16x32_bf16 v[86:89], v[216:219], v[184:187], v[86:89]
	v_mfma_f32_16x16x32_bf16 v[78:81], v[230:233], v[184:187], v[78:81]
	v_mfma_f32_16x16x32_bf16 v[70:73], v[216:219], v[208:211], v[70:73]
	v_mfma_f32_16x16x32_bf16 v[66:69], v[230:233], v[208:211], v[66:69]
	v_mfma_f32_16x16x32_bf16 v[118:121], v[226:229], v[172:175], v[118:121]
	v_mfma_f32_16x16x32_bf16 v[110:113], v[234:237], v[172:175], v[110:113]
	s_add_i32 m0, s37, 0x2000
	s_nop 0
	global_load_lds_dwordx4 v130, s[60:61]
	v_mfma_f32_16x16x32_bf16 v[102:105], v[226:229], v[180:183], v[102:105]
	v_mfma_f32_16x16x32_bf16 v[94:97], v[234:237], v[180:183], v[94:97]
	v_mfma_f32_16x16x32_bf16 v[86:89], v[226:229], v[204:207], v[86:89]
	v_mfma_f32_16x16x32_bf16 v[78:81], v[234:237], v[204:207], v[78:81]
	v_mfma_f32_16x16x32_bf16 v[70:73], v[226:229], v[212:215], v[70:73]
	v_mfma_f32_16x16x32_bf16 v[66:69], v[234:237], v[212:215], v[66:69]
	s_setprio 0
	s_barrier
	ds_read_b128 v[168:171], v152 offset:49152
	ds_read_b128 v[172:175], v152 offset:50176
	ds_read_b128 v[176:179], v152 offset:51200
	ds_read_b128 v[180:183], v152 offset:52224
	ds_read_b128 v[184:187], v152 offset:53248
	ds_read_b128 v[204:207], v152 offset:54272
	ds_read_b128 v[208:211], v152 offset:55296
	ds_read_b128 v[212:215], v152 offset:56320
	s_barrier
	s_waitcnt lgkmcnt(0)
	s_setprio 1
	s_waitcnt lgkmcnt(0)
	v_mfma_f32_16x16x32_bf16 v[62:65], v[140:143], v[168:171], v[62:65]
	v_mfma_f32_16x16x32_bf16 v[58:61], v[154:157], v[168:171], v[58:61]
	v_mfma_f32_16x16x32_bf16 v[50:53], v[140:143], v[176:179], v[50:53]
	v_mfma_f32_16x16x32_bf16 v[42:45], v[154:157], v[176:179], v[42:45]
	s_mov_b32 m0, s55
	s_nop 0
	global_load_lds_dwordx4 v134, vcc
	v_mfma_f32_16x16x32_bf16 v[34:37], v[140:143], v[184:187], v[34:37]
	v_mfma_f32_16x16x32_bf16 v[26:29], v[154:157], v[184:187], v[26:29]
	v_mfma_f32_16x16x32_bf16 v[18:21], v[140:143], v[208:211], v[18:21]
	v_mfma_f32_16x16x32_bf16 v[10:13], v[154:157], v[208:211], v[10:13]
	v_mfma_f32_16x16x32_bf16 v[62:65], v[144:147], v[172:175], v[62:65]
	v_mfma_f32_16x16x32_bf16 v[58:61], v[158:161], v[172:175], v[58:61]
	s_mov_b32 m0, s83
	s_nop 0
	global_load_lds_dwordx4 v132, vcc
	v_mfma_f32_16x16x32_bf16 v[50:53], v[144:147], v[180:183], v[50:53]
	v_mfma_f32_16x16x32_bf16 v[42:45], v[158:161], v[180:183], v[42:45]
	v_mfma_f32_16x16x32_bf16 v[34:37], v[144:147], v[204:207], v[34:37]
	v_mfma_f32_16x16x32_bf16 v[26:29], v[158:161], v[204:207], v[26:29]
	v_mfma_f32_16x16x32_bf16 v[18:21], v[144:147], v[212:215], v[18:21]
	v_mfma_f32_16x16x32_bf16 v[10:13], v[158:161], v[212:215], v[10:13]
	s_setprio 0
	s_barrier
	s_add_u32 s6, s6, 0x40080
	s_addc_u32 s7, s7, 0
	s_add_i32 s36, s36, s44
	s_waitcnt vmcnt(4)
	s_barrier
	s_setprio 1
	v_mfma_f32_16x16x32_bf16 v[54:57], v[216:219], v[168:171], v[54:57]
	v_mfma_f32_16x16x32_bf16 v[46:49], v[230:233], v[168:171], v[46:49]
	v_mfma_f32_16x16x32_bf16 v[38:41], v[216:219], v[176:179], v[38:41]
	v_mfma_f32_16x16x32_bf16 v[30:33], v[230:233], v[176:179], v[30:33]
	s_mov_b32 m0, s36
	s_nop 0
	global_load_lds_dwordx4 v0, s[6:7]
	v_mfma_f32_16x16x32_bf16 v[22:25], v[216:219], v[184:187], v[22:25]
	v_mfma_f32_16x16x32_bf16 v[14:17], v[230:233], v[184:187], v[14:17]
	v_mfma_f32_16x16x32_bf16 v[6:9], v[216:219], v[208:211], v[6:9]
	v_mfma_f32_16x16x32_bf16 v[2:5], v[230:233], v[208:211], v[2:5]
	v_mfma_f32_16x16x32_bf16 v[54:57], v[226:229], v[172:175], v[54:57]
	v_mfma_f32_16x16x32_bf16 v[46:49], v[234:237], v[172:175], v[46:49]
	s_add_i32 m0, s36, 0x2000
	s_nop 0
	global_load_lds_dwordx4 v130, s[6:7]
	v_mfma_f32_16x16x32_bf16 v[38:41], v[226:229], v[180:183], v[38:41]
	v_mfma_f32_16x16x32_bf16 v[30:33], v[234:237], v[180:183], v[30:33]
	v_mfma_f32_16x16x32_bf16 v[22:25], v[226:229], v[204:207], v[22:25]
	v_mfma_f32_16x16x32_bf16 v[14:17], v[234:237], v[204:207], v[14:17]
	v_mfma_f32_16x16x32_bf16 v[6:9], v[226:229], v[212:215], v[6:9]
	v_mfma_f32_16x16x32_bf16 v[2:5], v[234:237], v[212:215], v[2:5]
	s_setprio 0
	s_add_i32 s91, s91, 2
	s_add_u32 s24, s24, 0x100
	s_addc_u32 s25, s25, 0
	s_add_u32 s89, s89, 0x100
	s_addc_u32 s90, s90, 0
	s_cmp_gt_u32 s91, 13
	s_barrier
; #define PG8_STAGE(bufoff, gbase, voff) do { _Pragma("unroll") for (int _i = 0; _i < 2; ++_i) \
;         __builtin_amdgcn_global_load_lds((const unsigned*)((const char*)(gbase) + (voff)[_i]), (LAS unsigned*)(lds + (bufoff) + ldsw + _i * 8192), 16, 0, 0); } while (0)
; #define PG8_LDA(dst, b, h) do { _Pragma("unroll") for (int m = 0; m < 4; ++m) _Pragma("unroll") for (int k = 0; k < 2; ++k) dst[m][k] = *(const LAS bf16x8*)(lds + PG8_SA(b, h) + aoff + m * 2048 + k * 1024); } while (0)
; #define PG8_LDB(dst, b, h) do { _Pragma("unroll") for (int n = 0; n < 2; ++n) _Pragma("unroll") for (int k = 0; k < 2; ++k) dst[n][k] = *(const LAS bf16x8*)(lds + PG8_SB(b, h) + boff + n * 2048 + k * 1024); } while (0)
; #define PG8_WAIT_V(n) asm volatile("s_waitcnt vmcnt(" #n ")" ::: "memory")
; #define PG8_WAIT_L(n) asm volatile("s_waitcnt lgkmcnt(" #n ")" ::: "memory")
; #define PG8_BAR __builtin_amdgcn_s_barrier()
; #define PG8_SCHED __builtin_amdgcn_sched_barrier(0)
; template <class Epi>
; __device__ __forceinline__ void gemm_phase(LAS unsigned char* lds, const Gemm g, const StaticOrder& S, const Epi& E) {
;     ...
;             PG8_LDB(B0, 0, 0); PG8_SCHED; PG8_LDA(At, 0, 0); PG8_STAGE(PG8_SA(1, 1), a1 + hstep, voffA);
;             PG8_WAIT_L(8); PG8_BAR; PG8_WAIT_L(0); PG8_MMA(0, 0, At, B0); PG8_BAR; PG8_SCHED;
;             PG8_LDB(B1, 0, 1); PG8_STAGE(PG8_SB(0, 0), b2, voffB);
;             PG8_BAR; PG8_WAIT_L(0); PG8_MMA(0, 1, At, B1); PG8_BAR;
;             PG8_LDA(At, 0, 1); PG8_STAGE(PG8_SA(0, 0), a2, voffA);
;             PG8_BAR; PG8_WAIT_L(0); PG8_MMA(1, 0, At, B0); PG8_BAR; PG8_SCHED;
;             PG8_STAGE(PG8_SB(0, 1), b2 + hstep, voffB);
;             PG8_WAIT_V(6); PG8_BAR; PG8_MMA(1, 1, At, B1); PG8_BAR;
;             PG8_LDB(B0, 1, 0); PG8_SCHED; PG8_LDA(At, 1, 0); PG8_STAGE(PG8_SA(0, 1), a2 + hstep, voffA);
;             PG8_WAIT_L(8); PG8_BAR; PG8_WAIT_L(0); PG8_MMA(0, 0, At, B0); PG8_BAR; PG8_SCHED;
;             PG8_LDB(B1, 1, 1); PG8_STAGE(PG8_SB(1, 0), b3, voffB);
;             PG8_BAR; PG8_WAIT_L(0); PG8_MMA(0, 1, At, B1); PG8_BAR;
;             PG8_LDA(At, 1, 1); PG8_STAGE(PG8_SA(1, 0), a3, voffA);
;             PG8_BAR; PG8_WAIT_L(0); PG8_MMA(1, 0, At, B0); PG8_BAR; PG8_SCHED;
;             PG8_STAGE(PG8_SB(1, 1), b3 + hstep, voffB);
;             PG8_WAIT_V(6); PG8_BAR; PG8_MMA(1, 1, At, B1); PG8_BAR;
	s_add_u32 s6, s24, 0xfffc0080
	s_addc_u32 s7, s25, -1
	s_add_i32 s58, 0, 0x10000
	v_add_u32_e32 v153, s58, v149
	ds_read_b128 v[140:143], v153
	ds_read_b128 v[144:147], v153 offset:1024
	ds_read_b128 v[154:157], v153 offset:2048
	ds_read_b128 v[158:161], v153 offset:3072
	s_cmp_eq_u32 s91, 12
	s_cselect_b32 s37, s11, s7
	s_cselect_b32 s36, s71, s6
	s_cselect_b32 s7, s9, s90
	s_cselect_b32 s6, s88, s89
	ds_read_b128 v[168:171], v152
	ds_read_b128 v[172:175], v152 offset:1024
	ds_read_b128 v[176:179], v152 offset:2048
	ds_read_b128 v[180:183], v152 offset:3072
	ds_read_b128 v[184:187], v152 offset:4096
	ds_read_b128 v[204:207], v152 offset:5120
	ds_read_b128 v[208:211], v152 offset:6144
	ds_read_b128 v[212:215], v152 offset:7168
	s_waitcnt lgkmcnt(8)
	s_barrier
	s_waitcnt lgkmcnt(0)
	s_setprio 1
	s_waitcnt lgkmcnt(0)
	v_mfma_f32_16x16x32_bf16 v[126:129], v[140:143], v[168:171], v[126:129]
	v_mfma_f32_16x16x32_bf16 v[122:125], v[154:157], v[168:171], v[122:125]
	v_mfma_f32_16x16x32_bf16 v[114:117], v[140:143], v[176:179], v[114:117]
	v_mfma_f32_16x16x32_bf16 v[106:109], v[154:157], v[176:179], v[106:109]
	s_add_i32 m0, s47, 0xc000
	s_nop 0
	global_load_lds_dwordx4 v136, s[24:25]
	v_mfma_f32_16x16x32_bf16 v[98:101], v[140:143], v[184:187], v[98:101]
	v_mfma_f32_16x16x32_bf16 v[90:93], v[154:157], v[184:187], v[90:93]
	v_mfma_f32_16x16x32_bf16 v[82:85], v[140:143], v[208:211], v[82:85]
	v_mfma_f32_16x16x32_bf16 v[74:77], v[154:157], v[208:211], v[74:77]
	v_mfma_f32_16x16x32_bf16 v[126:129], v[144:147], v[172:175], v[126:129]
	v_mfma_f32_16x16x32_bf16 v[122:125], v[158:161], v[172:175], v[122:125]
	s_add_i32 m0, s47, 0xe000
	s_nop 0
	global_load_lds_dwordx4 v138, s[24:25]
	v_mfma_f32_16x16x32_bf16 v[114:117], v[144:147], v[180:183], v[114:117]
	v_mfma_f32_16x16x32_bf16 v[106:109], v[158:161], v[180:183], v[106:109]
	v_mfma_f32_16x16x32_bf16 v[98:101], v[144:147], v[204:207], v[98:101]
	v_mfma_f32_16x16x32_bf16 v[90:93], v[158:161], v[204:207], v[90:93]
	v_mfma_f32_16x16x32_bf16 v[82:85], v[144:147], v[212:215], v[82:85]
	v_mfma_f32_16x16x32_bf16 v[74:77], v[158:161], v[212:215], v[74:77]
	s_setprio 0
	s_barrier
	s_add_i32 s70, 0, 0x14000
	s_add_i32 s58, s58, s44
	v_add_u32_e32 v153, s70, v149
	ds_read_b128 v[216:219], v153
	ds_read_b128 v[226:229], v153 offset:1024
	ds_read_b128 v[230:233], v153 offset:2048
	ds_read_b128 v[234:237], v153 offset:3072
	s_barrier
	s_waitcnt lgkmcnt(0)
	s_setprio 1
	s_waitcnt lgkmcnt(0)
	v_mfma_f32_16x16x32_bf16 v[118:121], v[216:219], v[168:171], v[118:121]
	v_mfma_f32_16x16x32_bf16 v[110:113], v[230:233], v[168:171], v[110:113]
	v_mfma_f32_16x16x32_bf16 v[102:105], v[216:219], v[176:179], v[102:105]
	v_mfma_f32_16x16x32_bf16 v[94:97], v[230:233], v[176:179], v[94:97]
	s_mov_b32 m0, s58
	s_nop 0
	global_load_lds_dwordx4 v0, s[6:7]
	v_mfma_f32_16x16x32_bf16 v[86:89], v[216:219], v[184:187], v[86:89]
	v_mfma_f32_16x16x32_bf16 v[78:81], v[230:233], v[184:187], v[78:81]
	v_mfma_f32_16x16x32_bf16 v[70:73], v[216:219], v[208:211], v[70:73]
	v_mfma_f32_16x16x32_bf16 v[66:69], v[230:233], v[208:211], v[66:69]
	v_mfma_f32_16x16x32_bf16 v[118:121], v[226:229], v[172:175], v[118:121]
	v_mfma_f32_16x16x32_bf16 v[110:113], v[234:237], v[172:175], v[110:113]
	s_add_i32 m0, s58, 0x2000
	s_nop 0
	global_load_lds_dwordx4 v130, s[6:7]
	v_mfma_f32_16x16x32_bf16 v[102:105], v[226:229], v[180:183], v[102:105]
	v_mfma_f32_16x16x32_bf16 v[94:97], v[234:237], v[180:183], v[94:97]
	v_mfma_f32_16x16x32_bf16 v[86:89], v[226:229], v[204:207], v[86:89]
	v_mfma_f32_16x16x32_bf16 v[78:81], v[234:237], v[204:207], v[78:81]
	v_mfma_f32_16x16x32_bf16 v[70:73], v[226:229], v[212:215], v[70:73]
	v_mfma_f32_16x16x32_bf16 v[66:69], v[234:237], v[212:215], v[66:69]
	s_setprio 0
	s_add_u32 vcc_lo, s36, 0x80
	s_addc_u32 vcc_hi, s37, 0
	s_barrier
	ds_read_b128 v[168:171], v152 offset:16384
	ds_read_b128 v[172:175], v152 offset:17408
	ds_read_b128 v[176:179], v152 offset:18432
	ds_read_b128 v[180:183], v152 offset:19456
	ds_read_b128 v[184:187], v152 offset:20480
	ds_read_b128 v[204:207], v152 offset:21504
	ds_read_b128 v[208:211], v152 offset:22528
	ds_read_b128 v[212:215], v152 offset:23552
	s_barrier
	s_waitcnt lgkmcnt(0)
	s_setprio 1
	s_waitcnt lgkmcnt(0)
	v_mfma_f32_16x16x32_bf16 v[62:65], v[140:143], v[168:171], v[62:65]
	v_mfma_f32_16x16x32_bf16 v[58:61], v[154:157], v[168:171], v[58:61]
	v_mfma_f32_16x16x32_bf16 v[50:53], v[140:143], v[176:179], v[50:53]
	v_mfma_f32_16x16x32_bf16 v[42:45], v[154:157], v[176:179], v[42:45]
	s_mov_b32 m0, s47
	s_nop 0
	global_load_lds_dwordx4 v134, s[36:37]
	v_mfma_f32_16x16x32_bf16 v[34:37], v[140:143], v[184:187], v[34:37]
	v_mfma_f32_16x16x32_bf16 v[26:29], v[154:157], v[184:187], v[26:29]
	v_mfma_f32_16x16x32_bf16 v[18:21], v[140:143], v[208:211], v[18:21]
	v_mfma_f32_16x16x32_bf16 v[10:13], v[154:157], v[208:211], v[10:13]
	v_mfma_f32_16x16x32_bf16 v[62:65], v[144:147], v[172:175], v[62:65]
	v_mfma_f32_16x16x32_bf16 v[58:61], v[158:161], v[172:175], v[58:61]
	s_mov_b32 m0, s48
	s_nop 0
	global_load_lds_dwordx4 v132, s[36:37]
	v_mfma_f32_16x16x32_bf16 v[50:53], v[144:147], v[180:183], v[50:53]
	v_mfma_f32_16x16x32_bf16 v[42:45], v[158:161], v[180:183], v[42:45]
	v_mfma_f32_16x16x32_bf16 v[34:37], v[144:147], v[204:207], v[34:37]
	v_mfma_f32_16x16x32_bf16 v[26:29], v[158:161], v[204:207], v[26:29]
	v_mfma_f32_16x16x32_bf16 v[18:21], v[144:147], v[212:215], v[18:21]
	v_mfma_f32_16x16x32_bf16 v[10:13], v[158:161], v[212:215], v[10:13]
	s_setprio 0
	s_barrier
	s_add_u32 s60, s6, 0x40000
	s_addc_u32 s61, s7, 0
	s_add_i32 s58, s70, s44
	s_waitcnt vmcnt(4)
	s_barrier
; #define PG8_STAGE(bufoff, gbase, voff) do { _Pragma("unroll") for (int _i = 0; _i < 2; ++_i) \
;         __builtin_amdgcn_global_load_lds((const unsigned*)((const char*)(gbase) + (voff)[_i]), (LAS unsigned*)(lds + (bufoff) + ldsw + _i * 8192), 16, 0, 0); } while (0)
; #define PG8_LDA(dst, b, h) do { _Pragma("unroll") for (int m = 0; m < 4; ++m) _Pragma("unroll") for (int k = 0; k < 2; ++k) dst[m][k] = *(const LAS bf16x8*)(lds + PG8_SA(b, h) + aoff + m * 2048 + k * 1024); } while (0)
; #define PG8_LDB(dst, b, h) do { _Pragma("unroll") for (int n = 0; n < 2; ++n) _Pragma("unroll") for (int k = 0; k < 2; ++k) dst[n][k] = *(const LAS bf16x8*)(lds + PG8_SB(b, h) + boff + n * 2048 + k * 1024); } while (0)
; #define PG8_WAIT_V(n) asm volatile("s_waitcnt vmcnt(" #n ")" ::: "memory")
; #define PG8_WAIT_L(n) asm volatile("s_waitcnt lgkmcnt(" #n ")" ::: "memory")
; #define PG8_BAR __builtin_amdgcn_s_barrier()
; #define PG8_SCHED __builtin_amdgcn_sched_barrier(0)
; template <class Epi>
; __device__ __forceinline__ void gemm_phase(LAS unsigned char* lds, const Gemm g, const StaticOrder& S, const Epi& E) {
;     ...
;             PG8_LDB(B0, 0, 0); PG8_SCHED; PG8_LDA(At, 0, 0); PG8_STAGE(PG8_SA(1, 1), a1 + hstep, voffA);
;             PG8_WAIT_L(8); PG8_BAR; PG8_WAIT_L(0); PG8_MMA(0, 0, At, B0); PG8_BAR; PG8_SCHED;
;             PG8_LDB(B1, 0, 1); PG8_STAGE(PG8_SB(0, 0), b2, voffB);
;             PG8_BAR; PG8_WAIT_L(0); PG8_MMA(0, 1, At, B1); PG8_BAR;
;             PG8_LDA(At, 0, 1); PG8_STAGE(PG8_SA(0, 0), a2, voffA);
;             PG8_BAR; PG8_WAIT_L(0); PG8_MMA(1, 0, At, B0); PG8_BAR; PG8_SCHED;
;             PG8_STAGE(PG8_SB(0, 1), b2 + hstep, voffB);
;             PG8_WAIT_V(6); PG8_BAR; PG8_MMA(1, 1, At, B1); PG8_BAR;
;             PG8_LDB(B0, 1, 0); PG8_SCHED; PG8_LDA(At, 1, 0); PG8_STAGE(PG8_SA(0, 1), a2 + hstep, voffA);
;             PG8_WAIT_L(8); PG8_BAR; PG8_WAIT_L(0); PG8_MMA(0, 0, At, B0); PG8_BAR; PG8_SCHED;
;             PG8_LDB(B1, 1, 1); PG8_STAGE(PG8_SB(1, 0), b3, voffB);
;             PG8_BAR; PG8_WAIT_L(0); PG8_MMA(0, 1, At, B1); PG8_BAR;
;             PG8_LDA(At, 1, 1); PG8_STAGE(PG8_SA(1, 0), a3, voffA);
;             PG8_BAR; PG8_WAIT_L(0); PG8_MMA(1, 0, At, B0); PG8_BAR; PG8_SCHED;
;             PG8_STAGE(PG8_SB(1, 1), b3 + hstep, voffB);
;             PG8_WAIT_V(6); PG8_BAR; PG8_MMA(1, 1, At, B1); PG8_BAR;
	s_setprio 1
	v_mfma_f32_16x16x32_bf16 v[54:57], v[216:219], v[168:171], v[54:57]
	v_mfma_f32_16x16x32_bf16 v[46:49], v[230:233], v[168:171], v[46:49]
	v_mfma_f32_16x16x32_bf16 v[38:41], v[216:219], v[176:179], v[38:41]
	v_mfma_f32_16x16x32_bf16 v[30:33], v[230:233], v[176:179], v[30:33]
	s_mov_b32 m0, s58
	s_nop 0
	global_load_lds_dwordx4 v0, s[60:61]
	v_mfma_f32_16x16x32_bf16 v[22:25], v[216:219], v[184:187], v[22:25]
	v_mfma_f32_16x16x32_bf16 v[14:17], v[230:233], v[184:187], v[14:17]
	v_mfma_f32_16x16x32_bf16 v[6:9], v[216:219], v[208:211], v[6:9]
	v_mfma_f32_16x16x32_bf16 v[2:5], v[230:233], v[208:211], v[2:5]
	v_mfma_f32_16x16x32_bf16 v[54:57], v[226:229], v[172:175], v[54:57]
	v_mfma_f32_16x16x32_bf16 v[46:49], v[234:237], v[172:175], v[46:49]
	s_add_i32 m0, s58, 0x2000
	s_nop 0
	global_load_lds_dwordx4 v130, s[60:61]
	v_mfma_f32_16x16x32_bf16 v[38:41], v[226:229], v[180:183], v[38:41]
	v_mfma_f32_16x16x32_bf16 v[30:33], v[234:237], v[180:183], v[30:33]
	v_mfma_f32_16x16x32_bf16 v[22:25], v[226:229], v[204:207], v[22:25]
	v_mfma_f32_16x16x32_bf16 v[14:17], v[234:237], v[204:207], v[14:17]
	v_mfma_f32_16x16x32_bf16 v[6:9], v[226:229], v[212:215], v[6:9]
	v_mfma_f32_16x16x32_bf16 v[2:5], v[234:237], v[212:215], v[2:5]
	s_setprio 0
	s_add_i32 s58, 0, 0x18000
	v_add_u32_e32 v153, s58, v149
	s_barrier
	ds_read_b128 v[140:143], v153
	ds_read_b128 v[144:147], v153 offset:1024
	ds_read_b128 v[154:157], v153 offset:2048
	ds_read_b128 v[158:161], v153 offset:3072
	s_add_u32 s36, s36, 0x40000
	s_addc_u32 s37, s37, 0
	ds_read_b128 v[168:171], v152 offset:32768
	ds_read_b128 v[172:175], v152 offset:33792
	ds_read_b128 v[176:179], v152 offset:34816
	ds_read_b128 v[180:183], v152 offset:35840
	ds_read_b128 v[184:187], v152 offset:36864
	ds_read_b128 v[204:207], v152 offset:37888
	ds_read_b128 v[208:211], v152 offset:38912
	ds_read_b128 v[212:215], v152 offset:39936
	s_waitcnt lgkmcnt(8)
	s_barrier
	s_waitcnt lgkmcnt(0)
	s_setprio 1
	s_waitcnt lgkmcnt(0)
	v_mfma_f32_16x16x32_bf16 v[126:129], v[140:143], v[168:171], v[126:129]
	v_mfma_f32_16x16x32_bf16 v[122:125], v[154:157], v[168:171], v[122:125]
	s_cmp_eq_u32 s87, 0
	s_cbranch_scc1 .LdsA_skip_4
	global_store_dwordx4 v166, v[200:203], s[4:5]
.LdsA_skip_4:
	v_mfma_f32_16x16x32_bf16 v[114:117], v[140:143], v[176:179], v[114:117]
	v_mfma_f32_16x16x32_bf16 v[106:109], v[154:157], v[176:179], v[106:109]
	s_mov_b32 m0, s49
	s_nop 0
	global_load_lds_dwordx4 v134, s[36:37]
	v_mfma_f32_16x16x32_bf16 v[98:101], v[140:143], v[184:187], v[98:101]
	v_mfma_f32_16x16x32_bf16 v[90:93], v[154:157], v[184:187], v[90:93]
	v_mfma_f32_16x16x32_bf16 v[82:85], v[140:143], v[208:211], v[82:85]
	v_mfma_f32_16x16x32_bf16 v[74:77], v[154:157], v[208:211], v[74:77]
	v_mfma_f32_16x16x32_bf16 v[126:129], v[144:147], v[172:175], v[126:129]
	v_mfma_f32_16x16x32_bf16 v[122:125], v[158:161], v[172:175], v[122:125]
	s_mov_b32 m0, s54
	s_nop 0
	global_load_lds_dwordx4 v132, s[36:37]
	v_mfma_f32_16x16x32_bf16 v[114:117], v[144:147], v[180:183], v[114:117]
	v_mfma_f32_16x16x32_bf16 v[106:109], v[158:161], v[180:183], v[106:109]
	v_mfma_f32_16x16x32_bf16 v[98:101], v[144:147], v[204:207], v[98:101]
	v_mfma_f32_16x16x32_bf16 v[90:93], v[158:161], v[204:207], v[90:93]
	v_mfma_f32_16x16x32_bf16 v[82:85], v[144:147], v[212:215], v[82:85]
	v_mfma_f32_16x16x32_bf16 v[74:77], v[158:161], v[212:215], v[74:77]
	s_setprio 0
	s_barrier
	s_add_i32 s36, 0, 0x1c000
	s_add_i32 s37, s58, s44
	v_add_u32_e32 v153, s36, v149
	s_add_u32 s60, s6, 0x80
	s_addc_u32 s61, s7, 0
	ds_read_b128 v[216:219], v153
	ds_read_b128 v[226:229], v153 offset:1024
	ds_read_b128 v[230:233], v153 offset:2048
	ds_read_b128 v[234:237], v153 offset:3072
	s_barrier
	s_waitcnt lgkmcnt(0)
	s_setprio 1
	s_waitcnt lgkmcnt(0)
	v_mfma_f32_16x16x32_bf16 v[118:121], v[216:219], v[168:171], v[118:121]
	v_mfma_f32_16x16x32_bf16 v[110:113], v[230:233], v[168:171], v[110:113]
	v_mfma_f32_16x16x32_bf16 v[102:105], v[216:219], v[176:179], v[102:105]
	v_mfma_f32_16x16x32_bf16 v[94:97], v[230:233], v[176:179], v[94:97]
	s_mov_b32 m0, s37
	s_nop 0
	global_load_lds_dwordx4 v0, s[60:61]
	v_mfma_f32_16x16x32_bf16 v[86:89], v[216:219], v[184:187], v[86:89]
	v_mfma_f32_16x16x32_bf16 v[78:81], v[230:233], v[184:187], v[78:81]
	v_mfma_f32_16x16x32_bf16 v[70:73], v[216:219], v[208:211], v[70:73]
	v_mfma_f32_16x16x32_bf16 v[66:69], v[230:233], v[208:211], v[66:69]
	v_mfma_f32_16x16x32_bf16 v[118:121], v[226:229], v[172:175], v[118:121]
	v_mfma_f32_16x16x32_bf16 v[110:113], v[234:237], v[172:175], v[110:113]
	s_add_i32 m0, s37, 0x2000
	s_nop 0
	global_load_lds_dwordx4 v130, s[60:61]
	v_mfma_f32_16x16x32_bf16 v[102:105], v[226:229], v[180:183], v[102:105]
	v_mfma_f32_16x16x32_bf16 v[94:97], v[234:237], v[180:183], v[94:97]
	v_mfma_f32_16x16x32_bf16 v[86:89], v[226:229], v[204:207], v[86:89]
	v_mfma_f32_16x16x32_bf16 v[78:81], v[234:237], v[204:207], v[78:81]
	v_mfma_f32_16x16x32_bf16 v[70:73], v[226:229], v[212:215], v[70:73]
	v_mfma_f32_16x16x32_bf16 v[66:69], v[234:237], v[212:215], v[66:69]
	s_setprio 0
	s_barrier
	ds_read_b128 v[168:171], v152 offset:49152
	ds_read_b128 v[172:175], v152 offset:50176
	ds_read_b128 v[176:179], v152 offset:51200
	ds_read_b128 v[180:183], v152 offset:52224
	ds_read_b128 v[184:187], v152 offset:53248
	ds_read_b128 v[204:207], v152 offset:54272
	ds_read_b128 v[208:211], v152 offset:55296
	ds_read_b128 v[212:215], v152 offset:56320
	s_barrier
; #define PG8_STAGE(bufoff, gbase, voff) do { _Pragma("unroll") for (int _i = 0; _i < 2; ++_i) \
;         __builtin_amdgcn_global_load_lds((const unsigned*)((const char*)(gbase) + (voff)[_i]), (LAS unsigned*)(lds + (bufoff) + ldsw + _i * 8192), 16, 0, 0); } while (0)
; #define PG8_LDA(dst, b, h) do { _Pragma("unroll") for (int m = 0; m < 4; ++m) _Pragma("unroll") for (int k = 0; k < 2; ++k) dst[m][k] = *(const LAS bf16x8*)(lds + PG8_SA(b, h) + aoff + m * 2048 + k * 1024); } while (0)
; #define PG8_LDB(dst, b, h) do { _Pragma("unroll") for (int n = 0; n < 2; ++n) _Pragma("unroll") for (int k = 0; k < 2; ++k) dst[n][k] = *(const LAS bf16x8*)(lds + PG8_SB(b, h) + boff + n * 2048 + k * 1024); } while (0)
; #define PG8_WAIT_V(n) asm volatile("s_waitcnt vmcnt(" #n ")" ::: "memory")
; #define PG8_WAIT_L(n) asm volatile("s_waitcnt lgkmcnt(" #n ")" ::: "memory")
; #define PG8_BAR __builtin_amdgcn_s_barrier()
; #define PG8_SCHED __builtin_amdgcn_sched_barrier(0)
; template <class Epi>
; __device__ __forceinline__ void gemm_phase(LAS unsigned char* lds, const Gemm g, const StaticOrder& S, const Epi& E) {
;     ...
;             PG8_LDB(B0, 0, 0); PG8_SCHED; PG8_LDA(At, 0, 0); PG8_STAGE(PG8_SA(1, 1), a1 + hstep, voffA);
;             PG8_WAIT_L(8); PG8_BAR; PG8_WAIT_L(0); PG8_MMA(0, 0, At, B0); PG8_BAR; PG8_SCHED;
;             PG8_LDB(B1, 0, 1); PG8_STAGE(PG8_SB(0, 0), b2, voffB);
;             PG8_BAR; PG8_WAIT_L(0); PG8_MMA(0, 1, At, B1); PG8_BAR;
;             PG8_LDA(At, 0, 1); PG8_STAGE(PG8_SA(0, 0), a2, voffA);
;             PG8_BAR; PG8_WAIT_L(0); PG8_MMA(1, 0, At, B0); PG8_BAR; PG8_SCHED;
;             PG8_STAGE(PG8_SB(0, 1), b2 + hstep, voffB);
;             PG8_WAIT_V(6); PG8_BAR; PG8_MMA(1, 1, At, B1); PG8_BAR;
;             PG8_LDB(B0, 1, 0); PG8_SCHED; PG8_LDA(At, 1, 0); PG8_STAGE(PG8_SA(0, 1), a2 + hstep, voffA);
;             PG8_WAIT_L(8); PG8_BAR; PG8_WAIT_L(0); PG8_MMA(0, 0, At, B0); PG8_BAR; PG8_SCHED;
;             PG8_LDB(B1, 1, 1); PG8_STAGE(PG8_SB(1, 0), b3, voffB);
;             PG8_BAR; PG8_WAIT_L(0); PG8_MMA(0, 1, At, B1); PG8_BAR;
;             PG8_LDA(At, 1, 1); PG8_STAGE(PG8_SA(1, 0), a3, voffA);
;             PG8_BAR; PG8_WAIT_L(0); PG8_MMA(1, 0, At, B0); PG8_BAR; PG8_SCHED;
;             PG8_STAGE(PG8_SB(1, 1), b3 + hstep, voffB);
;             PG8_WAIT_V(6); PG8_BAR; PG8_MMA(1, 1, At, B1); PG8_BAR;
	s_waitcnt lgkmcnt(0)
	s_setprio 1
	s_waitcnt lgkmcnt(0)
	v_mfma_f32_16x16x32_bf16 v[62:65], v[140:143], v[168:171], v[62:65]
	v_mfma_f32_16x16x32_bf16 v[58:61], v[154:157], v[168:171], v[58:61]
	v_mfma_f32_16x16x32_bf16 v[50:53], v[140:143], v[176:179], v[50:53]
	v_mfma_f32_16x16x32_bf16 v[42:45], v[154:157], v[176:179], v[42:45]
	s_mov_b32 m0, s55
	s_nop 0
	global_load_lds_dwordx4 v134, vcc
	v_mfma_f32_16x16x32_bf16 v[34:37], v[140:143], v[184:187], v[34:37]
	v_mfma_f32_16x16x32_bf16 v[26:29], v[154:157], v[184:187], v[26:29]
	v_mfma_f32_16x16x32_bf16 v[18:21], v[140:143], v[208:211], v[18:21]
	v_mfma_f32_16x16x32_bf16 v[10:13], v[154:157], v[208:211], v[10:13]
	v_mfma_f32_16x16x32_bf16 v[62:65], v[144:147], v[172:175], v[62:65]
	v_mfma_f32_16x16x32_bf16 v[58:61], v[158:161], v[172:175], v[58:61]
	s_mov_b32 m0, s83
	s_nop 0
	global_load_lds_dwordx4 v132, vcc
	v_mfma_f32_16x16x32_bf16 v[50:53], v[144:147], v[180:183], v[50:53]
	v_mfma_f32_16x16x32_bf16 v[42:45], v[158:161], v[180:183], v[42:45]
	v_mfma_f32_16x16x32_bf16 v[34:37], v[144:147], v[204:207], v[34:37]
	v_mfma_f32_16x16x32_bf16 v[26:29], v[158:161], v[204:207], v[26:29]
	v_mfma_f32_16x16x32_bf16 v[18:21], v[144:147], v[212:215], v[18:21]
	v_mfma_f32_16x16x32_bf16 v[10:13], v[158:161], v[212:215], v[10:13]
	s_setprio 0
	s_barrier
	s_add_u32 s6, s6, 0x40080
	s_addc_u32 s7, s7, 0
	s_add_i32 s36, s36, s44
	s_waitcnt vmcnt(4)
	s_barrier
	s_setprio 1
	v_mfma_f32_16x16x32_bf16 v[54:57], v[216:219], v[168:171], v[54:57]
	v_mfma_f32_16x16x32_bf16 v[46:49], v[230:233], v[168:171], v[46:49]
	v_mfma_f32_16x16x32_bf16 v[38:41], v[216:219], v[176:179], v[38:41]
	v_mfma_f32_16x16x32_bf16 v[30:33], v[230:233], v[176:179], v[30:33]
	s_mov_b32 m0, s36
	s_nop 0
	global_load_lds_dwordx4 v0, s[6:7]
	v_mfma_f32_16x16x32_bf16 v[22:25], v[216:219], v[184:187], v[22:25]
	v_mfma_f32_16x16x32_bf16 v[14:17], v[230:233], v[184:187], v[14:17]
	v_mfma_f32_16x16x32_bf16 v[6:9], v[216:219], v[208:211], v[6:9]
	v_mfma_f32_16x16x32_bf16 v[2:5], v[230:233], v[208:211], v[2:5]
	v_mfma_f32_16x16x32_bf16 v[54:57], v[226:229], v[172:175], v[54:57]
	v_mfma_f32_16x16x32_bf16 v[46:49], v[234:237], v[172:175], v[46:49]
	s_add_i32 m0, s36, 0x2000
	s_nop 0
	global_load_lds_dwordx4 v130, s[6:7]
	v_mfma_f32_16x16x32_bf16 v[38:41], v[226:229], v[180:183], v[38:41]
	v_mfma_f32_16x16x32_bf16 v[30:33], v[234:237], v[180:183], v[30:33]
	v_mfma_f32_16x16x32_bf16 v[22:25], v[226:229], v[204:207], v[22:25]
	v_mfma_f32_16x16x32_bf16 v[14:17], v[234:237], v[204:207], v[14:17]
	v_mfma_f32_16x16x32_bf16 v[6:9], v[226:229], v[212:215], v[6:9]
	v_mfma_f32_16x16x32_bf16 v[2:5], v[234:237], v[212:215], v[2:5]
	s_setprio 0
	s_add_i32 s91, s91, 2
	s_add_u32 s24, s24, 0x100
	s_addc_u32 s25, s25, 0
	s_add_u32 s89, s89, 0x100
	s_addc_u32 s90, s90, 0
	s_cmp_gt_u32 s91, 13
	s_barrier
	s_add_u32 s6, s24, 0xfffc0080
	s_addc_u32 s7, s25, -1
	s_add_i32 s58, 0, 0x10000
	v_add_u32_e32 v153, s58, v149
	ds_read_b128 v[140:143], v153
	ds_read_b128 v[144:147], v153 offset:1024
	ds_read_b128 v[154:157], v153 offset:2048
	ds_read_b128 v[158:161], v153 offset:3072
	s_cmp_eq_u32 s91, 12
	s_cselect_b32 s37, s11, s7
	s_cselect_b32 s36, s71, s6
	s_cselect_b32 s7, s9, s90
	s_cselect_b32 s6, s88, s89
	ds_read_b128 v[168:171], v152
	ds_read_b128 v[172:175], v152 offset:1024
	ds_read_b128 v[176:179], v152 offset:2048
	ds_read_b128 v[180:183], v152 offset:3072
	ds_read_b128 v[184:187], v152 offset:4096
	ds_read_b128 v[204:207], v152 offset:5120
	ds_read_b128 v[208:211], v152 offset:6144
	ds_read_b128 v[212:215], v152 offset:7168
	s_waitcnt lgkmcnt(8)
	s_barrier
	s_waitcnt lgkmcnt(0)
	s_setprio 1
	s_waitcnt lgkmcnt(0)
	v_mfma_f32_16x16x32_bf16 v[126:129], v[140:143], v[168:171], v[126:129]
	v_mfma_f32_16x16x32_bf16 v[122:125], v[154:157], v[168:171], v[122:125]
	v_mfma_f32_16x16x32_bf16 v[114:117], v[140:143], v[176:179], v[114:117]
	v_mfma_f32_16x16x32_bf16 v[106:109], v[154:157], v[176:179], v[106:109]
	s_add_i32 m0, s47, 0xc000
	s_nop 0
	global_load_lds_dwordx4 v136, s[24:25]
	v_mfma_f32_16x16x32_bf16 v[98:101], v[140:143], v[184:187], v[98:101]
	v_mfma_f32_16x16x32_bf16 v[90:93], v[154:157], v[184:187], v[90:93]
	v_mfma_f32_16x16x32_bf16 v[82:85], v[140:143], v[208:211], v[82:85]
	v_mfma_f32_16x16x32_bf16 v[74:77], v[154:157], v[208:211], v[74:77]
	v_mfma_f32_16x16x32_bf16 v[126:129], v[144:147], v[172:175], v[126:129]
	v_mfma_f32_16x16x32_bf16 v[122:125], v[158:161], v[172:175], v[122:125]
	s_add_i32 m0, s47, 0xe000
	s_nop 0
	global_load_lds_dwordx4 v138, s[24:25]
	v_mfma_f32_16x16x32_bf16 v[114:117], v[144:147], v[180:183], v[114:117]
	v_mfma_f32_16x16x32_bf16 v[106:109], v[158:161], v[180:183], v[106:109]
	v_mfma_f32_16x16x32_bf16 v[98:101], v[144:147], v[204:207], v[98:101]
	v_mfma_f32_16x16x32_bf16 v[90:93], v[158:161], v[204:207], v[90:93]
	v_mfma_f32_16x16x32_bf16 v[82:85], v[144:147], v[212:215], v[82:85]
	v_mfma_f32_16x16x32_bf16 v[74:77], v[158:161], v[212:215], v[74:77]
	s_setprio 0
	s_barrier
	s_add_i32 s70, 0, 0x14000
	s_add_i32 s58, s58, s44
	v_add_u32_e32 v153, s70, v149
	ds_read_b128 v[216:219], v153
	ds_read_b128 v[226:229], v153 offset:1024
	ds_read_b128 v[230:233], v153 offset:2048
	ds_read_b128 v[234:237], v153 offset:3072
	s_barrier
; #define PG8_STAGE(bufoff, gbase, voff) do { _Pragma("unroll") for (int _i = 0; _i < 2; ++_i) \
;         __builtin_amdgcn_global_load_lds((const unsigned*)((const char*)(gbase) + (voff)[_i]), (LAS unsigned*)(lds + (bufoff) + ldsw + _i * 8192), 16, 0, 0); } while (0)
; #define PG8_LDA(dst, b, h) do { _Pragma("unroll") for (int m = 0; m < 4; ++m) _Pragma("unroll") for (int k = 0; k < 2; ++k) dst[m][k] = *(const LAS bf16x8*)(lds + PG8_SA(b, h) + aoff + m * 2048 + k * 1024); } while (0)
; #define PG8_LDB(dst, b, h) do { _Pragma("unroll") for (int n = 0; n < 2; ++n) _Pragma("unroll") for (int k = 0; k < 2; ++k) dst[n][k] = *(const LAS bf16x8*)(lds + PG8_SB(b, h) + boff + n * 2048 + k * 1024); } while (0)
; #define PG8_WAIT_V(n) asm volatile("s_waitcnt vmcnt(" #n ")" ::: "memory")
; #define PG8_WAIT_L(n) asm volatile("s_waitcnt lgkmcnt(" #n ")" ::: "memory")
; #define PG8_BAR __builtin_amdgcn_s_barrier()
; #define PG8_SCHED __builtin_amdgcn_sched_barrier(0)
; template <class Epi>
; __device__ __forceinline__ void gemm_phase(LAS unsigned char* lds, const Gemm g, const StaticOrder& S, const Epi& E) {
;     ...
;             PG8_LDB(B0, 0, 0); PG8_SCHED; PG8_LDA(At, 0, 0); PG8_STAGE(PG8_SA(1, 1), a1 + hstep, voffA);
;             PG8_WAIT_L(8); PG8_BAR; PG8_WAIT_L(0); PG8_MMA(0, 0, At, B0); PG8_BAR; PG8_SCHED;
;             PG8_LDB(B1, 0, 1); PG8_STAGE(PG8_SB(0, 0), b2, voffB);
;             PG8_BAR; PG8_WAIT_L(0); PG8_MMA(0, 1, At, B1); PG8_BAR;
;             PG8_LDA(At, 0, 1); PG8_STAGE(PG8_SA(0, 0), a2, voffA);
;             PG8_BAR; PG8_WAIT_L(0); PG8_MMA(1, 0, At, B0); PG8_BAR; PG8_SCHED;
;             PG8_STAGE(PG8_SB(0, 1), b2 + hstep, voffB);
;             PG8_WAIT_V(6); PG8_BAR; PG8_MMA(1, 1, At, B1); PG8_BAR;
;             PG8_LDB(B0, 1, 0); PG8_SCHED; PG8_LDA(At, 1, 0); PG8_STAGE(PG8_SA(0, 1), a2 + hstep, voffA);
;             PG8_WAIT_L(8); PG8_BAR; PG8_WAIT_L(0); PG8_MMA(0, 0, At, B0); PG8_BAR; PG8_SCHED;
;             PG8_LDB(B1, 1, 1); PG8_STAGE(PG8_SB(1, 0), b3, voffB);
;             PG8_BAR; PG8_WAIT_L(0); PG8_MMA(0, 1, At, B1); PG8_BAR;
;             PG8_LDA(At, 1, 1); PG8_STAGE(PG8_SA(1, 0), a3, voffA);
;             PG8_BAR; PG8_WAIT_L(0); PG8_MMA(1, 0, At, B0); PG8_BAR; PG8_SCHED;
;             PG8_STAGE(PG8_SB(1, 1), b3 + hstep, voffB);
;             PG8_WAIT_V(6); PG8_BAR; PG8_MMA(1, 1, At, B1); PG8_BAR;
	s_waitcnt lgkmcnt(0)
	s_setprio 1
	s_waitcnt lgkmcnt(0)
	v_mfma_f32_16x16x32_bf16 v[118:121], v[216:219], v[168:171], v[118:121]
	v_mfma_f32_16x16x32_bf16 v[110:113], v[230:233], v[168:171], v[110:113]
	v_mfma_f32_16x16x32_bf16 v[102:105], v[216:219], v[176:179], v[102:105]
	v_mfma_f32_16x16x32_bf16 v[94:97], v[230:233], v[176:179], v[94:97]
	s_mov_b32 m0, s58
	s_nop 0
	global_load_lds_dwordx4 v0, s[6:7]
	v_mfma_f32_16x16x32_bf16 v[86:89], v[216:219], v[184:187], v[86:89]
	v_mfma_f32_16x16x32_bf16 v[78:81], v[230:233], v[184:187], v[78:81]
	v_mfma_f32_16x16x32_bf16 v[70:73], v[216:219], v[208:211], v[70:73]
	v_mfma_f32_16x16x32_bf16 v[66:69], v[230:233], v[208:211], v[66:69]
	v_mfma_f32_16x16x32_bf16 v[118:121], v[226:229], v[172:175], v[118:121]
	v_mfma_f32_16x16x32_bf16 v[110:113], v[234:237], v[172:175], v[110:113]
	s_add_i32 m0, s58, 0x2000
	s_nop 0
	global_load_lds_dwordx4 v130, s[6:7]
	v_mfma_f32_16x16x32_bf16 v[102:105], v[226:229], v[180:183], v[102:105]
	v_mfma_f32_16x16x32_bf16 v[94:97], v[234:237], v[180:183], v[94:97]
	v_mfma_f32_16x16x32_bf16 v[86:89], v[226:229], v[204:207], v[86:89]
	v_mfma_f32_16x16x32_bf16 v[78:81], v[234:237], v[204:207], v[78:81]
	v_mfma_f32_16x16x32_bf16 v[70:73], v[226:229], v[212:215], v[70:73]
	v_mfma_f32_16x16x32_bf16 v[66:69], v[234:237], v[212:215], v[66:69]
	s_setprio 0
	s_add_u32 vcc_lo, s36, 0x80
	s_addc_u32 vcc_hi, s37, 0
	s_barrier
	ds_read_b128 v[168:171], v152 offset:16384
	ds_read_b128 v[172:175], v152 offset:17408
	ds_read_b128 v[176:179], v152 offset:18432
	ds_read_b128 v[180:183], v152 offset:19456
	ds_read_b128 v[184:187], v152 offset:20480
	ds_read_b128 v[204:207], v152 offset:21504
	ds_read_b128 v[208:211], v152 offset:22528
	ds_read_b128 v[212:215], v152 offset:23552
	s_barrier
	s_waitcnt lgkmcnt(0)
	s_setprio 1
	s_waitcnt lgkmcnt(0)
	v_mfma_f32_16x16x32_bf16 v[62:65], v[140:143], v[168:171], v[62:65]
	v_mfma_f32_16x16x32_bf16 v[58:61], v[154:157], v[168:171], v[58:61]
	v_mfma_f32_16x16x32_bf16 v[50:53], v[140:143], v[176:179], v[50:53]
	v_mfma_f32_16x16x32_bf16 v[42:45], v[154:157], v[176:179], v[42:45]
	s_mov_b32 m0, s47
	s_nop 0
	global_load_lds_dwordx4 v134, s[36:37]
	v_mfma_f32_16x16x32_bf16 v[34:37], v[140:143], v[184:187], v[34:37]
	v_mfma_f32_16x16x32_bf16 v[26:29], v[154:157], v[184:187], v[26:29]
	v_mfma_f32_16x16x32_bf16 v[18:21], v[140:143], v[208:211], v[18:21]
	v_mfma_f32_16x16x32_bf16 v[10:13], v[154:157], v[208:211], v[10:13]
	v_mfma_f32_16x16x32_bf16 v[62:65], v[144:147], v[172:175], v[62:65]
	v_mfma_f32_16x16x32_bf16 v[58:61], v[158:161], v[172:175], v[58:61]
	s_mov_b32 m0, s48
	s_nop 0
	global_load_lds_dwordx4 v132, s[36:37]
	v_mfma_f32_16x16x32_bf16 v[50:53], v[144:147], v[180:183], v[50:53]
	v_mfma_f32_16x16x32_bf16 v[42:45], v[158:161], v[180:183], v[42:45]
	v_mfma_f32_16x16x32_bf16 v[34:37], v[144:147], v[204:207], v[34:37]
	v_mfma_f32_16x16x32_bf16 v[26:29], v[158:161], v[204:207], v[26:29]
	v_mfma_f32_16x16x32_bf16 v[18:21], v[144:147], v[212:215], v[18:21]
	v_mfma_f32_16x16x32_bf16 v[10:13], v[158:161], v[212:215], v[10:13]
	s_setprio 0
	s_barrier
	s_add_u32 s60, s6, 0x40000
	s_addc_u32 s61, s7, 0
	s_add_i32 s58, s70, s44
	s_waitcnt vmcnt(4)
	s_barrier
	s_setprio 1
	v_mfma_f32_16x16x32_bf16 v[54:57], v[216:219], v[168:171], v[54:57]
	v_mfma_f32_16x16x32_bf16 v[46:49], v[230:233], v[168:171], v[46:49]
	v_mfma_f32_16x16x32_bf16 v[38:41], v[216:219], v[176:179], v[38:41]
	v_mfma_f32_16x16x32_bf16 v[30:33], v[230:233], v[176:179], v[30:33]
	s_mov_b32 m0, s58
	s_nop 0
	global_load_lds_dwordx4 v0, s[60:61]
	v_mfma_f32_16x16x32_bf16 v[22:25], v[216:219], v[184:187], v[22:25]
	v_mfma_f32_16x16x32_bf16 v[14:17], v[230:233], v[184:187], v[14:17]
	v_mfma_f32_16x16x32_bf16 v[6:9], v[216:219], v[208:211], v[6:9]
	v_mfma_f32_16x16x32_bf16 v[2:5], v[230:233], v[208:211], v[2:5]
	v_mfma_f32_16x16x32_bf16 v[54:57], v[226:229], v[172:175], v[54:57]
	v_mfma_f32_16x16x32_bf16 v[46:49], v[234:237], v[172:175], v[46:49]
	s_add_i32 m0, s58, 0x2000
	s_nop 0
	global_load_lds_dwordx4 v130, s[60:61]
	v_mfma_f32_16x16x32_bf16 v[38:41], v[226:229], v[180:183], v[38:41]
	v_mfma_f32_16x16x32_bf16 v[30:33], v[234:237], v[180:183], v[30:33]
	v_mfma_f32_16x16x32_bf16 v[22:25], v[226:229], v[204:207], v[22:25]
	v_mfma_f32_16x16x32_bf16 v[14:17], v[234:237], v[204:207], v[14:17]
	v_mfma_f32_16x16x32_bf16 v[6:9], v[226:229], v[212:215], v[6:9]
	v_mfma_f32_16x16x32_bf16 v[2:5], v[234:237], v[212:215], v[2:5]
	s_setprio 0
	s_add_i32 s58, 0, 0x18000
	v_add_u32_e32 v153, s58, v149
	s_barrier
	ds_read_b128 v[140:143], v153
	ds_read_b128 v[144:147], v153 offset:1024
	ds_read_b128 v[154:157], v153 offset:2048
	ds_read_b128 v[158:161], v153 offset:3072
	s_add_u32 s36, s36, 0x40000
	s_addc_u32 s37, s37, 0
	ds_read_b128 v[168:171], v152 offset:32768
	ds_read_b128 v[172:175], v152 offset:33792
	ds_read_b128 v[176:179], v152 offset:34816
	ds_read_b128 v[180:183], v152 offset:35840
	ds_read_b128 v[184:187], v152 offset:36864
	ds_read_b128 v[204:207], v152 offset:37888
	ds_read_b128 v[208:211], v152 offset:38912
	ds_read_b128 v[212:215], v152 offset:39936
	s_waitcnt lgkmcnt(8)
	s_barrier
	s_waitcnt lgkmcnt(0)
	s_setprio 1
	s_waitcnt lgkmcnt(0)
	v_mfma_f32_16x16x32_bf16 v[126:129], v[140:143], v[168:171], v[126:129]
	v_mfma_f32_16x16x32_bf16 v[122:125], v[154:157], v[168:171], v[122:125]
	s_cmp_eq_u32 s87, 0
	s_cbranch_scc1 .LdsA_skip_5
	global_store_dwordx4 v166, v[222:225], s[4:5] offset:256
	s_nop 1
	v_add_u32_e32 v166, 0xe000, v166
; #define PG8_STAGE(bufoff, gbase, voff) do { _Pragma("unroll") for (int _i = 0; _i < 2; ++_i) \
;         __builtin_amdgcn_global_load_lds((const unsigned*)((const char*)(gbase) + (voff)[_i]), (LAS unsigned*)(lds + (bufoff) + ldsw + _i * 8192), 16, 0, 0); } while (0)
; #define PG8_LDA(dst, b, h) do { _Pragma("unroll") for (int m = 0; m < 4; ++m) _Pragma("unroll") for (int k = 0; k < 2; ++k) dst[m][k] = *(const LAS bf16x8*)(lds + PG8_SA(b, h) + aoff + m * 2048 + k * 1024); } while (0)
; #define PG8_LDB(dst, b, h) do { _Pragma("unroll") for (int n = 0; n < 2; ++n) _Pragma("unroll") for (int k = 0; k < 2; ++k) dst[n][k] = *(const LAS bf16x8*)(lds + PG8_SB(b, h) + boff + n * 2048 + k * 1024); } while (0)
; #define PG8_WAIT_V(n) asm volatile("s_waitcnt vmcnt(" #n ")" ::: "memory")
; #define PG8_WAIT_L(n) asm volatile("s_waitcnt lgkmcnt(" #n ")" ::: "memory")
; #define PG8_BAR __builtin_amdgcn_s_barrier()
; #define PG8_SCHED __builtin_amdgcn_sched_barrier(0)
; template <class Epi>
; __device__ __forceinline__ void gemm_phase(LAS unsigned char* lds, const Gemm g, const StaticOrder& S, const Epi& E) {
;     ...
;             PG8_LDB(B0, 0, 0); PG8_SCHED; PG8_LDA(At, 0, 0); PG8_STAGE(PG8_SA(1, 1), a1 + hstep, voffA);
;             PG8_WAIT_L(8); PG8_BAR; PG8_WAIT_L(0); PG8_MMA(0, 0, At, B0); PG8_BAR; PG8_SCHED;
;             PG8_LDB(B1, 0, 1); PG8_STAGE(PG8_SB(0, 0), b2, voffB);
;             PG8_BAR; PG8_WAIT_L(0); PG8_MMA(0, 1, At, B1); PG8_BAR;
;             PG8_LDA(At, 0, 1); PG8_STAGE(PG8_SA(0, 0), a2, voffA);
;             PG8_BAR; PG8_WAIT_L(0); PG8_MMA(1, 0, At, B0); PG8_BAR; PG8_SCHED;
;             PG8_STAGE(PG8_SB(0, 1), b2 + hstep, voffB);
;             PG8_WAIT_V(6); PG8_BAR; PG8_MMA(1, 1, At, B1); PG8_BAR;
;             PG8_LDB(B0, 1, 0); PG8_SCHED; PG8_LDA(At, 1, 0); PG8_STAGE(PG8_SA(0, 1), a2 + hstep, voffA);
;             PG8_WAIT_L(8); PG8_BAR; PG8_WAIT_L(0); PG8_MMA(0, 0, At, B0); PG8_BAR; PG8_SCHED;
;             PG8_LDB(B1, 1, 1); PG8_STAGE(PG8_SB(1, 0), b3, voffB);
;             PG8_BAR; PG8_WAIT_L(0); PG8_MMA(0, 1, At, B1); PG8_BAR;
;             PG8_LDA(At, 1, 1); PG8_STAGE(PG8_SA(1, 0), a3, voffA);
;             PG8_BAR; PG8_WAIT_L(0); PG8_MMA(1, 0, At, B0); PG8_BAR; PG8_SCHED;
;             PG8_STAGE(PG8_SB(1, 1), b3 + hstep, voffB);
;             PG8_WAIT_V(6); PG8_BAR; PG8_MMA(1, 1, At, B1); PG8_BAR;
.LdsA_skip_5:
	v_mfma_f32_16x16x32_bf16 v[114:117], v[140:143], v[176:179], v[114:117]
	v_mfma_f32_16x16x32_bf16 v[106:109], v[154:157], v[176:179], v[106:109]
	s_mov_b32 m0, s49
	s_nop 0
	global_load_lds_dwordx4 v134, s[36:37]
	v_mfma_f32_16x16x32_bf16 v[98:101], v[140:143], v[184:187], v[98:101]
	v_mfma_f32_16x16x32_bf16 v[90:93], v[154:157], v[184:187], v[90:93]
	v_mfma_f32_16x16x32_bf16 v[82:85], v[140:143], v[208:211], v[82:85]
	v_mfma_f32_16x16x32_bf16 v[74:77], v[154:157], v[208:211], v[74:77]
	v_mfma_f32_16x16x32_bf16 v[126:129], v[144:147], v[172:175], v[126:129]
	v_mfma_f32_16x16x32_bf16 v[122:125], v[158:161], v[172:175], v[122:125]
	s_mov_b32 m0, s54
	s_nop 0
	global_load_lds_dwordx4 v132, s[36:37]
	v_mfma_f32_16x16x32_bf16 v[114:117], v[144:147], v[180:183], v[114:117]
	v_mfma_f32_16x16x32_bf16 v[106:109], v[158:161], v[180:183], v[106:109]
	v_mfma_f32_16x16x32_bf16 v[98:101], v[144:147], v[204:207], v[98:101]
	v_mfma_f32_16x16x32_bf16 v[90:93], v[158:161], v[204:207], v[90:93]
	v_mfma_f32_16x16x32_bf16 v[82:85], v[144:147], v[212:215], v[82:85]
	v_mfma_f32_16x16x32_bf16 v[74:77], v[158:161], v[212:215], v[74:77]
	s_setprio 0
	s_barrier
	s_add_i32 s36, 0, 0x1c000
	s_add_i32 s37, s58, s44
	v_add_u32_e32 v153, s36, v149
	s_add_u32 s60, s6, 0x80
	s_addc_u32 s61, s7, 0
	ds_read_b128 v[216:219], v153
	ds_read_b128 v[226:229], v153 offset:1024
	ds_read_b128 v[230:233], v153 offset:2048
	ds_read_b128 v[234:237], v153 offset:3072
	s_barrier
	s_waitcnt lgkmcnt(0)
	s_setprio 1
	s_waitcnt lgkmcnt(0)
	v_mfma_f32_16x16x32_bf16 v[118:121], v[216:219], v[168:171], v[118:121]
	v_mfma_f32_16x16x32_bf16 v[110:113], v[230:233], v[168:171], v[110:113]
	v_mfma_f32_16x16x32_bf16 v[102:105], v[216:219], v[176:179], v[102:105]
	v_mfma_f32_16x16x32_bf16 v[94:97], v[230:233], v[176:179], v[94:97]
	s_mov_b32 m0, s37
	s_nop 0
	global_load_lds_dwordx4 v0, s[60:61]
	v_mfma_f32_16x16x32_bf16 v[86:89], v[216:219], v[184:187], v[86:89]
	v_mfma_f32_16x16x32_bf16 v[78:81], v[230:233], v[184:187], v[78:81]
	v_mfma_f32_16x16x32_bf16 v[70:73], v[216:219], v[208:211], v[70:73]
	v_mfma_f32_16x16x32_bf16 v[66:69], v[230:233], v[208:211], v[66:69]
	v_mfma_f32_16x16x32_bf16 v[118:121], v[226:229], v[172:175], v[118:121]
	v_mfma_f32_16x16x32_bf16 v[110:113], v[234:237], v[172:175], v[110:113]
	s_add_i32 m0, s37, 0x2000
	s_nop 0
	global_load_lds_dwordx4 v130, s[60:61]
	v_mfma_f32_16x16x32_bf16 v[102:105], v[226:229], v[180:183], v[102:105]
	v_mfma_f32_16x16x32_bf16 v[94:97], v[234:237], v[180:183], v[94:97]
	v_mfma_f32_16x16x32_bf16 v[86:89], v[226:229], v[204:207], v[86:89]
	v_mfma_f32_16x16x32_bf16 v[78:81], v[234:237], v[204:207], v[78:81]
	v_mfma_f32_16x16x32_bf16 v[70:73], v[226:229], v[212:215], v[70:73]
	v_mfma_f32_16x16x32_bf16 v[66:69], v[234:237], v[212:215], v[66:69]
	s_setprio 0
	s_barrier
	ds_read_b128 v[168:171], v152 offset:49152
	ds_read_b128 v[172:175], v152 offset:50176
	ds_read_b128 v[176:179], v152 offset:51200
	ds_read_b128 v[180:183], v152 offset:52224
	ds_read_b128 v[184:187], v152 offset:53248
	ds_read_b128 v[204:207], v152 offset:54272
	ds_read_b128 v[208:211], v152 offset:55296
	ds_read_b128 v[212:215], v152 offset:56320
	s_barrier
	s_waitcnt lgkmcnt(0)
	s_setprio 1
	s_waitcnt lgkmcnt(0)
	v_mfma_f32_16x16x32_bf16 v[62:65], v[140:143], v[168:171], v[62:65]
	v_mfma_f32_16x16x32_bf16 v[58:61], v[154:157], v[168:171], v[58:61]
	v_mfma_f32_16x16x32_bf16 v[50:53], v[140:143], v[176:179], v[50:53]
	v_mfma_f32_16x16x32_bf16 v[42:45], v[154:157], v[176:179], v[42:45]
	s_mov_b32 m0, s55
	s_nop 0
	global_load_lds_dwordx4 v134, vcc
	v_mfma_f32_16x16x32_bf16 v[34:37], v[140:143], v[184:187], v[34:37]
	v_mfma_f32_16x16x32_bf16 v[26:29], v[154:157], v[184:187], v[26:29]
	v_mfma_f32_16x16x32_bf16 v[18:21], v[140:143], v[208:211], v[18:21]
	v_mfma_f32_16x16x32_bf16 v[10:13], v[154:157], v[208:211], v[10:13]
	v_mfma_f32_16x16x32_bf16 v[62:65], v[144:147], v[172:175], v[62:65]
	v_mfma_f32_16x16x32_bf16 v[58:61], v[158:161], v[172:175], v[58:61]
	s_mov_b32 m0, s83
	s_nop 0
	global_load_lds_dwordx4 v132, vcc
	v_mfma_f32_16x16x32_bf16 v[50:53], v[144:147], v[180:183], v[50:53]
	v_mfma_f32_16x16x32_bf16 v[42:45], v[158:161], v[180:183], v[42:45]
	v_mfma_f32_16x16x32_bf16 v[34:37], v[144:147], v[204:207], v[34:37]
	v_mfma_f32_16x16x32_bf16 v[26:29], v[158:161], v[204:207], v[26:29]
	v_mfma_f32_16x16x32_bf16 v[18:21], v[144:147], v[212:215], v[18:21]
	v_mfma_f32_16x16x32_bf16 v[10:13], v[158:161], v[212:215], v[10:13]
	s_setprio 0
	s_barrier
	s_add_u32 s6, s6, 0x40080
	s_addc_u32 s7, s7, 0
	s_add_i32 s36, s36, s44
	s_waitcnt vmcnt(4)
	s_barrier
	s_setprio 1
	v_mfma_f32_16x16x32_bf16 v[54:57], v[216:219], v[168:171], v[54:57]
	v_mfma_f32_16x16x32_bf16 v[46:49], v[230:233], v[168:171], v[46:49]
	v_mfma_f32_16x16x32_bf16 v[38:41], v[216:219], v[176:179], v[38:41]
	v_mfma_f32_16x16x32_bf16 v[30:33], v[230:233], v[176:179], v[30:33]
	s_mov_b32 m0, s36
	s_nop 0
	global_load_lds_dwordx4 v0, s[6:7]
	v_mfma_f32_16x16x32_bf16 v[22:25], v[216:219], v[184:187], v[22:25]
	v_mfma_f32_16x16x32_bf16 v[14:17], v[230:233], v[184:187], v[14:17]
	v_mfma_f32_16x16x32_bf16 v[6:9], v[216:219], v[208:211], v[6:9]
	v_mfma_f32_16x16x32_bf16 v[2:5], v[230:233], v[208:211], v[2:5]
	v_mfma_f32_16x16x32_bf16 v[54:57], v[226:229], v[172:175], v[54:57]
	v_mfma_f32_16x16x32_bf16 v[46:49], v[234:237], v[172:175], v[46:49]
	s_add_i32 m0, s36, 0x2000
	s_nop 0
	global_load_lds_dwordx4 v130, s[6:7]
	v_mfma_f32_16x16x32_bf16 v[38:41], v[226:229], v[180:183], v[38:41]
	v_mfma_f32_16x16x32_bf16 v[30:33], v[234:237], v[180:183], v[30:33]
	v_mfma_f32_16x16x32_bf16 v[22:25], v[226:229], v[204:207], v[22:25]
	v_mfma_f32_16x16x32_bf16 v[14:17], v[234:237], v[204:207], v[14:17]
	v_mfma_f32_16x16x32_bf16 v[6:9], v[226:229], v[212:215], v[6:9]
	v_mfma_f32_16x16x32_bf16 v[2:5], v[234:237], v[212:215], v[2:5]
	s_setprio 0
	s_add_i32 s91, s91, 2
	s_add_u32 s24, s24, 0x100
	s_addc_u32 s25, s25, 0
	s_add_u32 s89, s89, 0x100
	s_addc_u32 s90, s90, 0
	s_cmp_gt_u32 s91, 13
	s_barrier
; #define PG8_STAGE(bufoff, gbase, voff) do { _Pragma("unroll") for (int _i = 0; _i < 2; ++_i) \
;         __builtin_amdgcn_global_load_lds((const unsigned*)((const char*)(gbase) + (voff)[_i]), (LAS unsigned*)(lds + (bufoff) + ldsw + _i * 8192), 16, 0, 0); } while (0)
; #define PG8_LDA(dst, b, h) do { _Pragma("unroll") for (int m = 0; m < 4; ++m) _Pragma("unroll") for (int k = 0; k < 2; ++k) dst[m][k] = *(const LAS bf16x8*)(lds + PG8_SA(b, h) + aoff + m * 2048 + k * 1024); } while (0)
; #define PG8_LDB(dst, b, h) do { _Pragma("unroll") for (int n = 0; n < 2; ++n) _Pragma("unroll") for (int k = 0; k < 2; ++k) dst[n][k] = *(const LAS bf16x8*)(lds + PG8_SB(b, h) + boff + n * 2048 + k * 1024); } while (0)
; #define PG8_WAIT_V(n) asm volatile("s_waitcnt vmcnt(" #n ")" ::: "memory")
; #define PG8_WAIT_L(n) asm volatile("s_waitcnt lgkmcnt(" #n ")" ::: "memory")
; #define PG8_BAR __builtin_amdgcn_s_barrier()
; #define PG8_SCHED __builtin_amdgcn_sched_barrier(0)
; template <class Epi>
; __device__ __forceinline__ void gemm_phase(LAS unsigned char* lds, const Gemm g, const StaticOrder& S, const Epi& E) {
;     ...
;             PG8_LDB(B0, 0, 0); PG8_SCHED; PG8_LDA(At, 0, 0); PG8_STAGE(PG8_SA(1, 1), a1 + hstep, voffA);
;             PG8_WAIT_L(8); PG8_BAR; PG8_WAIT_L(0); PG8_MMA(0, 0, At, B0); PG8_BAR; PG8_SCHED;
;             PG8_LDB(B1, 0, 1); PG8_STAGE(PG8_SB(0, 0), b2, voffB);
;             PG8_BAR; PG8_WAIT_L(0); PG8_MMA(0, 1, At, B1); PG8_BAR;
;             PG8_LDA(At, 0, 1); PG8_STAGE(PG8_SA(0, 0), a2, voffA);
;             PG8_BAR; PG8_WAIT_L(0); PG8_MMA(1, 0, At, B0); PG8_BAR; PG8_SCHED;
;             PG8_STAGE(PG8_SB(0, 1), b2 + hstep, voffB);
;             PG8_WAIT_V(6); PG8_BAR; PG8_MMA(1, 1, At, B1); PG8_BAR;
;             PG8_LDB(B0, 1, 0); PG8_SCHED; PG8_LDA(At, 1, 0); PG8_STAGE(PG8_SA(0, 1), a2 + hstep, voffA);
;             PG8_WAIT_L(8); PG8_BAR; PG8_WAIT_L(0); PG8_MMA(0, 0, At, B0); PG8_BAR; PG8_SCHED;
;             PG8_LDB(B1, 1, 1); PG8_STAGE(PG8_SB(1, 0), b3, voffB);
;             PG8_BAR; PG8_WAIT_L(0); PG8_MMA(0, 1, At, B1); PG8_BAR;
;             PG8_LDA(At, 1, 1); PG8_STAGE(PG8_SA(1, 0), a3, voffA);
;             PG8_BAR; PG8_WAIT_L(0); PG8_MMA(1, 0, At, B0); PG8_BAR; PG8_SCHED;
;             PG8_STAGE(PG8_SB(1, 1), b3 + hstep, voffB);
;             PG8_WAIT_V(6); PG8_BAR; PG8_MMA(1, 1, At, B1); PG8_BAR;
	s_add_u32 s6, s24, 0xfffc0080
	s_addc_u32 s7, s25, -1
	s_add_i32 s58, 0, 0x10000
	v_add_u32_e32 v153, s58, v149
	ds_read_b128 v[140:143], v153
	ds_read_b128 v[144:147], v153 offset:1024
	ds_read_b128 v[154:157], v153 offset:2048
	ds_read_b128 v[158:161], v153 offset:3072
	s_cmp_eq_u32 s91, 12
	s_cselect_b32 s37, s11, s7
	s_cselect_b32 s36, s71, s6
	s_cselect_b32 s7, s9, s90
	s_cselect_b32 s6, s88, s89
	ds_read_b128 v[168:171], v152
	ds_read_b128 v[172:175], v152 offset:1024
	ds_read_b128 v[176:179], v152 offset:2048
	ds_read_b128 v[180:183], v152 offset:3072
	ds_read_b128 v[184:187], v152 offset:4096
	ds_read_b128 v[204:207], v152 offset:5120
	ds_read_b128 v[208:211], v152 offset:6144
	ds_read_b128 v[212:215], v152 offset:7168
	s_waitcnt lgkmcnt(8)
	s_barrier
	s_waitcnt lgkmcnt(0)
	s_setprio 1
	s_waitcnt lgkmcnt(0)
	v_mfma_f32_16x16x32_bf16 v[126:129], v[140:143], v[168:171], v[126:129]
	v_mfma_f32_16x16x32_bf16 v[122:125], v[154:157], v[168:171], v[122:125]
	v_mfma_f32_16x16x32_bf16 v[114:117], v[140:143], v[176:179], v[114:117]
	v_mfma_f32_16x16x32_bf16 v[106:109], v[154:157], v[176:179], v[106:109]
	s_add_i32 m0, s47, 0xc000
	s_nop 0
	global_load_lds_dwordx4 v136, s[24:25]
	v_mfma_f32_16x16x32_bf16 v[98:101], v[140:143], v[184:187], v[98:101]
	v_mfma_f32_16x16x32_bf16 v[90:93], v[154:157], v[184:187], v[90:93]
	v_mfma_f32_16x16x32_bf16 v[82:85], v[140:143], v[208:211], v[82:85]
	v_mfma_f32_16x16x32_bf16 v[74:77], v[154:157], v[208:211], v[74:77]
	v_mfma_f32_16x16x32_bf16 v[126:129], v[144:147], v[172:175], v[126:129]
	v_mfma_f32_16x16x32_bf16 v[122:125], v[158:161], v[172:175], v[122:125]
	s_add_i32 m0, s47, 0xe000
	s_nop 0
	global_load_lds_dwordx4 v138, s[24:25]
	v_mfma_f32_16x16x32_bf16 v[114:117], v[144:147], v[180:183], v[114:117]
	v_mfma_f32_16x16x32_bf16 v[106:109], v[158:161], v[180:183], v[106:109]
	v_mfma_f32_16x16x32_bf16 v[98:101], v[144:147], v[204:207], v[98:101]
	v_mfma_f32_16x16x32_bf16 v[90:93], v[158:161], v[204:207], v[90:93]
	v_mfma_f32_16x16x32_bf16 v[82:85], v[144:147], v[212:215], v[82:85]
	v_mfma_f32_16x16x32_bf16 v[74:77], v[158:161], v[212:215], v[74:77]
	s_setprio 0
	s_barrier
	s_add_i32 s70, 0, 0x14000
	s_add_i32 s58, s58, s44
	v_add_u32_e32 v153, s70, v149
	ds_read_b128 v[216:219], v153
	ds_read_b128 v[226:229], v153 offset:1024
	ds_read_b128 v[230:233], v153 offset:2048
	ds_read_b128 v[234:237], v153 offset:3072
	s_barrier
	s_waitcnt lgkmcnt(0)
	s_setprio 1
	s_waitcnt lgkmcnt(0)
	v_mfma_f32_16x16x32_bf16 v[118:121], v[216:219], v[168:171], v[118:121]
	v_mfma_f32_16x16x32_bf16 v[110:113], v[230:233], v[168:171], v[110:113]
	v_mfma_f32_16x16x32_bf16 v[102:105], v[216:219], v[176:179], v[102:105]
	v_mfma_f32_16x16x32_bf16 v[94:97], v[230:233], v[176:179], v[94:97]
	s_mov_b32 m0, s58
	s_nop 0
	global_load_lds_dwordx4 v0, s[6:7]
	v_mfma_f32_16x16x32_bf16 v[86:89], v[216:219], v[184:187], v[86:89]
	v_mfma_f32_16x16x32_bf16 v[78:81], v[230:233], v[184:187], v[78:81]
	v_mfma_f32_16x16x32_bf16 v[70:73], v[216:219], v[208:211], v[70:73]
	v_mfma_f32_16x16x32_bf16 v[66:69], v[230:233], v[208:211], v[66:69]
	v_mfma_f32_16x16x32_bf16 v[118:121], v[226:229], v[172:175], v[118:121]
	v_mfma_f32_16x16x32_bf16 v[110:113], v[234:237], v[172:175], v[110:113]
	s_add_i32 m0, s58, 0x2000
	s_nop 0
	global_load_lds_dwordx4 v130, s[6:7]
	v_mfma_f32_16x16x32_bf16 v[102:105], v[226:229], v[180:183], v[102:105]
	v_mfma_f32_16x16x32_bf16 v[94:97], v[234:237], v[180:183], v[94:97]
	v_mfma_f32_16x16x32_bf16 v[86:89], v[226:229], v[204:207], v[86:89]
	v_mfma_f32_16x16x32_bf16 v[78:81], v[234:237], v[204:207], v[78:81]
	v_mfma_f32_16x16x32_bf16 v[70:73], v[226:229], v[212:215], v[70:73]
	v_mfma_f32_16x16x32_bf16 v[66:69], v[234:237], v[212:215], v[66:69]
	s_setprio 0
	s_add_u32 vcc_lo, s36, 0x80
	s_addc_u32 vcc_hi, s37, 0
	s_barrier
	ds_read_b128 v[168:171], v152 offset:16384
	ds_read_b128 v[172:175], v152 offset:17408
	ds_read_b128 v[176:179], v152 offset:18432
	ds_read_b128 v[180:183], v152 offset:19456
	ds_read_b128 v[184:187], v152 offset:20480
	ds_read_b128 v[204:207], v152 offset:21504
	ds_read_b128 v[208:211], v152 offset:22528
	ds_read_b128 v[212:215], v152 offset:23552
	s_barrier
	s_waitcnt lgkmcnt(0)
	s_setprio 1
	s_waitcnt lgkmcnt(0)
	v_mfma_f32_16x16x32_bf16 v[62:65], v[140:143], v[168:171], v[62:65]
	v_mfma_f32_16x16x32_bf16 v[58:61], v[154:157], v[168:171], v[58:61]
	v_mfma_f32_16x16x32_bf16 v[50:53], v[140:143], v[176:179], v[50:53]
	v_mfma_f32_16x16x32_bf16 v[42:45], v[154:157], v[176:179], v[42:45]
	s_mov_b32 m0, s47
	s_nop 0
	global_load_lds_dwordx4 v134, s[36:37]
	v_mfma_f32_16x16x32_bf16 v[34:37], v[140:143], v[184:187], v[34:37]
	v_mfma_f32_16x16x32_bf16 v[26:29], v[154:157], v[184:187], v[26:29]
	v_mfma_f32_16x16x32_bf16 v[18:21], v[140:143], v[208:211], v[18:21]
	v_mfma_f32_16x16x32_bf16 v[10:13], v[154:157], v[208:211], v[10:13]
	v_mfma_f32_16x16x32_bf16 v[62:65], v[144:147], v[172:175], v[62:65]
	v_mfma_f32_16x16x32_bf16 v[58:61], v[158:161], v[172:175], v[58:61]
	s_mov_b32 m0, s48
	s_nop 0
	global_load_lds_dwordx4 v132, s[36:37]
	v_mfma_f32_16x16x32_bf16 v[50:53], v[144:147], v[180:183], v[50:53]
	v_mfma_f32_16x16x32_bf16 v[42:45], v[158:161], v[180:183], v[42:45]
	v_mfma_f32_16x16x32_bf16 v[34:37], v[144:147], v[204:207], v[34:37]
	v_mfma_f32_16x16x32_bf16 v[26:29], v[158:161], v[204:207], v[26:29]
	v_mfma_f32_16x16x32_bf16 v[18:21], v[144:147], v[212:215], v[18:21]
	v_mfma_f32_16x16x32_bf16 v[10:13], v[158:161], v[212:215], v[10:13]
	s_setprio 0
	s_barrier
	s_add_u32 s60, s6, 0x40000
	s_addc_u32 s61, s7, 0
	s_add_i32 s58, s70, s44
	s_waitcnt vmcnt(4)
	s_barrier
; #define PG8_STAGE(bufoff, gbase, voff) do { _Pragma("unroll") for (int _i = 0; _i < 2; ++_i) \
;         __builtin_amdgcn_global_load_lds((const unsigned*)((const char*)(gbase) + (voff)[_i]), (LAS unsigned*)(lds + (bufoff) + ldsw + _i * 8192), 16, 0, 0); } while (0)
; #define PG8_LDA(dst, b, h) do { _Pragma("unroll") for (int m = 0; m < 4; ++m) _Pragma("unroll") for (int k = 0; k < 2; ++k) dst[m][k] = *(const LAS bf16x8*)(lds + PG8_SA(b, h) + aoff + m * 2048 + k * 1024); } while (0)
; #define PG8_LDB(dst, b, h) do { _Pragma("unroll") for (int n = 0; n < 2; ++n) _Pragma("unroll") for (int k = 0; k < 2; ++k) dst[n][k] = *(const LAS bf16x8*)(lds + PG8_SB(b, h) + boff + n * 2048 + k * 1024); } while (0)
; #define PG8_WAIT_V(n) asm volatile("s_waitcnt vmcnt(" #n ")" ::: "memory")
; #define PG8_WAIT_L(n) asm volatile("s_waitcnt lgkmcnt(" #n ")" ::: "memory")
; #define PG8_BAR __builtin_amdgcn_s_barrier()
; #define PG8_SCHED __builtin_amdgcn_sched_barrier(0)
; template <class Epi>
; __device__ __forceinline__ void gemm_phase(LAS unsigned char* lds, const Gemm g, const StaticOrder& S, const Epi& E) {
;     ...
;             PG8_LDB(B0, 0, 0); PG8_SCHED; PG8_LDA(At, 0, 0); PG8_STAGE(PG8_SA(1, 1), a1 + hstep, voffA);
;             PG8_WAIT_L(8); PG8_BAR; PG8_WAIT_L(0); PG8_MMA(0, 0, At, B0); PG8_BAR; PG8_SCHED;
;             PG8_LDB(B1, 0, 1); PG8_STAGE(PG8_SB(0, 0), b2, voffB);
;             PG8_BAR; PG8_WAIT_L(0); PG8_MMA(0, 1, At, B1); PG8_BAR;
;             PG8_LDA(At, 0, 1); PG8_STAGE(PG8_SA(0, 0), a2, voffA);
;             PG8_BAR; PG8_WAIT_L(0); PG8_MMA(1, 0, At, B0); PG8_BAR; PG8_SCHED;
;             PG8_STAGE(PG8_SB(0, 1), b2 + hstep, voffB);
;             PG8_WAIT_V(6); PG8_BAR; PG8_MMA(1, 1, At, B1); PG8_BAR;
;             PG8_LDB(B0, 1, 0); PG8_SCHED; PG8_LDA(At, 1, 0); PG8_STAGE(PG8_SA(0, 1), a2 + hstep, voffA);
;             PG8_WAIT_L(8); PG8_BAR; PG8_WAIT_L(0); PG8_MMA(0, 0, At, B0); PG8_BAR; PG8_SCHED;
;             PG8_LDB(B1, 1, 1); PG8_STAGE(PG8_SB(1, 0), b3, voffB);
;             PG8_BAR; PG8_WAIT_L(0); PG8_MMA(0, 1, At, B1); PG8_BAR;
;             PG8_LDA(At, 1, 1); PG8_STAGE(PG8_SA(1, 0), a3, voffA);
;             PG8_BAR; PG8_WAIT_L(0); PG8_MMA(1, 0, At, B0); PG8_BAR; PG8_SCHED;
;             PG8_STAGE(PG8_SB(1, 1), b3 + hstep, voffB);
;             PG8_WAIT_V(6); PG8_BAR; PG8_MMA(1, 1, At, B1); PG8_BAR;
	s_setprio 1
	v_mfma_f32_16x16x32_bf16 v[54:57], v[216:219], v[168:171], v[54:57]
	v_mfma_f32_16x16x32_bf16 v[46:49], v[230:233], v[168:171], v[46:49]
	v_mfma_f32_16x16x32_bf16 v[38:41], v[216:219], v[176:179], v[38:41]
	v_mfma_f32_16x16x32_bf16 v[30:33], v[230:233], v[176:179], v[30:33]
	s_mov_b32 m0, s58
	s_nop 0
	global_load_lds_dwordx4 v0, s[60:61]
	v_mfma_f32_16x16x32_bf16 v[22:25], v[216:219], v[184:187], v[22:25]
	v_mfma_f32_16x16x32_bf16 v[14:17], v[230:233], v[184:187], v[14:17]
	v_mfma_f32_16x16x32_bf16 v[6:9], v[216:219], v[208:211], v[6:9]
	v_mfma_f32_16x16x32_bf16 v[2:5], v[230:233], v[208:211], v[2:5]
	v_mfma_f32_16x16x32_bf16 v[54:57], v[226:229], v[172:175], v[54:57]
	v_mfma_f32_16x16x32_bf16 v[46:49], v[234:237], v[172:175], v[46:49]
	s_add_i32 m0, s58, 0x2000
	s_nop 0
	global_load_lds_dwordx4 v130, s[60:61]
	v_mfma_f32_16x16x32_bf16 v[38:41], v[226:229], v[180:183], v[38:41]
	v_mfma_f32_16x16x32_bf16 v[30:33], v[234:237], v[180:183], v[30:33]
	v_mfma_f32_16x16x32_bf16 v[22:25], v[226:229], v[204:207], v[22:25]
	v_mfma_f32_16x16x32_bf16 v[14:17], v[234:237], v[204:207], v[14:17]
	v_mfma_f32_16x16x32_bf16 v[6:9], v[226:229], v[212:215], v[6:9]
	v_mfma_f32_16x16x32_bf16 v[2:5], v[234:237], v[212:215], v[2:5]
	s_setprio 0
	s_add_i32 s58, 0, 0x18000
	v_add_u32_e32 v153, s58, v149
	s_barrier
	ds_read_b128 v[140:143], v153
	ds_read_b128 v[144:147], v153 offset:1024
	ds_read_b128 v[154:157], v153 offset:2048
	ds_read_b128 v[158:161], v153 offset:3072
	s_add_u32 s36, s36, 0x40000
	s_addc_u32 s37, s37, 0
	ds_read_b128 v[168:171], v152 offset:32768
	ds_read_b128 v[172:175], v152 offset:33792
	ds_read_b128 v[176:179], v152 offset:34816
	ds_read_b128 v[180:183], v152 offset:35840
	ds_read_b128 v[184:187], v152 offset:36864
	ds_read_b128 v[204:207], v152 offset:37888
	ds_read_b128 v[208:211], v152 offset:38912
	ds_read_b128 v[212:215], v152 offset:39936
	s_waitcnt lgkmcnt(8)
	s_barrier
	s_waitcnt lgkmcnt(0)
	s_setprio 1
	s_waitcnt lgkmcnt(0)
	v_mfma_f32_16x16x32_bf16 v[126:129], v[140:143], v[168:171], v[126:129]
	v_mfma_f32_16x16x32_bf16 v[122:125], v[154:157], v[168:171], v[122:125]
	s_cmp_eq_u32 s87, 0
	s_cbranch_scc1 .LdsA_skip_6
	global_store_dwordx4 v166, v[244:247], s[4:5]
.LdsA_skip_6:
	v_mfma_f32_16x16x32_bf16 v[114:117], v[140:143], v[176:179], v[114:117]
	v_mfma_f32_16x16x32_bf16 v[106:109], v[154:157], v[176:179], v[106:109]
	s_mov_b32 m0, s49
	s_nop 0
	global_load_lds_dwordx4 v134, s[36:37]
	v_mfma_f32_16x16x32_bf16 v[98:101], v[140:143], v[184:187], v[98:101]
	v_mfma_f32_16x16x32_bf16 v[90:93], v[154:157], v[184:187], v[90:93]
	v_mfma_f32_16x16x32_bf16 v[82:85], v[140:143], v[208:211], v[82:85]
	v_mfma_f32_16x16x32_bf16 v[74:77], v[154:157], v[208:211], v[74:77]
	v_mfma_f32_16x16x32_bf16 v[126:129], v[144:147], v[172:175], v[126:129]
	v_mfma_f32_16x16x32_bf16 v[122:125], v[158:161], v[172:175], v[122:125]
	s_mov_b32 m0, s54
	s_nop 0
	global_load_lds_dwordx4 v132, s[36:37]
	v_mfma_f32_16x16x32_bf16 v[114:117], v[144:147], v[180:183], v[114:117]
	v_mfma_f32_16x16x32_bf16 v[106:109], v[158:161], v[180:183], v[106:109]
	v_mfma_f32_16x16x32_bf16 v[98:101], v[144:147], v[204:207], v[98:101]
	v_mfma_f32_16x16x32_bf16 v[90:93], v[158:161], v[204:207], v[90:93]
	v_mfma_f32_16x16x32_bf16 v[82:85], v[144:147], v[212:215], v[82:85]
	v_mfma_f32_16x16x32_bf16 v[74:77], v[158:161], v[212:215], v[74:77]
	s_setprio 0
	s_barrier
	s_add_i32 s36, 0, 0x1c000
	s_add_i32 s37, s58, s44
	v_add_u32_e32 v153, s36, v149
	s_add_u32 s60, s6, 0x80
	s_addc_u32 s61, s7, 0
	ds_read_b128 v[216:219], v153
	ds_read_b128 v[226:229], v153 offset:1024
	ds_read_b128 v[230:233], v153 offset:2048
	ds_read_b128 v[234:237], v153 offset:3072
	s_barrier
	s_waitcnt lgkmcnt(0)
	s_setprio 1
	s_waitcnt lgkmcnt(0)
	v_mfma_f32_16x16x32_bf16 v[118:121], v[216:219], v[168:171], v[118:121]
	v_mfma_f32_16x16x32_bf16 v[110:113], v[230:233], v[168:171], v[110:113]
	v_mfma_f32_16x16x32_bf16 v[102:105], v[216:219], v[176:179], v[102:105]
	v_mfma_f32_16x16x32_bf16 v[94:97], v[230:233], v[176:179], v[94:97]
	s_mov_b32 m0, s37
	s_nop 0
	global_load_lds_dwordx4 v0, s[60:61]
	v_mfma_f32_16x16x32_bf16 v[86:89], v[216:219], v[184:187], v[86:89]
	v_mfma_f32_16x16x32_bf16 v[78:81], v[230:233], v[184:187], v[78:81]
	v_mfma_f32_16x16x32_bf16 v[70:73], v[216:219], v[208:211], v[70:73]
	v_mfma_f32_16x16x32_bf16 v[66:69], v[230:233], v[208:211], v[66:69]
	v_mfma_f32_16x16x32_bf16 v[118:121], v[226:229], v[172:175], v[118:121]
	v_mfma_f32_16x16x32_bf16 v[110:113], v[234:237], v[172:175], v[110:113]
	s_add_i32 m0, s37, 0x2000
	s_nop 0
	global_load_lds_dwordx4 v130, s[60:61]
	v_mfma_f32_16x16x32_bf16 v[102:105], v[226:229], v[180:183], v[102:105]
	v_mfma_f32_16x16x32_bf16 v[94:97], v[234:237], v[180:183], v[94:97]
	v_mfma_f32_16x16x32_bf16 v[86:89], v[226:229], v[204:207], v[86:89]
	v_mfma_f32_16x16x32_bf16 v[78:81], v[234:237], v[204:207], v[78:81]
	v_mfma_f32_16x16x32_bf16 v[70:73], v[226:229], v[212:215], v[70:73]
	v_mfma_f32_16x16x32_bf16 v[66:69], v[234:237], v[212:215], v[66:69]
	s_setprio 0
	s_barrier
	ds_read_b128 v[168:171], v152 offset:49152
	ds_read_b128 v[172:175], v152 offset:50176
	ds_read_b128 v[176:179], v152 offset:51200
	ds_read_b128 v[180:183], v152 offset:52224
	ds_read_b128 v[184:187], v152 offset:53248
	ds_read_b128 v[204:207], v152 offset:54272
	ds_read_b128 v[208:211], v152 offset:55296
	ds_read_b128 v[212:215], v152 offset:56320
	s_barrier
; #define PG8_STAGE(bufoff, gbase, voff) do { _Pragma("unroll") for (int _i = 0; _i < 2; ++_i) \
;         __builtin_amdgcn_global_load_lds((const unsigned*)((const char*)(gbase) + (voff)[_i]), (LAS unsigned*)(lds + (bufoff) + ldsw + _i * 8192), 16, 0, 0); } while (0)
; #define PG8_LDA(dst, b, h) do { _Pragma("unroll") for (int m = 0; m < 4; ++m) _Pragma("unroll") for (int k = 0; k < 2; ++k) dst[m][k] = *(const LAS bf16x8*)(lds + PG8_SA(b, h) + aoff + m * 2048 + k * 1024); } while (0)
; #define PG8_LDB(dst, b, h) do { _Pragma("unroll") for (int n = 0; n < 2; ++n) _Pragma("unroll") for (int k = 0; k < 2; ++k) dst[n][k] = *(const LAS bf16x8*)(lds + PG8_SB(b, h) + boff + n * 2048 + k * 1024); } while (0)
; #define PG8_WAIT_V(n) asm volatile("s_waitcnt vmcnt(" #n ")" ::: "memory")
; #define PG8_WAIT_L(n) asm volatile("s_waitcnt lgkmcnt(" #n ")" ::: "memory")
; #define PG8_BAR __builtin_amdgcn_s_barrier()
; #define PG8_SCHED __builtin_amdgcn_sched_barrier(0)
; template <class Epi>
; __device__ __forceinline__ void gemm_phase(LAS unsigned char* lds, const Gemm g, const StaticOrder& S, const Epi& E) {
;     ...
;             PG8_LDB(B0, 0, 0); PG8_SCHED; PG8_LDA(At, 0, 0); PG8_STAGE(PG8_SA(1, 1), a1 + hstep, voffA);
;             PG8_WAIT_L(8); PG8_BAR; PG8_WAIT_L(0); PG8_MMA(0, 0, At, B0); PG8_BAR; PG8_SCHED;
;             PG8_LDB(B1, 0, 1); PG8_STAGE(PG8_SB(0, 0), b2, voffB);
;             PG8_BAR; PG8_WAIT_L(0); PG8_MMA(0, 1, At, B1); PG8_BAR;
;             PG8_LDA(At, 0, 1); PG8_STAGE(PG8_SA(0, 0), a2, voffA);
;             PG8_BAR; PG8_WAIT_L(0); PG8_MMA(1, 0, At, B0); PG8_BAR; PG8_SCHED;
;             PG8_STAGE(PG8_SB(0, 1), b2 + hstep, voffB);
;             PG8_WAIT_V(6); PG8_BAR; PG8_MMA(1, 1, At, B1); PG8_BAR;
;             PG8_LDB(B0, 1, 0); PG8_SCHED; PG8_LDA(At, 1, 0); PG8_STAGE(PG8_SA(0, 1), a2 + hstep, voffA);
;             PG8_WAIT_L(8); PG8_BAR; PG8_WAIT_L(0); PG8_MMA(0, 0, At, B0); PG8_BAR; PG8_SCHED;
;             PG8_LDB(B1, 1, 1); PG8_STAGE(PG8_SB(1, 0), b3, voffB);
;             PG8_BAR; PG8_WAIT_L(0); PG8_MMA(0, 1, At, B1); PG8_BAR;
;             PG8_LDA(At, 1, 1); PG8_STAGE(PG8_SA(1, 0), a3, voffA);
;             PG8_BAR; PG8_WAIT_L(0); PG8_MMA(1, 0, At, B0); PG8_BAR; PG8_SCHED;
;             PG8_STAGE(PG8_SB(1, 1), b3 + hstep, voffB);
;             PG8_WAIT_V(6); PG8_BAR; PG8_MMA(1, 1, At, B1); PG8_BAR;
	s_waitcnt lgkmcnt(0)
	s_setprio 1
	s_waitcnt lgkmcnt(0)
	v_mfma_f32_16x16x32_bf16 v[62:65], v[140:143], v[168:171], v[62:65]
	v_mfma_f32_16x16x32_bf16 v[58:61], v[154:157], v[168:171], v[58:61]
	v_mfma_f32_16x16x32_bf16 v[50:53], v[140:143], v[176:179], v[50:53]
	v_mfma_f32_16x16x32_bf16 v[42:45], v[154:157], v[176:179], v[42:45]
	s_mov_b32 m0, s55
	s_nop 0
	global_load_lds_dwordx4 v134, vcc
	v_mfma_f32_16x16x32_bf16 v[34:37], v[140:143], v[184:187], v[34:37]
	v_mfma_f32_16x16x32_bf16 v[26:29], v[154:157], v[184:187], v[26:29]
	v_mfma_f32_16x16x32_bf16 v[18:21], v[140:143], v[208:211], v[18:21]
	v_mfma_f32_16x16x32_bf16 v[10:13], v[154:157], v[208:211], v[10:13]
	v_mfma_f32_16x16x32_bf16 v[62:65], v[144:147], v[172:175], v[62:65]
	v_mfma_f32_16x16x32_bf16 v[58:61], v[158:161], v[172:175], v[58:61]
	s_mov_b32 m0, s83
	s_nop 0
	global_load_lds_dwordx4 v132, vcc
	v_mfma_f32_16x16x32_bf16 v[50:53], v[144:147], v[180:183], v[50:53]
	v_mfma_f32_16x16x32_bf16 v[42:45], v[158:161], v[180:183], v[42:45]
	v_mfma_f32_16x16x32_bf16 v[34:37], v[144:147], v[204:207], v[34:37]
	v_mfma_f32_16x16x32_bf16 v[26:29], v[158:161], v[204:207], v[26:29]
	v_mfma_f32_16x16x32_bf16 v[18:21], v[144:147], v[212:215], v[18:21]
	v_mfma_f32_16x16x32_bf16 v[10:13], v[158:161], v[212:215], v[10:13]
	s_setprio 0
	s_barrier
	s_add_u32 s6, s6, 0x40080
	s_addc_u32 s7, s7, 0
	s_add_i32 s36, s36, s44
	s_waitcnt vmcnt(4)
	s_barrier
	s_setprio 1
	v_mfma_f32_16x16x32_bf16 v[54:57], v[216:219], v[168:171], v[54:57]
	v_mfma_f32_16x16x32_bf16 v[46:49], v[230:233], v[168:171], v[46:49]
	v_mfma_f32_16x16x32_bf16 v[38:41], v[216:219], v[176:179], v[38:41]
	v_mfma_f32_16x16x32_bf16 v[30:33], v[230:233], v[176:179], v[30:33]
	s_mov_b32 m0, s36
	s_nop 0
	global_load_lds_dwordx4 v0, s[6:7]
	v_mfma_f32_16x16x32_bf16 v[22:25], v[216:219], v[184:187], v[22:25]
	v_mfma_f32_16x16x32_bf16 v[14:17], v[230:233], v[184:187], v[14:17]
	v_mfma_f32_16x16x32_bf16 v[6:9], v[216:219], v[208:211], v[6:9]
	v_mfma_f32_16x16x32_bf16 v[2:5], v[230:233], v[208:211], v[2:5]
	v_mfma_f32_16x16x32_bf16 v[54:57], v[226:229], v[172:175], v[54:57]
	v_mfma_f32_16x16x32_bf16 v[46:49], v[234:237], v[172:175], v[46:49]
	s_add_i32 m0, s36, 0x2000
	s_nop 0
	global_load_lds_dwordx4 v130, s[6:7]
	v_mfma_f32_16x16x32_bf16 v[38:41], v[226:229], v[180:183], v[38:41]
	v_mfma_f32_16x16x32_bf16 v[30:33], v[234:237], v[180:183], v[30:33]
	v_mfma_f32_16x16x32_bf16 v[22:25], v[226:229], v[204:207], v[22:25]
	v_mfma_f32_16x16x32_bf16 v[14:17], v[234:237], v[204:207], v[14:17]
	v_mfma_f32_16x16x32_bf16 v[6:9], v[226:229], v[212:215], v[6:9]
	v_mfma_f32_16x16x32_bf16 v[2:5], v[234:237], v[212:215], v[2:5]
	s_setprio 0
	s_add_i32 s91, s91, 2
	s_add_u32 s24, s24, 0x100
	s_addc_u32 s25, s25, 0
	s_add_u32 s89, s89, 0x100
	s_addc_u32 s90, s90, 0
	s_cmp_gt_u32 s91, 13
	s_barrier
	s_add_u32 s6, s24, 0xfffc0080
	s_addc_u32 s7, s25, -1
	s_add_i32 s58, 0, 0x10000
	v_add_u32_e32 v153, s58, v149
	ds_read_b128 v[140:143], v153
	ds_read_b128 v[144:147], v153 offset:1024
	ds_read_b128 v[154:157], v153 offset:2048
	ds_read_b128 v[158:161], v153 offset:3072
	s_cmp_eq_u32 s91, 12
	s_cselect_b32 s37, s11, s7
	s_cselect_b32 s36, s71, s6
	s_cselect_b32 s7, s9, s90
	s_cselect_b32 s6, s88, s89
	ds_read_b128 v[168:171], v152
	ds_read_b128 v[172:175], v152 offset:1024
	ds_read_b128 v[176:179], v152 offset:2048
	ds_read_b128 v[180:183], v152 offset:3072
	ds_read_b128 v[184:187], v152 offset:4096
	ds_read_b128 v[204:207], v152 offset:5120
	ds_read_b128 v[208:211], v152 offset:6144
	ds_read_b128 v[212:215], v152 offset:7168
	s_waitcnt lgkmcnt(8)
	s_barrier
	s_waitcnt lgkmcnt(0)
	s_setprio 1
	s_waitcnt lgkmcnt(0)
	v_mfma_f32_16x16x32_bf16 v[126:129], v[140:143], v[168:171], v[126:129]
	v_mfma_f32_16x16x32_bf16 v[122:125], v[154:157], v[168:171], v[122:125]
	v_mfma_f32_16x16x32_bf16 v[114:117], v[140:143], v[176:179], v[114:117]
	v_mfma_f32_16x16x32_bf16 v[106:109], v[154:157], v[176:179], v[106:109]
	s_add_i32 m0, s47, 0xc000
	s_nop 0
	global_load_lds_dwordx4 v136, s[24:25]
	v_mfma_f32_16x16x32_bf16 v[98:101], v[140:143], v[184:187], v[98:101]
	v_mfma_f32_16x16x32_bf16 v[90:93], v[154:157], v[184:187], v[90:93]
	v_mfma_f32_16x16x32_bf16 v[82:85], v[140:143], v[208:211], v[82:85]
	v_mfma_f32_16x16x32_bf16 v[74:77], v[154:157], v[208:211], v[74:77]
	v_mfma_f32_16x16x32_bf16 v[126:129], v[144:147], v[172:175], v[126:129]
	v_mfma_f32_16x16x32_bf16 v[122:125], v[158:161], v[172:175], v[122:125]
	s_add_i32 m0, s47, 0xe000
	s_nop 0
	global_load_lds_dwordx4 v138, s[24:25]
	v_mfma_f32_16x16x32_bf16 v[114:117], v[144:147], v[180:183], v[114:117]
	v_mfma_f32_16x16x32_bf16 v[106:109], v[158:161], v[180:183], v[106:109]
	v_mfma_f32_16x16x32_bf16 v[98:101], v[144:147], v[204:207], v[98:101]
	v_mfma_f32_16x16x32_bf16 v[90:93], v[158:161], v[204:207], v[90:93]
	v_mfma_f32_16x16x32_bf16 v[82:85], v[144:147], v[212:215], v[82:85]
	v_mfma_f32_16x16x32_bf16 v[74:77], v[158:161], v[212:215], v[74:77]
	s_setprio 0
	s_barrier
	s_add_i32 s70, 0, 0x14000
	s_add_i32 s58, s58, s44
	v_add_u32_e32 v153, s70, v149
	ds_read_b128 v[216:219], v153
	ds_read_b128 v[226:229], v153 offset:1024
	ds_read_b128 v[230:233], v153 offset:2048
	ds_read_b128 v[234:237], v153 offset:3072
	s_barrier
; #define PG8_STAGE(bufoff, gbase, voff) do { _Pragma("unroll") for (int _i = 0; _i < 2; ++_i) \
;         __builtin_amdgcn_global_load_lds((const unsigned*)((const char*)(gbase) + (voff)[_i]), (LAS unsigned*)(lds + (bufoff) + ldsw + _i * 8192), 16, 0, 0); } while (0)
; #define PG8_LDA(dst, b, h) do { _Pragma("unroll") for (int m = 0; m < 4; ++m) _Pragma("unroll") for (int k = 0; k < 2; ++k) dst[m][k] = *(const LAS bf16x8*)(lds + PG8_SA(b, h) + aoff + m * 2048 + k * 1024); } while (0)
; #define PG8_LDB(dst, b, h) do { _Pragma("unroll") for (int n = 0; n < 2; ++n) _Pragma("unroll") for (int k = 0; k < 2; ++k) dst[n][k] = *(const LAS bf16x8*)(lds + PG8_SB(b, h) + boff + n * 2048 + k * 1024); } while (0)
; #define PG8_WAIT_V(n) asm volatile("s_waitcnt vmcnt(" #n ")" ::: "memory")
; #define PG8_WAIT_L(n) asm volatile("s_waitcnt lgkmcnt(" #n ")" ::: "memory")
; #define PG8_BAR __builtin_amdgcn_s_barrier()
; #define PG8_SCHED __builtin_amdgcn_sched_barrier(0)
; template <class Epi>
; __device__ __forceinline__ void gemm_phase(LAS unsigned char* lds, const Gemm g, const StaticOrder& S, const Epi& E) {
;     ...
;             PG8_LDB(B0, 0, 0); PG8_SCHED; PG8_LDA(At, 0, 0); PG8_STAGE(PG8_SA(1, 1), a1 + hstep, voffA);
;             PG8_WAIT_L(8); PG8_BAR; PG8_WAIT_L(0); PG8_MMA(0, 0, At, B0); PG8_BAR; PG8_SCHED;
;             PG8_LDB(B1, 0, 1); PG8_STAGE(PG8_SB(0, 0), b2, voffB);
;             PG8_BAR; PG8_WAIT_L(0); PG8_MMA(0, 1, At, B1); PG8_BAR;
;             PG8_LDA(At, 0, 1); PG8_STAGE(PG8_SA(0, 0), a2, voffA);
;             PG8_BAR; PG8_WAIT_L(0); PG8_MMA(1, 0, At, B0); PG8_BAR; PG8_SCHED;
;             PG8_STAGE(PG8_SB(0, 1), b2 + hstep, voffB);
;             PG8_WAIT_V(6); PG8_BAR; PG8_MMA(1, 1, At, B1); PG8_BAR;
;             PG8_LDB(B0, 1, 0); PG8_SCHED; PG8_LDA(At, 1, 0); PG8_STAGE(PG8_SA(0, 1), a2 + hstep, voffA);
;             PG8_WAIT_L(8); PG8_BAR; PG8_WAIT_L(0); PG8_MMA(0, 0, At, B0); PG8_BAR; PG8_SCHED;
;             PG8_LDB(B1, 1, 1); PG8_STAGE(PG8_SB(1, 0), b3, voffB);
;             PG8_BAR; PG8_WAIT_L(0); PG8_MMA(0, 1, At, B1); PG8_BAR;
;             PG8_LDA(At, 1, 1); PG8_STAGE(PG8_SA(1, 0), a3, voffA);
;             PG8_BAR; PG8_WAIT_L(0); PG8_MMA(1, 0, At, B0); PG8_BAR; PG8_SCHED;
;             PG8_STAGE(PG8_SB(1, 1), b3 + hstep, voffB);
;             PG8_WAIT_V(6); PG8_BAR; PG8_MMA(1, 1, At, B1); PG8_BAR;
	s_waitcnt lgkmcnt(0)
	s_setprio 1
	s_waitcnt lgkmcnt(0)
	v_mfma_f32_16x16x32_bf16 v[118:121], v[216:219], v[168:171], v[118:121]
	v_mfma_f32_16x16x32_bf16 v[110:113], v[230:233], v[168:171], v[110:113]
	v_mfma_f32_16x16x32_bf16 v[102:105], v[216:219], v[176:179], v[102:105]
	v_mfma_f32_16x16x32_bf16 v[94:97], v[230:233], v[176:179], v[94:97]
	s_mov_b32 m0, s58
	s_nop 0
	global_load_lds_dwordx4 v0, s[6:7]
	v_mfma_f32_16x16x32_bf16 v[86:89], v[216:219], v[184:187], v[86:89]
	v_mfma_f32_16x16x32_bf16 v[78:81], v[230:233], v[184:187], v[78:81]
	v_mfma_f32_16x16x32_bf16 v[70:73], v[216:219], v[208:211], v[70:73]
	v_mfma_f32_16x16x32_bf16 v[66:69], v[230:233], v[208:211], v[66:69]
	v_mfma_f32_16x16x32_bf16 v[118:121], v[226:229], v[172:175], v[118:121]
	v_mfma_f32_16x16x32_bf16 v[110:113], v[234:237], v[172:175], v[110:113]
	s_add_i32 m0, s58, 0x2000
	s_nop 0
	global_load_lds_dwordx4 v130, s[6:7]
	v_mfma_f32_16x16x32_bf16 v[102:105], v[226:229], v[180:183], v[102:105]
	v_mfma_f32_16x16x32_bf16 v[94:97], v[234:237], v[180:183], v[94:97]
	v_mfma_f32_16x16x32_bf16 v[86:89], v[226:229], v[204:207], v[86:89]
	v_mfma_f32_16x16x32_bf16 v[78:81], v[234:237], v[204:207], v[78:81]
	v_mfma_f32_16x16x32_bf16 v[70:73], v[226:229], v[212:215], v[70:73]
	v_mfma_f32_16x16x32_bf16 v[66:69], v[234:237], v[212:215], v[66:69]
	s_setprio 0
	s_add_u32 vcc_lo, s36, 0x80
	s_addc_u32 vcc_hi, s37, 0
	s_barrier
	ds_read_b128 v[168:171], v152 offset:16384
	ds_read_b128 v[172:175], v152 offset:17408
	ds_read_b128 v[176:179], v152 offset:18432
	ds_read_b128 v[180:183], v152 offset:19456
	ds_read_b128 v[184:187], v152 offset:20480
	ds_read_b128 v[204:207], v152 offset:21504
	ds_read_b128 v[208:211], v152 offset:22528
	ds_read_b128 v[212:215], v152 offset:23552
	s_barrier
	s_waitcnt lgkmcnt(0)
	s_setprio 1
	s_waitcnt lgkmcnt(0)
	v_mfma_f32_16x16x32_bf16 v[62:65], v[140:143], v[168:171], v[62:65]
	v_mfma_f32_16x16x32_bf16 v[58:61], v[154:157], v[168:171], v[58:61]
	v_mfma_f32_16x16x32_bf16 v[50:53], v[140:143], v[176:179], v[50:53]
	v_mfma_f32_16x16x32_bf16 v[42:45], v[154:157], v[176:179], v[42:45]
	s_mov_b32 m0, s47
	s_nop 0
	global_load_lds_dwordx4 v134, s[36:37]
	v_mfma_f32_16x16x32_bf16 v[34:37], v[140:143], v[184:187], v[34:37]
	v_mfma_f32_16x16x32_bf16 v[26:29], v[154:157], v[184:187], v[26:29]
	v_mfma_f32_16x16x32_bf16 v[18:21], v[140:143], v[208:211], v[18:21]
	v_mfma_f32_16x16x32_bf16 v[10:13], v[154:157], v[208:211], v[10:13]
	v_mfma_f32_16x16x32_bf16 v[62:65], v[144:147], v[172:175], v[62:65]
	v_mfma_f32_16x16x32_bf16 v[58:61], v[158:161], v[172:175], v[58:61]
	s_mov_b32 m0, s48
	s_nop 0
	global_load_lds_dwordx4 v132, s[36:37]
	v_mfma_f32_16x16x32_bf16 v[50:53], v[144:147], v[180:183], v[50:53]
	v_mfma_f32_16x16x32_bf16 v[42:45], v[158:161], v[180:183], v[42:45]
	v_mfma_f32_16x16x32_bf16 v[34:37], v[144:147], v[204:207], v[34:37]
	v_mfma_f32_16x16x32_bf16 v[26:29], v[158:161], v[204:207], v[26:29]
	v_mfma_f32_16x16x32_bf16 v[18:21], v[144:147], v[212:215], v[18:21]
	v_mfma_f32_16x16x32_bf16 v[10:13], v[158:161], v[212:215], v[10:13]
	s_setprio 0
	s_barrier
	s_add_u32 s60, s6, 0x40000
	s_addc_u32 s61, s7, 0
	s_add_i32 s58, s70, s44
	s_waitcnt vmcnt(4)
	s_barrier
	s_setprio 1
	v_mfma_f32_16x16x32_bf16 v[54:57], v[216:219], v[168:171], v[54:57]
	v_mfma_f32_16x16x32_bf16 v[46:49], v[230:233], v[168:171], v[46:49]
	v_mfma_f32_16x16x32_bf16 v[38:41], v[216:219], v[176:179], v[38:41]
	v_mfma_f32_16x16x32_bf16 v[30:33], v[230:233], v[176:179], v[30:33]
	s_mov_b32 m0, s58
	s_nop 0
	global_load_lds_dwordx4 v0, s[60:61]
	v_mfma_f32_16x16x32_bf16 v[22:25], v[216:219], v[184:187], v[22:25]
	v_mfma_f32_16x16x32_bf16 v[14:17], v[230:233], v[184:187], v[14:17]
	v_mfma_f32_16x16x32_bf16 v[6:9], v[216:219], v[208:211], v[6:9]
	v_mfma_f32_16x16x32_bf16 v[2:5], v[230:233], v[208:211], v[2:5]
	v_mfma_f32_16x16x32_bf16 v[54:57], v[226:229], v[172:175], v[54:57]
	v_mfma_f32_16x16x32_bf16 v[46:49], v[234:237], v[172:175], v[46:49]
	s_add_i32 m0, s58, 0x2000
	s_nop 0
	global_load_lds_dwordx4 v130, s[60:61]
	v_mfma_f32_16x16x32_bf16 v[38:41], v[226:229], v[180:183], v[38:41]
	v_mfma_f32_16x16x32_bf16 v[30:33], v[234:237], v[180:183], v[30:33]
	v_mfma_f32_16x16x32_bf16 v[22:25], v[226:229], v[204:207], v[22:25]
	v_mfma_f32_16x16x32_bf16 v[14:17], v[234:237], v[204:207], v[14:17]
	v_mfma_f32_16x16x32_bf16 v[6:9], v[226:229], v[212:215], v[6:9]
	v_mfma_f32_16x16x32_bf16 v[2:5], v[234:237], v[212:215], v[2:5]
	s_setprio 0
	s_add_i32 s58, 0, 0x18000
	v_add_u32_e32 v153, s58, v149
	s_barrier
	ds_read_b128 v[140:143], v153
	ds_read_b128 v[144:147], v153 offset:1024
	ds_read_b128 v[154:157], v153 offset:2048
	ds_read_b128 v[158:161], v153 offset:3072
	s_add_u32 s36, s36, 0x40000
	s_addc_u32 s37, s37, 0
	ds_read_b128 v[168:171], v152 offset:32768
	ds_read_b128 v[172:175], v152 offset:33792
	ds_read_b128 v[176:179], v152 offset:34816
	ds_read_b128 v[180:183], v152 offset:35840
	ds_read_b128 v[184:187], v152 offset:36864
	ds_read_b128 v[204:207], v152 offset:37888
	ds_read_b128 v[208:211], v152 offset:38912
	ds_read_b128 v[212:215], v152 offset:39936
	s_waitcnt lgkmcnt(8)
	s_barrier
	s_waitcnt lgkmcnt(0)
	s_setprio 1
	s_waitcnt lgkmcnt(0)
	v_mfma_f32_16x16x32_bf16 v[126:129], v[140:143], v[168:171], v[126:129]
	v_mfma_f32_16x16x32_bf16 v[122:125], v[154:157], v[168:171], v[122:125]
	s_cmp_eq_u32 s87, 0
	s_cbranch_scc1 .LdsA_skip_7
	global_store_dwordx4 v166, v[248:251], s[4:5] offset:256
; #define PG8_STAGE(bufoff, gbase, voff) do { _Pragma("unroll") for (int _i = 0; _i < 2; ++_i) \
;         __builtin_amdgcn_global_load_lds((const unsigned*)((const char*)(gbase) + (voff)[_i]), (LAS unsigned*)(lds + (bufoff) + ldsw + _i * 8192), 16, 0, 0); } while (0)
; #define PG8_LDA(dst, b, h) do { _Pragma("unroll") for (int m = 0; m < 4; ++m) _Pragma("unroll") for (int k = 0; k < 2; ++k) dst[m][k] = *(const LAS bf16x8*)(lds + PG8_SA(b, h) + aoff + m * 2048 + k * 1024); } while (0)
; #define PG8_LDB(dst, b, h) do { _Pragma("unroll") for (int n = 0; n < 2; ++n) _Pragma("unroll") for (int k = 0; k < 2; ++k) dst[n][k] = *(const LAS bf16x8*)(lds + PG8_SB(b, h) + boff + n * 2048 + k * 1024); } while (0)
; #define PG8_WAIT_V(n) asm volatile("s_waitcnt vmcnt(" #n ")" ::: "memory")
; #define PG8_WAIT_L(n) asm volatile("s_waitcnt lgkmcnt(" #n ")" ::: "memory")
; #define PG8_BAR __builtin_amdgcn_s_barrier()
; #define PG8_SCHED __builtin_amdgcn_sched_barrier(0)
; template <class Epi>
; __device__ __forceinline__ void gemm_phase(LAS unsigned char* lds, const Gemm g, const StaticOrder& S, const Epi& E) {
;     ...
;             PG8_LDB(B0, 0, 0); PG8_SCHED; PG8_LDA(At, 0, 0); PG8_STAGE(PG8_SA(1, 1), a1 + hstep, voffA);
;             PG8_WAIT_L(8); PG8_BAR; PG8_WAIT_L(0); PG8_MMA(0, 0, At, B0); PG8_BAR; PG8_SCHED;
;             PG8_LDB(B1, 0, 1); PG8_STAGE(PG8_SB(0, 0), b2, voffB);
;             PG8_BAR; PG8_WAIT_L(0); PG8_MMA(0, 1, At, B1); PG8_BAR;
;             PG8_LDA(At, 0, 1); PG8_STAGE(PG8_SA(0, 0), a2, voffA);
;             PG8_BAR; PG8_WAIT_L(0); PG8_MMA(1, 0, At, B0); PG8_BAR; PG8_SCHED;
;             PG8_STAGE(PG8_SB(0, 1), b2 + hstep, voffB);
;             PG8_WAIT_V(6); PG8_BAR; PG8_MMA(1, 1, At, B1); PG8_BAR;
;             PG8_LDB(B0, 1, 0); PG8_SCHED; PG8_LDA(At, 1, 0); PG8_STAGE(PG8_SA(0, 1), a2 + hstep, voffA);
;             PG8_WAIT_L(8); PG8_BAR; PG8_WAIT_L(0); PG8_MMA(0, 0, At, B0); PG8_BAR; PG8_SCHED;
;             PG8_LDB(B1, 1, 1); PG8_STAGE(PG8_SB(1, 0), b3, voffB);
;             PG8_BAR; PG8_WAIT_L(0); PG8_MMA(0, 1, At, B1); PG8_BAR;
;             PG8_LDA(At, 1, 1); PG8_STAGE(PG8_SA(1, 0), a3, voffA);
;             PG8_BAR; PG8_WAIT_L(0); PG8_MMA(1, 0, At, B0); PG8_BAR; PG8_SCHED;
;             PG8_STAGE(PG8_SB(1, 1), b3 + hstep, voffB);
;             PG8_WAIT_V(6); PG8_BAR; PG8_MMA(1, 1, At, B1); PG8_BAR;
.LdsA_skip_7:
	v_mfma_f32_16x16x32_bf16 v[114:117], v[140:143], v[176:179], v[114:117]
	v_mfma_f32_16x16x32_bf16 v[106:109], v[154:157], v[176:179], v[106:109]
	s_mov_b32 m0, s49
	s_nop 0
	global_load_lds_dwordx4 v134, s[36:37]
	v_mfma_f32_16x16x32_bf16 v[98:101], v[140:143], v[184:187], v[98:101]
	v_mfma_f32_16x16x32_bf16 v[90:93], v[154:157], v[184:187], v[90:93]
	v_mfma_f32_16x16x32_bf16 v[82:85], v[140:143], v[208:211], v[82:85]
	v_mfma_f32_16x16x32_bf16 v[74:77], v[154:157], v[208:211], v[74:77]
	v_mfma_f32_16x16x32_bf16 v[126:129], v[144:147], v[172:175], v[126:129]
	v_mfma_f32_16x16x32_bf16 v[122:125], v[158:161], v[172:175], v[122:125]
	s_mov_b32 m0, s54
	s_nop 0
	global_load_lds_dwordx4 v132, s[36:37]
	v_mfma_f32_16x16x32_bf16 v[114:117], v[144:147], v[180:183], v[114:117]
	v_mfma_f32_16x16x32_bf16 v[106:109], v[158:161], v[180:183], v[106:109]
	v_mfma_f32_16x16x32_bf16 v[98:101], v[144:147], v[204:207], v[98:101]
	v_mfma_f32_16x16x32_bf16 v[90:93], v[158:161], v[204:207], v[90:93]
	v_mfma_f32_16x16x32_bf16 v[82:85], v[144:147], v[212:215], v[82:85]
	v_mfma_f32_16x16x32_bf16 v[74:77], v[158:161], v[212:215], v[74:77]
	s_setprio 0
	s_barrier
	s_add_i32 s36, 0, 0x1c000
	s_add_i32 s37, s58, s44
	v_add_u32_e32 v153, s36, v149
	s_add_u32 s60, s6, 0x80
	s_addc_u32 s61, s7, 0
	ds_read_b128 v[216:219], v153
	ds_read_b128 v[226:229], v153 offset:1024
	ds_read_b128 v[230:233], v153 offset:2048
	ds_read_b128 v[234:237], v153 offset:3072
	s_barrier
	s_waitcnt lgkmcnt(0)
	s_setprio 1
	s_waitcnt lgkmcnt(0)
	v_mfma_f32_16x16x32_bf16 v[118:121], v[216:219], v[168:171], v[118:121]
	v_mfma_f32_16x16x32_bf16 v[110:113], v[230:233], v[168:171], v[110:113]
	v_mfma_f32_16x16x32_bf16 v[102:105], v[216:219], v[176:179], v[102:105]
	v_mfma_f32_16x16x32_bf16 v[94:97], v[230:233], v[176:179], v[94:97]
	s_mov_b32 m0, s37
	s_nop 0
	global_load_lds_dwordx4 v0, s[60:61]
	v_mfma_f32_16x16x32_bf16 v[86:89], v[216:219], v[184:187], v[86:89]
	v_mfma_f32_16x16x32_bf16 v[78:81], v[230:233], v[184:187], v[78:81]
	v_mfma_f32_16x16x32_bf16 v[70:73], v[216:219], v[208:211], v[70:73]
	v_mfma_f32_16x16x32_bf16 v[66:69], v[230:233], v[208:211], v[66:69]
	v_mfma_f32_16x16x32_bf16 v[118:121], v[226:229], v[172:175], v[118:121]
	v_mfma_f32_16x16x32_bf16 v[110:113], v[234:237], v[172:175], v[110:113]
	s_add_i32 m0, s37, 0x2000
	s_nop 0
	global_load_lds_dwordx4 v130, s[60:61]
	v_mfma_f32_16x16x32_bf16 v[102:105], v[226:229], v[180:183], v[102:105]
	v_mfma_f32_16x16x32_bf16 v[94:97], v[234:237], v[180:183], v[94:97]
	v_mfma_f32_16x16x32_bf16 v[86:89], v[226:229], v[204:207], v[86:89]
	v_mfma_f32_16x16x32_bf16 v[78:81], v[234:237], v[204:207], v[78:81]
	v_mfma_f32_16x16x32_bf16 v[70:73], v[226:229], v[212:215], v[70:73]
	v_mfma_f32_16x16x32_bf16 v[66:69], v[234:237], v[212:215], v[66:69]
	s_setprio 0
	s_barrier
	ds_read_b128 v[168:171], v152 offset:49152
	ds_read_b128 v[172:175], v152 offset:50176
	ds_read_b128 v[176:179], v152 offset:51200
	ds_read_b128 v[180:183], v152 offset:52224
	ds_read_b128 v[184:187], v152 offset:53248
	ds_read_b128 v[204:207], v152 offset:54272
	ds_read_b128 v[208:211], v152 offset:55296
	ds_read_b128 v[212:215], v152 offset:56320
	s_barrier
	s_waitcnt lgkmcnt(0)
	s_setprio 1
	s_waitcnt lgkmcnt(0)
	v_mfma_f32_16x16x32_bf16 v[62:65], v[140:143], v[168:171], v[62:65]
	v_mfma_f32_16x16x32_bf16 v[58:61], v[154:157], v[168:171], v[58:61]
	v_mfma_f32_16x16x32_bf16 v[50:53], v[140:143], v[176:179], v[50:53]
	v_mfma_f32_16x16x32_bf16 v[42:45], v[154:157], v[176:179], v[42:45]
	s_mov_b32 m0, s55
	s_nop 0
	global_load_lds_dwordx4 v134, vcc
	v_mfma_f32_16x16x32_bf16 v[34:37], v[140:143], v[184:187], v[34:37]
	v_mfma_f32_16x16x32_bf16 v[26:29], v[154:157], v[184:187], v[26:29]
	v_mfma_f32_16x16x32_bf16 v[18:21], v[140:143], v[208:211], v[18:21]
	v_mfma_f32_16x16x32_bf16 v[10:13], v[154:157], v[208:211], v[10:13]
	v_mfma_f32_16x16x32_bf16 v[62:65], v[144:147], v[172:175], v[62:65]
	v_mfma_f32_16x16x32_bf16 v[58:61], v[158:161], v[172:175], v[58:61]
	s_mov_b32 m0, s83
	s_nop 0
	global_load_lds_dwordx4 v132, vcc
	v_mfma_f32_16x16x32_bf16 v[50:53], v[144:147], v[180:183], v[50:53]
	v_mfma_f32_16x16x32_bf16 v[42:45], v[158:161], v[180:183], v[42:45]
	v_mfma_f32_16x16x32_bf16 v[34:37], v[144:147], v[204:207], v[34:37]
	v_mfma_f32_16x16x32_bf16 v[26:29], v[158:161], v[204:207], v[26:29]
	v_mfma_f32_16x16x32_bf16 v[18:21], v[144:147], v[212:215], v[18:21]
	v_mfma_f32_16x16x32_bf16 v[10:13], v[158:161], v[212:215], v[10:13]
	s_setprio 0
	s_barrier
	s_add_u32 s6, s6, 0x40080
	s_addc_u32 s7, s7, 0
	s_add_i32 s36, s36, s44
	s_waitcnt vmcnt(4)
	s_barrier
	s_setprio 1
	v_mfma_f32_16x16x32_bf16 v[54:57], v[216:219], v[168:171], v[54:57]
	v_mfma_f32_16x16x32_bf16 v[46:49], v[230:233], v[168:171], v[46:49]
	v_mfma_f32_16x16x32_bf16 v[38:41], v[216:219], v[176:179], v[38:41]
	v_mfma_f32_16x16x32_bf16 v[30:33], v[230:233], v[176:179], v[30:33]
	s_mov_b32 m0, s36
	s_nop 0
	global_load_lds_dwordx4 v0, s[6:7]
	v_mfma_f32_16x16x32_bf16 v[22:25], v[216:219], v[184:187], v[22:25]
	v_mfma_f32_16x16x32_bf16 v[14:17], v[230:233], v[184:187], v[14:17]
	v_mfma_f32_16x16x32_bf16 v[6:9], v[216:219], v[208:211], v[6:9]
	v_mfma_f32_16x16x32_bf16 v[2:5], v[230:233], v[208:211], v[2:5]
	v_mfma_f32_16x16x32_bf16 v[54:57], v[226:229], v[172:175], v[54:57]
	v_mfma_f32_16x16x32_bf16 v[46:49], v[234:237], v[172:175], v[46:49]
	s_add_i32 m0, s36, 0x2000
	s_nop 0
	global_load_lds_dwordx4 v130, s[6:7]
	v_mfma_f32_16x16x32_bf16 v[38:41], v[226:229], v[180:183], v[38:41]
	v_mfma_f32_16x16x32_bf16 v[30:33], v[234:237], v[180:183], v[30:33]
	v_mfma_f32_16x16x32_bf16 v[22:25], v[226:229], v[204:207], v[22:25]
	v_mfma_f32_16x16x32_bf16 v[14:17], v[234:237], v[204:207], v[14:17]
	v_mfma_f32_16x16x32_bf16 v[6:9], v[226:229], v[212:215], v[6:9]
	v_mfma_f32_16x16x32_bf16 v[2:5], v[234:237], v[212:215], v[2:5]
	s_setprio 0
	s_add_i32 s91, s91, 2
	s_add_u32 s24, s24, 0x100
	s_addc_u32 s25, s25, 0
	s_add_u32 s89, s89, 0x100
	s_addc_u32 s90, s90, 0
	s_cmp_gt_u32 s91, 13
	s_barrier
; __device__ __forceinline__ unsigned pk2(float lo, float hi) { unsigned r; asm("v_cvt_pk_bf16_f32 %0, %1, %2" : "=v"(r) : "v"(lo), "v"(hi)); return r; }
;     __device__ __forceinline__ void operator()(const f32x4 (&acc)[2][2][4][2], const Unit& u, int ui, int wr, int wc, int fr, int fq) const {
;         const int lrow0 = wr * 64 + fr, row0 = u.pm * BM + lrow0, col0 = u.pn * BM + wc * 32 + 8 * fq;
;         float rsv[2][4];
; #pragma unroll
;         for (int ai = 0; ai < 2; ++ai)
; #pragma unroll
;             for (int m = 0; m < 4; ++m) rsv[ai][m] = rstab[ui * 256 + lrow0 + ai * HALF + m * 16];
; #pragma unroll
;         for (int ai = 0; ai < 2; ++ai)
; #pragma unroll
;             for (int m = 0; m < 4; ++m) {
;                 const int row = row0 + ai * HALF + m * 16; const float rs = rsv[ai][m];
;                 bf16_t* rowp = O + (size_t)row * ldc + col0;
; #pragma unroll
;                 for (int bj = 0; bj < 2; ++bj) {
;                     f32x4 v0 = acc[ai][bj][m][0] * rs, v1 = acc[ai][bj][m][1] * rs;
;                     if (ACT == 1) {
; #pragma unroll
;                         for (int j = 0; j < 4; ++j) { const float a = fmaxf(v0[j], 0.f), b = fmaxf(v1[j], 0.f); v0[j] = a * a; v1[j] = b * b; }
;                     }
;                     u32x4 w; w.x = pk2(v0[0], v0[1]); w.y = pk2(v0[2], v0[3]); w.z = pk2(v1[0], v1[1]); w.w = pk2(v1[2], v1[3]);
;                     *(u32x4*)(rowp + bj * HALF) = w;
	v_lshl_add_u32 v140, s87, 10, v150
	v_lshl_or_b32 v144, s85, 8, v151
	v_lshl_add_u32 v153, s86, 8, v148
	v_mul_u32_u24_e32 v166, 0xe00, v153
	v_lshl_add_u32 v166, v144, 1, v166
	v_add_u32_e32 v166, 0x70000, v166
	ds_read2_b32 v[154:155], v140 offset1:16
	ds_read2_b32 v[156:157], v140 offset0:32 offset1:48
	ds_read2_b32 v[146:147], v140 offset0:128 offset1:144
	ds_read2_b32 v[140:141], v140 offset0:160 offset1:176
	v_ashrrev_i32_e32 v145, 31, v144
	v_mov_b64_e32 v[142:143], s[4:5]
	v_mad_i64_i32 v[158:159], s[6:7], v153, s65, v[142:143]
	v_lshlrev_b64 v[144:145], 1, v[144:145]
	v_lshl_add_u64 v[158:159], v[158:159], 0, v[144:145]
	s_waitcnt lgkmcnt(0)
	v_pk_mul_f32 v[128:129], v[128:129], v[154:155] op_sel_hi:[1,0]
	v_pk_mul_f32 v[126:127], v[126:127], v[154:155] op_sel_hi:[1,0]
	v_pk_mul_f32 v[160:161], v[124:125], v[154:155] op_sel_hi:[1,0]
	v_pk_mul_f32 v[124:125], v[122:123], v[154:155] op_sel_hi:[1,0]
	v_cvt_pk_bf16_f32 v122, v126, v127
	v_cvt_pk_bf16_f32 v123, v128, v129
	v_pk_mul_f32 v[118:119], v[118:119], v[154:155] op_sel_hi:[1,0]
	v_cvt_pk_bf16_f32 v124, v124, v125
	v_cvt_pk_bf16_f32 v125, v160, v161
	global_store_dwordx4 v[158:159], v[122:125], off
	v_pk_mul_f32 v[120:121], v[120:121], v[154:155] op_sel_hi:[1,0]
	v_pk_mul_f32 v[98:99], v[98:99], v[156:157] op_sel_hi:[1,0]
	v_pk_mul_f32 v[122:123], v[112:113], v[154:155] op_sel_hi:[1,0]
	v_pk_mul_f32 v[112:113], v[110:111], v[154:155] op_sel_hi:[1,0]
	v_cvt_pk_bf16_f32 v110, v118, v119
	v_cvt_pk_bf16_f32 v111, v120, v121
	v_pk_mul_f32 v[86:87], v[86:87], v[156:157] op_sel_hi:[1,0]
	v_cvt_pk_bf16_f32 v112, v112, v113
	v_cvt_pk_bf16_f32 v113, v122, v123
	global_store_dwordx4 v[158:159], v[110:113], off offset:256
	v_pk_mul_f32 v[88:89], v[88:89], v[156:157] op_sel_hi:[1,0]
	v_pk_mul_f32 v[64:65], v[64:65], v[146:147] op_sel_hi:[1,0]
	v_or_b32_e32 v110, 16, v153
	v_mad_i64_i32 v[110:111], s[6:7], v110, s65, v[142:143]
	v_mov_b32_e32 v112, v155
	v_lshl_add_u64 v[110:111], v[110:111], 0, v[144:145]
	v_pk_mul_f32 v[116:117], v[116:117], v[112:113] op_sel_hi:[1,0]
	v_pk_mul_f32 v[114:115], v[114:115], v[112:113] op_sel_hi:[1,0]
	v_pk_mul_f32 v[118:119], v[108:109], v[112:113] op_sel_hi:[1,0]
	v_pk_mul_f32 v[108:109], v[106:107], v[112:113] op_sel_hi:[1,0]
	v_cvt_pk_bf16_f32 v106, v114, v115
	v_cvt_pk_bf16_f32 v107, v116, v117
	v_pk_mul_f32 v[102:103], v[102:103], v[112:113] op_sel_hi:[1,0]
	v_cvt_pk_bf16_f32 v108, v108, v109
	v_cvt_pk_bf16_f32 v109, v118, v119
	global_store_dwordx4 v[110:111], v[106:109], off
	v_pk_mul_f32 v[104:105], v[104:105], v[112:113] op_sel_hi:[1,0]
	v_pk_mul_f32 v[62:63], v[62:63], v[146:147] op_sel_hi:[1,0]
	v_pk_mul_f32 v[106:107], v[96:97], v[112:113] op_sel_hi:[1,0]
	v_pk_mul_f32 v[96:97], v[94:95], v[112:113] op_sel_hi:[1,0]
	v_cvt_pk_bf16_f32 v94, v102, v103
	v_cvt_pk_bf16_f32 v95, v104, v105
	v_pk_mul_f32 v[54:55], v[54:55], v[146:147] op_sel_hi:[1,0]
	v_cvt_pk_bf16_f32 v96, v96, v97
	v_cvt_pk_bf16_f32 v97, v106, v107
	global_store_dwordx4 v[110:111], v[94:97], off offset:256
	v_pk_mul_f32 v[56:57], v[56:57], v[146:147] op_sel_hi:[1,0]
	v_pk_mul_f32 v[34:35], v[34:35], v[140:141] op_sel_hi:[1,0]
	v_or_b32_e32 v94, 32, v153
	v_mad_i64_i32 v[94:95], s[6:7], v94, s65, v[142:143]
	v_lshl_add_u64 v[94:95], v[94:95], 0, v[144:145]
	v_pk_mul_f32 v[96:97], v[100:101], v[156:157] op_sel_hi:[1,0]
	v_pk_mul_f32 v[100:101], v[92:93], v[156:157] op_sel_hi:[1,0]
	v_pk_mul_f32 v[92:93], v[90:91], v[156:157] op_sel_hi:[1,0]
	v_cvt_pk_bf16_f32 v90, v98, v99
	v_cvt_pk_bf16_f32 v91, v96, v97
	v_pk_mul_f32 v[22:23], v[22:23], v[140:141] op_sel_hi:[1,0]
	v_cvt_pk_bf16_f32 v92, v92, v93
	v_cvt_pk_bf16_f32 v93, v100, v101
	global_store_dwordx4 v[94:95], v[90:93], off
	v_pk_mul_f32 v[24:25], v[24:25], v[140:141] op_sel_hi:[1,0]
	s_and_b64 vcc, exec, s[40:41]
	v_pk_mul_f32 v[90:91], v[80:81], v[156:157] op_sel_hi:[1,0]
	v_pk_mul_f32 v[80:81], v[78:79], v[156:157] op_sel_hi:[1,0]
	v_cvt_pk_bf16_f32 v78, v86, v87
	v_cvt_pk_bf16_f32 v79, v88, v89
	s_mov_b32 s85, s8
	v_cvt_pk_bf16_f32 v80, v80, v81
	v_cvt_pk_bf16_f32 v81, v90, v91
	global_store_dwordx4 v[94:95], v[78:81], off offset:256
	s_mov_b32 s86, s10
	s_mov_b64 s[24:25], s[12:13]
	v_or_b32_e32 v78, 48, v153
	v_mad_i64_i32 v[78:79], s[6:7], v78, s65, v[142:143]
	v_mov_b32_e32 v80, v157
	v_lshl_add_u64 v[78:79], v[78:79], 0, v[144:145]
	v_pk_mul_f32 v[84:85], v[84:85], v[80:81] op_sel_hi:[1,0]
	v_pk_mul_f32 v[82:83], v[82:83], v[80:81] op_sel_hi:[1,0]
	v_pk_mul_f32 v[86:87], v[76:77], v[80:81] op_sel_hi:[1,0]
	v_pk_mul_f32 v[76:77], v[74:75], v[80:81] op_sel_hi:[1,0]
	v_cvt_pk_bf16_f32 v74, v82, v83
	v_cvt_pk_bf16_f32 v75, v84, v85
	v_pk_mul_f32 v[70:71], v[70:71], v[80:81] op_sel_hi:[1,0]
	v_cvt_pk_bf16_f32 v76, v76, v77
	v_cvt_pk_bf16_f32 v77, v86, v87
	global_store_dwordx4 v[78:79], v[74:77], off
	v_pk_mul_f32 v[72:73], v[72:73], v[80:81] op_sel_hi:[1,0]
	s_mov_b32 s87, s84
	v_pk_mul_f32 v[74:75], v[68:69], v[80:81] op_sel_hi:[1,0]
	v_pk_mul_f32 v[68:69], v[66:67], v[80:81] op_sel_hi:[1,0]
	v_cvt_pk_bf16_f32 v66, v70, v71
	v_cvt_pk_bf16_f32 v67, v72, v73
	s_nop 0
	v_cvt_pk_bf16_f32 v68, v68, v69
	v_cvt_pk_bf16_f32 v69, v74, v75
	global_store_dwordx4 v[78:79], v[66:69], off offset:256
	s_nop 1
	v_add_u32_e32 v66, 0x80, v153
	v_mad_i64_i32 v[66:67], s[6:7], v66, s65, v[142:143]
	v_lshl_add_u64 v[66:67], v[66:67], 0, v[144:145]
; __device__ __forceinline__ unsigned pk2(float lo, float hi) { unsigned r; asm("v_cvt_pk_bf16_f32 %0, %1, %2" : "=v"(r) : "v"(lo), "v"(hi)); return r; }
; #define PG8_WAIT_V(n) asm volatile("s_waitcnt vmcnt(" #n ")" ::: "memory")
; #define PG8_BAR __builtin_amdgcn_s_barrier()
;     __device__ __forceinline__ void operator()(const f32x4 (&acc)[2][2][4][2], const Unit& u, int ui, int wr, int wc, int fr, int fq) const {
;     ...
;         for (int ai = 0; ai < 2; ++ai)
; #pragma unroll
;             for (int m = 0; m < 4; ++m) {
;                 const int row = row0 + ai * HALF + m * 16; const float rs = rsv[ai][m];
;                 bf16_t* rowp = O + (size_t)row * ldc + col0;
; #pragma unroll
;                 for (int bj = 0; bj < 2; ++bj) {
;                     f32x4 v0 = acc[ai][bj][m][0] * rs, v1 = acc[ai][bj][m][1] * rs;
;                     if (ACT == 1) {
; #pragma unroll
;                         for (int j = 0; j < 4; ++j) { const float a = fmaxf(v0[j], 0.f), b = fmaxf(v1[j], 0.f); v0[j] = a * a; v1[j] = b * b; }
;                     }
;                     u32x4 w; w.x = pk2(v0[0], v0[1]); w.y = pk2(v0[2], v0[3]); w.z = pk2(v1[0], v1[1]); w.w = pk2(v1[2], v1[3]);
;                     *(u32x4*)(rowp + bj * HALF) = w;
;                 }
; template <class Epi>
; __device__ __forceinline__ void gemm_phase(LAS unsigned char* lds, const Gemm g, const StaticOrder& S, const Epi& E) {
;     ...
;         E(acc, cur, ui, wr, wc, fr, fq);
;         if (!has_next) break;
; #pragma unroll
;         for (int a = 0; a < 2; ++a)
; #pragma unroll
;             for (int b = 0; b < 2; ++b)
; #pragma unroll
;                 for (int m = 0; m < 4; ++m)
; #pragma unroll
;                     for (int n = 0; n < 2; ++n) acc[a][b][m][n] = (f32x4){0.f, 0.f, 0.f, 0.f};
;         cur = nxt; cA = nA; cB = nB; ++ui;
;     }
;     PG8_WAIT_V(0);
;     if (wr == 0) PG8_BAR;
;     PG8_BAR;
	v_pk_mul_f32 v[68:69], v[60:61], v[146:147] op_sel_hi:[1,0]
	v_pk_mul_f32 v[60:61], v[58:59], v[146:147] op_sel_hi:[1,0]
	v_cvt_pk_bf16_f32 v58, v62, v63
	v_cvt_pk_bf16_f32 v59, v64, v65
	s_nop 0
	v_cvt_pk_bf16_f32 v60, v60, v61
	v_cvt_pk_bf16_f32 v61, v68, v69
	v_mov_b32_e32 v162, v58
	v_mov_b32_e32 v163, v59
	v_mov_b32_e32 v164, v60
	v_mov_b32_e32 v165, v61
	s_nop 1
	v_pk_mul_f32 v[58:59], v[48:49], v[146:147] op_sel_hi:[1,0]
	v_pk_mul_f32 v[48:49], v[46:47], v[146:147] op_sel_hi:[1,0]
	v_cvt_pk_bf16_f32 v46, v54, v55
	v_cvt_pk_bf16_f32 v47, v56, v57
	s_nop 0
	v_cvt_pk_bf16_f32 v48, v48, v49
	v_cvt_pk_bf16_f32 v49, v58, v59
	v_mov_b32_e32 v188, v46
	v_mov_b32_e32 v189, v47
	v_mov_b32_e32 v190, v48
	v_mov_b32_e32 v191, v49
	s_nop 1
	v_add_u32_e32 v46, 0x90, v153
	v_mad_i64_i32 v[46:47], s[6:7], v46, s65, v[142:143]
	v_mov_b32_e32 v48, v147
	v_lshl_add_u64 v[46:47], v[46:47], 0, v[144:145]
	v_pk_mul_f32 v[52:53], v[52:53], v[48:49] op_sel_hi:[1,0]
	v_pk_mul_f32 v[50:51], v[50:51], v[48:49] op_sel_hi:[1,0]
	v_pk_mul_f32 v[54:55], v[44:45], v[48:49] op_sel_hi:[1,0]
	v_pk_mul_f32 v[44:45], v[42:43], v[48:49] op_sel_hi:[1,0]
	v_cvt_pk_bf16_f32 v42, v50, v51
	v_cvt_pk_bf16_f32 v43, v52, v53
	v_pk_mul_f32 v[38:39], v[38:39], v[48:49] op_sel_hi:[1,0]
	v_cvt_pk_bf16_f32 v44, v44, v45
	v_cvt_pk_bf16_f32 v45, v54, v55
	v_mov_b32_e32 v192, v42
	v_mov_b32_e32 v193, v43
	v_mov_b32_e32 v194, v44
	v_mov_b32_e32 v195, v45
	v_pk_mul_f32 v[40:41], v[40:41], v[48:49] op_sel_hi:[1,0]
	s_nop 0
	v_pk_mul_f32 v[42:43], v[32:33], v[48:49] op_sel_hi:[1,0]
	v_pk_mul_f32 v[32:33], v[30:31], v[48:49] op_sel_hi:[1,0]
	v_cvt_pk_bf16_f32 v30, v38, v39
	v_cvt_pk_bf16_f32 v31, v40, v41
	s_nop 0
	v_cvt_pk_bf16_f32 v32, v32, v33
	v_cvt_pk_bf16_f32 v33, v42, v43
	v_mov_b32_e32 v196, v30
	v_mov_b32_e32 v197, v31
	v_mov_b32_e32 v198, v32
	v_mov_b32_e32 v199, v33
	s_nop 1
	v_add_u32_e32 v30, 0xa0, v153
	v_mad_i64_i32 v[30:31], s[6:7], v30, s65, v[142:143]
	v_lshl_add_u64 v[30:31], v[30:31], 0, v[144:145]
	v_pk_mul_f32 v[32:33], v[36:37], v[140:141] op_sel_hi:[1,0]
	v_pk_mul_f32 v[36:37], v[28:29], v[140:141] op_sel_hi:[1,0]
	v_pk_mul_f32 v[28:29], v[26:27], v[140:141] op_sel_hi:[1,0]
	v_cvt_pk_bf16_f32 v26, v34, v35
	v_cvt_pk_bf16_f32 v27, v32, v33
	s_nop 0
	v_cvt_pk_bf16_f32 v28, v28, v29
	v_cvt_pk_bf16_f32 v29, v36, v37
	v_mov_b32_e32 v200, v26
	v_mov_b32_e32 v201, v27
	v_mov_b32_e32 v202, v28
	v_mov_b32_e32 v203, v29
	s_nop 1
	v_pk_mul_f32 v[26:27], v[16:17], v[140:141] op_sel_hi:[1,0]
	v_pk_mul_f32 v[16:17], v[14:15], v[140:141] op_sel_hi:[1,0]
	v_cvt_pk_bf16_f32 v14, v22, v23
	v_cvt_pk_bf16_f32 v15, v24, v25
	s_nop 0
	v_cvt_pk_bf16_f32 v16, v16, v17
	v_cvt_pk_bf16_f32 v17, v26, v27
	v_mov_b32_e32 v222, v14
	v_mov_b32_e32 v223, v15
	v_mov_b32_e32 v224, v16
	v_mov_b32_e32 v225, v17
	s_nop 1
	v_add_u32_e32 v14, 0xb0, v153
	v_mad_i64_i32 v[14:15], s[6:7], v14, s65, v[142:143]
	v_mov_b32_e32 v16, v141
	v_lshl_add_u64 v[14:15], v[14:15], 0, v[144:145]
	v_pk_mul_f32 v[20:21], v[20:21], v[16:17] op_sel_hi:[1,0]
	v_pk_mul_f32 v[18:19], v[18:19], v[16:17] op_sel_hi:[1,0]
	v_pk_mul_f32 v[22:23], v[12:13], v[16:17] op_sel_hi:[1,0]
	v_pk_mul_f32 v[12:13], v[10:11], v[16:17] op_sel_hi:[1,0]
	v_cvt_pk_bf16_f32 v10, v18, v19
	v_cvt_pk_bf16_f32 v11, v20, v21
	s_mov_b64 s[6:7], s[22:23]
	v_cvt_pk_bf16_f32 v12, v12, v13
	v_cvt_pk_bf16_f32 v13, v22, v23
	v_mov_b32_e32 v244, v10
	v_mov_b32_e32 v245, v11
	v_mov_b32_e32 v246, v12
	v_mov_b32_e32 v247, v13
	v_pk_mul_f32 v[8:9], v[8:9], v[16:17] op_sel_hi:[1,0]
	v_pk_mul_f32 v[6:7], v[6:7], v[16:17] op_sel_hi:[1,0]
	v_pk_mul_f32 v[10:11], v[4:5], v[16:17] op_sel_hi:[1,0]
	v_pk_mul_f32 v[4:5], v[2:3], v[16:17] op_sel_hi:[1,0]
	v_cvt_pk_bf16_f32 v2, v6, v7
	v_cvt_pk_bf16_f32 v3, v8, v9
	s_nop 0
	v_cvt_pk_bf16_f32 v4, v4, v5
	v_cvt_pk_bf16_f32 v5, v10, v11
	v_mov_b32_e32 v248, v2
	v_mov_b32_e32 v249, v3
	v_mov_b32_e32 v250, v4
	v_mov_b32_e32 v251, v5
	s_cbranch_vccz .LBB0_460
	global_store_dwordx4 v166, v[162:165], s[4:5]
	global_store_dwordx4 v166, v[188:191], s[4:5] offset:256
	s_nop 1
	v_add_u32_e32 v166, 0xe000, v166
	global_store_dwordx4 v166, v[192:195], s[4:5]
	global_store_dwordx4 v166, v[196:199], s[4:5] offset:256
	s_nop 1
	v_add_u32_e32 v166, 0xe000, v166
	global_store_dwordx4 v166, v[200:203], s[4:5]
	global_store_dwordx4 v166, v[222:225], s[4:5] offset:256
	s_nop 1
	v_add_u32_e32 v166, 0xe000, v166
	global_store_dwordx4 v166, v[244:247], s[4:5]
	global_store_dwordx4 v166, v[248:251], s[4:5] offset:256
	s_nop 1
	v_mov_b64_e32 v[164:165], 0x200
	v_mbcnt_lo_u32_b32 v193, -1, 0
	v_mbcnt_hi_u32_b32 v193, -1, v193
	v_mov_b32_e32 v188, 1
	v_mov_b32_e32 v189, 0x358637bd
	v_mov_b32_e32 v190, 0x260
	v_mov_b32_e32 v191, 0x3c0881c4
	v_mov_b32_e32 v192, 0xbab64f3b
	v_mov_b32_e32 v194, 0xf149f2ca
	v_mov_b32_e32 v195, 0xc0
	v_mov_b32_e32 v196, 0x70
	v_mov_b32_e32 v197, 0x71
	v_mov_b32_e32 v198, 5
	v_mov_b32_e32 v199, 2
	v_mov_b32_e32 v200, 3
	v_not_b32_e32 v201, 63
	v_not_b32_e32 v202, 31
	v_mov_b32_e32 v203, 0x7fc00000
	v_mov_b32_e32 v222, 0
	v_mov_b32_e32 v223, 0
	v_mov_b32_e32 v224, 0
	v_mov_b32_e32 v225, 0
	s_waitcnt vmcnt(0)
	v_readlane_b32 s70, v254, 40
	v_readlane_b32 s84, v254, 42
	s_cmpk_gt_u32 s18, 0xff
	v_readlane_b32 s71, v254, 41
	v_readlane_b32 s86, v254, 44
	v_readlane_b32 s87, v254, 45
	v_readlane_b32 s85, v254, 43
	s_cbranch_scc1 .LBB0_467
	s_barrier
